# packed f32 VALU ops split into scalar pairs everywhere (bit-identical)
# speedup vs baseline: 1.0091x; 1.0091x over previous
; __device__ void phase_prologue(const Params& p, char* lds) {
;     ...
;     for (int item = blockIdx.x; item < 192; item += gridDim.x) {
;       const int l = item / 96, n0 = (item % 96) * 32, col = tid & 31, kg = tid >> 5;
;       float acc[9];
; #pragma unroll
;       for (int bi = 0; bi < 9; ++bi) acc[bi] = 0.f;
;       const float* wp = p.in[5] + ((size_t)l * 1024 + kg * 64) * 3072 + n0 + col;
;       for (int kk = 0; kk < 64; ++kk) {
;         const float w = wp[(size_t)kk * 3072];
; #pragma unroll
;         for (int bi = 0; bi < 9; ++bi) acc[bi] += sil[bi * 1024 + kg * 64 + kk] * w;
;       }
; #pragma unroll
;       for (int bi = 0; bi < 9; ++bi) red[(kg * 9 + bi) * 32 + col] = acc[bi];
;       __syncthreads();
;       if (tid < 288) {
;         const int bi = tid >> 5;
;         float s = 0.f;
; #pragma unroll
;         for (int g = 0; g < 16; ++g) s += red[(g * 9 + bi) * 32 + col];
;         mod[((size_t)l * 9 + bi) * 3072 + n0 + col] = s + p.in[6][l * 3072 + n0 + col];
;       }
;       __syncthreads();
;     }
.LBB0_16:
	v_lshl_add_u64 v[22:23], v[8:9], 0, s[8:9]
	v_add_co_u32_e64 v24, s[0:1], s2, v22
	global_load_dword v58, v[22:23], off
	s_nop 0
	v_addc_co_u32_e64 v25, s[0:1], 0, v23, s[0:1]
	v_add_co_u32_e64 v26, s[0:1], s10, v22
	s_add_u32 s8, s8, 0xc000
	s_nop 0
	v_addc_co_u32_e64 v27, s[0:1], 0, v23, s[0:1]
	v_add_co_u32_e64 v22, s[0:1], s11, v22
	s_addc_u32 s9, s9, 0
	s_nop 0
	v_addc_co_u32_e64 v23, s[0:1], 0, v23, s[0:1]
	global_load_dword v60, v[24:25], off
	global_load_dword v62, v[26:27], off
	global_load_dword v64, v[22:23], off
	ds_read_b128 v[22:25], v21 offset:4096
	ds_read_b128 v[26:29], v21 offset:8192
	ds_read_b128 v[30:33], v21 offset:12288
	ds_read_b128 v[34:37], v21 offset:16384
	ds_read_b128 v[38:41], v21 offset:20480
	ds_read_b128 v[42:45], v21 offset:24576
	ds_read_b128 v[46:49], v21 offset:28672
	ds_read_b128 v[50:53], v21
	ds_read_b128 v[54:57], v21 offset:32768
	s_waitcnt lgkmcnt(7)
	v_mov_b32_e32 v66, v26
	v_mov_b32_e32 v67, v22
	v_mov_b32_e32 v22, v27
	v_mov_b32_e32 v26, v28
	v_mov_b32_e32 v27, v24
	v_mov_b32_e32 v24, v29
	s_waitcnt lgkmcnt(5)
	v_mov_b32_e32 v28, v34
	v_mov_b32_e32 v29, v30
	v_mov_b32_e32 v30, v35
	v_mov_b32_e32 v34, v36
	v_mov_b32_e32 v35, v32
	v_mov_b32_e32 v32, v37
	s_waitcnt lgkmcnt(3)
	v_mov_b32_e32 v36, v42
	v_mov_b32_e32 v37, v38
	v_mov_b32_e32 v38, v43
	v_mov_b32_e32 v42, v44
	v_mov_b32_e32 v43, v40
	v_mov_b32_e32 v40, v45
	s_waitcnt lgkmcnt(0)
	v_mov_b32_e32 v44, v54
	v_mov_b32_e32 v45, v46
	v_mov_b32_e32 v46, v55
	v_mov_b32_e32 v54, v56
	v_mov_b32_e32 v55, v48
	v_mov_b32_e32 v48, v57
	v_add_u32_e32 v21, 16, v21
	s_cmp_lg_u32 s8, 0xc0000
	s_waitcnt vmcnt(3)
	v_fmac_f32_e32 v20, v58, v50
	v_fma_f32 v16, v58, v66, v16
	v_fma_f32 v17, v58, v67, v17
	v_fma_f32 v14, v58, v28, v14
	v_fma_f32 v15, v58, v29, v15
	v_fma_f32 v12, v58, v36, v12
	v_fma_f32 v13, v58, v37, v13
	v_fma_f32 v10, v58, v44, v10
	v_fma_f32 v11, v58, v45, v11
	s_waitcnt vmcnt(2)
	v_fmac_f32_e32 v20, v60, v51
	v_fma_f32 v16, v60, v22, v16
	v_fma_f32 v17, v60, v23, v17
	v_fma_f32 v14, v60, v30, v14
	v_fma_f32 v15, v60, v31, v15
	v_fma_f32 v12, v60, v38, v12
	v_fma_f32 v13, v60, v39, v13
	v_fma_f32 v10, v60, v46, v10
	v_fma_f32 v11, v60, v47, v11
	s_waitcnt vmcnt(1)
	v_fmac_f32_e32 v20, v62, v52
	v_fma_f32 v16, v62, v26, v16
	v_fma_f32 v17, v62, v27, v17
	v_fma_f32 v14, v62, v34, v14
	v_fma_f32 v15, v62, v35, v15
	v_fma_f32 v12, v62, v42, v12
	v_fma_f32 v13, v62, v43, v13
	v_fma_f32 v10, v62, v54, v10
	v_fma_f32 v11, v62, v55, v11
	s_waitcnt vmcnt(0)
	v_fmac_f32_e32 v20, v64, v53
	v_fma_f32 v16, v64, v24, v16
	v_fma_f32 v17, v64, v25, v17
	v_fma_f32 v14, v64, v32, v14
	v_fma_f32 v15, v64, v33, v15
	v_fma_f32 v12, v64, v40, v12
	v_fma_f32 v13, v64, v41, v13
	v_fma_f32 v10, v64, v48, v10
	v_fma_f32 v11, v64, v49, v11
	s_cbranch_scc1 .LBB0_16
	v_add_u32_e32 v8, 0x9000, v18
	ds_write2_b32 v8, v20, v17 offset1:32
	ds_write2_b32 v8, v16, v15 offset0:64 offset1:96
	ds_write2_b32 v8, v14, v13 offset0:128 offset1:160
	ds_write2_b32 v8, v12, v11 offset0:192 offset1:224
	ds_write_b32 v18, v10 offset:37888
	s_waitcnt lgkmcnt(0)
	s_barrier
	s_and_saveexec_b64 s[0:1], vcc
	s_cbranch_execz .LBB0_14
	s_mul_i32 s7, s6, 0xc00
	s_add_i32 s7, s7, s4
	v_or_b32_e32 v8, s7, v180
	v_ashrrev_i32_e32 v9, 31, v8
	v_lshl_add_u64 v[8:9], v[8:9], 2, s[48:49]
	global_load_dword v12, v[8:9], off
	v_mad_i64_i32 v[8:9], s[6:7], s6, 9, v[184:185]
	v_mov_b64_e32 v[10:11], s[38:39]
	v_mad_u64_u32 v[10:11], s[6:7], v8, s2, v[10:11]
	v_mad_i32_i24 v11, v9, s2, v11
	ds_read_b32 v13, v19 offset:36864
	ds_read_b32 v14, v19 offset:38016
	ds_read_b32 v15, v19 offset:39168
	ds_read_b32 v16, v19 offset:40320
	ds_read_b32 v17, v19 offset:41472
	ds_read_b32 v20, v19 offset:42624
	ds_read_b32 v21, v19 offset:43776
	ds_read_b32 v22, v19 offset:44928
	ds_read_b32 v23, v19 offset:46080
	ds_read_b32 v24, v19 offset:47232
	ds_read_b32 v25, v19 offset:48384
	ds_read_b32 v26, v19 offset:49536
	ds_read_b32 v27, v19 offset:50688
	ds_read_b32 v28, v19 offset:51840
	ds_read_b32 v29, v19 offset:52992
	ds_read_b32 v30, v19 offset:54144
	v_lshl_add_u64 v[8:9], s[4:5], 2, v[10:11]
	s_waitcnt lgkmcnt(14)
	v_add_f32_e32 v10, 0, v13
	v_add_f32_e32 v10, v10, v14
	s_waitcnt lgkmcnt(13)
	v_add_f32_e32 v10, v10, v15
	s_waitcnt lgkmcnt(12)
	v_add_f32_e32 v10, v10, v16
	s_waitcnt lgkmcnt(11)
	v_add_f32_e32 v10, v10, v17
	s_waitcnt lgkmcnt(10)
	v_add_f32_e32 v10, v10, v20
	s_waitcnt lgkmcnt(9)
	v_add_f32_e32 v10, v10, v21
	s_waitcnt lgkmcnt(8)
	v_add_f32_e32 v10, v10, v22
	s_waitcnt lgkmcnt(7)
	v_add_f32_e32 v10, v10, v23
	s_waitcnt lgkmcnt(6)
	v_add_f32_e32 v10, v10, v24
	s_waitcnt lgkmcnt(5)
	v_add_f32_e32 v10, v10, v25
	s_waitcnt lgkmcnt(4)
	v_add_f32_e32 v10, v10, v26
	s_waitcnt lgkmcnt(3)
	v_add_f32_e32 v10, v10, v27
	s_waitcnt lgkmcnt(2)
	v_add_f32_e32 v10, v10, v28
	s_waitcnt lgkmcnt(1)
	v_add_f32_e32 v10, v10, v29
	s_waitcnt lgkmcnt(0)
	v_add_f32_e32 v10, v10, v30
	v_lshl_add_u64 v[8:9], v[8:9], 0, v[4:5]
	s_waitcnt vmcnt(0)
	v_add_f32_e32 v10, v10, v12
	global_store_dword v[8:9], v10, off
	s_branch .LBB0_14

; __device__ __forceinline__ unsigned cvtpk(float lo, float hi) { f32x2 v = {lo, hi}; bf16x2_t b = __builtin_convertvector(v, bf16x2_t); return *(unsigned*)&b; }
; __device__ __forceinline__ void fin_row(const float* mod, const f32x4 (&g4)[4], int lane, const RowX& r, float (&h)[16]) {
;   float ss = 0.f;
; #pragma unroll
;   for (int i = 0; i < 4; ++i) ss += r.v[i][0] * r.v[i][0] + r.v[i][1] * r.v[i][1] + r.v[i][2] * r.v[i][2] + r.v[i][3] * r.v[i][3];
;   ss = wave_sum(ss);
;   const float rstd = rsqrtf(ss * (1.f / 1024.f) + 1e-6f);
;   const float* m = mod + r.bi * 3072;
; #pragma unroll
;   for (int i = 0; i < 4; ++i) {
;     const int c = i * 256 + lane * 4;
;     const f32x4 sh = *(const f32x4*)(m + c), sc = *(const f32x4*)(m + 1024 + c);
; #pragma unroll
;     for (int e = 0; e < 4; ++e) {
;       const float hv = r.v[i][e] * rstd * g4[i][e] * (1.f + sc[e]) + sh[e];
;       h[4 * i + e] = __uint_as_float(cvtpk(hv, 0.f) << 16);
;     }
;   }
; }
; __device__ void phase_norm_lerp(const Params& p, const float* mod) {
;     ...
;   if (r0 > 0) fin_row(mod, g4, lane, xc, hp);
;   else {
; #pragma unroll
;     for (int e = 0; e < 16; ++e) hp[e] = 0.f;
;   }
.LBB0_48:
	s_or_saveexec_b64 s[4:5], s[4:5]
	v_mov_b32_e32 v191, 0
	v_mov_b32_e32 v196, 0
	v_mov_b32_e32 v197, 0
	v_mov_b32_e32 v194, 0
	v_mov_b32_e32 v195, 0
	v_mov_b32_e32 v200, 0
	v_mov_b32_e32 v201, 0
	v_mov_b32_e32 v198, 0
	v_mov_b32_e32 v199, 0
	v_mov_b32_e32 v204, 0
	v_mov_b32_e32 v205, 0
	v_mov_b32_e32 v202, 0
	v_mov_b32_e32 v203, 0
	v_mov_b32_e32 v214, 0
	v_mov_b32_e32 v215, 0
	v_mov_b32_e32 v212, 0
	v_mov_b32_e32 v213, 0
	s_xor_b64 exec, exec, s[4:5]
	s_cbranch_execz .LBB0_50
	s_waitcnt vmcnt(6)
	v_mov_b32_e32 v132, v85
	v_mov_b32_e32 v133, v81
	v_mov_b32_e32 v130, v84
	v_mov_b32_e32 v131, v80
	v_mul_f32_e64 v132, v132, v132
	v_mul_f32_e64 v133, v133, v133
	s_waitcnt vmcnt(4)
	v_mov_b32_e32 v134, v93
	v_fma_f32 v130, v130, v130, v132
	v_fma_f32 v131, v131, v131, v133
	v_mov_b32_e32 v132, v86
	v_mov_b32_e32 v133, v82
	v_fma_f32 v130, v132, v132, v130
	v_fma_f32 v131, v133, v133, v131
	v_mov_b32_e32 v132, v87
	v_mov_b32_e32 v133, v83
	v_mov_b32_e32 v135, v89
	v_fma_f32 v130, v132, v132, v130
	v_fma_f32 v131, v133, v133, v131
	v_mov_b32_e32 v132, v92
	v_mov_b32_e32 v133, v88
	v_mul_f32_e64 v134, v134, v134
	v_mul_f32_e64 v135, v135, v135
	v_add_f32_e32 v130, v130, v131
	v_fma_f32 v132, v132, v132, v134
	v_fma_f32 v133, v133, v133, v135
	v_mov_b32_e32 v134, v94
	v_mov_b32_e32 v135, v90
	v_fma_f32 v132, v134, v134, v132
	v_fma_f32 v133, v135, v135, v133
	v_mov_b32_e32 v134, v95
	v_mov_b32_e32 v135, v91
	v_fma_f32 v132, v134, v134, v132
	v_fma_f32 v133, v135, v135, v133
	s_movk_i32 s0, 0xc00
	v_add_f32_e32 v130, v133, v130
	v_add_f32_e32 v134, v132, v130
	v_mbcnt_lo_u32_b32 v130, -1, 0
	v_mbcnt_hi_u32_b32 v137, -1, v130
	v_and_b32_e32 v130, 64, v137
	v_add_u32_e32 v138, 64, v130
	v_xor_b32_e32 v139, 32, v137
	v_cmp_lt_i32_e32 vcc, v139, v138
	v_xor_b32_e32 v140, 16, v137
	v_xor_b32_e32 v141, 8, v137
	v_cndmask_b32_e32 v130, v137, v139, vcc
	v_lshlrev_b32_e32 v130, 2, v130
	ds_bpermute_b32 v135, v130, v134
	v_mul_lo_u32 v130, v181, s0
	v_ashrrev_i32_e32 v131, 31, v130
	v_lshl_add_u64 v[132:133], v[130:131], 2, s[38:39]
	s_mov_b64 s[0:1], 0x1000
	v_lshl_add_u64 v[168:169], v[132:133], 0, s[0:1]
	v_mov_b32_e32 v131, 0
	v_mov_b32_e32 v130, v190
	v_lshl_add_u64 v[172:173], v[132:133], 0, v[130:131]
	v_lshl_add_u64 v[132:133], v[168:169], 0, v[130:131]
	v_cmp_lt_i32_e32 vcc, v140, v138
	global_load_dwordx4 v[144:147], v[132:133], off
	global_load_dwordx4 v[148:151], v[172:173], off
	v_cndmask_b32_e32 v132, v137, v140, vcc
	s_waitcnt lgkmcnt(0)
	v_add_f32_e32 v130, v134, v135
	v_lshlrev_b32_e32 v132, 2, v132
	ds_bpermute_b32 v132, v132, v130
	v_cmp_lt_i32_e32 vcc, v141, v138
	v_mov_b32_e32 v133, v131
	v_xor_b32_e32 v142, 4, v137
	v_xor_b32_e32 v143, 2, v137
	s_waitcnt lgkmcnt(0)
	v_add_f32_e32 v134, v130, v132
	v_cndmask_b32_e32 v130, v137, v141, vcc
	v_lshlrev_b32_e32 v130, 2, v130
	ds_bpermute_b32 v135, v130, v134
	v_or_b32_e32 v130, 0x100, v136
	v_lshlrev_b32_e32 v132, 2, v130
	v_lshl_add_u64 v[132:133], v[168:169], 0, v[132:133]
	v_cmp_lt_i32_e32 vcc, v142, v138
	global_load_dwordx4 v[152:155], v[132:133], off
	global_load_dwordx4 v[156:159], v[172:173], off offset:1024
	v_cndmask_b32_e32 v133, v137, v142, vcc
	s_waitcnt lgkmcnt(0)
	v_add_f32_e32 v132, v134, v135
	v_lshlrev_b32_e32 v133, 2, v133
	ds_bpermute_b32 v133, v133, v132
	v_cmp_lt_i32_e32 vcc, v143, v138
	v_mov_b32_e32 v135, v131
	v_xor_b32_e32 v193, 1, v137
	s_mov_b32 s0, 0x800000
	s_waitcnt lgkmcnt(0)
	v_add_f32_e32 v133, v132, v133
	v_cndmask_b32_e32 v132, v137, v143, vcc
	v_lshlrev_b32_e32 v132, 2, v132
	ds_bpermute_b32 v170, v132, v133
	v_or_b32_e32 v132, 0x200, v136
	v_lshlrev_b32_e32 v134, 2, v132
	v_lshl_add_u64 v[134:135], v[168:169], 0, v[134:135]
	v_cmp_lt_i32_e32 vcc, v193, v138
	global_load_dwordx4 v[160:163], v[134:135], off
	global_load_dwordx4 v[164:167], v[172:173], off offset:2048
	v_cndmask_b32_e32 v134, v137, v193, vcc
	s_waitcnt lgkmcnt(0)
	v_add_f32_e32 v133, v133, v170
	v_lshlrev_b32_e32 v134, 2, v134
	ds_bpermute_b32 v134, v134, v133
	v_mov_b32_e32 v171, v131
	s_waitcnt lgkmcnt(0)
	v_add_f32_e32 v133, v133, v134
	v_mov_b32_e32 v134, 0x358637bd
	v_fmac_f32_e32 v134, 0x3a800000, v133
	v_mul_f32_e32 v133, 0x4b800000, v134
	v_cmp_gt_f32_e32 vcc, s0, v134
	s_nop 1
	v_cndmask_b32_e32 v133, v134, v133, vcc
	v_or_b32_e32 v134, 0x300, v136
	v_lshlrev_b32_e32 v170, 2, v134
	v_lshl_add_u64 v[168:169], v[168:169], 0, v[170:171]
	global_load_dwordx4 v[168:171], v[168:169], off
	s_nop 0
	global_load_dwordx4 v[172:175], v[172:173], off offset:3072
	v_rsq_f32_e32 v133, v133
	s_nop 0
	v_mul_f32_e32 v135, 0x45800000, v133
	v_cndmask_b32_e32 v136, v133, v135, vcc
	v_mul_f32_e32 v133, v80, v136
	v_mul_f32_e32 v133, v0, v133
	s_waitcnt vmcnt(7)
	v_add_f32_e32 v135, 1.0, v144
	s_waitcnt vmcnt(6)
	v_fma_f32 v133, v135, v133, v148
	v_mul_f32_e32 v135, v81, v136
	v_mul_f32_e32 v135, v1, v135
	v_add_f32_e32 v144, 1.0, v145
	v_cvt_pk_bf16_f32 v133, v133, 0
	v_fma_f32 v135, v144, v135, v149
	v_cvt_pk_bf16_f32 v135, v135, 0
	v_lshlrev_b32_e32 v194, 16, v133
	v_mul_f32_e32 v133, v82, v136
	v_lshlrev_b32_e32 v195, 16, v135
	v_mul_f32_e32 v133, v2, v133
	v_add_f32_e32 v135, 1.0, v146
	v_fma_f32 v133, v135, v133, v150
	v_mul_f32_e32 v135, v83, v136
	v_mul_f32_e32 v135, v3, v135
	v_add_f32_e32 v144, 1.0, v147
	v_cvt_pk_bf16_f32 v133, v133, 0
	v_fmac_f32_e32 v151, v144, v135
	v_cvt_pk_bf16_f32 v135, v151, 0
	v_lshlrev_b32_e32 v196, 16, v133
	v_mul_f32_e32 v133, v84, v136
	v_lshlrev_b32_e32 v197, 16, v135
	v_mul_f32_e32 v133, v56, v133
	s_waitcnt vmcnt(5)
	v_add_f32_e32 v135, 1.0, v152
	s_waitcnt vmcnt(4)
; __device__ __forceinline__ unsigned cvtpk(float lo, float hi) { f32x2 v = {lo, hi}; bf16x2_t b = __builtin_convertvector(v, bf16x2_t); return *(unsigned*)&b; }
; __device__ __forceinline__ void fin_row(const float* mod, const f32x4 (&g4)[4], int lane, const RowX& r, float (&h)[16]) {
;     ...
;   for (int i = 0; i < 4; ++i) {
;     const int c = i * 256 + lane * 4;
;     const f32x4 sh = *(const f32x4*)(m + c), sc = *(const f32x4*)(m + 1024 + c);
; #pragma unroll
;     for (int e = 0; e < 4; ++e) {
;       const float hv = r.v[i][e] * rstd * g4[i][e] * (1.f + sc[e]) + sh[e];
;       h[4 * i + e] = __uint_as_float(cvtpk(hv, 0.f) << 16);
;     }
;   }
	v_fma_f32 v133, v135, v133, v156
	v_mul_f32_e32 v135, v85, v136
	v_mul_f32_e32 v135, v57, v135
	v_add_f32_e32 v144, 1.0, v153
	v_cvt_pk_bf16_f32 v133, v133, 0
	v_fma_f32 v135, v144, v135, v157
	v_cvt_pk_bf16_f32 v135, v135, 0
	v_lshlrev_b32_e32 v198, 16, v133
	v_mul_f32_e32 v133, v86, v136
	v_lshlrev_b32_e32 v199, 16, v135
	v_mul_f32_e32 v133, v58, v133
	v_add_f32_e32 v135, 1.0, v154
	v_fma_f32 v133, v135, v133, v158
	v_mul_f32_e32 v135, v87, v136
	v_mul_f32_e32 v135, v59, v135
	v_add_f32_e32 v144, 1.0, v155
	v_fmac_f32_e32 v159, v144, v135
	v_cvt_pk_bf16_f32 v135, v159, 0
	v_lshlrev_b32_e32 v201, 16, v135
	v_mul_f32_e32 v135, v88, v136
	v_mul_f32_e32 v135, v64, v135
	s_waitcnt vmcnt(3)
	v_add_f32_e32 v144, 1.0, v160
	s_waitcnt vmcnt(2)
	v_fma_f32 v135, v144, v135, v164
	v_mul_f32_e32 v144, v89, v136
	v_mul_f32_e32 v144, v65, v144
	v_add_f32_e32 v145, 1.0, v161
	v_cvt_pk_bf16_f32 v135, v135, 0
	v_fma_f32 v144, v145, v144, v165
	v_cvt_pk_bf16_f32 v144, v144, 0
	v_lshlrev_b32_e32 v202, 16, v135
	v_mul_f32_e32 v135, v90, v136
	v_lshlrev_b32_e32 v203, 16, v144
	v_mul_f32_e32 v135, v66, v135
	v_add_f32_e32 v144, 1.0, v162
	v_fma_f32 v135, v144, v135, v166
	v_mul_f32_e32 v144, v91, v136
	v_mul_f32_e32 v144, v67, v144
	v_add_f32_e32 v145, 1.0, v163
	v_fmac_f32_e32 v167, v145, v144
	v_cvt_pk_bf16_f32 v144, v167, 0
	v_lshlrev_b32_e32 v205, 16, v144
	v_mul_f32_e32 v144, v92, v136
	v_mul_f32_e32 v144, v72, v144
	s_waitcnt vmcnt(1)
	v_add_f32_e32 v145, 1.0, v168
	s_waitcnt vmcnt(0)
	v_fma_f32 v144, v145, v144, v172
	v_mul_f32_e32 v145, v93, v136
	v_mul_f32_e32 v145, v73, v145
	v_add_f32_e32 v146, 1.0, v169
	v_cvt_pk_bf16_f32 v144, v144, 0
	v_fma_f32 v145, v146, v145, v173
	v_cvt_pk_bf16_f32 v145, v145, 0
	v_lshlrev_b32_e32 v212, 16, v144
	v_mul_f32_e32 v144, v94, v136
	v_lshlrev_b32_e32 v213, 16, v145
	v_mul_f32_e32 v144, v74, v144
	v_add_f32_e32 v145, 1.0, v170
	v_mul_f32_e32 v136, v95, v136
	v_fma_f32 v144, v145, v144, v174
	v_mul_f32_e32 v136, v75, v136
	v_add_f32_e32 v145, 1.0, v171
	v_fmac_f32_e32 v175, v145, v136
	v_cvt_pk_bf16_f32 v133, v133, 0
	v_cvt_pk_bf16_f32 v135, v135, 0
	v_cvt_pk_bf16_f32 v144, v144, 0
	v_cvt_pk_bf16_f32 v136, v175, 0
	v_lshlrev_b32_e32 v200, 16, v133
	v_mov_b32_e32 v133, v131
	v_lshlrev_b32_e32 v204, 16, v135
	v_mov_b32_e32 v135, v131
	v_lshlrev_b32_e32 v214, 16, v144
	v_lshlrev_b32_e32 v215, 16, v136
; __device__ __forceinline__ void fin_row(const float* mod, const f32x4 (&g4)[4], int lane, const RowX& r, float (&h)[16]) {
;   float ss = 0.f;
; #pragma unroll
;   for (int i = 0; i < 4; ++i) ss += r.v[i][0] * r.v[i][0] + r.v[i][1] * r.v[i][1] + r.v[i][2] * r.v[i][2] + r.v[i][3] * r.v[i][3];
;   ss = wave_sum(ss);
;   const float rstd = rsqrtf(ss * (1.f / 1024.f) + 1e-6f);
; __device__ void phase_norm_lerp(const Params& p, const float* mod) {
;     ...
;   fin_row(mod, g4, lane, xa, hc);
;   xa = xb;
;   if (r0 + 2 < NTOK) ld_row(p, r0 + 2, lane, xb);
.LBB0_50:
	s_or_b64 exec, exec, s[4:5]
	v_lshl_add_u64 v[128:129], v[128:129], 2, s[38:39]
	s_mov_b64 s[0:1], 0x1000
	v_lshlrev_b64 v[206:207], 2, v[130:131]
	v_lshl_add_u64 v[144:145], v[128:129], 0, s[0:1]
	v_lshl_add_u64 v[146:147], v[128:129], 0, v[190:191]
	v_lshl_add_u64 v[130:131], v[128:129], 0, v[206:207]
	v_lshlrev_b64 v[208:209], 2, v[132:133]
	v_lshlrev_b64 v[210:211], 2, v[134:135]
	v_lshl_add_u64 v[148:149], v[144:145], 0, v[190:191]
	global_load_dwordx4 v[168:171], v[146:147], off
	global_load_dwordx4 v[172:175], v[148:149], off
	v_lshl_add_u64 v[146:147], v[144:145], 0, v[206:207]
	global_load_dwordx4 v[160:163], v[130:131], off
	global_load_dwordx4 v[164:167], v[146:147], off
	v_lshl_add_u64 v[130:131], v[128:129], 0, v[208:209]
	v_lshl_add_u64 v[128:129], v[128:129], 0, v[210:211]
	v_lshl_add_u64 v[132:133], v[144:145], 0, v[208:209]
	global_load_dwordx4 v[152:155], v[130:131], off
	global_load_dwordx4 v[156:159], v[132:133], off
	v_lshl_add_u64 v[130:131], v[144:145], 0, v[210:211]
	global_load_dwordx4 v[144:147], v[128:129], off
	global_load_dwordx4 v[148:151], v[130:131], off
	s_waitcnt vmcnt(11)
	v_mov_b32_e32 v218, v125
	s_waitcnt vmcnt(10)
	v_mov_b32_e32 v219, v121
	v_mov_b32_e32 v216, v124
	v_mov_b32_e32 v217, v120
	v_mul_f32_e64 v128, v218, v218
	v_mul_f32_e64 v129, v219, v219
	v_mov_b32_e32 v130, v126
	v_fma_f32 v128, v216, v216, v128
	v_fma_f32 v129, v217, v217, v129
	v_mov_b32_e32 v131, v122
	v_fma_f32 v128, v130, v130, v128
	v_fma_f32 v129, v131, v131, v129
	v_mov_b32_e32 v130, v127
	v_mov_b32_e32 v131, v123
	s_waitcnt vmcnt(9)
	v_mov_b32_e32 v132, v117
	s_waitcnt vmcnt(8)
	v_mov_b32_e32 v133, v113
	v_fma_f32 v128, v130, v130, v128
	v_fma_f32 v129, v131, v131, v129
	v_mov_b32_e32 v130, v116
	v_mov_b32_e32 v131, v112
	v_mul_f32_e64 v132, v132, v132
	v_mul_f32_e64 v133, v133, v133
	v_add_f32_e32 v128, v128, v129
	v_fma_f32 v130, v130, v130, v132
	v_fma_f32 v131, v131, v131, v133
	v_mov_b32_e32 v132, v118
	v_mov_b32_e32 v133, v114
	v_fma_f32 v130, v132, v132, v130
	v_fma_f32 v131, v133, v133, v131
	v_mov_b32_e32 v132, v119
	v_mov_b32_e32 v133, v115
	v_fma_f32 v130, v132, v132, v130
	v_fma_f32 v131, v133, v133, v131
	v_cmp_lt_i32_e32 vcc, v139, v138
	v_add_f32_e32 v128, v128, v130
	v_add_f32_e32 v128, v128, v131
	v_cndmask_b32_e32 v129, v137, v139, vcc
	v_lshlrev_b32_e32 v185, 2, v129
	ds_bpermute_b32 v129, v185, v128
	v_cmp_lt_i32_e32 vcc, v140, v138
	s_mov_b32 s0, 0x107fe
	v_mov_b64_e32 v[134:135], v[106:107]
	v_mov_b64_e32 v[132:133], v[104:105]
	s_waitcnt lgkmcnt(0)
	v_add_f32_e32 v128, v128, v129
	v_cndmask_b32_e32 v129, v137, v140, vcc
	v_lshlrev_b32_e32 v187, 2, v129
	ds_bpermute_b32 v129, v187, v128
	v_cmp_lt_i32_e32 vcc, v141, v138
	v_mov_b32_e32 v223, v183
	s_waitcnt lgkmcnt(0)
	v_add_f32_e32 v128, v128, v129
	v_cndmask_b32_e32 v129, v137, v141, vcc
	v_lshlrev_b32_e32 v189, 2, v129
	ds_bpermute_b32 v129, v189, v128
	v_cmp_lt_i32_e32 vcc, v142, v138
	s_waitcnt lgkmcnt(0)
	v_add_f32_e32 v128, v128, v129
	v_cndmask_b32_e32 v129, v137, v142, vcc
	v_lshlrev_b32_e32 v218, 2, v129
	ds_bpermute_b32 v129, v218, v128
	v_cmp_lt_i32_e32 vcc, v143, v138
	s_waitcnt lgkmcnt(0)
	v_add_f32_e32 v128, v128, v129
	v_cndmask_b32_e32 v129, v137, v143, vcc
	v_lshlrev_b32_e32 v219, 2, v129
	ds_bpermute_b32 v129, v219, v128
	v_cmp_lt_i32_e32 vcc, v193, v138
	v_mov_b64_e32 v[142:143], v[98:99]
	v_mov_b64_e32 v[140:141], v[96:97]
	s_waitcnt lgkmcnt(0)
	v_add_f32_e32 v216, v128, v129
	v_cndmask_b32_e32 v128, v137, v193, vcc
	v_lshlrev_b32_e32 v220, 2, v128
	ds_bpermute_b32 v193, v220, v216
	v_mov_b64_e32 v[130:131], v[110:111]
	v_mov_b64_e32 v[138:139], v[102:103]
	v_cmp_gt_i32_e32 vcc, s0, v192
	v_mov_b64_e32 v[128:129], v[108:109]
	v_mov_b64_e32 v[136:137], v[100:101]
	s_and_saveexec_b64 s[4:5], vcc
	s_cbranch_execz .LBB0_56
	v_add_u32_e32 v129, 2, v192
	s_mov_b32 s0, 0x3e0f83e1
	v_mul_hi_i32 v128, v129, s0
	v_lshrrev_b32_e32 v130, 31, v128
	v_ashrrev_i32_e32 v128, 11, v128
	v_add_u32_e32 v128, v128, v130
	s_movk_i32 s0, 0xdf00
	v_mad_i32_i24 v130, v128, s0, v129
	s_movk_i32 s0, 0x1fff
	v_cmp_lt_i32_e32 vcc, s0, v130
	v_mov_b64_e32 v[132:133], s[36:37]
	s_and_saveexec_b64 s[0:1], vcc
	s_xor_b64 s[6:7], exec, s[0:1]
	v_add_u32_e32 v130, 0xffffe000, v130
	v_mov_b32_e32 v131, 0
	v_mov_b64_e32 v[132:133], s[40:41]
	s_or_saveexec_b64 s[6:7], s[6:7]
	v_mov_b32_e32 v223, 8
	v_mov_b64_e32 v[134:135], 20
	s_xor_b64 exec, exec, s[6:7]
	v_ashrrev_i32_e32 v131, 31, v130
	v_mov_b64_e32 v[134:135], 25
	v_mov_b32_e32 v223, v128
	s_or_b64 exec, exec, s[6:7]
	v_ashrrev_i32_e32 v129, 31, v128
	v_lshlrev_b64 v[128:129], v134, v[128:129]
	v_lshl_add_u64 v[128:129], v[132:133], 0, v[128:129]
	v_lshlrev_b64 v[130:131], 12, v[130:131]
	v_lshl_add_u64 v[128:129], v[128:129], 0, v[130:131]
	v_mov_b32_e32 v191, 0
	v_lshl_add_u64 v[140:141], v[128:129], 0, v[190:191]
	global_load_dwordx4 v[128:131], v[140:141], off
	global_load_dwordx4 v[132:135], v[140:141], off offset:1024
	global_load_dwordx4 v[136:139], v[140:141], off offset:2048
	s_nop 0
	global_load_dwordx4 v[140:143], v[140:141], off offset:3072

; __device__ __forceinline__ void st_bf16x4_nt(bf16_t* p, float a, float b, float c, float d) { u32x2 w = {cvtpk(a, b), cvtpk(c, d)}; __builtin_nontemporal_store(w, (u32x2*)p); }
; __device__ void phase_norm_lerp(const Params& p, const float* mod) {
;     ...
;   for (int n = r0; n < r1; ++n) {
;     const int t = n % TL;
;     if (n + 3 < NTOK) ld_row(p, n + 3, lane, xc);
;     if (n + 1 < NTOK) fin_row(mod, g4, lane, xa, hn);
;     else {
; #pragma unroll
;       for (int e = 0; e < 16; ++e) hn[e] = 0.f;
;     }
;     const float fp = (t != 0 && t != T) ? 0.5f : 0.f, fn = (t != T - 1 && t != TL - 1) ? 0.5f : 0.f;
; #pragma unroll
;     for (int i = 0; i < 4; ++i) st_bf16x4_nt(H + (size_t)n * 1024 + i * 256 + lane * 4, hc[4 * i], hc[4 * i + 1], hc[4 * i + 2], hc[4 * i + 3]);
; #pragma unroll
;     for (int j = 0; j < 4; ++j) {
;       bf16_t* dst = lerp_base(p, j, n) + (size_t)n * 1024 + lane * 4;
; #pragma unroll
;       for (int i = 0; i < 4; ++i) {
;         float o[4];
; #pragma unroll
;         for (int e = 0; e < 4; ++e) { const float c = hc[4 * i + e]; o[e] = c + (fp * hp[4 * i + e] + fn * hn[4 * i + e] - c) * mu[j][4 * i + e]; }
;         st_bf16x4_nt(dst + i * 256, o[0], o[1], o[2], o[3]);
;       }
;     }
.LBB0_57:
	s_or_b64 exec, exec, s[4:5]
	v_mul_hi_i32 v96, v128, s19
	v_lshrrev_b32_e32 v97, 31, v96
	v_ashrrev_i32_e32 v96, 11, v96
	v_add_u32_e32 v96, v96, v97
	v_mul_i32_i24_e32 v96, 0x2100, v96
	v_sub_u32_e32 v96, v128, v96
	v_and_b32_e32 v100, 0xffffdfff, v96
	v_cmp_ne_u32_e32 vcc, s21, v96
	v_cmp_ne_u32_e64 s[4:5], s24, v96
	v_lshl_add_u64 v[96:97], s[86:87], 0, v[144:145]
	v_cvt_pk_bf16_f32 v98, v158, v159
	v_cvt_pk_bf16_f32 v99, v160, v161
	global_store_dwordx2 v[96:97], v[98:99], off nt
	v_cvt_pk_bf16_f32 v98, v154, v155
	v_cvt_pk_bf16_f32 v99, v156, v157
	global_store_dwordx2 v[96:97], v[98:99], off offset:512 nt
	v_cvt_pk_bf16_f32 v98, v150, v151
	v_cvt_pk_bf16_f32 v99, v152, v153
	s_and_b64 s[4:5], vcc, s[4:5]
	global_store_dwordx2 v[96:97], v[98:99], off offset:1024 nt
	v_cvt_pk_bf16_f32 v98, v146, v147
	v_cvt_pk_bf16_f32 v99, v148, v149
	v_cmp_eq_u32_e64 s[6:7], 0, v100
	v_cndmask_b32_e64 v100, 0, 0.5, s[4:5]
	global_store_dwordx2 v[96:97], v[98:99], off offset:1536 nt
	v_cndmask_b32_e64 v98, 0.5, 0, s[6:7]
	v_mul_f32_e64 v102, v100, v168
	v_mul_f32_e64 v103, v100, v169
	v_mul_f32_e64 v106, v100, v170
	v_mul_f32_e64 v107, v100, v171
	v_pk_fma_f32 v[102:103], v[194:195], v[98:99], v[102:103] op_sel:[0,0,1] op_sel_hi:[1,0,0]
	v_pk_fma_f32 v[106:107], v[196:197], v[98:99], v[106:107] op_sel:[0,0,1] op_sel_hi:[1,0,0]
	v_add_f32_e64 v102, v102, -v158
	v_add_f32_e64 v103, v103, -v159
	v_add_f32_e64 v106, v106, -v160
	v_add_f32_e64 v107, v107, -v161
	v_fma_f32 v104, v4, v102, v158
	v_fma_f32 v105, v5, v103, v159
	v_fma_f32 v108, v6, v106, v160
	v_fma_f32 v109, v7, v107, v161
	v_cvt_pk_bf16_f32 v104, v104, v105
	v_cvt_pk_bf16_f32 v105, v108, v109
	v_add_co_u32_e32 v108, vcc, s26, v96
	v_mul_f32_e64 v130, v100, v162
	v_mul_f32_e64 v131, v100, v163
	s_nop 0
	v_addc_co_u32_e32 v109, vcc, 0, v97, vcc
	global_store_dwordx2 v[108:109], v[104:105], off nt
	v_mul_f32_e64 v104, v100, v164
	v_mul_f32_e64 v105, v100, v165
	v_pk_fma_f32 v[104:105], v[198:199], v[98:99], v[104:105] op_sel:[0,0,1] op_sel_hi:[1,0,0]
	v_pk_fma_f32 v[130:131], v[200:201], v[98:99], v[130:131] op_sel:[0,0,1] op_sel_hi:[1,0,0]
	v_add_f32_e64 v104, v104, -v154
	v_add_f32_e64 v105, v105, -v155
	v_add_f32_e64 v130, v130, -v156
	v_add_f32_e64 v131, v131, -v157
	v_fma_f32 v110, v60, v104, v154
	v_fma_f32 v111, v61, v105, v155
	v_fma_f32 v132, v62, v130, v156
	v_fma_f32 v133, v63, v131, v157
	v_cvt_pk_bf16_f32 v110, v110, v111
	v_cvt_pk_bf16_f32 v111, v132, v133
	global_store_dwordx2 v[108:109], v[110:111], off offset:512 nt
	v_mul_f32_e64 v110, v100, v166
	v_mul_f32_e64 v111, v100, v167
	v_mul_f32_e64 v134, v100, v172
	v_mul_f32_e64 v135, v100, v173
	v_pk_fma_f32 v[110:111], v[202:203], v[98:99], v[110:111] op_sel:[0,0,1] op_sel_hi:[1,0,0]
	v_pk_fma_f32 v[134:135], v[204:205], v[98:99], v[134:135] op_sel:[0,0,1] op_sel_hi:[1,0,0]
	v_add_f32_e64 v110, v110, -v150
	v_add_f32_e64 v111, v111, -v151
	v_add_f32_e64 v134, v134, -v152
	v_add_f32_e64 v135, v135, -v153
	v_fma_f32 v132, v68, v110, v150
	v_fma_f32 v133, v69, v111, v151
	v_fma_f32 v136, v70, v134, v152
	v_fma_f32 v137, v71, v135, v153
	v_cvt_pk_bf16_f32 v132, v132, v133
	v_cvt_pk_bf16_f32 v133, v136, v137
	global_store_dwordx2 v[108:109], v[132:133], off offset:1024 nt
	v_mul_f32_e64 v132, v100, v174
	v_mul_f32_e64 v133, v100, v175
	v_mul_f32_e64 v101, v100, v217
	v_mul_f32_e64 v100, v100, v216
	v_pk_fma_f32 v[132:133], v[212:213], v[98:99], v[132:133] op_sel:[0,0,1] op_sel_hi:[1,0,0]
	v_fma_f32 v99, v215, v98, v100
	v_fma_f32 v98, v214, v98, v101
	v_add_f32_e64 v132, v132, -v146
	v_add_f32_e64 v133, v133, -v147
	v_add_f32_e64 v98, v98, -v148
	v_add_f32_e64 v99, v99, -v149
	v_fma_f32 v136, v76, v132, v146
	v_fma_f32 v137, v77, v133, v147
	v_fma_f32 v100, v78, v98, v148
	v_fma_f32 v101, v79, v99, v149
	v_cvt_pk_bf16_f32 v136, v136, v137
	v_cvt_pk_bf16_f32 v137, v100, v101
	global_store_dwordx2 v[108:109], v[136:137], off offset:1536 nt
	v_fma_f32 v100, v8, v102, v158
	v_fma_f32 v101, v9, v103, v159
	v_fma_f32 v108, v10, v106, v160
	v_fma_f32 v109, v11, v107, v161
	v_add_co_u32_e32 v96, vcc, s27, v96
	v_cvt_pk_bf16_f32 v100, v100, v101
	v_cvt_pk_bf16_f32 v101, v108, v109
	v_addc_co_u32_e32 v97, vcc, 0, v97, vcc
	global_store_dwordx2 v[96:97], v[100:101], off nt
	v_fma_f32 v100, v12, v104, v154
	v_fma_f32 v101, v13, v105, v155
	v_fma_f32 v108, v14, v130, v156
	v_fma_f32 v109, v15, v131, v157
	v_cvt_pk_bf16_f32 v100, v100, v101
; __device__ __forceinline__ void st_bf16x4_nt(bf16_t* p, float a, float b, float c, float d) { u32x2 w = {cvtpk(a, b), cvtpk(c, d)}; __builtin_nontemporal_store(w, (u32x2*)p); }
; __device__ void phase_norm_lerp(const Params& p, const float* mod) {
;     ...
; #pragma unroll
;     for (int i = 0; i < 4; ++i) st_bf16x4_nt(H + (size_t)n * 1024 + i * 256 + lane * 4, hc[4 * i], hc[4 * i + 1], hc[4 * i + 2], hc[4 * i + 3]);
; #pragma unroll
;     for (int j = 0; j < 4; ++j) {
;       bf16_t* dst = lerp_base(p, j, n) + (size_t)n * 1024 + lane * 4;
; #pragma unroll
;       for (int i = 0; i < 4; ++i) {
;         float o[4];
; #pragma unroll
;         for (int e = 0; e < 4; ++e) { const float c = hc[4 * i + e]; o[e] = c + (fp * hp[4 * i + e] + fn * hn[4 * i + e] - c) * mu[j][4 * i + e]; }
;         st_bf16x4_nt(dst + i * 256, o[0], o[1], o[2], o[3]);
;       }
;     }
; #pragma unroll
;     for (int e = 0; e < 16; ++e) { hp[e] = hc[e]; hc[e] = hn[e]; }
;     xa = xb; xb = xc;
	v_cvt_pk_bf16_f32 v101, v108, v109
	global_store_dwordx2 v[96:97], v[100:101], off offset:512 nt
	v_fma_f32 v100, v16, v110, v150
	v_fma_f32 v101, v17, v111, v151
	v_fma_f32 v108, v18, v134, v152
	v_fma_f32 v109, v19, v135, v153
	v_cvt_pk_bf16_f32 v100, v100, v101
	v_cvt_pk_bf16_f32 v101, v108, v109
	global_store_dwordx2 v[96:97], v[100:101], off offset:1024 nt
	v_fma_f32 v100, v20, v132, v146
	v_fma_f32 v101, v21, v133, v147
	v_fma_f32 v108, v22, v98, v148
	v_fma_f32 v109, v23, v99, v149
	v_cvt_pk_bf16_f32 v100, v100, v101
	v_cvt_pk_bf16_f32 v101, v108, v109
	global_store_dwordx2 v[96:97], v[100:101], off offset:1536 nt
	v_fma_f32 v100, v24, v102, v158
	v_fma_f32 v101, v25, v103, v159
	v_fma_f32 v108, v26, v106, v160
	v_fma_f32 v109, v27, v107, v161
	v_lshl_add_u64 v[96:97], s[84:85], 0, v[144:145]
	v_cvt_pk_bf16_f32 v100, v100, v101
	v_cvt_pk_bf16_f32 v101, v108, v109
	global_store_dwordx2 v[96:97], v[100:101], off nt
	v_fma_f32 v100, v28, v104, v154
	v_fma_f32 v101, v29, v105, v155
	v_fma_f32 v108, v30, v130, v156
	v_fma_f32 v109, v31, v131, v157
	v_cvt_pk_bf16_f32 v100, v100, v101
	v_cvt_pk_bf16_f32 v101, v108, v109
	global_store_dwordx2 v[96:97], v[100:101], off offset:512 nt
	v_fma_f32 v100, v32, v110, v150
	v_fma_f32 v101, v33, v111, v151
	v_fma_f32 v108, v34, v134, v152
	v_fma_f32 v109, v35, v135, v153
	v_cvt_pk_bf16_f32 v100, v100, v101
	v_cvt_pk_bf16_f32 v101, v108, v109
	global_store_dwordx2 v[96:97], v[100:101], off offset:1024 nt
	v_fma_f32 v100, v36, v132, v146
	v_fma_f32 v101, v37, v133, v147
	v_fma_f32 v108, v38, v98, v148
	v_fma_f32 v109, v39, v99, v149
	v_cvt_pk_bf16_f32 v100, v100, v101
	v_cvt_pk_bf16_f32 v101, v108, v109
	global_store_dwordx2 v[96:97], v[100:101], off offset:1536 nt
	v_mov_b32_e32 v96, s17
	v_mov_b32_e32 v97, s2
	v_cmp_gt_i32_e32 vcc, s25, v128
	v_mov_b32_e32 v100, s1
	v_fma_f32 v98, v54, v98, v148
	v_fma_f32 v99, v55, v99, v149
	v_cndmask_b32_e32 v97, v96, v97, vcc
	v_mov_b32_e32 v96, s16
	v_cndmask_b32_e32 v96, v96, v100, vcc
	v_fma_f32 v100, v40, v102, v158
	v_fma_f32 v101, v41, v103, v159
	v_fma_f32 v102, v42, v106, v160
	v_fma_f32 v103, v43, v107, v161
	v_lshl_add_u64 v[96:97], v[96:97], 0, v[144:145]
	v_cvt_pk_bf16_f32 v100, v100, v101
	v_cvt_pk_bf16_f32 v101, v102, v103
	global_store_dwordx2 v[96:97], v[100:101], off nt
	v_fma_f32 v100, v44, v104, v154
	v_fma_f32 v101, v45, v105, v155
	v_fma_f32 v102, v46, v130, v156
	v_fma_f32 v103, v47, v131, v157
	v_cvt_pk_bf16_f32 v100, v100, v101
	v_cvt_pk_bf16_f32 v101, v102, v103
	global_store_dwordx2 v[96:97], v[100:101], off offset:512 nt
	v_fma_f32 v100, v48, v110, v150
	v_fma_f32 v101, v49, v111, v151
	v_fma_f32 v102, v50, v134, v152
	v_fma_f32 v103, v51, v135, v153
	v_cvt_pk_bf16_f32 v100, v100, v101
	v_cvt_pk_bf16_f32 v101, v102, v103
	global_store_dwordx2 v[96:97], v[100:101], off offset:1024 nt
	v_fma_f32 v100, v52, v132, v146
	v_fma_f32 v101, v53, v133, v147
	s_waitcnt vmcnt(22)
	v_mov_b64_e32 v[130:131], v[82:83]
	v_cvt_pk_bf16_f32 v100, v100, v101
	v_cvt_pk_bf16_f32 v101, v98, v99
	global_store_dwordx2 v[96:97], v[100:101], off offset:1536 nt
	v_add_u32_e32 v96, 1, v222
	v_add_u32_e32 v97, -2, v222
	v_cmp_ge_i32_e32 vcc, v97, v177
	v_mov_b32_e32 v222, v96
	s_waitcnt vmcnt(22)
	v_mov_b64_e32 v[134:135], v[86:87]
	s_waitcnt vmcnt(21)
	v_mov_b64_e32 v[138:139], v[90:91]
	s_waitcnt vmcnt(20)
	v_mov_b64_e32 v[142:143], v[94:95]
	v_mov_b64_e32 v[108:109], v[124:125]
	v_mov_b64_e32 v[104:105], v[120:121]
	v_mov_b64_e32 v[100:101], v[116:117]
	v_mov_b64_e32 v[96:97], v[112:113]
	v_lshl_add_u64 v[144:145], v[144:145], 0, s[14:15]
	s_or_b64 s[10:11], vcc, s[10:11]
	v_mov_b64_e32 v[128:129], v[80:81]
	v_mov_b64_e32 v[132:133], v[84:85]
	v_mov_b64_e32 v[136:137], v[88:89]
	v_mov_b64_e32 v[140:141], v[92:93]
	v_mov_b32_e32 v223, v181
	v_mov_b64_e32 v[110:111], v[126:127]
	v_mov_b64_e32 v[106:107], v[122:123]
	v_mov_b64_e32 v[102:103], v[118:119]
	v_mov_b64_e32 v[98:99], v[114:115]
	v_mov_b32_e32 v183, v192
	v_mov_b32_e32 v196, v160
	v_mov_b32_e32 v197, v161
	v_mov_b32_e32 v194, v158
	v_mov_b32_e32 v195, v159
	v_mov_b32_e32 v200, v156
	v_mov_b32_e32 v201, v157
	v_mov_b32_e32 v198, v154
	v_mov_b32_e32 v199, v155
	v_mov_b32_e32 v204, v152
	v_mov_b32_e32 v205, v153
	v_mov_b32_e32 v202, v150
	v_mov_b32_e32 v203, v151
	v_mov_b32_e32 v214, v148
	v_mov_b32_e32 v215, v149
	v_mov_b32_e32 v212, v146
	v_mov_b32_e32 v213, v147
	s_andn2_b64 exec, exec, s[10:11]
	s_cbranch_execz .LBB0_66

; __device__ __forceinline__ unsigned cvtpk(float lo, float hi) { f32x2 v = {lo, hi}; bf16x2_t b = __builtin_convertvector(v, bf16x2_t); return *(unsigned*)&b; }
; __device__ __forceinline__ void fin_row(const float* mod, const f32x4 (&g4)[4], int lane, const RowX& r, float (&h)[16]) {
;   float ss = 0.f;
; #pragma unroll
;   for (int i = 0; i < 4; ++i) ss += r.v[i][0] * r.v[i][0] + r.v[i][1] * r.v[i][1] + r.v[i][2] * r.v[i][2] + r.v[i][3] * r.v[i][3];
;   ss = wave_sum(ss);
;   const float rstd = rsqrtf(ss * (1.f / 1024.f) + 1e-6f);
;   const float* m = mod + r.bi * 3072;
; #pragma unroll
;   for (int i = 0; i < 4; ++i) {
;     const int c = i * 256 + lane * 4;
;     const f32x4 sh = *(const f32x4*)(m + c), sc = *(const f32x4*)(m + 1024 + c);
; #pragma unroll
;     for (int e = 0; e < 4; ++e) {
;       const float hv = r.v[i][e] * rstd * g4[i][e] * (1.f + sc[e]) + sh[e];
;       h[4 * i + e] = __uint_as_float(cvtpk(hv, 0.f) << 16);
;     }
;   }
; }
; __device__ void phase_norm_lerp(const Params& p, const float* mod) {
;     ...
;     if (n + 1 < NTOK) fin_row(mod, g4, lane, xa, hn);
;     else {
; #pragma unroll
;       for (int e = 0; e < 16; ++e) hn[e] = 0.f;
;     }
.LBB0_64:
	s_or_b64 exec, exec, s[4:5]
	v_mov_b32_e32 v216, 0
	v_cmp_gt_i32_e32 vcc, s22, v128
	v_mov_b32_e32 v217, v216
	v_mov_b32_e32 v174, v216
	v_mov_b32_e32 v175, v216
	v_mov_b32_e32 v172, v216
	v_mov_b32_e32 v173, v216
	v_mov_b32_e32 v166, v216
	v_mov_b32_e32 v167, v216
	v_mov_b32_e32 v162, v216
	v_mov_b32_e32 v163, v216
	v_mov_b32_e32 v164, v216
	v_mov_b32_e32 v165, v216
	v_mov_b32_e32 v170, v216
	v_mov_b32_e32 v171, v216
	v_mov_b32_e32 v168, v216
	v_mov_b32_e32 v169, v216
	s_and_saveexec_b64 s[4:5], vcc
	s_cbranch_execz .LBB0_57
	v_mov_b32_e32 v132, v109
	v_mov_b32_e32 v133, v105
	v_mov_b32_e32 v130, v108
	v_mov_b32_e32 v131, v104
	v_mul_f32_e64 v132, v132, v132
	v_mul_f32_e64 v133, v133, v133
	v_mov_b32_e32 v140, v111
	v_fma_f32 v130, v130, v130, v132
	v_fma_f32 v131, v131, v131, v133
	v_mov_b32_e32 v132, v110
	v_mov_b32_e32 v133, v106
	v_fma_f32 v138, v132, v132, v130
	v_fma_f32 v139, v133, v133, v131
	v_mov_b32_e32 v141, v107
	v_mov_b32_e32 v164, v97
	v_mov_b32_e32 v165, v101
	v_fma_f32 v138, v140, v140, v138
	v_fma_f32 v139, v141, v141, v139
	v_mov_b32_e32 v140, v96
	v_mov_b32_e32 v141, v100
	v_mul_f32_e64 v164, v164, v164
	v_mul_f32_e64 v165, v165, v165
	v_add_f32_e32 v129, v138, v139
	v_fma_f32 v140, v140, v140, v164
	v_fma_f32 v141, v141, v141, v165
	v_mov_b32_e32 v164, v98
	v_mov_b32_e32 v165, v102
	v_fma_f32 v140, v164, v164, v140
	v_fma_f32 v141, v165, v165, v141
	v_mov_b32_e32 v164, v99
	v_mov_b32_e32 v165, v103
	v_fma_f32 v168, v164, v164, v140
	v_fma_f32 v169, v165, v165, v141
	v_mul_lo_u32 v130, v183, s23
	v_add_f32_e32 v129, v169, v129
	v_add_f32_e32 v129, v168, v129
	ds_bpermute_b32 v168, v185, v129
	v_ashrrev_i32_e32 v131, 31, v130
	v_lshl_add_u64 v[142:143], v[130:131], 2, s[38:39]
	v_lshl_add_u64 v[162:163], v[142:143], 0, s[12:13]
	v_lshl_add_u64 v[130:131], v[142:143], 0, v[190:191]
	s_waitcnt lgkmcnt(0)
	v_add_f32_e32 v129, v129, v168
	ds_bpermute_b32 v168, v187, v129
	v_lshl_add_u64 v[134:135], v[162:163], 0, v[190:191]
	global_load_dwordx4 v[130:133], v[130:131], off
	s_nop 0
	global_load_dwordx4 v[134:137], v[134:135], off
	v_lshl_add_u64 v[138:139], v[142:143], 0, v[206:207]
	v_lshl_add_u64 v[164:165], v[162:163], 0, v[206:207]
	global_load_dwordx4 v[138:141], v[138:139], off
	s_nop 0
	global_load_dwordx4 v[164:167], v[164:165], off
	s_waitcnt lgkmcnt(0)
	v_add_f32_e32 v129, v129, v168
	ds_bpermute_b32 v168, v189, v129
	v_lshl_add_u64 v[170:171], v[162:163], 0, v[208:209]
	v_lshl_add_u64 v[162:163], v[162:163], 0, v[210:211]
	s_waitcnt lgkmcnt(0)
	v_add_f32_e32 v129, v129, v168
	v_lshl_add_u64 v[168:169], v[142:143], 0, v[208:209]
	global_load_dwordx4 v[172:175], v[168:169], off
	global_load_dwordx4 v[224:227], v[170:171], off
	v_lshl_add_u64 v[142:143], v[142:143], 0, v[210:211]
	global_load_dwordx4 v[228:231], v[162:163], off
	global_load_dwordx4 v[232:235], v[142:143], off
	ds_bpermute_b32 v168, v218, v129
	s_waitcnt lgkmcnt(0)
	v_add_f32_e32 v129, v129, v168
	ds_bpermute_b32 v168, v219, v129
	s_waitcnt lgkmcnt(0)
	v_add_f32_e32 v129, v129, v168
	ds_bpermute_b32 v168, v220, v129
	s_waitcnt lgkmcnt(0)
	v_add_f32_e32 v129, v129, v168
	v_fmamk_f32 v129, v129, 0x3a800000, v221
	v_mul_f32_e32 v168, 0x4b800000, v129
	v_cmp_gt_f32_e32 vcc, s0, v129
	s_waitcnt vmcnt(6)
	v_add_f32_e32 v134, 1.0, v134
	v_cndmask_b32_e32 v129, v129, v168, vcc
	v_rsq_f32_e32 v129, v129
	v_add_f32_e32 v135, 1.0, v135
	v_add_f32_e32 v136, 1.0, v136
	v_add_f32_e32 v137, 1.0, v137
	v_mul_f32_e32 v142, 0x45800000, v129
	v_cndmask_b32_e32 v129, v129, v142, vcc
	v_mul_f32_e32 v108, v108, v129
	v_mul_f32_e32 v108, v0, v108
	v_fma_f32 v108, v134, v108, v130
	v_cvt_pk_bf16_f32 v108, v108, 0
	v_mul_f32_e32 v104, v104, v129
	v_lshlrev_b32_e32 v169, 16, v108
	v_mul_f32_e32 v104, v56, v104
	s_waitcnt vmcnt(4)
	v_add_f32_e32 v108, 1.0, v164
	v_mul_f32_e32 v105, v105, v129
	v_fma_f32 v104, v108, v104, v138
	v_mul_f32_e32 v105, v57, v105
	v_add_f32_e32 v108, 1.0, v165
	v_cvt_pk_bf16_f32 v104, v104, 0
	v_fma_f32 v105, v108, v105, v139
	v_cvt_pk_bf16_f32 v105, v105, 0
	v_lshlrev_b32_e32 v165, 16, v104
	v_mul_f32_e32 v104, v106, v129
	v_lshlrev_b32_e32 v164, 16, v105
	v_mul_f32_e32 v104, v58, v104
	v_add_f32_e32 v105, 1.0, v166
	v_fma_f32 v104, v105, v104, v140
	v_cvt_pk_bf16_f32 v104, v104, 0
	v_mul_f32_e32 v100, v100, v129
	v_lshlrev_b32_e32 v163, 16, v104
	v_mul_f32_e32 v100, v64, v100
	s_waitcnt vmcnt(2)
	v_add_f32_e32 v104, 1.0, v224
	v_mul_f32_e32 v101, v101, v129
	v_fma_f32 v100, v104, v100, v172
	v_mul_f32_e32 v101, v65, v101
	v_add_f32_e32 v104, 1.0, v225
	v_cvt_pk_bf16_f32 v100, v100, 0
	v_fma_f32 v101, v104, v101, v173
	v_add_f32_e32 v106, 1.0, v167
	v_cvt_pk_bf16_f32 v101, v101, 0
	v_lshlrev_b32_e32 v167, 16, v100
	v_mul_f32_e32 v100, v102, v129
	v_lshlrev_b32_e32 v166, 16, v101
	v_mul_f32_e32 v100, v66, v100
	v_add_f32_e32 v101, 1.0, v226
	v_fma_f32 v100, v101, v100, v174
	v_cvt_pk_bf16_f32 v100, v100, 0
	v_mul_f32_e32 v96, v96, v129
	v_mul_f32_e32 v101, v103, v129
	v_lshlrev_b32_e32 v173, 16, v100
	v_mul_f32_e32 v96, v72, v96
	s_waitcnt vmcnt(1)
	v_add_f32_e32 v100, 1.0, v228
	v_mul_f32_e32 v97, v97, v129
	v_mul_f32_e32 v101, v67, v101
	v_add_f32_e32 v102, 1.0, v227
	s_waitcnt vmcnt(0)
	v_fma_f32 v96, v100, v96, v232
	v_mul_f32_e32 v97, v73, v97
	v_add_f32_e32 v100, 1.0, v229
	v_fmac_f32_e32 v175, v102, v101
	v_cvt_pk_bf16_f32 v96, v96, 0
	v_fma_f32 v97, v100, v97, v233
	v_cvt_pk_bf16_f32 v101, v175, 0
	v_cvt_pk_bf16_f32 v97, v97, 0
	v_lshlrev_b32_e32 v175, 16, v96
	v_mul_f32_e32 v96, v98, v129
	v_lshlrev_b32_e32 v174, 16, v97
	v_mul_f32_e32 v96, v74, v96
	v_add_f32_e32 v97, 1.0, v230
	v_mul_f32_e32 v109, v109, v129
	v_mul_f32_e32 v110, v110, v129
	v_mul_f32_e32 v111, v111, v129
	v_mul_f32_e32 v105, v107, v129
	v_fma_f32 v96, v97, v96, v234
	v_mul_f32_e32 v97, v99, v129
	v_mul_f32_e32 v109, v1, v109
	v_mul_f32_e32 v110, v2, v110
	v_mul_f32_e32 v111, v3, v111
	v_mul_f32_e32 v105, v59, v105
	v_mul_f32_e32 v97, v75, v97
	v_add_f32_e32 v98, 1.0, v231
	v_fma_f32 v109, v135, v109, v131
	v_fma_f32 v110, v136, v110, v132
	v_fmac_f32_e32 v133, v137, v111
	v_fmac_f32_e32 v141, v106, v105
	v_fmac_f32_e32 v235, v98, v97
	v_cvt_pk_bf16_f32 v109, v109, 0
	v_cvt_pk_bf16_f32 v110, v110, 0
	v_cvt_pk_bf16_f32 v111, v133, 0
	v_cvt_pk_bf16_f32 v105, v141, 0
	v_cvt_pk_bf16_f32 v96, v96, 0
	v_cvt_pk_bf16_f32 v97, v235, 0
	v_lshlrev_b32_e32 v168, 16, v109
	v_lshlrev_b32_e32 v170, 16, v111
	v_lshlrev_b32_e32 v171, 16, v110
	v_lshlrev_b32_e32 v162, 16, v105
	v_lshlrev_b32_e32 v172, 16, v101
	v_lshlrev_b32_e32 v216, 16, v97
	v_lshlrev_b32_e32 v217, 16, v96
	s_branch .LBB0_57

; template <int AMODE, int BN, class Epi>
; __device__ __forceinline__ void gemm_tile(const bf16_t* A, const int lda, const bf16_t* Bt, const int K, const int m0, const float* mu, char* lds, const Epi& epi) {
;     ...
;     const int t0 = m0 % TL;
; #pragma unroll
;     for (int i = 0; i < 4; ++i) { const int t = t0 + srow + 64 * i; dprev[i] = (t != 0 && t != T) ? 1 : 0; dnext[i] = (t != T - 1 && t != TL - 1) ? 1 : 0; }
;   }
;   auto gload = [&](int k0) {
; #pragma unroll
;     for (int i = 0; i < 4; ++i) {
;       const bf16_t* ap = A + (size_t)(m0 + srow + 64 * i) * lda + k0 + scc;
;       ra[i] = *(const bf16x8*)ap;
;       if constexpr (AMODE == 1) { rp[i] = *(const bf16x8*)(ap - dprev[i] * lda); rn[i] = *(const bf16x8*)(ap + dnext[i] * lda); }
;     }
; #pragma unroll
;     for (int i = 0; i < NBR; ++i) rb[i] = *(const bf16x8*)(Bt + (size_t)browi[i] * K + k0 + scc);
;   };
;   auto lstore = [&](int s, int k0) {
;     char* base = lds + s * G_STAGE;
;     if constexpr (AMODE == 1) {
;       const f32x4 m0v = *(const f32x4*)(mu + k0 + scc), m1v = *(const f32x4*)(mu + k0 + scc + 4);
;       const float mm[8] = {m0v[0], m0v[1], m0v[2], m0v[3], m1v[0], m1v[1], m1v[2], m1v[3]};
; #pragma unroll
;       for (int i = 0; i < 4; ++i) {
;         const u32x4 hc = *(const u32x4*)&ra[i], hp = *(const u32x4*)&rp[i], hn = *(const u32x4*)&rn[i];
;         const float fp = dprev[i] ? 0.5f : 0.f, fn = dnext[i] ? 0.5f : 0.f;
;         u32x4 w;
; #pragma unroll
;         for (int q = 0; q < 4; ++q) {
;           const float c0 = lo16(hc[q]), c1 = hi16(hc[q]);
;           const float x0 = fp * lo16(hp[q]) + fn * lo16(hn[q]) - c0, x1 = fp * hi16(hp[q]) + fn * hi16(hn[q]) - c1;
;           w[q] = cvtpk(c0 + x0 * mm[2 * q], c1 + x1 * mm[2 * q + 1]);
;         }
;         *(u32x4*)(base + (srow + 64 * i) * G_LDT + scc * 2) = w;
;       }
;     } else {
; #pragma unroll
;       for (int i = 0; i < 4; ++i) {
;         *(bf16x8*)(base + (srow + 64 * i) * G_LDT + scc * 2) = ra[i];
;         if constexpr (AMODE == 2) {
;           const u32x4 hc = *(const u32x4*)&ra[i];
; #pragma unroll
;           for (int q = 0; q < 4; ++q) { const float c0 = lo16(hc[q]), c1 = hi16(hc[q]); ssq[i] += c0 * c0 + c1 * c1; }
;         }
;       }
;     }
; #pragma unroll
;     for (int i = 0; i < NBR; ++i) *(bf16x8*)(base + 256 * G_LDT + (srow + 64 * i) * G_LDT + scc * 2) = rb[i];
;   };
.LBB0_463:
	s_add_i32 s4, s62, s0
	s_bfe_u32 s64, s4, 0x10003
	s_lshl_b32 s5, s4, 7
	s_lshl_b32 s4, s4, 8
	s_and_b32 s5, s5, 0xfffff800
	s_and_b32 s4, s4, 0x700
	s_or_b32 s63, s5, s4
	s_lshl_b32 s48, s64, 18
	s_lshl_b32 s22, s64, 12
	s_add_u32 s4, s50, s22
	s_mul_hi_i32 s6, s63, 0x3e0f83e1
	s_addc_u32 s5, s51, 0
	s_lshr_b32 s7, s6, 31
	s_ashr_i32 s6, s6, 11
	s_add_i32 s6, s6, s7
	s_mulk_i32 s6, 0x2100
	s_sub_i32 s10, s63, s6
	v_or_b32_e32 v8, s63, v161
	v_bitop3_b32 v0, s10, v207, v161 bitop3:0xc8
	v_ashrrev_i32_e32 v9, 31, v8
	v_lshlrev_b64 v[120:121], 11, v[8:9]
	v_cmp_eq_u32_e64 s[6:7], 0, v0
	v_lshl_add_u64 v[154:155], v[132:133], 0, v[120:121]
	global_load_dwordx4 v[44:47], v[154:155], off offset:2048
	v_cndmask_b32_e64 v123, -1, 0, s[6:7]
	v_cndmask_b32_e64 v122, v208, 0, s[6:7]
	s_waitcnt vmcnt(13)
	v_lshl_add_u64 v[68:69], v[154:155], 0, v[122:123]
	global_load_dwordx4 v[40:43], v[68:69], off
	v_lshl_add_u64 v[0:1], s[4:5], 0, v[152:153]
	global_load_dwordx4 v[28:31], v[154:155], off
	v_add_co_u32_e32 v2, vcc, s43, v0
	s_mov_b32 s62, s12
	s_nop 0
	v_addc_co_u32_e32 v3, vcc, 0, v1, vcc
	global_load_dwordx4 v[4:7], v[2:3], off
	v_or_b32_e32 v2, s10, v161
	v_add_u32_e32 v3, 64, v2
	v_cmp_eq_u32_e64 s[12:13], s30, v2
	v_cmp_eq_u32_e64 s[14:15], s31, v2
	v_add_u32_e32 v2, 0xc0, v2
	v_lshl_add_u64 v[0:1], v[0:1], 0, s[28:29]
	v_and_b32_e32 v9, 0xffffdfff, v3
	v_cmp_eq_u32_e32 vcc, s1, v3
	v_cmp_eq_u32_e64 s[10:11], s2, v3
	v_and_b32_e32 v12, 0xffffdfff, v2
	v_cmp_eq_u32_e64 s[16:17], s1, v2
	v_cmp_eq_u32_e64 s[18:19], s2, v2
	global_load_dwordx4 v[0:3], v[0:1], off offset:16
	v_lshl_add_u64 v[124:125], v[120:121], 0, s[26:27]
	v_cmp_eq_u32_e64 s[4:5], 0, v9
	s_or_b64 s[60:61], vcc, s[10:11]
	v_lshl_add_u64 v[156:157], v[132:133], 0, v[124:125]
	v_cndmask_b32_e64 v127, -1, 0, s[4:5]
	v_cndmask_b32_e64 v126, v208, 0, s[4:5]
	v_cndmask_b32_e64 v198, v209, 0, s[60:61]
	v_mov_b32_e32 v199, v129
	s_waitcnt vmcnt(13)
	v_lshl_add_u64 v[84:85], v[156:157], 0, v[126:127]
	v_lshl_add_u64 v[80:81], v[156:157], 0, v[198:199]
	global_load_dwordx4 v[56:59], v[84:85], off
	global_load_dwordx4 v[60:63], v[80:81], off
	global_load_dwordx4 v[52:55], v[156:157], off
	v_or_b32_e32 v10, 0x80, v8
	v_ashrrev_i32_e32 v11, 31, v10
	v_lshlrev_b64 v[196:197], 11, v[10:11]
	s_or_b64 s[14:15], s[12:13], s[14:15]
	v_lshl_add_u64 v[158:159], v[132:133], 0, v[196:197]
	v_cndmask_b32_e64 v200, v209, 0, s[14:15]
	v_mov_b32_e32 v201, v129
	v_lshl_add_u64 v[96:97], v[158:159], 0, v[200:201]
	global_load_dwordx4 v[36:39], v[158:159], off
	global_load_dwordx4 v[32:35], v[158:159], off offset:-2048
	global_load_dwordx4 v[48:51], v[96:97], off
	v_add_u32_e32 v8, 0xc0, v8
	v_ashrrev_i32_e32 v9, 31, v8
	v_lshlrev_b64 v[192:193], 11, v[8:9]
	v_cmp_eq_u32_e32 vcc, 0, v12
	s_or_b64 s[12:13], s[16:17], s[18:19]
	v_lshl_add_u64 v[162:163], v[132:133], 0, v[192:193]
	v_cndmask_b32_e64 v195, -1, 0, vcc
	v_cndmask_b32_e64 v194, v208, 0, vcc
	v_cndmask_b32_e64 v190, v209, 0, s[12:13]
	v_mov_b32_e32 v191, v129
	v_lshl_add_u64 v[108:109], v[162:163], 0, v[194:195]
	v_lshl_add_u64 v[104:105], v[162:163], 0, v[190:191]
	global_load_dwordx4 v[12:15], v[108:109], off
	global_load_dwordx4 v[24:27], v[104:105], off
	global_load_dwordx4 v[8:11], v[162:163], off
	global_load_dwordx4 v[100:103], v[162:163], off offset:128
	v_cndmask_b32_e64 v164, 0.5, 0, s[6:7]
	s_mov_b32 s49, s23
	v_mov_b32_e32 v165, v164
	v_lshl_add_u64 v[16:17], v[130:131], 0, s[48:49]
	v_lshl_add_u64 v[20:21], v[16:17], 0, v[140:141]
	v_add_co_u32_e64 v112, s[10:11], s34, v20
	global_load_dwordx4 v[64:67], v[154:155], off offset:128
	s_nop 0
	v_addc_co_u32_e64 v113, s[10:11], 0, v21, s[10:11]
	v_add_co_u32_e64 v116, s[10:11], s35, v20
	global_load_dwordx4 v[16:19], v[112:113], off
	s_nop 0
	v_addc_co_u32_e64 v117, s[10:11], 0, v21, s[10:11]
	s_waitcnt vmcnt(16)
	v_lshlrev_b32_e32 v82, 16, v44
	v_and_b32_e32 v83, 0xffff0000, v44
	v_mul_f32_e64 v82, v82, 0.5
	v_mul_f32_e64 v83, v83, 0.5
	v_lshlrev_b32_e32 v44, 16, v45
	s_waitcnt vmcnt(15)
	v_lshlrev_b32_e32 v78, 16, v40
	v_and_b32_e32 v79, 0xffff0000, v40
	s_waitcnt vmcnt(14)
	v_lshlrev_b32_e32 v76, 16, v28
	v_and_b32_e32 v77, 0xffff0000, v28
	v_fma_f32 v78, v164, v78, v82
	v_fma_f32 v79, v164, v79, v83
	v_add_f32_e64 v78, v78, -v76
	v_add_f32_e64 v79, v79, -v77
	v_and_b32_e32 v45, 0xffff0000, v45
	v_lshlrev_b32_e32 v40, 16, v41
	s_waitcnt vmcnt(13)
	v_fma_f32 v76, v78, v4, v76
	v_fma_f32 v77, v79, v5, v77
	v_and_b32_e32 v41, 0xffff0000, v41
	v_mul_f32_e64 v44, v44, 0.5
	v_mul_f32_e64 v45, v45, 0.5
	v_cvt_pk_bf16_f32 v28, v76, v77
	v_lshlrev_b32_e32 v76, 16, v29
	v_and_b32_e32 v77, 0xffff0000, v29
	v_fma_f32 v40, v164, v40, v44
	v_fma_f32 v41, v164, v41, v45
	v_add_f32_e64 v40, v40, -v76
	v_add_f32_e64 v41, v41, -v77
	global_load_dwordx4 v[20:23], v[116:117], off
	v_fma_f32 v40, v40, v6, v76
	v_fma_f32 v41, v41, v7, v77
	v_lshlrev_b32_e32 v76, 16, v46
	v_and_b32_e32 v77, 0xffff0000, v46
	v_lshlrev_b32_e32 v44, 16, v42
	v_and_b32_e32 v45, 0xffff0000, v42
	v_mul_f32_e64 v76, v76, 0.5
	v_mul_f32_e64 v77, v77, 0.5
	global_load_dwordx4 v[68:71], v[68:69], off offset:128
	v_fma_f32 v44, v164, v44, v76
	v_fma_f32 v45, v164, v45, v77
	global_load_dwordx4 v[72:75], v[154:155], off offset:2176
	global_load_dwordx4 v[76:79], v[156:157], off offset:128
	global_load_dwordx4 v[88:91], v[158:159], off offset:128
	global_load_dwordx4 v[92:95], v[158:159], off offset:-1920
	v_cvt_pk_bf16_f32 v29, v40, v41
	global_load_dwordx4 v[80:83], v[80:81], off offset:128
	v_lshlrev_b32_e32 v40, 16, v30
	global_load_dwordx4 v[84:87], v[84:85], off offset:128
	v_and_b32_e32 v41, 0xffff0000, v30
	global_load_dwordx4 v[96:99], v[96:97], off offset:128
	v_add_f32_e64 v44, v44, -v40
	v_add_f32_e64 v45, v45, -v41
	global_load_dwordx4 v[104:107], v[104:105], off offset:128
	s_waitcnt vmcnt(22)
; __device__ __forceinline__ unsigned cvtpk(float lo, float hi) { f32x2 v = {lo, hi}; bf16x2_t b = __builtin_convertvector(v, bf16x2_t); return *(unsigned*)&b; }
; __device__ __forceinline__ float lo16(unsigned w) { return __uint_as_float(w << 16); }
; __device__ __forceinline__ float hi16(unsigned w) { return __uint_as_float(w & 0xffff0000u); }
; template <int AMODE, int BN, class Epi>
; __device__ __forceinline__ void gemm_tile(const bf16_t* A, const int lda, const bf16_t* Bt, const int K, const int m0, const float* mu, char* lds, const Epi& epi) {
;     ...
;   auto lstore = [&](int s, int k0) {
;     char* base = lds + s * G_STAGE;
;     if constexpr (AMODE == 1) {
;       const f32x4 m0v = *(const f32x4*)(mu + k0 + scc), m1v = *(const f32x4*)(mu + k0 + scc + 4);
;       const float mm[8] = {m0v[0], m0v[1], m0v[2], m0v[3], m1v[0], m1v[1], m1v[2], m1v[3]};
; #pragma unroll
;       for (int i = 0; i < 4; ++i) {
;         const u32x4 hc = *(const u32x4*)&ra[i], hp = *(const u32x4*)&rp[i], hn = *(const u32x4*)&rn[i];
;         const float fp = dprev[i] ? 0.5f : 0.f, fn = dnext[i] ? 0.5f : 0.f;
;         u32x4 w;
; #pragma unroll
;         for (int q = 0; q < 4; ++q) {
;           const float c0 = lo16(hc[q]), c1 = hi16(hc[q]);
;           const float x0 = fp * lo16(hp[q]) + fn * lo16(hn[q]) - c0, x1 = fp * hi16(hp[q]) + fn * hi16(hn[q]) - c1;
;           w[q] = cvtpk(c0 + x0 * mm[2 * q], c1 + x1 * mm[2 * q + 1]);
;         }
;         *(u32x4*)(base + (srow + 64 * i) * G_LDT + scc * 2) = w;
;       }
	v_fma_f32 v40, v44, v0, v40
	v_fma_f32 v41, v45, v1, v41
	global_load_dwordx4 v[108:111], v[108:109], off offset:128
	v_lshlrev_b32_e32 v44, 16, v47
	global_load_dwordx4 v[112:115], v[112:113], off offset:128
	v_and_b32_e32 v45, 0xffff0000, v47
	global_load_dwordx4 v[116:119], v[116:117], off offset:128
	v_lshlrev_b32_e32 v42, 16, v43
	v_and_b32_e32 v43, 0xffff0000, v43
	v_mul_f32_e64 v44, v44, 0.5
	v_mul_f32_e64 v45, v45, 0.5
	v_cvt_pk_bf16_f32 v30, v40, v41
	v_lshlrev_b32_e32 v40, 16, v31
	v_and_b32_e32 v41, 0xffff0000, v31
	v_fma_f32 v42, v164, v42, v44
	v_fma_f32 v43, v164, v43, v45
	v_add_f32_e64 v42, v42, -v40
	v_add_f32_e64 v43, v43, -v41
	v_cndmask_b32_e64 v167, 0.5, 0, s[60:61]
	v_fma_f32 v40, v42, v2, v40
	v_fma_f32 v41, v43, v3, v41
	v_cndmask_b32_e64 v166, 0.5, 0, s[4:5]
	v_cvt_pk_bf16_f32 v31, v40, v41
	s_waitcnt vmcnt(24)
	v_lshlrev_b32_e32 v40, 16, v56
	s_waitcnt vmcnt(23)
	v_and_b32_e32 v41, 0xffff0000, v60
	ds_write_b128 v185, v[28:31]
	v_lshlrev_b32_e32 v30, 16, v60
	v_and_b32_e32 v31, 0xffff0000, v56
	v_mul_f32_e64 v40, v166, v40
	v_mul_f32_e64 v41, v167, v41
	s_waitcnt vmcnt(22)
	v_lshlrev_b32_e32 v28, 16, v52
	v_and_b32_e32 v29, 0xffff0000, v52
	v_fma_f32 v30, v167, v30, v40
	v_fma_f32 v31, v166, v31, v41
	v_lshlrev_b32_e32 v42, 16, v57
	v_and_b32_e32 v43, 0xffff0000, v61
	v_add_f32_e64 v30, v30, -v28
	v_add_f32_e64 v31, v31, -v29
	v_lshlrev_b32_e32 v40, 16, v61
	v_and_b32_e32 v41, 0xffff0000, v57
	v_mul_f32_e64 v42, v166, v42
	v_mul_f32_e64 v43, v167, v43
	v_fma_f32 v28, v30, v4, v28
	v_fma_f32 v29, v31, v5, v29
	v_lshlrev_b32_e32 v30, 16, v53
	v_and_b32_e32 v31, 0xffff0000, v53
	v_fma_f32 v40, v167, v40, v42
	v_fma_f32 v41, v166, v41, v43
	v_add_f32_e64 v40, v40, -v30
	v_add_f32_e64 v41, v41, -v31
	v_lshlrev_b32_e32 v42, 16, v58
	v_and_b32_e32 v43, 0xffff0000, v62
	v_fma_f32 v30, v40, v6, v30
	v_fma_f32 v31, v41, v7, v31
	v_lshlrev_b32_e32 v40, 16, v62
	v_and_b32_e32 v41, 0xffff0000, v58
	v_mul_f32_e64 v42, v166, v42
	v_mul_f32_e64 v43, v167, v43
	v_cvt_pk_bf16_f32 v28, v28, v29
	v_cvt_pk_bf16_f32 v29, v30, v31
	v_lshlrev_b32_e32 v30, 16, v54
	v_and_b32_e32 v31, 0xffff0000, v54
	v_fma_f32 v40, v167, v40, v42
	v_fma_f32 v41, v166, v41, v43
	v_lshlrev_b32_e32 v44, 16, v59
	v_and_b32_e32 v45, 0xffff0000, v63
	v_add_f32_e64 v40, v40, -v30
	v_add_f32_e64 v41, v41, -v31
	v_lshlrev_b32_e32 v42, 16, v63
	v_and_b32_e32 v43, 0xffff0000, v59
	v_mul_f32_e64 v44, v166, v44
	v_mul_f32_e64 v45, v167, v45
	v_fma_f32 v30, v40, v0, v30
	v_fma_f32 v31, v41, v1, v31
	v_lshlrev_b32_e32 v40, 16, v55
	v_and_b32_e32 v41, 0xffff0000, v55
	v_fma_f32 v42, v167, v42, v44
	v_fma_f32 v43, v166, v43, v45
	v_add_f32_e64 v42, v42, -v40
	v_add_f32_e64 v43, v43, -v41
	v_cndmask_b32_e64 v170, 0.5, 0, s[14:15]
	v_fma_f32 v40, v42, v2, v40
	v_fma_f32 v41, v43, v3, v41
	v_cvt_pk_bf16_f32 v30, v30, v31
	v_cvt_pk_bf16_f32 v31, v40, v41
	s_waitcnt vmcnt(19)
	v_lshlrev_b32_e32 v40, 16, v48
	v_and_b32_e32 v41, 0xffff0000, v48
	v_mov_b32_e32 v171, v170
	ds_write_b128 v185, v[28:31] offset:9216
	v_lshlrev_b32_e32 v30, 16, v32
	v_and_b32_e32 v31, 0xffff0000, v32
	v_mul_f32_e64 v40, v170, v40
	v_mul_f32_e64 v41, v170, v41
	v_lshlrev_b32_e32 v28, 16, v36
	v_and_b32_e32 v29, 0xffff0000, v36
	v_fma_f32 v30, v30, 0.5, v40
	v_fma_f32 v31, v31, 0.5, v41
	v_lshlrev_b32_e32 v36, 16, v49
	v_add_f32_e64 v30, v30, -v28
	v_add_f32_e64 v31, v31, -v29
	v_lshlrev_b32_e32 v32, 16, v33
	v_fma_f32 v28, v30, v4, v28
	v_fma_f32 v29, v31, v5, v29
	v_lshlrev_b32_e32 v30, 16, v37
	v_and_b32_e32 v31, 0xffff0000, v37
	v_and_b32_e32 v37, 0xffff0000, v49
	v_and_b32_e32 v33, 0xffff0000, v33
	v_mul_f32_e64 v36, v170, v36
	v_mul_f32_e64 v37, v170, v37
	v_fma_f32 v32, v32, 0.5, v36
	v_fma_f32 v33, v33, 0.5, v37
	v_lshlrev_b32_e32 v36, 16, v50
	v_add_f32_e64 v32, v32, -v30
	v_add_f32_e64 v33, v33, -v31
	v_and_b32_e32 v37, 0xffff0000, v50
	v_fma_f32 v30, v32, v6, v30
	v_fma_f32 v31, v33, v7, v31
	v_lshlrev_b32_e32 v32, 16, v34
	v_and_b32_e32 v33, 0xffff0000, v34
	v_mul_f32_e64 v36, v170, v36
	v_mul_f32_e64 v37, v170, v37
	v_cvt_pk_bf16_f32 v28, v28, v29
	v_cvt_pk_bf16_f32 v29, v30, v31
	v_lshlrev_b32_e32 v30, 16, v38
	v_and_b32_e32 v31, 0xffff0000, v38
	v_fma_f32 v32, v32, 0.5, v36
	v_fma_f32 v33, v33, 0.5, v37
	v_lshlrev_b32_e32 v36, 16, v51
	v_and_b32_e32 v37, 0xffff0000, v51
	v_add_f32_e64 v32, v32, -v30
	v_add_f32_e64 v33, v33, -v31
	v_lshlrev_b32_e32 v34, 16, v35
	v_and_b32_e32 v35, 0xffff0000, v35
	v_mul_f32_e64 v36, v170, v36
	v_mul_f32_e64 v37, v170, v37
	v_fma_f32 v30, v32, v0, v30
	v_fma_f32 v31, v33, v1, v31
	v_lshlrev_b32_e32 v32, 16, v39
	v_and_b32_e32 v33, 0xffff0000, v39
	v_fma_f32 v34, v34, 0.5, v36
	v_fma_f32 v35, v35, 0.5, v37
	v_cvt_pk_bf16_f32 v30, v30, v31
	v_add_f32_e64 v34, v34, -v32
	v_add_f32_e64 v35, v35, -v33
	v_cndmask_b32_e64 v172, 0.5, 0, s[12:13]
	v_fma_f32 v32, v34, v2, v32
	v_fma_f32 v33, v35, v3, v33
	v_cndmask_b32_e64 v173, 0.5, 0, vcc
	v_cvt_pk_bf16_f32 v31, v32, v33
	s_waitcnt vmcnt(18)
; __device__ __forceinline__ unsigned cvtpk(float lo, float hi) { f32x2 v = {lo, hi}; bf16x2_t b = __builtin_convertvector(v, bf16x2_t); return *(unsigned*)&b; }
; __device__ __forceinline__ float lo16(unsigned w) { return __uint_as_float(w << 16); }
; __device__ __forceinline__ float hi16(unsigned w) { return __uint_as_float(w & 0xffff0000u); }
; template <int AMODE, int BN, class Epi>
; __device__ __forceinline__ void gemm_tile(const bf16_t* A, const int lda, const bf16_t* Bt, const int K, const int m0, const float* mu, char* lds, const Epi& epi) {
;     ...
;   f32x16 acc[MI][2];
; #pragma unroll
;   for (int i = 0; i < MI; ++i)
; #pragma unroll
;     for (int j = 0; j < 2; ++j)
; #pragma unroll
;       for (int r = 0; r < 16; ++r) acc[i][j][r] = 0.f;
;     ...
;   auto lstore = [&](int s, int k0) {
;     char* base = lds + s * G_STAGE;
;     if constexpr (AMODE == 1) {
;       const f32x4 m0v = *(const f32x4*)(mu + k0 + scc), m1v = *(const f32x4*)(mu + k0 + scc + 4);
;       const float mm[8] = {m0v[0], m0v[1], m0v[2], m0v[3], m1v[0], m1v[1], m1v[2], m1v[3]};
; #pragma unroll
;       for (int i = 0; i < 4; ++i) {
;         const u32x4 hc = *(const u32x4*)&ra[i], hp = *(const u32x4*)&rp[i], hn = *(const u32x4*)&rn[i];
;         const float fp = dprev[i] ? 0.5f : 0.f, fn = dnext[i] ? 0.5f : 0.f;
;         u32x4 w;
; #pragma unroll
;         for (int q = 0; q < 4; ++q) {
;           const float c0 = lo16(hc[q]), c1 = hi16(hc[q]);
;           const float x0 = fp * lo16(hp[q]) + fn * lo16(hn[q]) - c0, x1 = fp * hi16(hp[q]) + fn * hi16(hn[q]) - c1;
;           w[q] = cvtpk(c0 + x0 * mm[2 * q], c1 + x1 * mm[2 * q + 1]);
;         }
;         *(u32x4*)(base + (srow + 64 * i) * G_LDT + scc * 2) = w;
;       }
;     } else {
; #pragma unroll
;       for (int i = 0; i < 4; ++i) {
;         *(bf16x8*)(base + (srow + 64 * i) * G_LDT + scc * 2) = ra[i];
;         if constexpr (AMODE == 2) {
;           const u32x4 hc = *(const u32x4*)&ra[i];
; #pragma unroll
;           for (int q = 0; q < 4; ++q) { const float c0 = lo16(hc[q]), c1 = hi16(hc[q]); ssq[i] += c0 * c0 + c1 * c1; }
;         }
;       }
;     }
; #pragma unroll
;     for (int i = 0; i < NBR; ++i) *(bf16x8*)(base + 256 * G_LDT + (srow + 64 * i) * G_LDT + scc * 2) = rb[i];
;   };
;   const int nk = K >> 6;
;   gload(0);
;   lstore(0, 0);
;   if (nk > 1) gload(64);
	v_lshlrev_b32_e32 v32, 16, v12
	s_waitcnt vmcnt(17)
	v_and_b32_e32 v33, 0xffff0000, v24
	ds_write_b128 v185, v[28:31] offset:18432
	v_lshlrev_b32_e32 v30, 16, v24
	v_and_b32_e32 v31, 0xffff0000, v12
	v_mul_f32_e64 v32, v173, v32
	v_mul_f32_e64 v33, v172, v33
	s_waitcnt vmcnt(16)
	v_lshlrev_b32_e32 v28, 16, v8
	v_and_b32_e32 v29, 0xffff0000, v8
	v_fma_f32 v30, v172, v30, v32
	v_fma_f32 v31, v173, v31, v33
	v_lshlrev_b32_e32 v12, 16, v13
	v_add_f32_e64 v30, v30, -v28
	v_add_f32_e64 v31, v31, -v29
	v_lshlrev_b32_e32 v8, 16, v9
	v_fma_f32 v4, v4, v30, v28
	v_fma_f32 v5, v5, v31, v29
	v_and_b32_e32 v29, 0xffff0000, v13
	v_and_b32_e32 v13, 0xffff0000, v25
	v_lshlrev_b32_e32 v28, 16, v25
	v_mul_f32_e64 v12, v173, v12
	v_mul_f32_e64 v13, v172, v13
	v_and_b32_e32 v9, 0xffff0000, v9
	v_fma_f32 v12, v172, v28, v12
	v_fma_f32 v13, v173, v29, v13
	v_cvt_pk_bf16_f32 v4, v4, v5
	v_add_f32_e64 v12, v12, -v8
	v_add_f32_e64 v13, v13, -v9
	v_pk_mov_b32 v[168:169], v[166:167], v[166:167] op_sel:[1,0]
	v_fma_f32 v6, v6, v12, v8
	v_fma_f32 v7, v7, v13, v9
	v_lshlrev_b32_e32 v12, 16, v14
	v_and_b32_e32 v13, 0xffff0000, v26
	v_lshlrev_b32_e32 v8, 16, v26
	v_and_b32_e32 v9, 0xffff0000, v14
	v_mul_f32_e64 v12, v173, v12
	v_mul_f32_e64 v13, v172, v13
	v_cvt_pk_bf16_f32 v5, v6, v7
	v_lshlrev_b32_e32 v6, 16, v10
	v_and_b32_e32 v7, 0xffff0000, v10
	v_fma_f32 v8, v172, v8, v12
	v_fma_f32 v9, v173, v9, v13
	v_lshlrev_b32_e32 v10, 16, v15
	v_add_f32_e64 v8, v8, -v6
	v_add_f32_e64 v9, v9, -v7
	v_pk_mov_b32 v[174:175], v[172:173], v[172:173] op_sel:[1,0]
	v_fma_f32 v0, v0, v8, v6
	v_fma_f32 v1, v1, v9, v7
	v_lshlrev_b32_e32 v8, 16, v27
	v_cvt_pk_bf16_f32 v6, v0, v1
	v_lshlrev_b32_e32 v0, 16, v11
	v_and_b32_e32 v1, 0xffff0000, v11
	v_and_b32_e32 v11, 0xffff0000, v27
	v_and_b32_e32 v9, 0xffff0000, v15
	v_mul_f32_e64 v10, v173, v10
	v_mul_f32_e64 v11, v172, v11
	v_fma_f32 v8, v172, v8, v10
	v_fma_f32 v9, v173, v9, v11
	s_waitcnt vmcnt(13)
	ds_write_b128 v185, v[16:19] offset:36864
	v_add_f32_e64 v8, v8, -v0
	v_add_f32_e64 v9, v9, -v1
	s_waitcnt vmcnt(12)
	ds_write_b128 v185, v[20:23] offset:46080
	v_fma_f32 v0, v2, v8, v0
	v_fma_f32 v1, v3, v9, v1
	v_lshl_add_u64 v[188:189], v[134:135], 0, s[48:49]
	v_cvt_pk_bf16_f32 v7, v0, v1
	v_lshl_add_u64 v[0:1], v[192:193], 0, v[190:191]
	v_lshl_add_u64 v[190:191], v[136:137], 0, v[0:1]
	v_lshl_add_u64 v[0:1], v[192:193], 0, v[194:195]
	v_lshl_add_u64 v[192:193], v[136:137], 0, v[0:1]
	v_lshl_add_u64 v[0:1], v[196:197], 0, v[200:201]
	v_lshl_add_u64 v[196:197], v[136:137], 0, v[0:1]
	v_lshl_add_u64 v[0:1], v[124:125], 0, v[198:199]
	v_lshl_add_u64 v[198:199], v[136:137], 0, v[0:1]
	v_lshl_add_u64 v[0:1], v[124:125], 0, v[126:127]
	v_lshl_add_u64 v[200:201], v[136:137], 0, v[0:1]
	v_lshl_add_u64 v[0:1], v[120:121], 0, v[122:123]
	ds_write_b128 v185, v[4:7] offset:27648
	v_lshl_add_u64 v[194:195], v[138:139], 0, s[22:23]
	v_lshl_add_u64 v[202:203], v[136:137], 0, v[0:1]
	s_mov_b64 s[4:5], 0
	s_mov_b32 s6, 0
	v_mov_b32_e32 v48, 0
	v_mov_b32_e32 v49, v129
	v_mov_b32_e32 v50, v129
	v_mov_b32_e32 v51, v129
	v_mov_b32_e32 v52, v129
	v_mov_b32_e32 v53, v129
	v_mov_b32_e32 v54, v129
	v_mov_b32_e32 v55, v129
	v_mov_b32_e32 v56, v129
	v_mov_b32_e32 v57, v129
	v_mov_b32_e32 v58, v129
	v_mov_b32_e32 v59, v129
	v_mov_b32_e32 v60, v129
	v_mov_b32_e32 v61, v129
	v_mov_b32_e32 v62, v129
	v_mov_b32_e32 v63, v129
	v_mov_b32_e32 v32, 0
	v_mov_b32_e32 v33, v129
	v_mov_b32_e32 v34, v129
	v_mov_b32_e32 v35, v129
	v_mov_b32_e32 v36, v129
	v_mov_b32_e32 v37, v129
	v_mov_b32_e32 v38, v129
	v_mov_b32_e32 v39, v129
	v_mov_b32_e32 v40, v129
	v_mov_b32_e32 v41, v129
	v_mov_b32_e32 v42, v129
	v_mov_b32_e32 v43, v129
	v_mov_b32_e32 v44, v129
	v_mov_b32_e32 v45, v129
	v_mov_b32_e32 v46, v129
	v_mov_b32_e32 v47, v129
	v_mov_b32_e32 v16, 0
	v_mov_b32_e32 v17, v129
	v_mov_b32_e32 v18, v129
	v_mov_b32_e32 v19, v129
	v_mov_b32_e32 v20, v129
	v_mov_b32_e32 v21, v129
	v_mov_b32_e32 v22, v129
	v_mov_b32_e32 v23, v129
	v_mov_b32_e32 v24, v129
	v_mov_b32_e32 v25, v129
	v_mov_b32_e32 v26, v129
	v_mov_b32_e32 v27, v129
	v_mov_b32_e32 v28, v129
	v_mov_b32_e32 v29, v129
	v_mov_b32_e32 v30, v129
	v_mov_b32_e32 v31, v129
	v_mov_b32_e32 v0, 0
	v_mov_b32_e32 v1, v129
	v_mov_b32_e32 v2, v129
	v_mov_b32_e32 v3, v129
	v_mov_b32_e32 v4, v129
	v_mov_b32_e32 v5, v129
	v_mov_b32_e32 v6, v129
	v_mov_b32_e32 v7, v129
	v_mov_b32_e32 v8, v129
	v_mov_b32_e32 v9, v129
	v_mov_b32_e32 v10, v129
	v_mov_b32_e32 v11, v129
	v_mov_b32_e32 v12, v129
	v_mov_b32_e32 v13, v129
	v_mov_b32_e32 v14, v129
	v_mov_b32_e32 v15, v129
	s_waitcnt lgkmcnt(0)
	s_barrier
	s_branch .LBB0_465

; __device__ __forceinline__ unsigned cvtpk(float lo, float hi) { f32x2 v = {lo, hi}; bf16x2_t b = __builtin_convertvector(v, bf16x2_t); return *(unsigned*)&b; }
; __device__ __forceinline__ float lo16(unsigned w) { return __uint_as_float(w << 16); }
; __device__ __forceinline__ float hi16(unsigned w) { return __uint_as_float(w & 0xffff0000u); }
; template <int AMODE, int BN, class Epi>
; __device__ __forceinline__ void gemm_tile(const bf16_t* A, const int lda, const bf16_t* Bt, const int K, const int m0, const float* mu, char* lds, const Epi& epi) {
;     ...
;   auto lstore = [&](int s, int k0) {
;     char* base = lds + s * G_STAGE;
;     if constexpr (AMODE == 1) {
;       const f32x4 m0v = *(const f32x4*)(mu + k0 + scc), m1v = *(const f32x4*)(mu + k0 + scc + 4);
;       const float mm[8] = {m0v[0], m0v[1], m0v[2], m0v[3], m1v[0], m1v[1], m1v[2], m1v[3]};
; #pragma unroll
;       for (int i = 0; i < 4; ++i) {
;         const u32x4 hc = *(const u32x4*)&ra[i], hp = *(const u32x4*)&rp[i], hn = *(const u32x4*)&rn[i];
;         const float fp = dprev[i] ? 0.5f : 0.f, fn = dnext[i] ? 0.5f : 0.f;
;         u32x4 w;
; #pragma unroll
;         for (int q = 0; q < 4; ++q) {
;           const float c0 = lo16(hc[q]), c1 = hi16(hc[q]);
;           const float x0 = fp * lo16(hp[q]) + fn * lo16(hn[q]) - c0, x1 = fp * hi16(hp[q]) + fn * hi16(hn[q]) - c1;
;           w[q] = cvtpk(c0 + x0 * mm[2 * q], c1 + x1 * mm[2 * q + 1]);
;         }
;         *(u32x4*)(base + (srow + 64 * i) * G_LDT + scc * 2) = w;
;       }
;     ...
;   for (int kt = 0; kt < nk; ++kt) {
;     const int s = kt & 1;
;     if (kt + 1 < nk) lstore(s ^ 1, (kt + 1) * 64);
;     if (kt + 2 < nk) gload((kt + 2) * 64);
.LBB0_465:
	s_and_b32 s7, s6, 1
	s_cmpk_eq_i32 s4, 0x780
	s_cbranch_scc1 .LBB0_467
	global_load_dwordx4 v[124:127], v[194:195], off offset:-16
	global_load_dwordx4 v[120:123], v[194:195], off
	s_waitcnt vmcnt(13)
	v_lshlrev_b32_e32 v214, 16, v68
	v_and_b32_e32 v215, 0xffff0000, v68
	v_lshlrev_b32_e32 v220, 16, v69
	v_and_b32_e32 v221, 0xffff0000, v69
	v_lshlrev_b32_e32 v226, 16, v70
	v_and_b32_e32 v227, 0xffff0000, v70
	v_lshlrev_b32_e32 v232, 16, v71
	v_and_b32_e32 v233, 0xffff0000, v71
	s_waitcnt vmcnt(12)
	v_lshlrev_b32_e32 v216, 16, v72
	v_and_b32_e32 v217, 0xffff0000, v72
	v_lshlrev_b32_e32 v222, 16, v73
	v_and_b32_e32 v223, 0xffff0000, v73
	v_lshlrev_b32_e32 v228, 16, v74
	v_and_b32_e32 v229, 0xffff0000, v74
	v_lshlrev_b32_e32 v234, 16, v75
	v_and_b32_e32 v235, 0xffff0000, v75
	v_mul_f32_e64 v214, v164, v214
	v_mul_f32_e64 v215, v165, v215
	v_mul_f32_e64 v220, v164, v220
	v_mul_f32_e64 v221, v165, v221
	v_mul_f32_e64 v226, v164, v226
	v_mul_f32_e64 v227, v165, v227
	v_mul_f32_e64 v232, v164, v232
	v_mul_f32_e64 v233, v165, v233
	v_lshlrev_b32_e32 v212, 16, v64
	v_and_b32_e32 v213, 0xffff0000, v64
	v_lshlrev_b32_e32 v218, 16, v65
	v_and_b32_e32 v219, 0xffff0000, v65
	v_lshlrev_b32_e32 v224, 16, v66
	v_and_b32_e32 v225, 0xffff0000, v66
	v_lshlrev_b32_e32 v230, 16, v67
	v_and_b32_e32 v231, 0xffff0000, v67
	s_waitcnt vmcnt(8)
	v_lshlrev_b32_e32 v238, 16, v80
	s_waitcnt vmcnt(7)
	v_and_b32_e32 v239, 0xffff0000, v84
	v_fma_f32 v214, v216, 0.5, v214
	v_fma_f32 v215, v217, 0.5, v215
	v_fma_f32 v216, v222, 0.5, v220
	v_fma_f32 v217, v223, 0.5, v221
	v_fma_f32 v220, v228, 0.5, v226
	v_fma_f32 v221, v229, 0.5, v227
	v_fma_f32 v222, v234, 0.5, v232
	v_fma_f32 v223, v235, 0.5, v233
	s_xor_b32 s10, s7, 1
	v_lshlrev_b32_e32 v240, 16, v84
	v_and_b32_e32 v241, 0xffff0000, v80
	v_mul_f32_e64 v238, v168, v238
	v_mul_f32_e64 v239, v169, v239
	v_add_f32_e64 v214, v214, -v212
	v_add_f32_e64 v215, v215, -v213
	v_add_f32_e64 v216, v216, -v218
	v_add_f32_e64 v217, v217, -v219
	v_add_f32_e64 v220, v220, -v224
	v_add_f32_e64 v221, v221, -v225
	v_add_f32_e64 v222, v222, -v230
	v_add_f32_e64 v223, v223, -v231
	v_lshlrev_b32_e32 v236, 16, v76
	v_and_b32_e32 v237, 0xffff0000, v76
	s_mul_i32 s10, s10, 0xd800
	v_fma_f32 v226, v166, v240, v238
	v_fma_f32 v227, v167, v241, v239
	v_add_u32_e32 v143, s10, v185
	v_add_f32_e64 v226, v226, -v236
	v_add_f32_e64 v227, v227, -v237
	v_lshlrev_b32_e32 v244, 16, v81
	v_and_b32_e32 v245, 0xffff0000, v85
	v_lshlrev_b32_e32 v250, 16, v82
	v_and_b32_e32 v251, 0xffff0000, v86
	v_lshlrev_b32_e32 v246, 16, v85
	v_and_b32_e32 v247, 0xffff0000, v81
	v_lshlrev_b32_e32 v252, 16, v86
	v_and_b32_e32 v253, 0xffff0000, v82
	v_mul_f32_e64 v244, v168, v244
	v_mul_f32_e64 v245, v169, v245
	v_mul_f32_e64 v250, v168, v250
	v_mul_f32_e64 v251, v169, v251
	v_lshlrev_b32_e32 v242, 16, v77
	v_and_b32_e32 v243, 0xffff0000, v77
	v_lshlrev_b32_e32 v248, 16, v78
	v_and_b32_e32 v249, 0xffff0000, v78
	v_fma_f32 v228, v166, v246, v244
	v_fma_f32 v229, v167, v247, v245
	v_fma_f32 v232, v166, v252, v250
	v_fma_f32 v233, v167, v253, v251
	v_add_f32_e64 v228, v228, -v242
	v_add_f32_e64 v229, v229, -v243
	v_add_f32_e64 v232, v232, -v248
	v_add_f32_e64 v233, v233, -v249
	s_waitcnt vmcnt(1)
	v_fma_f32 v212, v214, v124, v212
	v_fma_f32 v213, v215, v125, v213
	v_fma_f32 v214, v216, v126, v218
	v_fma_f32 v215, v217, v127, v219
	s_waitcnt vmcnt(0)
; __device__ __forceinline__ unsigned cvtpk(float lo, float hi) { f32x2 v = {lo, hi}; bf16x2_t b = __builtin_convertvector(v, bf16x2_t); return *(unsigned*)&b; }
; __device__ __forceinline__ float lo16(unsigned w) { return __uint_as_float(w << 16); }
; __device__ __forceinline__ float hi16(unsigned w) { return __uint_as_float(w & 0xffff0000u); }
; template <int AMODE, int BN, class Epi>
; __device__ __forceinline__ void gemm_tile(const bf16_t* A, const int lda, const bf16_t* Bt, const int K, const int m0, const float* mu, char* lds, const Epi& epi) {
;     ...
;   auto lstore = [&](int s, int k0) {
;     char* base = lds + s * G_STAGE;
;     if constexpr (AMODE == 1) {
;       const f32x4 m0v = *(const f32x4*)(mu + k0 + scc), m1v = *(const f32x4*)(mu + k0 + scc + 4);
;       const float mm[8] = {m0v[0], m0v[1], m0v[2], m0v[3], m1v[0], m1v[1], m1v[2], m1v[3]};
; #pragma unroll
;       for (int i = 0; i < 4; ++i) {
;         const u32x4 hc = *(const u32x4*)&ra[i], hp = *(const u32x4*)&rp[i], hn = *(const u32x4*)&rn[i];
;         const float fp = dprev[i] ? 0.5f : 0.f, fn = dnext[i] ? 0.5f : 0.f;
;         u32x4 w;
; #pragma unroll
;         for (int q = 0; q < 4; ++q) {
;           const float c0 = lo16(hc[q]), c1 = hi16(hc[q]);
;           const float x0 = fp * lo16(hp[q]) + fn * lo16(hn[q]) - c0, x1 = fp * hi16(hp[q]) + fn * hi16(hn[q]) - c1;
;           w[q] = cvtpk(c0 + x0 * mm[2 * q], c1 + x1 * mm[2 * q + 1]);
;         }
;         *(u32x4*)(base + (srow + 64 * i) * G_LDT + scc * 2) = w;
;       }
;     } else {
; #pragma unroll
;       for (int i = 0; i < 4; ++i) {
;         *(bf16x8*)(base + (srow + 64 * i) * G_LDT + scc * 2) = ra[i];
;         if constexpr (AMODE == 2) {
;           const u32x4 hc = *(const u32x4*)&ra[i];
; #pragma unroll
;           for (int q = 0; q < 4; ++q) { const float c0 = lo16(hc[q]), c1 = hi16(hc[q]); ssq[i] += c0 * c0 + c1 * c1; }
;         }
;       }
;     }
; #pragma unroll
;     for (int i = 0; i < NBR; ++i) *(bf16x8*)(base + 256 * G_LDT + (srow + 64 * i) * G_LDT + scc * 2) = rb[i];
	v_fma_f32 v216, v220, v120, v224
	v_fma_f32 v217, v221, v121, v225
	v_fma_f32 v218, v222, v122, v230
	v_fma_f32 v219, v223, v123, v231
	v_cvt_pk_bf16_f32 v212, v212, v213
	v_cvt_pk_bf16_f32 v213, v214, v215
	v_cvt_pk_bf16_f32 v214, v216, v217
	v_cvt_pk_bf16_f32 v215, v218, v219
	v_fma_f32 v220, v226, v124, v236
	v_fma_f32 v221, v227, v125, v237
	ds_write_b128 v143, v[212:215]
	v_lshlrev_b32_e32 v214, 16, v83
	v_and_b32_e32 v215, 0xffff0000, v87
	v_cvt_pk_bf16_f32 v216, v220, v221
	v_mul_f32_e64 v214, v168, v214
	v_mul_f32_e64 v215, v169, v215
	v_lshlrev_b32_e32 v220, 16, v87
	v_and_b32_e32 v221, 0xffff0000, v83
	v_lshlrev_b32_e32 v212, 16, v79
	v_and_b32_e32 v213, 0xffff0000, v79
	v_fma_f32 v214, v166, v220, v214
	v_fma_f32 v215, v167, v221, v215
	v_fma_f32 v222, v228, v126, v242
	v_fma_f32 v223, v229, v127, v243
	v_add_f32_e64 v214, v214, -v212
	v_add_f32_e64 v215, v215, -v213
	v_fma_f32 v224, v232, v120, v248
	v_fma_f32 v225, v233, v121, v249
	v_fma_f32 v212, v214, v122, v212
	v_fma_f32 v213, v215, v123, v213
	v_cvt_pk_bf16_f32 v217, v222, v223
	v_cvt_pk_bf16_f32 v218, v224, v225
	v_cvt_pk_bf16_f32 v219, v212, v213
	ds_write_b128 v143, v[216:219] offset:9216
	v_lshlrev_b32_e32 v216, 16, v96
	v_and_b32_e32 v217, 0xffff0000, v96
	v_lshlrev_b32_e32 v214, 16, v92
	v_and_b32_e32 v215, 0xffff0000, v92
	v_mul_f32_e64 v216, v170, v216
	v_mul_f32_e64 v217, v171, v217
	v_lshlrev_b32_e32 v212, 16, v88
	v_and_b32_e32 v213, 0xffff0000, v88
	v_fma_f32 v214, v214, 0.5, v216
	v_fma_f32 v215, v215, 0.5, v217
	v_lshlrev_b32_e32 v218, 16, v97
	v_and_b32_e32 v219, 0xffff0000, v97
	v_add_f32_e64 v214, v214, -v212
	v_add_f32_e64 v215, v215, -v213
	v_lshlrev_b32_e32 v216, 16, v93
	v_and_b32_e32 v217, 0xffff0000, v93
	v_mul_f32_e64 v218, v170, v218
	v_mul_f32_e64 v219, v171, v219
	v_fma_f32 v212, v214, v124, v212
	v_fma_f32 v213, v215, v125, v213
	v_lshlrev_b32_e32 v214, 16, v89
	v_and_b32_e32 v215, 0xffff0000, v89
	v_fma_f32 v216, v216, 0.5, v218
	v_fma_f32 v217, v217, 0.5, v219
	v_lshlrev_b32_e32 v218, 16, v98
	v_add_f32_e64 v216, v216, -v214
	v_add_f32_e64 v217, v217, -v215
	v_and_b32_e32 v219, 0xffff0000, v98
	v_fma_f32 v214, v216, v126, v214
	v_fma_f32 v215, v217, v127, v215
	v_lshlrev_b32_e32 v216, 16, v94
	v_and_b32_e32 v217, 0xffff0000, v94
	v_mul_f32_e64 v218, v170, v218
	v_mul_f32_e64 v219, v171, v219
	v_cvt_pk_bf16_f32 v212, v212, v213
	v_cvt_pk_bf16_f32 v213, v214, v215
	v_lshlrev_b32_e32 v214, 16, v90
	v_and_b32_e32 v215, 0xffff0000, v90
	v_fma_f32 v216, v216, 0.5, v218
	v_fma_f32 v217, v217, 0.5, v219
	v_lshlrev_b32_e32 v220, 16, v99
	v_and_b32_e32 v221, 0xffff0000, v99
	v_add_f32_e64 v216, v216, -v214
	v_add_f32_e64 v217, v217, -v215
	v_lshlrev_b32_e32 v218, 16, v95
	v_and_b32_e32 v219, 0xffff0000, v95
	v_mul_f32_e64 v220, v170, v220
	v_mul_f32_e64 v221, v171, v221
	v_fma_f32 v214, v216, v120, v214
	v_fma_f32 v215, v217, v121, v215
	v_lshlrev_b32_e32 v216, 16, v91
	v_and_b32_e32 v217, 0xffff0000, v91
	v_fma_f32 v218, v218, 0.5, v220
	v_fma_f32 v219, v219, 0.5, v221
	v_cvt_pk_bf16_f32 v214, v214, v215
	v_add_f32_e64 v218, v218, -v216
	v_add_f32_e64 v219, v219, -v217
	s_nop 0
	v_fma_f32 v216, v218, v122, v216
	v_fma_f32 v217, v219, v123, v217
	s_nop 0
	v_cvt_pk_bf16_f32 v215, v216, v217
	v_lshlrev_b32_e32 v216, 16, v108
	v_and_b32_e32 v217, 0xffff0000, v104
	ds_write_b128 v143, v[212:215] offset:18432
	v_lshlrev_b32_e32 v214, 16, v104
	v_and_b32_e32 v215, 0xffff0000, v108
	v_mul_f32_e64 v216, v174, v216
	v_mul_f32_e64 v217, v175, v217
	v_lshlrev_b32_e32 v212, 16, v100
	v_and_b32_e32 v213, 0xffff0000, v100
	v_fma_f32 v214, v172, v214, v216
	v_fma_f32 v215, v173, v215, v217
	v_lshlrev_b32_e32 v216, 16, v109
	v_add_f32_e64 v214, v214, -v212
	v_add_f32_e64 v215, v215, -v213
	v_and_b32_e32 v217, 0xffff0000, v105
	v_fma_f32 v124, v214, v124, v212
	v_fma_f32 v125, v215, v125, v213
	v_lshlrev_b32_e32 v214, 16, v105
	v_and_b32_e32 v215, 0xffff0000, v109
	v_mul_f32_e64 v216, v174, v216
	v_mul_f32_e64 v217, v175, v217
	v_lshlrev_b32_e32 v212, 16, v101
	v_and_b32_e32 v213, 0xffff0000, v101
	v_fma_f32 v214, v172, v214, v216
	v_fma_f32 v215, v173, v215, v217
	v_cvt_pk_bf16_f32 v124, v124, v125
	v_add_f32_e64 v214, v214, -v212
	v_add_f32_e64 v215, v215, -v213
	s_nop 0
	v_fma_f32 v126, v214, v126, v212
	v_fma_f32 v127, v215, v127, v213
	v_lshlrev_b32_e32 v214, 16, v110
	v_and_b32_e32 v215, 0xffff0000, v106
	v_lshlrev_b32_e32 v212, 16, v106
	v_and_b32_e32 v213, 0xffff0000, v110
	v_mul_f32_e64 v214, v174, v214
	v_mul_f32_e64 v215, v175, v215
	v_cvt_pk_bf16_f32 v125, v126, v127
	v_lshlrev_b32_e32 v126, 16, v102
	v_and_b32_e32 v127, 0xffff0000, v102
	v_fma_f32 v212, v172, v212, v214
	v_fma_f32 v213, v173, v213, v215
	v_lshlrev_b32_e32 v214, 16, v111
	v_add_f32_e64 v212, v212, -v126
	v_add_f32_e64 v213, v213, -v127
	v_and_b32_e32 v215, 0xffff0000, v107
	v_fma_f32 v120, v212, v120, v126
	v_fma_f32 v121, v213, v121, v127
	v_lshlrev_b32_e32 v212, 16, v107
	v_and_b32_e32 v213, 0xffff0000, v111
	v_mul_f32_e64 v214, v174, v214
	v_mul_f32_e64 v215, v175, v215
	v_cvt_pk_bf16_f32 v126, v120, v121
	v_lshlrev_b32_e32 v120, 16, v103
	v_and_b32_e32 v121, 0xffff0000, v103
	v_fma_f32 v212, v172, v212, v214
	v_fma_f32 v213, v173, v213, v215
	s_nop 0
	v_add_f32_e64 v212, v212, -v120
	v_add_f32_e64 v213, v213, -v121
	s_nop 0
	v_fma_f32 v120, v212, v122, v120
	v_fma_f32 v121, v213, v123, v121
	s_nop 0
	v_cvt_pk_bf16_f32 v127, v120, v121
	ds_write_b128 v143, v[124:127] offset:27648
	ds_write_b128 v143, v[112:115] offset:36864
	ds_write_b128 v143, v[116:119] offset:46080

; __device__ __forceinline__ unsigned cvtpk(float lo, float hi) { f32x2 v = {lo, hi}; bf16x2_t b = __builtin_convertvector(v, bf16x2_t); return *(unsigned*)&b; }
; #define TANH_(x) (1.f - 2.f * __builtin_amdgcn_rcpf(__expf(2.f * (x) * sc) + 1.f))
;   __device__ __forceinline__ void operator()(int lrow, int nc, const f32x16& a0, const f32x16& a1, float aux) const {
;     ...
;     if (act) {
;     ...
;       const u32x4 w0 = {cvtpk(TANH_(a0[0]), TANH_(a0[1])), cvtpk(TANH_(a0[2]), TANH_(a0[3])), cvtpk(TANH_(a0[4]), TANH_(a0[5])), cvtpk(TANH_(a0[6]), TANH_(a0[7]))};
;       const u32x4 w1 = {cvtpk(TANH_(a0[8]), TANH_(a0[9])), cvtpk(TANH_(a0[10]), TANH_(a0[11])), cvtpk(TANH_(a0[12]), TANH_(a0[13])), cvtpk(TANH_(a0[14]), TANH_(a0[15]))};
;       const u32x4 w2 = {cvtpk(TANH_(a1[0]), TANH_(a1[1])), cvtpk(TANH_(a1[2]), TANH_(a1[3])), cvtpk(TANH_(a1[4]), TANH_(a1[5])), cvtpk(TANH_(a1[6]), TANH_(a1[7]))};
;       const u32x4 w3 = {cvtpk(TANH_(a1[8]), TANH_(a1[9])), cvtpk(TANH_(a1[10]), TANH_(a1[11])), cvtpk(TANH_(a1[12]), TANH_(a1[13])), cvtpk(TANH_(a1[14]), TANH_(a1[15]))};
;     ...
;       *(u32x4*)(wp) = w0; *(u32x4*)(wp + 16) = w1; *(u32x4*)(wp + 64) = w2; *(u32x4*)(wp + 80) = w3;
.LBB0_471:
	s_andn2_b64 vcc, exec, s[6:7]
	s_cbranch_vccnz .LBB0_473
	s_nop 0
	v_add_f32_e32 v48, v48, v48
	v_add_f32_e32 v49, v49, v49
	v_mul_f32_e32 v48, 0x3fb8aa3b, v48
	v_mul_f32_e32 v49, 0x3fb8aa3b, v49
	v_exp_f32_e32 v48, v48
	v_exp_f32_e32 v49, v49
	v_add_f32_e32 v50, v50, v50
	v_add_f32_e32 v51, v51, v51
	v_add_f32_e32 v48, 1.0, v48
	v_add_f32_e32 v49, 1.0, v49
	v_rcp_f32_e32 v48, v48
	v_rcp_f32_e32 v49, v49
	v_mul_f32_e32 v50, 0x3fb8aa3b, v50
	v_mul_f32_e32 v51, 0x3fb8aa3b, v51
	v_exp_f32_e32 v50, v50
	v_exp_f32_e32 v51, v51
	v_fma_f32 v48, -v48, 2.0, 1.0
	v_fma_f32 v49, -v49, 2.0, 1.0
	v_add_f32_e32 v32, v32, v32
	s_waitcnt vmcnt(13)
	v_cvt_pk_bf16_f32 v64, v48, v49
	v_add_f32_e32 v48, 1.0, v50
	v_add_f32_e32 v49, 1.0, v51
	v_add_f32_e32 v50, v52, v52
	v_add_f32_e32 v51, v53, v53
	v_mul_f32_e32 v50, 0x3fb8aa3b, v50
	v_mul_f32_e32 v51, 0x3fb8aa3b, v51
	v_exp_f32_e32 v50, v50
	v_exp_f32_e32 v51, v51
	v_add_f32_e32 v52, v54, v54
	v_add_f32_e32 v53, v55, v55
	v_rcp_f32_e32 v48, v48
	v_rcp_f32_e32 v49, v49
	v_add_f32_e32 v50, 1.0, v50
	v_add_f32_e32 v51, 1.0, v51
	v_mul_f32_e32 v52, 0x3fb8aa3b, v52
	v_mul_f32_e32 v53, 0x3fb8aa3b, v53
	v_rcp_f32_e32 v50, v50
	v_exp_f32_e32 v52, v52
	v_exp_f32_e32 v53, v53
	v_rcp_f32_e32 v51, v51
	v_fma_f32 v48, -v48, 2.0, 1.0
	v_fma_f32 v49, -v49, 2.0, 1.0
	v_add_f32_e32 v52, 1.0, v52
	v_add_f32_e32 v53, 1.0, v53
	v_cvt_pk_bf16_f32 v65, v48, v49
	v_fma_f32 v48, -v50, 2.0, 1.0
	v_fma_f32 v49, -v51, 2.0, 1.0
	v_add_f32_e32 v50, v56, v56
	v_add_f32_e32 v51, v57, v57
	v_rcp_f32_e32 v52, v52
	v_rcp_f32_e32 v53, v53
	v_mul_f32_e32 v50, 0x3fb8aa3b, v50
	v_mul_f32_e32 v51, 0x3fb8aa3b, v51
	v_exp_f32_e32 v50, v50
	v_exp_f32_e32 v51, v51
	v_cvt_pk_bf16_f32 v66, v48, v49
	v_fma_f32 v48, -v52, 2.0, 1.0
	v_fma_f32 v49, -v53, 2.0, 1.0
	v_add_f32_e32 v52, v60, v60
	v_cvt_pk_bf16_f32 v67, v48, v49
	v_add_f32_e32 v48, 1.0, v50
	v_add_f32_e32 v49, 1.0, v51
	v_add_f32_e32 v50, v58, v58
	v_add_f32_e32 v51, v59, v59
	v_mul_f32_e32 v50, 0x3fb8aa3b, v50
	v_mul_f32_e32 v51, 0x3fb8aa3b, v51
	v_exp_f32_e32 v50, v50
	v_exp_f32_e32 v51, v51
	v_add_f32_e32 v53, v61, v61
	v_rcp_f32_e32 v48, v48
	v_rcp_f32_e32 v49, v49
	v_add_f32_e32 v50, 1.0, v50
	v_add_f32_e32 v51, 1.0, v51
	v_mul_f32_e32 v52, 0x3fb8aa3b, v52
	v_mul_f32_e32 v53, 0x3fb8aa3b, v53
	v_rcp_f32_e32 v50, v50
	v_exp_f32_e32 v52, v52
	v_exp_f32_e32 v53, v53
	v_rcp_f32_e32 v51, v51
	v_fma_f32 v48, -v48, 2.0, 1.0
	v_fma_f32 v49, -v49, 2.0, 1.0
	v_add_f32_e32 v52, 1.0, v52
	v_add_f32_e32 v53, 1.0, v53
	s_waitcnt vmcnt(11)
	v_cvt_pk_bf16_f32 v68, v48, v49
	v_fma_f32 v48, -v50, 2.0, 1.0
	v_fma_f32 v49, -v51, 2.0, 1.0
	v_add_f32_e32 v50, v62, v62
	v_rcp_f32_e32 v52, v52
	v_rcp_f32_e32 v53, v53
	v_mul_f32_e32 v50, 0x3fb8aa3b, v50
	v_add_f32_e32 v51, v63, v63
	v_exp_f32_e32 v50, v50
	v_mul_f32_e32 v51, 0x3fb8aa3b, v51
	v_exp_f32_e32 v51, v51
	v_cvt_pk_bf16_f32 v69, v48, v49
	v_fma_f32 v48, -v52, 2.0, 1.0
	v_fma_f32 v49, -v53, 2.0, 1.0
	v_mul_f32_e32 v32, 0x3fb8aa3b, v32
	v_cvt_pk_bf16_f32 v70, v48, v49
	v_add_f32_e32 v48, 1.0, v50
	v_exp_f32_e32 v50, v32
	v_add_f32_e32 v32, v33, v33
	v_add_f32_e32 v49, 1.0, v51
	v_mul_f32_e32 v32, 0x3fb8aa3b, v32
	v_add_f32_e32 v34, v34, v34
	v_add_f32_e32 v35, v35, v35
	v_rcp_f32_e32 v48, v48
	v_rcp_f32_e32 v49, v49
	v_exp_f32_e32 v51, v32
	v_mul_f32_e32 v34, 0x3fb8aa3b, v34
	v_mul_f32_e32 v35, 0x3fb8aa3b, v35
	v_exp_f32_e32 v34, v34
	v_exp_f32_e32 v35, v35
	v_fma_f32 v32, -v48, 2.0, 1.0
	v_fma_f32 v33, -v49, 2.0, 1.0
	v_add_f32_e32 v48, 1.0, v50
	v_add_f32_e32 v49, 1.0, v51
	v_rcp_f32_e32 v48, v48
	v_rcp_f32_e32 v49, v49
	v_add_f32_e32 v34, 1.0, v34
	v_add_f32_e32 v35, 1.0, v35
	v_rcp_f32_e32 v34, v34
	v_rcp_f32_e32 v35, v35
	v_cvt_pk_bf16_f32 v71, v32, v33
	v_fma_f32 v32, -v48, 2.0, 1.0
	v_fma_f32 v33, -v49, 2.0, 1.0
	s_waitcnt vmcnt(10)
	v_cvt_pk_bf16_f32 v72, v32, v33
	v_fma_f32 v32, -v34, 2.0, 1.0
	v_fma_f32 v33, -v35, 2.0, 1.0
	v_add_f32_e32 v34, v36, v36
	v_add_f32_e32 v35, v37, v37
	v_mul_f32_e32 v34, 0x3fb8aa3b, v34
	v_mul_f32_e32 v35, 0x3fb8aa3b, v35
	v_exp_f32_e32 v34, v34
	v_exp_f32_e32 v35, v35
	v_cvt_pk_bf16_f32 v73, v32, v33
	v_add_f32_e32 v36, v40, v40
	v_add_f32_e32 v32, 1.0, v34
	v_add_f32_e32 v33, 1.0, v35
	v_add_f32_e32 v34, v38, v38
	v_add_f32_e32 v35, v39, v39
	v_mul_f32_e32 v34, 0x3fb8aa3b, v34
	v_mul_f32_e32 v35, 0x3fb8aa3b, v35
	v_exp_f32_e32 v34, v34
	v_exp_f32_e32 v35, v35
	v_add_f32_e32 v37, v41, v41
	v_rcp_f32_e32 v32, v32
	v_rcp_f32_e32 v33, v33
	v_add_f32_e32 v34, 1.0, v34
	v_add_f32_e32 v35, 1.0, v35
	v_mul_f32_e32 v36, 0x3fb8aa3b, v36
	v_mul_f32_e32 v37, 0x3fb8aa3b, v37
	v_rcp_f32_e32 v34, v34
	v_exp_f32_e32 v36, v36
	v_exp_f32_e32 v37, v37
	v_rcp_f32_e32 v35, v35
	v_fma_f32 v32, -v32, 2.0, 1.0
	v_fma_f32 v33, -v33, 2.0, 1.0
	v_add_f32_e32 v36, 1.0, v36
	v_add_f32_e32 v37, 1.0, v37
	v_cvt_pk_bf16_f32 v74, v32, v33
	v_fma_f32 v32, -v34, 2.0, 1.0
	v_fma_f32 v33, -v35, 2.0, 1.0
	v_add_f32_e32 v34, v42, v42
	v_add_f32_e32 v35, v43, v43
	v_rcp_f32_e32 v36, v36
	v_rcp_f32_e32 v37, v37
	v_mul_f32_e32 v34, 0x3fb8aa3b, v34
	v_mul_f32_e32 v35, 0x3fb8aa3b, v35
	v_exp_f32_e32 v34, v34
	v_exp_f32_e32 v35, v35
	v_cvt_pk_bf16_f32 v75, v32, v33
	v_fma_f32 v32, -v36, 2.0, 1.0
	v_fma_f32 v33, -v37, 2.0, 1.0
	v_add_f32_e32 v36, v46, v46
	s_waitcnt vmcnt(9)
	v_cvt_pk_bf16_f32 v76, v32, v33
	v_add_f32_e32 v32, 1.0, v34
	v_add_f32_e32 v33, 1.0, v35
	v_add_f32_e32 v34, v44, v44
	v_add_f32_e32 v35, v45, v45
	v_mul_f32_e32 v34, 0x3fb8aa3b, v34
	v_mul_f32_e32 v35, 0x3fb8aa3b, v35
	v_add_f32_e32 v37, v47, v47
	v_exp_f32_e32 v34, v34
	v_exp_f32_e32 v35, v35
	v_mul_f32_e32 v36, 0x3fb8aa3b, v36
	v_mul_f32_e32 v37, 0x3fb8aa3b, v37
	v_exp_f32_e32 v36, v36
	v_exp_f32_e32 v37, v37
	v_rcp_f32_e32 v32, v32
	v_rcp_f32_e32 v33, v33
	v_add_f32_e32 v34, 1.0, v34
	v_add_f32_e32 v35, 1.0, v35
	v_rcp_f32_e32 v34, v34
	v_rcp_f32_e32 v35, v35
	v_add_f32_e32 v36, 1.0, v36
	v_add_f32_e32 v37, 1.0, v37
	v_rcp_f32_e32 v36, v36
	v_rcp_f32_e32 v37, v37
	v_fma_f32 v32, -v32, 2.0, 1.0
	v_fma_f32 v33, -v33, 2.0, 1.0
	v_fma_f32 v46, -v36, 2.0, 1.0
	v_fma_f32 v47, -v37, 2.0, 1.0
	v_cvt_pk_bf16_f32 v77, v32, v33
	v_fma_f32 v32, -v34, 2.0, 1.0
	v_fma_f32 v33, -v35, 2.0, 1.0
	s_nop 0
	v_cvt_pk_bf16_f32 v78, v32, v33

; __device__ __forceinline__ unsigned cvtpk(float lo, float hi) { f32x2 v = {lo, hi}; bf16x2_t b = __builtin_convertvector(v, bf16x2_t); return *(unsigned*)&b; }
; #define TANH_(x) (1.f - 2.f * __builtin_amdgcn_rcpf(__expf(2.f * (x) * sc) + 1.f))
;   __device__ __forceinline__ void operator()(int lrow, int nc, const f32x16& a0, const f32x16& a1, float aux) const {
;     ...
;     if (act) {
;     ...
;       const u32x4 w0 = {cvtpk(TANH_(a0[0]), TANH_(a0[1])), cvtpk(TANH_(a0[2]), TANH_(a0[3])), cvtpk(TANH_(a0[4]), TANH_(a0[5])), cvtpk(TANH_(a0[6]), TANH_(a0[7]))};
;       const u32x4 w1 = {cvtpk(TANH_(a0[8]), TANH_(a0[9])), cvtpk(TANH_(a0[10]), TANH_(a0[11])), cvtpk(TANH_(a0[12]), TANH_(a0[13])), cvtpk(TANH_(a0[14]), TANH_(a0[15]))};
;       const u32x4 w2 = {cvtpk(TANH_(a1[0]), TANH_(a1[1])), cvtpk(TANH_(a1[2]), TANH_(a1[3])), cvtpk(TANH_(a1[4]), TANH_(a1[5])), cvtpk(TANH_(a1[6]), TANH_(a1[7]))};
;       const u32x4 w3 = {cvtpk(TANH_(a1[8]), TANH_(a1[9])), cvtpk(TANH_(a1[10]), TANH_(a1[11])), cvtpk(TANH_(a1[12]), TANH_(a1[13])), cvtpk(TANH_(a1[14]), TANH_(a1[15]))};
;     ...
;       *(u32x4*)(wp) = w0; *(u32x4*)(wp + 16) = w1; *(u32x4*)(wp + 64) = w2; *(u32x4*)(wp + 80) = w3;
.LBB0_475:
	s_andn2_b64 vcc, exec, s[6:7]
	s_cbranch_vccnz .LBB0_462
	v_add_f32_e32 v16, v16, v16
	v_add_f32_e32 v17, v17, v17
	v_mul_f32_e32 v16, 0x3fb8aa3b, v16
	v_mul_f32_e32 v17, 0x3fb8aa3b, v17
	v_exp_f32_e32 v16, v16
	v_exp_f32_e32 v17, v17
	v_add_f32_e32 v18, v18, v18
	v_add_f32_e32 v19, v19, v19
	v_add_f32_e32 v16, 1.0, v16
	v_add_f32_e32 v17, 1.0, v17
	v_rcp_f32_e32 v16, v16
	v_rcp_f32_e32 v17, v17
	v_mul_f32_e32 v18, 0x3fb8aa3b, v18
	v_mul_f32_e32 v19, 0x3fb8aa3b, v19
	v_exp_f32_e32 v18, v18
	v_exp_f32_e32 v19, v19
	v_fma_f32 v16, -v16, 2.0, 1.0
	v_fma_f32 v17, -v17, 2.0, 1.0
	v_add_f32_e32 v0, v0, v0
	v_cvt_pk_bf16_f32 v32, v16, v17
	v_add_f32_e32 v16, 1.0, v18
	v_add_f32_e32 v17, 1.0, v19
	v_add_f32_e32 v18, v20, v20
	v_add_f32_e32 v19, v21, v21
	v_mul_f32_e32 v18, 0x3fb8aa3b, v18
	v_mul_f32_e32 v19, 0x3fb8aa3b, v19
	v_exp_f32_e32 v18, v18
	v_exp_f32_e32 v19, v19
	v_add_f32_e32 v20, v22, v22
	v_add_f32_e32 v21, v23, v23
	v_rcp_f32_e32 v16, v16
	v_rcp_f32_e32 v17, v17
	v_add_f32_e32 v18, 1.0, v18
	v_add_f32_e32 v19, 1.0, v19
	v_mul_f32_e32 v20, 0x3fb8aa3b, v20
	v_mul_f32_e32 v21, 0x3fb8aa3b, v21
	v_rcp_f32_e32 v18, v18
	v_exp_f32_e32 v20, v20
	v_exp_f32_e32 v21, v21
	v_rcp_f32_e32 v19, v19
	v_fma_f32 v16, -v16, 2.0, 1.0
	v_fma_f32 v17, -v17, 2.0, 1.0
	v_add_f32_e32 v20, 1.0, v20
	v_add_f32_e32 v21, 1.0, v21
	v_cvt_pk_bf16_f32 v33, v16, v17
	v_fma_f32 v16, -v18, 2.0, 1.0
	v_fma_f32 v17, -v19, 2.0, 1.0
	v_add_f32_e32 v18, v24, v24
	v_add_f32_e32 v19, v25, v25
	v_rcp_f32_e32 v20, v20
	v_rcp_f32_e32 v21, v21
	v_mul_f32_e32 v18, 0x3fb8aa3b, v18
	v_mul_f32_e32 v19, 0x3fb8aa3b, v19
	v_exp_f32_e32 v18, v18
	v_exp_f32_e32 v19, v19
	v_cvt_pk_bf16_f32 v34, v16, v17
	v_fma_f32 v16, -v20, 2.0, 1.0
	v_fma_f32 v17, -v21, 2.0, 1.0
	v_add_f32_e32 v20, v28, v28
	v_cvt_pk_bf16_f32 v35, v16, v17
	v_add_f32_e32 v16, 1.0, v18
	v_add_f32_e32 v17, 1.0, v19
	v_add_f32_e32 v18, v26, v26
	v_add_f32_e32 v19, v27, v27
	v_mul_f32_e32 v18, 0x3fb8aa3b, v18
	v_mul_f32_e32 v19, 0x3fb8aa3b, v19
	v_exp_f32_e32 v18, v18
	v_exp_f32_e32 v19, v19
	v_add_f32_e32 v21, v29, v29
	v_rcp_f32_e32 v16, v16
	v_rcp_f32_e32 v17, v17
	v_add_f32_e32 v18, 1.0, v18
	v_add_f32_e32 v19, 1.0, v19
	v_mul_f32_e32 v20, 0x3fb8aa3b, v20
	v_mul_f32_e32 v21, 0x3fb8aa3b, v21
	v_rcp_f32_e32 v18, v18
	v_exp_f32_e32 v20, v20
	v_exp_f32_e32 v21, v21
	v_rcp_f32_e32 v19, v19
	v_fma_f32 v16, -v16, 2.0, 1.0
	v_fma_f32 v17, -v17, 2.0, 1.0
	v_add_f32_e32 v20, 1.0, v20
	v_add_f32_e32 v21, 1.0, v21
	v_cvt_pk_bf16_f32 v36, v16, v17
	v_fma_f32 v16, -v18, 2.0, 1.0
	v_fma_f32 v17, -v19, 2.0, 1.0
	v_add_f32_e32 v18, v30, v30
	v_rcp_f32_e32 v20, v20
	v_rcp_f32_e32 v21, v21
	v_mul_f32_e32 v18, 0x3fb8aa3b, v18
	v_add_f32_e32 v19, v31, v31
	v_exp_f32_e32 v18, v18
	v_mul_f32_e32 v19, 0x3fb8aa3b, v19
	v_exp_f32_e32 v19, v19
	v_cvt_pk_bf16_f32 v37, v16, v17
	v_fma_f32 v16, -v20, 2.0, 1.0
	v_fma_f32 v17, -v21, 2.0, 1.0
	v_mul_f32_e32 v0, 0x3fb8aa3b, v0
	v_cvt_pk_bf16_f32 v38, v16, v17
	v_add_f32_e32 v16, 1.0, v18
	v_exp_f32_e32 v18, v0
	v_add_f32_e32 v0, v1, v1
	v_add_f32_e32 v17, 1.0, v19
	v_mul_f32_e32 v0, 0x3fb8aa3b, v0
	v_add_f32_e32 v2, v2, v2
	v_add_f32_e32 v3, v3, v3
	v_rcp_f32_e32 v16, v16
	v_rcp_f32_e32 v17, v17
	v_exp_f32_e32 v19, v0
	v_mul_f32_e32 v2, 0x3fb8aa3b, v2
	v_mul_f32_e32 v3, 0x3fb8aa3b, v3
	v_exp_f32_e32 v2, v2
	v_exp_f32_e32 v3, v3
	v_fma_f32 v0, -v16, 2.0, 1.0
	v_fma_f32 v1, -v17, 2.0, 1.0
	v_add_f32_e32 v16, 1.0, v18
	v_add_f32_e32 v17, 1.0, v19
	v_rcp_f32_e32 v16, v16
	v_rcp_f32_e32 v17, v17
	v_add_f32_e32 v2, 1.0, v2
	v_add_f32_e32 v3, 1.0, v3
	v_rcp_f32_e32 v2, v2
	v_rcp_f32_e32 v3, v3
	v_cvt_pk_bf16_f32 v39, v0, v1
	v_fma_f32 v0, -v16, 2.0, 1.0
	v_fma_f32 v1, -v17, 2.0, 1.0
	s_nop 0
	v_cvt_pk_bf16_f32 v40, v0, v1
	v_fma_f32 v0, -v2, 2.0, 1.0
	v_fma_f32 v1, -v3, 2.0, 1.0
	v_add_f32_e32 v2, v4, v4
	v_add_f32_e32 v3, v5, v5
	v_mul_f32_e32 v2, 0x3fb8aa3b, v2
	v_mul_f32_e32 v3, 0x3fb8aa3b, v3
	v_exp_f32_e32 v2, v2
	v_exp_f32_e32 v3, v3
	v_cvt_pk_bf16_f32 v41, v0, v1
	v_add_f32_e32 v4, v8, v8
	v_add_f32_e32 v0, 1.0, v2
	v_add_f32_e32 v1, 1.0, v3
	v_add_f32_e32 v2, v6, v6
	v_add_f32_e32 v3, v7, v7
	v_mul_f32_e32 v2, 0x3fb8aa3b, v2
	v_mul_f32_e32 v3, 0x3fb8aa3b, v3
	v_exp_f32_e32 v2, v2
	v_exp_f32_e32 v3, v3
	v_add_f32_e32 v5, v9, v9
	v_rcp_f32_e32 v0, v0
	v_rcp_f32_e32 v1, v1
	v_add_f32_e32 v2, 1.0, v2
	v_add_f32_e32 v3, 1.0, v3
	v_mul_f32_e32 v4, 0x3fb8aa3b, v4
	v_mul_f32_e32 v5, 0x3fb8aa3b, v5
	v_rcp_f32_e32 v2, v2
	v_exp_f32_e32 v4, v4
	v_exp_f32_e32 v5, v5
	v_rcp_f32_e32 v3, v3
	v_fma_f32 v0, -v0, 2.0, 1.0
	v_fma_f32 v1, -v1, 2.0, 1.0
	v_add_f32_e32 v4, 1.0, v4
	v_add_f32_e32 v5, 1.0, v5
	v_cvt_pk_bf16_f32 v42, v0, v1
	v_fma_f32 v0, -v2, 2.0, 1.0
	v_fma_f32 v1, -v3, 2.0, 1.0
	v_add_f32_e32 v2, v10, v10
	v_add_f32_e32 v3, v11, v11
	v_rcp_f32_e32 v4, v4
	v_rcp_f32_e32 v5, v5
	v_mul_f32_e32 v2, 0x3fb8aa3b, v2
	v_mul_f32_e32 v3, 0x3fb8aa3b, v3
	v_exp_f32_e32 v2, v2
	v_exp_f32_e32 v3, v3
	v_cvt_pk_bf16_f32 v43, v0, v1
	v_fma_f32 v0, -v4, 2.0, 1.0
	v_fma_f32 v1, -v5, 2.0, 1.0
	v_add_f32_e32 v4, v14, v14
	v_cvt_pk_bf16_f32 v44, v0, v1
	v_add_f32_e32 v0, 1.0, v2
	v_add_f32_e32 v1, 1.0, v3
	v_add_f32_e32 v2, v12, v12
	v_add_f32_e32 v3, v13, v13
	v_mul_f32_e32 v2, 0x3fb8aa3b, v2
	v_mul_f32_e32 v3, 0x3fb8aa3b, v3
	v_add_f32_e32 v5, v15, v15
	v_exp_f32_e32 v2, v2
	v_exp_f32_e32 v3, v3
	v_mul_f32_e32 v4, 0x3fb8aa3b, v4
	v_mul_f32_e32 v5, 0x3fb8aa3b, v5
	v_exp_f32_e32 v4, v4
	v_exp_f32_e32 v5, v5
	v_rcp_f32_e32 v0, v0
	v_rcp_f32_e32 v1, v1
	v_add_f32_e32 v2, 1.0, v2
	v_add_f32_e32 v3, 1.0, v3
	v_rcp_f32_e32 v2, v2
	v_rcp_f32_e32 v3, v3
	v_add_f32_e32 v4, 1.0, v4
	v_add_f32_e32 v5, 1.0, v5
	v_rcp_f32_e32 v4, v4
	v_rcp_f32_e32 v5, v5
	v_fma_f32 v0, -v0, 2.0, 1.0
	v_fma_f32 v1, -v1, 2.0, 1.0
	v_fma_f32 v14, -v4, 2.0, 1.0
	v_fma_f32 v15, -v5, 2.0, 1.0
	v_cvt_pk_bf16_f32 v45, v0, v1
	v_fma_f32 v0, -v2, 2.0, 1.0
	v_fma_f32 v1, -v3, 2.0, 1.0
	s_nop 0
	v_cvt_pk_bf16_f32 v46, v0, v1
	s_branch .LBB0_462

; __device__ __forceinline__ int crow(int r, int hi) { return (r & 3) + 8 * (r >> 2) + 4 * hi; }
; __device__ void phase_scan(const Params& p, char* lds) {
;     ...
;         if (mat == 0) {
;           float cc[16];
; #pragma unroll
;           for (int r = 0; r < 16; ++r) cc[r] = -0.6065306597126334f * __builtin_amdgcn_rcpf(1.f + __expf(-(acc[r] + bias)));
; #pragma unroll
;           for (int g = 0; g < 4; ++g) { cc[4 * g + 1] += cc[4 * g]; cc[4 * g + 2] += cc[4 * g + 1]; cc[4 * g + 3] += cc[4 * g + 2]; }
;           float run = 0.f;
; #pragma unroll
;           for (int g = 0; g < 4; ++g) {
;             const float own = cc[4 * g + 3];
;             auto rr2 = __builtin_amdgcn_permlane32_swap(__float_as_uint(own), __float_as_uint(own), false, false);
;             const float both = __uint_as_float(rr2[0]) + __uint_as_float(rr2[1]), partner = both - own;
;             const float off = hi ? run + partner : run;
; #pragma unroll
;             for (int e = 0; e < 4; ++e) Pd[crow(4 * g + e, hi) * 64 + jh * 32 + r32] = __expf(off + cc[4 * g + e]);
;             run += both;
;           }
.LBB0_493:
	v_add_f32_e32 v9, v99, v15
	v_mul_f32_e32 v9, 0xbfb8aa3b, v9
	v_exp_f32_e32 v9, v9
	s_andn2_b64 vcc, exec, s[80:81]
	v_add_f32_e32 v9, 1.0, v9
	v_rcp_f32_e32 v9, v9
	s_cbranch_vccnz .LBB0_495
	v_mul_f32_e64 v0, v0, s74
	v_mul_f32_e64 v1, v1, s75
	v_mul_f32_e64 v2, v2, s74
	v_mul_f32_e64 v3, v3, s75
	v_sub_f32_e32 v1, v0, v1
	v_fmamk_f32 v13, v16, 0xbf1b4598, v1
	v_fmamk_f32 v14, v62, 0xbf1b4598, v13
	v_sub_f32_e32 v3, v2, v3
	v_fmamk_f32 v15, v8, 0xbf1b4598, v3
	v_mov_b32_e32 v8, v14
	v_mov_b32_e32 v62, v14
	s_nop 1
	v_permlane32_swap_b32_e32 v8, v62
	v_add_f32_e32 v8, v8, v62
	v_sub_f32_e32 v62, v8, v14
	v_add_f32_e32 v62, 0, v62
	v_cndmask_b32_e64 v62, v62, 0, s[26:27]
	v_add_f32_e32 v0, v0, v62
	v_add_f32_e32 v1, v1, v62
	v_mul_f32_e32 v0, 0x3fb8aa3b, v0
	v_mul_f32_e32 v1, 0x3fb8aa3b, v1
	v_add_f32_e32 v13, v13, v62
	v_add_f32_e32 v14, v14, v62
	v_exp_f32_e32 v0, v0
	v_exp_f32_e32 v1, v1
	v_mul_f32_e32 v13, 0x3fb8aa3b, v13
	v_mul_f32_e32 v14, 0x3fb8aa3b, v14
	v_exp_f32_e32 v13, v13
	v_exp_f32_e32 v14, v14
	v_fmamk_f32 v16, v63, 0xbf1b4598, v15
	ds_write2st64_b32 v187, v0, v1 offset1:1
	ds_write2st64_b32 v187, v13, v14 offset0:2 offset1:3
	v_add_f32_e32 v0, 0, v8
	v_mov_b32_e32 v1, v16
	v_mov_b32_e32 v8, v16
	s_nop 1
	v_permlane32_swap_b32_e32 v1, v8
	v_add_f32_e32 v8, v1, v8
	v_mul_f32_e64 v6, v6, s74
	v_mul_f32_e64 v7, v7, s75
	v_sub_f32_e32 v1, v8, v16
	v_mul_f32_e64 v4, v4, s74
	v_mul_f32_e64 v5, v5, s75
	v_sub_f32_e32 v7, v6, v7
	v_add_f32_e32 v1, v0, v1
	v_sub_f32_e32 v5, v4, v5
	v_fmamk_f32 v12, v12, 0xbf1b4598, v7
	v_cndmask_b32_e64 v1, v1, v0, s[26:27]
	v_fmamk_f32 v10, v10, 0xbf1b4598, v5
	v_fmamk_f32 v62, v9, 0xbf1b4598, v12
	v_add_f32_e32 v2, v2, v1
	v_add_f32_e32 v3, v3, v1
	v_add_f32_e32 v9, v15, v1
	v_add_f32_e32 v1, v16, v1
	v_fmamk_f32 v11, v11, 0xbf1b4598, v10
	v_mul_f32_e32 v9, 0x3fb8aa3b, v9
	v_mul_f32_e32 v1, 0x3fb8aa3b, v1
	v_exp_f32_e32 v13, v9
	v_exp_f32_e32 v14, v1
	v_mov_b32_e32 v1, v11
	v_mov_b32_e32 v9, v11
	s_nop 1
	v_permlane32_swap_b32_e32 v1, v9
	v_add_f32_e64 v0, v0, v8
	v_add_f32_e64 v1, v1, v9
	v_mul_f32_e32 v2, 0x3fb8aa3b, v2
	v_sub_f32_e32 v8, v1, v11
	v_add_f32_e32 v8, v0, v8
	v_mul_f32_e32 v3, 0x3fb8aa3b, v3
	v_cndmask_b32_e64 v8, v8, v0, s[26:27]
	v_exp_f32_e32 v2, v2
	v_exp_f32_e32 v3, v3
	v_add_f32_e32 v4, v4, v8
	v_add_f32_e32 v5, v5, v8
	v_mul_f32_e32 v4, 0x3fb8aa3b, v4
	v_mul_f32_e32 v5, 0x3fb8aa3b, v5
	v_add_f32_e32 v9, v10, v8
	v_add_f32_e32 v8, v11, v8
	v_exp_f32_e32 v4, v4
	v_exp_f32_e32 v5, v5
	v_mul_f32_e32 v9, 0x3fb8aa3b, v9
	v_mul_f32_e32 v8, 0x3fb8aa3b, v8
	v_exp_f32_e32 v9, v9
	v_exp_f32_e32 v8, v8
	ds_write2st64_b32 v187, v2, v3 offset0:8 offset1:9
	ds_write2st64_b32 v187, v13, v14 offset0:10 offset1:11
	ds_write2st64_b32 v187, v4, v5 offset0:16 offset1:17
	ds_write2st64_b32 v187, v9, v8 offset0:18 offset1:19
	v_mov_b32_e32 v3, v62
	v_mov_b32_e32 v5, v62
	s_nop 1
	v_permlane32_swap_b32_e32 v3, v5
	v_mov_b32_e32 v2, v0
	v_mov_b32_e32 v4, v1
	v_add_f32_e64 v0, v2, v4
	v_add_f32_e64 v1, v3, v5
	s_mov_b32 s66, 0
	v_sub_f32_e32 v1, v1, v62
	v_add_f32_e32 v1, v0, v1
	v_cndmask_b32_e64 v0, v1, v0, s[26:27]
	v_add_f32_e32 v1, v6, v0
	v_add_f32_e32 v2, v7, v0
	v_add_f32_e32 v3, v12, v0
	v_add_f32_e32 v0, v62, v0
	v_mul_f32_e32 v1, 0x3fb8aa3b, v1
	v_mul_f32_e32 v2, 0x3fb8aa3b, v2
	v_mul_f32_e32 v0, 0x3fb8aa3b, v0
	v_exp_f32_e32 v1, v1
	v_exp_f32_e32 v2, v2
	v_mul_f32_e32 v3, 0x3fb8aa3b, v3
	v_exp_f32_e32 v9, v0
	v_exp_f32_e32 v3, v3
	ds_write2st64_b32 v187, v1, v2 offset0:24 offset1:25
	ds_write_b32 v187, v3 offset:6656
	s_branch .LBB0_496

; __device__ __forceinline__ float lo16(unsigned w) { return __uint_as_float(w << 16); }
; __device__ __forceinline__ float hi16(unsigned w) { return __uint_as_float(w & 0xffff0000u); }
; __device__ __forceinline__ float red8(float v) { v += dpp_f(v, 0); v += dpp_f(v, 1); v += dpp_f(v, 2); return v; }
; __device__ void phase_scan(const Params& p, char* lds) {
;     ...
;       auto prefetch = [&](int c) {
;         const size_t row = (size_t)scan_row(c * 32 + pstep, d, b) * 1024 + h * 64 + j0;
;         pR = *(const u32x4*)(Rg + row); pK = *(const u32x4*)(Kg + row); pV = *(const u32x4*)(Vg + row);
;         const size_t lrow = (size_t)scan_row(c * 32 + r32, d, b);
; #pragma unroll
;         for (int ks = 0; ks < 4; ++ks) pl[ks] = *(const bf16x8*)(Lg + lrow * 256 + mat * 128 + d * 64 + ks * 16 + hi * 8);
;     ...
;         float ss = 0.f;
; #pragma unroll
;         for (int w = 0; w < 4; ++w) {
;           rr[2 * w] = lo16(pR[w]); rr[2 * w + 1] = hi16(pR[w]);
;           kr[2 * w] = lo16(pK[w]); kr[2 * w + 1] = hi16(pK[w]);
;         }
;         const float vv[8] = {lo16(pV[0]), hi16(pV[0]), lo16(pV[1]), hi16(pV[1]), lo16(pV[2]), hi16(pV[2]), lo16(pV[3]), hi16(pV[3])};
;         if (c + 1 < NCH) prefetch(c + 1);
; #pragma unroll
;         for (int e = 0; e < 8; ++e) VV[(pblk * 64 + j0 + e) * 4 + psb] = vv[e];
; #pragma unroll
;         for (int e = 0; e < 8; ++e) { kk[e] = kr[e] * kkc[e]; ss += kk[e] * kk[e]; }
;         ss = red8(ss);
;         const float inv = rsqrtf(fmaxf(ss, 1e-24f));
; #pragma unroll
;         for (int e = 0; e < 8; ++e) kk[e] *= inv;
;       };
;       auto stageB = [&](int c) {
;         char* buf = lds + (c & 1) * SC_BUF;
;         const f32x4 i0 = *(const f32x4*)(IC + pstep * 64 + j0), i1 = *(const f32x4*)(IC + pstep * 64 + j0 + 4);
;         const float ic[8] = {i0[0], i0[1], i0[2], i0[3], i1[0], i1[1], i1[2], i1[3]};
;         const float* Pt = (const float*)(buf + SC_P) + pstep * 64 + j0;
;         const f32x4 pt0 = *(const f32x4*)(Pt), pt1 = *(const f32x4*)(Pt + 4);
;         f32x4 pm0 = {1.f, 1.f, 1.f, 1.f}, pm1 = pm0;
;         if (pstep > 0) { pm0 = *(const f32x4*)(Pt - 64); pm1 = *(const f32x4*)(Pt - 60); }
;         const float pt[8] = {pt0[0], pt0[1], pt0[2], pt0[3], pt1[0], pt1[1], pt1[2], pt1[3]};
;         const float pm[8] = {pm0[0], pm0[1], pm0[2], pm0[3], pm1[0], pm1[1], pm1[2], pm1[3]};
.LBB0_496:
	v_add_u32_e32 v0, 32, v139
	v_sub_u32_e32 v1, 0xdf, v139
	v_cndmask_b32_e64 v0, v1, v0, s[22:23]
	v_add_u32_e32 v16, s35, v0
	v_lshlrev_b64 v[0:1], 10, v[16:17]
	v_or3_b32 v1, v1, 0, 0
	v_or3_b32 v0, v0, s30, v138
	v_lshlrev_b64 v[0:1], 1, v[0:1]
	v_lshl_add_u64 v[2:3], s[28:29], 0, v[0:1]
	v_lshl_add_u64 v[4:5], s[50:51], 0, v[0:1]
	global_load_dwordx4 v[86:89], v[2:3], off
	global_load_dwordx4 v[90:93], v[4:5], off
	v_or_b32_e32 v2, 32, v180
	v_xor_b32_e32 v3, 0xdf, v180
	v_cndmask_b32_e64 v2, v3, v2, s[22:23]
	v_add_u32_e32 v2, s34, v2
	v_lshl_add_u32 v2, v2, 9, v219
	v_mov_b32_e32 v3, v17
	v_lshl_add_u64 v[2:3], s[64:65], 0, v[2:3]
	v_lshl_add_u64 v[0:1], s[48:49], 0, v[0:1]
	v_lshl_add_u64 v[2:3], s[78:79], 1, v[2:3]
	v_mov_b32_e32 v101, v17
	v_lshl_add_u64 v[4:5], v[2:3], 0, v[100:101]
	global_load_dwordx4 v[94:97], v[0:1], off
	s_nop 0
	global_load_dwordx4 v[0:3], v[4:5], off
	global_load_dwordx4 v[70:73], v[4:5], off offset:32
	global_load_dwordx4 v[66:69], v[4:5], off offset:64
	global_load_dwordx4 v[62:65], v[4:5], off offset:96
	v_lshl_add_u32 v4, v177, 2, s66
	s_waitcnt vmcnt(8)
	v_lshlrev_b32_e32 v110, 16, v74
	v_and_b32_e32 v111, 0xffff0000, v74
	ds_write_b32 v4, v9 offset:6912
	s_waitcnt vmcnt(7)
	v_and_b32_e32 v4, 0xffff0000, v81
	v_lshlrev_b32_e32 v5, 16, v81
	v_and_b32_e32 v10, 0xffff0000, v78
	v_lshlrev_b32_e32 v11, 16, v78
	v_add_u32_e32 v12, 0x6400, v189
	v_mul_f32_e64 v112, v38, v110
	v_mul_f32_e64 v113, v39, v111
	v_lshlrev_b32_e32 v108, 16, v75
	v_and_b32_e32 v109, 0xffff0000, v75
	v_and_b32_e32 v6, 0xffff0000, v80
	v_lshlrev_b32_e32 v7, 16, v80
	v_and_b32_e32 v8, 0xffff0000, v79
	v_lshlrev_b32_e32 v9, 16, v79
	ds_write2_b32 v12, v11, v10 offset1:4
	ds_write2_b32 v12, v9, v8 offset0:8 offset1:12
	ds_write2_b32 v12, v7, v6 offset0:16 offset1:20
	ds_write2_b32 v12, v5, v4 offset0:24 offset1:28
	v_mul_f32_e64 v4, v112, v112
	v_mul_f32_e64 v5, v113, v113
	v_mul_f32_e64 v114, v40, v108
	v_mul_f32_e64 v115, v41, v109
	v_lshlrev_b32_e32 v106, 16, v76
	v_mul_f32_e64 v6, v114, v114
	v_mul_f32_e64 v7, v115, v115
	v_and_b32_e32 v107, 0xffff0000, v76
	v_add_f32_e32 v4, v4, v5
	v_mul_f32_e64 v116, v34, v106
	v_mul_f32_e64 v117, v35, v107
	v_add_f32_e32 v4, v6, v4
	v_mul_f32_e64 v8, v116, v116
	v_mul_f32_e64 v9, v117, v117
	v_lshlrev_b32_e32 v104, 16, v77
	v_and_b32_e32 v105, 0xffff0000, v77
	v_add_f32_e32 v4, v7, v4
	v_mul_f32_e64 v118, v36, v104
	v_mul_f32_e64 v119, v37, v105
	v_add_f32_e32 v4, v8, v4
	v_mul_f32_e64 v10, v118, v118
	v_mul_f32_e64 v11, v119, v119
	v_add_f32_e32 v4, v9, v4
	v_add_f32_e32 v4, v10, v4
	v_add_f32_e32 v4, v11, v4
	s_waitcnt lgkmcnt(0)
	s_barrier
	v_add_f32_dpp v4, v4, v4 quad_perm:[1,0,3,2] row_mask:0xf bank_mask:0xf bound_ctrl:1
	v_mov_b32_e32 v78, 1.0
	s_nop 0
	v_add_f32_dpp v101, v4, v4 quad_perm:[2,3,0,1] row_mask:0xf bank_mask:0xf bound_ctrl:1
	ds_read_b128 v[12:15], v190
	ds_read_b128 v[4:7], v190 offset:16
	ds_read_b128 v[74:77], v191
	ds_read_b128 v[8:11], v191 offset:16
	v_mov_b32_dpp v120, v101 row_half_mirror row_mask:0xf bank_mask:0xf bound_ctrl:1
	v_mov_b32_e32 v79, 1.0
	v_mov_b32_e32 v80, 1.0
	v_mov_b32_e32 v81, 1.0
	v_mov_b32_e32 v82, 1.0
	v_mov_b32_e32 v83, 1.0
	v_mov_b32_e32 v84, 1.0
	v_mov_b32_e32 v85, 1.0
	s_and_saveexec_b64 s[80:81], s[6:7]
	s_cbranch_execz .LBB0_498
	v_add_u32_e32 v78, 0xffffff00, v191
	ds_read_b128 v[82:85], v78
	v_add_u32_e32 v78, 0xffffff10, v191
	ds_read_b128 v[78:81], v78
; __device__ void phase_scan(const Params& p, char* lds) {
;     ...
;         const float inv = rsqrtf(fmaxf(ss, 1e-24f));
; #pragma unroll
;         for (int e = 0; e < 8; ++e) kk[e] *= inv;
;       };
;       auto stageB = [&](int c) {
;         char* buf = lds + (c & 1) * SC_BUF;
;         const f32x4 i0 = *(const f32x4*)(IC + pstep * 64 + j0), i1 = *(const f32x4*)(IC + pstep * 64 + j0 + 4);
;         const float ic[8] = {i0[0], i0[1], i0[2], i0[3], i1[0], i1[1], i1[2], i1[3]};
;         const float* Pt = (const float*)(buf + SC_P) + pstep * 64 + j0;
;         const f32x4 pt0 = *(const f32x4*)(Pt), pt1 = *(const f32x4*)(Pt + 4);
;         f32x4 pm0 = {1.f, 1.f, 1.f, 1.f}, pm1 = pm0;
;         if (pstep > 0) { pm0 = *(const f32x4*)(Pt - 64); pm1 = *(const f32x4*)(Pt - 60); }
;         const float pt[8] = {pt0[0], pt0[1], pt0[2], pt0[3], pt1[0], pt1[1], pt1[2], pt1[3]};
;         const float pm[8] = {pm0[0], pm0[1], pm0[2], pm0[3], pm1[0], pm1[1], pm1[2], pm1[3]};
;         const u32x4 an = {cvtpk(-kk[0] * pm[0], -kk[1] * pm[1]), cvtpk(-kk[2] * pm[2], -kk[3] * pm[3]), cvtpk(-kk[4] * pm[4], -kk[5] * pm[5]), cvtpk(-kk[6] * pm[6], -kk[7] * pm[7])};
;         const u32x4 rn = {cvtpk(rr[0] * pt[0], rr[1] * pt[1]), cvtpk(rr[2] * pt[2], rr[3] * pt[3]), cvtpk(rr[4] * pt[4], rr[5] * pt[5]), cvtpk(rr[6] * pt[6], rr[7] * pt[7])};
;         bf16_t* ARa = (bf16_t*)(buf + SC_ARA) + (pblk * 4 + psb) * 64; bf16_t* ARr = (bf16_t*)(buf + SC_ARR) + (pblk * 4 + psb) * 64;
;         { u32x2 lo = {an[0], an[1]}, hi2 = {an[2], an[3]}; *(u32x2*)(ARa + apos0) = lo; *(u32x2*)(ARa + apos1) = hi2; }
;         { u32x2 lo = {rn[0], rn[1]}, hi2 = {rn[2], rn[3]}; *(u32x2*)(ARr + apos0) = lo; *(u32x2*)(ARr + apos1) = hi2; }
;         *(u32x4*)(SCR + (pstep * 4 + 0) * 64 + j0) = an; *(u32x4*)(SCR + (pstep * 4 + 1) * 64 + j0) = rn;
;         float bs = 0.f;
;         unsigned bq[8], kq[8];
;         unsigned* BK = (unsigned*)(buf + SC_BK) + (pblk * 64 + j0) * 4 + psb;
; #pragma unroll
;         for (int e = 0; e < 8; ++e) {
;           const float kd = kr[e] * (1.f + (ic[e] - 1.f) * kac[e]);
;           const float ip = __builtin_amdgcn_rcpf(pt[e]);
;           const unsigned pr2 = cvtpk(kk[e] * ic[e] * ip, kd * ip);
;           BK[e * 4] = pr2;
;           bq[e] = pr2 & 0xffffu; kq[e] = pr2 >> 16;
;           bs += rr[e] * kd * rkc[e];
;         }
.LBB0_498:
	s_or_b64 exec, exec, s[80:81]
	v_add_f32_e32 v101, v101, v120
	v_max_f32_e32 v101, 0x179abe15, v101
	v_rsq_f32_e32 v120, v101
	v_lshlrev_b32_e32 v122, 16, v58
	v_and_b32_e32 v123, 0xffff0000, v58
	v_lshlrev_b32_e32 v124, 16, v59
	v_mul_f32_e64 v112, v112, v120
	v_mul_f32_e64 v113, v113, v120
	v_mul_f32_e64 v114, v114, v120
	v_mul_f32_e64 v115, v115, v120
	v_and_b32_e32 v125, 0xffff0000, v59
	v_lshlrev_b32_e32 v126, 16, v60
	v_and_b32_e32 v127, 0xffff0000, v60
	v_lshlrev_b32_e32 v128, 16, v61
	v_and_b32_e32 v129, 0xffff0000, v61
	v_mul_f32_e64 v116, v116, v120
	v_mul_f32_e64 v117, v117, v120
	v_mul_f32_e64 v118, v118, v120
	v_mul_f32_e64 v119, v119, v120
	s_waitcnt lgkmcnt(1)
	v_mul_f32_e64 v58, v82, -v112
	v_mul_f32_e64 v59, v83, -v113
	v_mul_f32_e64 v60, v84, -v114
	v_mul_f32_e64 v61, v85, -v115
	v_cvt_pk_bf16_f32 v58, v58, v59
	v_cvt_pk_bf16_f32 v59, v60, v61
	s_waitcnt lgkmcnt(0)
	v_mul_f32_e64 v60, v78, -v116
	v_mul_f32_e64 v61, v79, -v117
	v_mul_f32_e64 v78, v80, -v118
	v_mul_f32_e64 v79, v81, -v119
	v_cvt_pk_bf16_f32 v60, v60, v61
	v_cvt_pk_bf16_f32 v61, v78, v79
	v_mul_f32_e64 v78, v74, v122
	v_mul_f32_e64 v79, v75, v123
	v_mul_f32_e64 v80, v76, v124
	v_mul_f32_e64 v81, v77, v125
	v_cvt_pk_bf16_f32 v78, v78, v79
	v_cvt_pk_bf16_f32 v79, v80, v81
	v_mul_f32_e64 v80, v8, v126
	v_mul_f32_e64 v81, v9, v127
	v_mul_f32_e64 v82, v10, v128
	v_mul_f32_e64 v83, v11, v129
	v_cvt_pk_bf16_f32 v80, v80, v81
	v_cvt_pk_bf16_f32 v81, v82, v83
	v_add_u32_e32 v82, 0x2000, v194
	ds_write2_b64 v82, v[58:59], v[60:61] offset1:2
	v_add_u32_e32 v82, 0x3000, v194
	ds_write2_b64 v82, v[78:79], v[80:81] offset1:2
	ds_write_b128 v195, v[58:61]
	ds_write_b128 v195, v[78:81] offset:128
	v_add_f32_e32 v58, -1.0, v12
	v_fma_f32 v59, v22, v58, 1.0
	v_rcp_f32_e32 v60, v74
	v_mov_b32_e32 v58, v12
	v_mov_b32_e32 v78, v112
	v_mov_b32_e32 v79, v110
	v_mul_f32_e64 v58, v58, v78
	v_mul_f32_e64 v59, v59, v79
	v_mov_b32_e32 v110, v113
	v_mul_f32_e32 v12, v59, v122
	v_fma_f32 v79, v30, v12, 0
	v_add_f32_e32 v12, -1.0, v13
	v_mul_f32_e64 v61, v59, v60
	v_mul_f32_e64 v60, v58, v60
	v_fma_f32 v59, v23, v12, 1.0
	v_rcp_f32_e32 v12, v75
	v_mov_b32_e32 v58, v13
	v_mul_f32_e64 v58, v58, v110
	v_mul_f32_e64 v59, v59, v111
	v_cvt_pk_bf16_f32 v60, v60, v61
	v_mul_f32_e64 v13, v59, v12
	v_mul_f32_e64 v12, v58, v12
	v_rcp_f32_e32 v58, v76
	v_cvt_pk_bf16_f32 v75, v12, v13
	v_mul_f32_e32 v12, v59, v123
	v_add_u32_e32 v80, 0x4000, v198
	v_fmac_f32_e32 v79, v31, v12
	v_add_f32_e32 v12, -1.0, v14
	v_and_b32_e32 v74, 0xffff, v60
	v_lshrrev_b32_e32 v78, 16, v60
	ds_write2_b32 v80, v60, v75 offset1:4
	v_fma_f32 v13, v24, v12, 1.0
	v_mov_b32_e32 v12, v14
	v_mov_b32_e32 v60, v114
	v_mov_b32_e32 v61, v108
	v_mul_f32_e64 v12, v12, v60
	v_mul_f32_e64 v13, v13, v61
	v_rcp_f32_e32 v14, v77
	v_mul_f32_e64 v59, v13, v58
	v_mul_f32_e64 v58, v12, v58
	v_mul_f32_e32 v12, v13, v124
	v_fmac_f32_e32 v79, v32, v12
	v_add_f32_e32 v12, -1.0, v15
	v_fma_f32 v13, v25, v12, 1.0
	v_mov_b32_e32 v12, v15
	v_mov_b32_e32 v108, v115
	v_mul_f32_e64 v12, v12, v108
	v_mul_f32_e64 v13, v13, v109
	v_rcp_f32_e32 v8, v8
	v_mul_f32_e64 v15, v13, v14
	v_mul_f32_e64 v14, v12, v14
	v_mul_f32_e32 v12, v13, v125
	v_fmac_f32_e32 v79, v33, v12
	v_add_f32_e32 v12, -1.0, v4
	v_cvt_pk_bf16_f32 v61, v14, v15
	v_fma_f32 v13, v18, v12, 1.0
	v_mov_b32_e32 v12, v116
	v_mov_b32_e32 v14, v4
	v_mov_b32_e32 v15, v106
	v_mul_f32_e64 v12, v12, v14
	v_mul_f32_e64 v13, v13, v15
	v_mov_b32_e32 v106, v5
	v_mul_f32_e32 v4, v13, v126
	v_fmac_f32_e32 v79, v26, v4
	v_add_f32_e32 v4, -1.0, v5
	v_mul_f32_e64 v14, v12, v8
	v_mul_f32_e64 v15, v13, v8
	v_fma_f32 v13, v19, v4, 1.0
	v_rcp_f32_e32 v4, v9
	v_mov_b32_e32 v12, v117
	v_mul_f32_e64 v8, v12, v106
	v_mul_f32_e64 v9, v13, v107
	v_mov_b32_e32 v12, v6
	v_mul_f32_e64 v5, v9, v4
	v_mul_f32_e64 v4, v8, v4
	v_rcp_f32_e32 v8, v10
	v_cvt_pk_bf16_f32 v76, v4, v5
	v_mul_f32_e32 v4, v9, v127
	v_fmac_f32_e32 v79, v27, v4
	v_add_f32_e32 v4, -1.0, v6
	v_fma_f32 v5, v20, v4, 1.0
	v_mov_b32_e32 v4, v118
	v_mov_b32_e32 v13, v104
	v_mul_f32_e64 v4, v4, v12
	v_mul_f32_e64 v5, v5, v13
	v_rcp_f32_e32 v6, v11
	v_mul_f32_e64 v9, v5, v8
	v_mul_f32_e64 v8, v4, v8
	v_mul_f32_e32 v4, v5, v128
	v_fmac_f32_e32 v79, v28, v4
	v_add_f32_e32 v4, -1.0, v7
	v_fma_f32 v5, v21, v4, 1.0
	v_mov_b32_e32 v4, v119
	v_mov_b32_e32 v104, v7
	v_mul_f32_e64 v4, v4, v104
	v_mul_f32_e64 v5, v5, v105
	v_cvt_pk_bf16_f32 v58, v58, v59
	v_cvt_pk_bf16_f32 v14, v14, v15
	v_cvt_pk_bf16_f32 v8, v8, v9
	v_mul_f32_e64 v7, v5, v6
	v_mul_f32_e64 v6, v4, v6
	v_and_b32_e32 v59, 0xffff, v58
	v_and_b32_e32 v15, 0xffff, v14
	v_and_b32_e32 v9, 0xffff, v8
	v_cvt_pk_bf16_f32 v11, v6, v7
	v_mul_f32_e32 v4, v5, v129
	v_lshrrev_b32_e32 v60, 16, v58
	ds_write2_b32 v80, v58, v61 offset0:8 offset1:12
	v_lshrrev_b32_e32 v58, 16, v14
	v_lshrrev_b32_e32 v12, 16, v8
	v_fmac_f32_e32 v79, v29, v4
	v_lshl_or_b32 v4, v75, 16, v74
	v_lshl_or_b32 v5, v61, 16, v59
	v_lshl_or_b32 v6, v76, 16, v15
	v_lshl_or_b32 v7, v11, 16, v9
	s_mul_i32 s73, s76, 0x420000
	ds_write2_b32 v80, v14, v76 offset0:16 offset1:20
	ds_write2_b32 v80, v8, v11 offset0:24 offset1:28
	v_and_or_b32 v8, v75, s1, v78
	v_and_or_b32 v9, v61, s1, v60
	v_and_or_b32 v10, v76, s1, v58
	v_and_or_b32 v11, v11, s1, v12
	ds_write_b128 v195, v[4:7] offset:256
	ds_write_b128 v195, v[8:11] offset:384
	v_add_f32_dpp v4, v79, v79 quad_perm:[1,0,3,2] row_mask:0xf bank_mask:0xf bound_ctrl:1
	s_mul_hi_i32 s66, s76, 0x420000
	s_add_u32 s76, s43, s73
	v_add_f32_dpp v4, v4, v4 quad_perm:[2,3,0,1] row_mask:0xf bank_mask:0xf bound_ctrl:1
	s_addc_u32 s77, s95, s66
	s_nop 0
	v_mov_b32_dpp v5, v4 row_half_mirror row_mask:0xf bank_mask:0xf bound_ctrl:1
	s_and_saveexec_b64 s[80:81], s[8:9]
	s_cbranch_execz .LBB0_500
	v_lshlrev_b64 v[6:7], 6, v[102:103]
	v_lshl_add_u64 v[6:7], s[76:77], 0, v[6:7]
	s_lshl_b32 s66, s31, 2
	v_lshl_add_u64 v[6:7], v[6:7], 0, s[66:67]
	v_add_f32_e32 v4, v4, v5
	global_store_dword v[6:7], v4, off

; __device__ __forceinline__ int crow(int r, int hi) { return (r & 3) + 8 * (r >> 2) + 4 * hi; }
; __device__ void phase_scan(const Params& p, char* lds) {
;     ...
;         if (mat == 0) {
;           float cc[16];
; #pragma unroll
;           for (int r = 0; r < 16; ++r) cc[r] = -0.6065306597126334f * __builtin_amdgcn_rcpf(1.f + __expf(-(acc[r] + bias)));
; #pragma unroll
;           for (int g = 0; g < 4; ++g) { cc[4 * g + 1] += cc[4 * g]; cc[4 * g + 2] += cc[4 * g + 1]; cc[4 * g + 3] += cc[4 * g + 2]; }
;           float run = 0.f;
; #pragma unroll
;           for (int g = 0; g < 4; ++g) {
;             const float own = cc[4 * g + 3];
;             auto rr2 = __builtin_amdgcn_permlane32_swap(__float_as_uint(own), __float_as_uint(own), false, false);
;             const float both = __uint_as_float(rr2[0]) + __uint_as_float(rr2[1]), partner = both - own;
;             const float off = hi ? run + partner : run;
; #pragma unroll
;             for (int e = 0; e < 4; ++e) Pd[crow(4 * g + e, hi) * 64 + jh * 32 + r32] = __expf(off + cc[4 * g + e]);
;             run += both;
;           }
.LBB0_518:
	v_add_f32_e32 v8, v99, v15
	v_mul_f32_e32 v8, 0xbfb8aa3b, v8
	v_exp_f32_e32 v8, v8
	s_andn2_b64 vcc, exec, s[80:81]
	v_add_f32_e32 v8, 1.0, v8
	v_rcp_f32_e32 v8, v8
	s_cbranch_vccnz .LBB0_520
	v_mul_f32_e64 v0, v0, s74
	v_mul_f32_e64 v1, v1, s75
	v_mul_f32_e64 v2, v2, s74
	v_mul_f32_e64 v3, v3, s75
	v_sub_f32_e32 v1, v0, v1
	v_fmamk_f32 v12, v58, 0xbf1b4598, v1
	v_fmamk_f32 v13, v59, 0xbf1b4598, v12
	v_mov_b32_e32 v58, v13
	v_mov_b32_e32 v59, v13
	s_nop 1
	v_permlane32_swap_b32_e32 v58, v59
	v_add_f32_e32 v58, v58, v59
	v_sub_f32_e32 v59, v58, v13
	v_add_f32_e32 v59, 0, v59
	v_cndmask_b32_e64 v59, v59, 0, s[26:27]
	v_add_f32_e32 v0, v0, v59
	v_add_f32_e32 v1, v1, v59
	v_mul_f32_e32 v0, 0x3fb8aa3b, v0
	v_mul_f32_e32 v1, 0x3fb8aa3b, v1
	v_add_f32_e32 v12, v12, v59
	v_add_f32_e32 v13, v13, v59
	v_exp_f32_e32 v0, v0
	v_exp_f32_e32 v1, v1
	v_mul_f32_e32 v12, 0x3fb8aa3b, v12
	v_mul_f32_e32 v13, 0x3fb8aa3b, v13
	v_mul_f32_e64 v6, v6, s74
	v_mul_f32_e64 v7, v7, s75
	v_sub_f32_e32 v3, v2, v3
	v_exp_f32_e32 v12, v12
	v_exp_f32_e32 v13, v13
	v_fmamk_f32 v14, v60, 0xbf1b4598, v3
	v_sub_f32_e32 v7, v6, v7
	v_fmamk_f32 v15, v61, 0xbf1b4598, v14
	v_fmamk_f32 v59, v9, 0xbf1b4598, v7
	v_fmamk_f32 v60, v8, 0xbf1b4598, v59
	ds_write2st64_b32 v187, v0, v1 offset0:132 offset1:133
	ds_write2st64_b32 v187, v12, v13 offset0:134 offset1:135
	v_mov_b32_e32 v1, v15
	v_mov_b32_e32 v8, v15
	s_nop 1
	v_permlane32_swap_b32_e32 v1, v8
	v_add_f32_e32 v8, v1, v8
	v_add_f32_e32 v0, 0, v58
	v_sub_f32_e32 v1, v8, v15
	v_mul_f32_e64 v4, v4, s74
	v_mul_f32_e64 v5, v5, s75
	v_add_f32_e32 v1, v0, v1
	v_sub_f32_e32 v5, v4, v5
	v_cndmask_b32_e64 v1, v1, v0, s[26:27]
	v_fmamk_f32 v10, v10, 0xbf1b4598, v5
	v_add_f32_e32 v2, v2, v1
	v_add_f32_e32 v3, v3, v1
	v_add_f32_e32 v9, v14, v1
	v_add_f32_e32 v1, v15, v1
	v_fmamk_f32 v11, v11, 0xbf1b4598, v10
	v_mul_f32_e32 v9, 0x3fb8aa3b, v9
	v_mul_f32_e32 v1, 0x3fb8aa3b, v1
	v_exp_f32_e32 v12, v9
	v_exp_f32_e32 v13, v1
	v_mov_b32_e32 v1, v11
	v_mov_b32_e32 v9, v11
	s_nop 1
	v_permlane32_swap_b32_e32 v1, v9
	v_add_f32_e64 v0, v0, v8
	v_add_f32_e64 v1, v1, v9
	v_mul_f32_e32 v2, 0x3fb8aa3b, v2
	v_sub_f32_e32 v8, v1, v11
	v_add_f32_e32 v8, v0, v8
	v_mul_f32_e32 v3, 0x3fb8aa3b, v3
	v_cndmask_b32_e64 v8, v8, v0, s[26:27]
	v_exp_f32_e32 v2, v2
	v_exp_f32_e32 v3, v3
	v_add_f32_e32 v4, v4, v8
	v_add_f32_e32 v5, v5, v8
	v_mul_f32_e32 v4, 0x3fb8aa3b, v4
	v_mul_f32_e32 v5, 0x3fb8aa3b, v5
	v_add_f32_e32 v9, v10, v8
	v_add_f32_e32 v8, v11, v8
	v_exp_f32_e32 v4, v4
	v_exp_f32_e32 v5, v5
	v_mul_f32_e32 v9, 0x3fb8aa3b, v9
	v_mul_f32_e32 v8, 0x3fb8aa3b, v8
	v_exp_f32_e32 v9, v9
	v_exp_f32_e32 v8, v8
	ds_write2st64_b32 v187, v2, v3 offset0:140 offset1:141
	ds_write2st64_b32 v187, v12, v13 offset0:142 offset1:143
	ds_write2st64_b32 v187, v4, v5 offset0:148 offset1:149
	ds_write2st64_b32 v187, v9, v8 offset0:150 offset1:151
	v_mov_b32_e32 v3, v60
	v_mov_b32_e32 v5, v60
	s_nop 1
	v_permlane32_swap_b32_e32 v3, v5
	v_mov_b32_e32 v2, v0
	v_mov_b32_e32 v4, v1
	v_add_f32_e64 v0, v2, v4
	v_add_f32_e64 v1, v3, v5
	v_readlane_b32 s66, v255, 15
	v_sub_f32_e32 v1, v1, v60
	v_add_f32_e32 v1, v0, v1
	v_cndmask_b32_e64 v0, v1, v0, s[26:27]
	v_add_f32_e32 v1, v6, v0
	v_add_f32_e32 v2, v7, v0
	v_add_f32_e32 v3, v59, v0
	v_add_f32_e32 v0, v60, v0
	v_mul_f32_e32 v1, 0x3fb8aa3b, v1
	v_mul_f32_e32 v2, 0x3fb8aa3b, v2
	v_mul_f32_e32 v0, 0x3fb8aa3b, v0
	v_exp_f32_e32 v1, v1
	v_exp_f32_e32 v2, v2
	v_mul_f32_e32 v3, 0x3fb8aa3b, v3
	v_exp_f32_e32 v8, v0
	v_exp_f32_e32 v3, v3
	ds_write2st64_b32 v187, v1, v2 offset0:156 offset1:157
	ds_write_b32 v187, v3 offset:40448
	s_branch .LBB0_521

; __device__ __forceinline__ float lo16(unsigned w) { return __uint_as_float(w << 16); }
; __device__ __forceinline__ float hi16(unsigned w) { return __uint_as_float(w & 0xffff0000u); }
; __device__ __forceinline__ float red8(float v) { v += dpp_f(v, 0); v += dpp_f(v, 1); v += dpp_f(v, 2); return v; }
; __device__ void phase_scan(const Params& p, char* lds) {
;     ...
;       auto prefetch = [&](int c) {
;         const size_t row = (size_t)scan_row(c * 32 + pstep, d, b) * 1024 + h * 64 + j0;
;         pR = *(const u32x4*)(Rg + row); pK = *(const u32x4*)(Kg + row); pV = *(const u32x4*)(Vg + row);
;         const size_t lrow = (size_t)scan_row(c * 32 + r32, d, b);
; #pragma unroll
;         for (int ks = 0; ks < 4; ++ks) pl[ks] = *(const bf16x8*)(Lg + lrow * 256 + mat * 128 + d * 64 + ks * 16 + hi * 8);
;     ...
;         float ss = 0.f;
; #pragma unroll
;         for (int w = 0; w < 4; ++w) {
;           rr[2 * w] = lo16(pR[w]); rr[2 * w + 1] = hi16(pR[w]);
;           kr[2 * w] = lo16(pK[w]); kr[2 * w + 1] = hi16(pK[w]);
;         }
;         const float vv[8] = {lo16(pV[0]), hi16(pV[0]), lo16(pV[1]), hi16(pV[1]), lo16(pV[2]), hi16(pV[2]), lo16(pV[3]), hi16(pV[3])};
;         if (c + 1 < NCH) prefetch(c + 1);
; #pragma unroll
;         for (int e = 0; e < 8; ++e) VV[(pblk * 64 + j0 + e) * 4 + psb] = vv[e];
; #pragma unroll
;         for (int e = 0; e < 8; ++e) { kk[e] = kr[e] * kkc[e]; ss += kk[e] * kk[e]; }
;         ss = red8(ss);
;         const float inv = rsqrtf(fmaxf(ss, 1e-24f));
; #pragma unroll
;         for (int e = 0; e < 8; ++e) kk[e] *= inv;
;       };
;       auto stageB = [&](int c) {
;         char* buf = lds + (c & 1) * SC_BUF;
;         const f32x4 i0 = *(const f32x4*)(IC + pstep * 64 + j0), i1 = *(const f32x4*)(IC + pstep * 64 + j0 + 4);
;         const float ic[8] = {i0[0], i0[1], i0[2], i0[3], i1[0], i1[1], i1[2], i1[3]};
;         const float* Pt = (const float*)(buf + SC_P) + pstep * 64 + j0;
;         const f32x4 pt0 = *(const f32x4*)(Pt), pt1 = *(const f32x4*)(Pt + 4);
;         f32x4 pm0 = {1.f, 1.f, 1.f, 1.f}, pm1 = pm0;
;         if (pstep > 0) { pm0 = *(const f32x4*)(Pt - 64); pm1 = *(const f32x4*)(Pt - 60); }
;         const float pt[8] = {pt0[0], pt0[1], pt0[2], pt0[3], pt1[0], pt1[1], pt1[2], pt1[3]};
;         const float pm[8] = {pm0[0], pm0[1], pm0[2], pm0[3], pm1[0], pm1[1], pm1[2], pm1[3]};
.LBB0_521:
	v_add_u32_e32 v0, 64, v139
	v_sub_u32_e32 v1, 0xbf, v139
	v_cndmask_b32_e64 v0, v1, v0, s[22:23]
	v_add_u32_e32 v0, s35, v0
	v_mov_b32_e32 v1, v17
	v_lshlrev_b64 v[0:1], 10, v[0:1]
	v_or3_b32 v1, v1, 0, 0
	v_or3_b32 v0, v0, v138, s30
	v_lshlrev_b64 v[0:1], 1, v[0:1]
	v_lshl_add_u64 v[2:3], s[28:29], 0, v[0:1]
	v_lshl_add_u64 v[4:5], s[50:51], 0, v[0:1]
	global_load_dwordx4 v[74:77], v[2:3], off
	global_load_dwordx4 v[78:81], v[4:5], off
	v_or_b32_e32 v2, 64, v180
	s_lshl_b64 s[78:79], s[78:79], 1
	v_cndmask_b32_e64 v2, v211, v2, s[22:23]
	s_add_u32 s80, s64, s78
	v_or_b32_e32 v2, s35, v2
	s_addc_u32 s81, s65, s79
	v_lshlrev_b32_e32 v2, 9, v2
	v_mov_b32_e32 v3, v17
	v_lshl_add_u64 v[0:1], s[48:49], 0, v[0:1]
	v_lshl_add_u64 v[2:3], s[80:81], 0, v[2:3]
	v_mov_b32_e32 v101, v17
	v_lshl_add_u64 v[2:3], v[2:3], 0, v[100:101]
	global_load_dwordx4 v[82:85], v[0:1], off
	global_load_dwordx4 v[58:61], v[2:3], off
	global_load_dwordx4 v[62:65], v[2:3], off offset:32
	global_load_dwordx4 v[66:69], v[2:3], off offset:64
	global_load_dwordx4 v[70:73], v[2:3], off offset:96
	v_lshl_add_u32 v0, v177, 2, s66
	v_lshlrev_b32_e32 v108, 16, v90
	v_and_b32_e32 v109, 0xffff0000, v90
	ds_write_b32 v0, v8 offset:6912
	v_and_b32_e32 v0, 0xffff0000, v97
	v_lshlrev_b32_e32 v1, 16, v97
	v_and_b32_e32 v6, 0xffff0000, v94
	v_lshlrev_b32_e32 v7, 16, v94
	v_add_u32_e32 v8, 0xe800, v189
	v_mul_f32_e64 v110, v38, v108
	v_mul_f32_e64 v111, v39, v109
	v_lshlrev_b32_e32 v106, 16, v91
	v_and_b32_e32 v107, 0xffff0000, v91
	v_and_b32_e32 v2, 0xffff0000, v96
	v_lshlrev_b32_e32 v3, 16, v96
	v_and_b32_e32 v4, 0xffff0000, v95
	v_lshlrev_b32_e32 v5, 16, v95
	ds_write2_b32 v8, v7, v6 offset1:4
	ds_write2_b32 v8, v5, v4 offset0:8 offset1:12
	ds_write2_b32 v8, v3, v2 offset0:16 offset1:20
	ds_write2_b32 v8, v1, v0 offset0:24 offset1:28
	v_mul_f32_e64 v0, v110, v110
	v_mul_f32_e64 v1, v111, v111
	v_mul_f32_e64 v112, v40, v106
	v_mul_f32_e64 v113, v41, v107
	v_lshlrev_b32_e32 v104, 16, v92
	v_mul_f32_e64 v2, v112, v112
	v_mul_f32_e64 v3, v113, v113
	v_and_b32_e32 v105, 0xffff0000, v92
	v_add_f32_e32 v0, v0, v1
	v_mul_f32_e64 v114, v34, v104
	v_mul_f32_e64 v115, v35, v105
	v_add_f32_e32 v0, v2, v0
	v_mul_f32_e64 v4, v114, v114
	v_mul_f32_e64 v5, v115, v115
	v_lshlrev_b32_e32 v102, 16, v93
	v_and_b32_e32 v103, 0xffff0000, v93
	v_add_f32_e32 v0, v3, v0
	v_mul_f32_e64 v116, v36, v102
	v_mul_f32_e64 v117, v37, v103
	v_add_f32_e32 v0, v4, v0
	v_mul_f32_e64 v6, v116, v116
	v_mul_f32_e64 v7, v117, v117
	v_add_f32_e32 v0, v5, v0
	v_add_f32_e32 v0, v6, v0
	v_add_f32_e32 v0, v7, v0
	s_waitcnt lgkmcnt(0)
	s_barrier
	v_add_f32_dpp v0, v0, v0 quad_perm:[1,0,3,2] row_mask:0xf bank_mask:0xf bound_ctrl:1
	v_mov_b32_e32 v90, 1.0
	s_nop 0
	v_add_f32_dpp v101, v0, v0 quad_perm:[2,3,0,1] row_mask:0xf bank_mask:0xf bound_ctrl:1
	ds_read_b128 v[8:11], v190
	ds_read_b128 v[0:3], v190 offset:16
	ds_read_b128 v[12:15], v191 offset:33792
	ds_read_b128 v[4:7], v191 offset:33808
	v_mov_b32_dpp v118, v101 row_half_mirror row_mask:0xf bank_mask:0xf bound_ctrl:1
	v_mov_b32_e32 v91, 1.0
	v_mov_b32_e32 v92, 1.0
	v_mov_b32_e32 v93, 1.0
	v_mov_b32_e32 v94, 1.0
	v_mov_b32_e32 v95, 1.0
	v_mov_b32_e32 v96, 1.0
	v_mov_b32_e32 v97, 1.0
	s_and_saveexec_b64 s[78:79], s[6:7]
	s_cbranch_execz .LBB0_523
	ds_read_b128 v[94:97], v191 offset:33536
	ds_read_b128 v[90:93], v191 offset:33552
; __device__ void phase_scan(const Params& p, char* lds) {
;     ...
;         const float inv = rsqrtf(fmaxf(ss, 1e-24f));
; #pragma unroll
;         for (int e = 0; e < 8; ++e) kk[e] *= inv;
;       };
;       auto stageB = [&](int c) {
;         char* buf = lds + (c & 1) * SC_BUF;
;         const f32x4 i0 = *(const f32x4*)(IC + pstep * 64 + j0), i1 = *(const f32x4*)(IC + pstep * 64 + j0 + 4);
;         const float ic[8] = {i0[0], i0[1], i0[2], i0[3], i1[0], i1[1], i1[2], i1[3]};
;         const float* Pt = (const float*)(buf + SC_P) + pstep * 64 + j0;
;         const f32x4 pt0 = *(const f32x4*)(Pt), pt1 = *(const f32x4*)(Pt + 4);
;         f32x4 pm0 = {1.f, 1.f, 1.f, 1.f}, pm1 = pm0;
;         if (pstep > 0) { pm0 = *(const f32x4*)(Pt - 64); pm1 = *(const f32x4*)(Pt - 60); }
;         const float pt[8] = {pt0[0], pt0[1], pt0[2], pt0[3], pt1[0], pt1[1], pt1[2], pt1[3]};
;         const float pm[8] = {pm0[0], pm0[1], pm0[2], pm0[3], pm1[0], pm1[1], pm1[2], pm1[3]};
;         const u32x4 an = {cvtpk(-kk[0] * pm[0], -kk[1] * pm[1]), cvtpk(-kk[2] * pm[2], -kk[3] * pm[3]), cvtpk(-kk[4] * pm[4], -kk[5] * pm[5]), cvtpk(-kk[6] * pm[6], -kk[7] * pm[7])};
;         const u32x4 rn = {cvtpk(rr[0] * pt[0], rr[1] * pt[1]), cvtpk(rr[2] * pt[2], rr[3] * pt[3]), cvtpk(rr[4] * pt[4], rr[5] * pt[5]), cvtpk(rr[6] * pt[6], rr[7] * pt[7])};
;         bf16_t* ARa = (bf16_t*)(buf + SC_ARA) + (pblk * 4 + psb) * 64; bf16_t* ARr = (bf16_t*)(buf + SC_ARR) + (pblk * 4 + psb) * 64;
;         { u32x2 lo = {an[0], an[1]}, hi2 = {an[2], an[3]}; *(u32x2*)(ARa + apos0) = lo; *(u32x2*)(ARa + apos1) = hi2; }
;         { u32x2 lo = {rn[0], rn[1]}, hi2 = {rn[2], rn[3]}; *(u32x2*)(ARr + apos0) = lo; *(u32x2*)(ARr + apos1) = hi2; }
;         *(u32x4*)(SCR + (pstep * 4 + 0) * 64 + j0) = an; *(u32x4*)(SCR + (pstep * 4 + 1) * 64 + j0) = rn;
;         float bs = 0.f;
;         unsigned bq[8], kq[8];
;         unsigned* BK = (unsigned*)(buf + SC_BK) + (pblk * 64 + j0) * 4 + psb;
; #pragma unroll
;         for (int e = 0; e < 8; ++e) {
;           const float kd = kr[e] * (1.f + (ic[e] - 1.f) * kac[e]);
;           const float ip = __builtin_amdgcn_rcpf(pt[e]);
;           const unsigned pr2 = cvtpk(kk[e] * ic[e] * ip, kd * ip);
;           BK[e * 4] = pr2;
;           bq[e] = pr2 & 0xffffu; kq[e] = pr2 >> 16;
;           bs += rr[e] * kd * rkc[e];
;         }
.LBB0_523:
	s_or_b64 exec, exec, s[78:79]
	v_add_f32_e32 v101, v101, v118
	v_max_f32_e32 v101, 0x179abe15, v101
	v_rsq_f32_e32 v118, v101
	v_lshlrev_b32_e32 v120, 16, v86
	v_and_b32_e32 v121, 0xffff0000, v86
	v_lshlrev_b32_e32 v122, 16, v87
	v_mul_f32_e64 v110, v110, v118
	v_mul_f32_e64 v111, v111, v118
	v_mul_f32_e64 v112, v112, v118
	v_mul_f32_e64 v113, v113, v118
	v_and_b32_e32 v123, 0xffff0000, v87
	v_lshlrev_b32_e32 v124, 16, v88
	v_and_b32_e32 v125, 0xffff0000, v88
	v_lshlrev_b32_e32 v126, 16, v89
	v_and_b32_e32 v127, 0xffff0000, v89
	v_mul_f32_e64 v114, v114, v118
	v_mul_f32_e64 v115, v115, v118
	v_mul_f32_e64 v116, v116, v118
	v_mul_f32_e64 v117, v117, v118
	s_waitcnt lgkmcnt(1)
	v_mul_f32_e64 v86, v94, -v110
	v_mul_f32_e64 v87, v95, -v111
	v_mul_f32_e64 v88, v96, -v112
	v_mul_f32_e64 v89, v97, -v113
	v_cvt_pk_bf16_f32 v86, v86, v87
	v_cvt_pk_bf16_f32 v87, v88, v89
	s_waitcnt lgkmcnt(0)
	v_mul_f32_e64 v88, v90, -v114
	v_mul_f32_e64 v89, v91, -v115
	v_mul_f32_e64 v90, v92, -v116
	v_mul_f32_e64 v91, v93, -v117
	v_cvt_pk_bf16_f32 v88, v88, v89
	v_cvt_pk_bf16_f32 v89, v90, v91
	v_mul_f32_e64 v90, v12, v120
	v_mul_f32_e64 v91, v13, v121
	v_mul_f32_e64 v92, v14, v122
	v_mul_f32_e64 v93, v15, v123
	v_cvt_pk_bf16_f32 v90, v90, v91
	v_cvt_pk_bf16_f32 v91, v92, v93
	v_mul_f32_e64 v92, v4, v124
	v_mul_f32_e64 v93, v5, v125
	v_mul_f32_e64 v94, v6, v126
	v_mul_f32_e64 v95, v7, v127
	v_cvt_pk_bf16_f32 v92, v92, v93
	v_cvt_pk_bf16_f32 v93, v94, v95
	v_add_u32_e32 v94, 0xa000, v194
	ds_write2_b64 v94, v[86:87], v[88:89] offset0:128 offset1:130
	v_add_u32_e32 v94, 0xb000, v194
	ds_write2_b64 v94, v[90:91], v[92:93] offset0:128 offset1:130
	ds_write_b128 v195, v[86:89]
	ds_write_b128 v195, v[90:93] offset:128
	v_add_f32_e32 v86, -1.0, v8
	v_fma_f32 v87, v22, v86, 1.0
	v_rcp_f32_e32 v12, v12
	v_mov_b32_e32 v86, v110
	v_mov_b32_e32 v88, v8
	v_mov_b32_e32 v89, v108
	v_mul_f32_e64 v86, v86, v88
	v_mul_f32_e64 v87, v87, v89
	v_mov_b32_e32 v108, v9
	v_mul_f32_e32 v8, v87, v120
	v_fma_f32 v91, v30, v8, 0
	v_add_f32_e32 v8, -1.0, v9
	v_mul_f32_e64 v88, v86, v12
	v_mul_f32_e64 v89, v87, v12
	v_fma_f32 v87, v23, v8, 1.0
	v_rcp_f32_e32 v8, v13
	v_mov_b32_e32 v86, v111
	v_mul_f32_e64 v12, v86, v108
	v_mul_f32_e64 v13, v87, v109
	v_mov_b32_e32 v86, v10
	v_mul_f32_e64 v9, v13, v8
	v_mul_f32_e64 v8, v12, v8
	v_rcp_f32_e32 v12, v14
	v_cvt_pk_bf16_f32 v92, v8, v9
	v_mul_f32_e32 v8, v13, v121
	v_fmac_f32_e32 v91, v31, v8
	v_add_f32_e32 v8, -1.0, v10
	v_fma_f32 v9, v24, v8, 1.0
	v_mov_b32_e32 v8, v112
	v_mov_b32_e32 v87, v106
	v_mul_f32_e64 v8, v8, v86
	v_mul_f32_e64 v9, v9, v87
	v_rcp_f32_e32 v10, v15
	v_mul_f32_e64 v13, v9, v12
	v_mul_f32_e64 v12, v8, v12
	v_mul_f32_e32 v8, v9, v122
	v_fmac_f32_e32 v91, v32, v8
	v_add_f32_e32 v8, -1.0, v11
	v_fma_f32 v9, v25, v8, 1.0
	v_mov_b32_e32 v8, v113
	v_mov_b32_e32 v106, v11
	v_mul_f32_e64 v8, v8, v106
	v_mul_f32_e64 v9, v9, v107
	v_rcp_f32_e32 v4, v4
	v_mul_f32_e64 v11, v9, v10
	v_mul_f32_e64 v10, v8, v10
	v_mul_f32_e32 v8, v9, v123
	v_fmac_f32_e32 v91, v33, v8
	v_add_f32_e32 v8, -1.0, v0
	v_cvt_pk_bf16_f32 v15, v10, v11
	v_fma_f32 v9, v18, v8, 1.0
	v_mov_b32_e32 v8, v114
	v_mov_b32_e32 v10, v0
	v_mov_b32_e32 v11, v104
	v_mul_f32_e64 v8, v8, v10
	v_mul_f32_e64 v9, v9, v11
	v_mov_b32_e32 v104, v1
	v_mul_f32_e32 v0, v9, v124
	v_fmac_f32_e32 v91, v26, v0
	v_add_f32_e32 v0, -1.0, v1
	v_mul_f32_e64 v10, v8, v4
	v_mul_f32_e64 v11, v9, v4
	v_fma_f32 v9, v19, v0, 1.0
	v_rcp_f32_e32 v0, v5
	v_mov_b32_e32 v8, v115
	v_mul_f32_e64 v4, v8, v104
	v_mul_f32_e64 v5, v9, v105
	v_mov_b32_e32 v8, v2
	v_mul_f32_e64 v1, v5, v0
	v_mul_f32_e64 v0, v4, v0
	v_rcp_f32_e32 v4, v6
	v_cvt_pk_bf16_f32 v86, v0, v1
	v_mul_f32_e32 v0, v5, v125
	v_fmac_f32_e32 v91, v27, v0
	v_add_f32_e32 v0, -1.0, v2
	v_fma_f32 v1, v20, v0, 1.0
	v_mov_b32_e32 v0, v116
	v_mov_b32_e32 v9, v102
	v_mul_f32_e64 v0, v0, v8
	v_mul_f32_e64 v1, v1, v9
	v_rcp_f32_e32 v2, v7
	v_mul_f32_e64 v5, v1, v4
	v_mul_f32_e64 v4, v0, v4
	v_mul_f32_e32 v0, v1, v126
	v_fmac_f32_e32 v91, v28, v0
	v_add_f32_e32 v0, -1.0, v3
	v_fma_f32 v1, v21, v0, 1.0
	v_mov_b32_e32 v0, v117
	v_mov_b32_e32 v102, v3
	v_mul_f32_e64 v0, v0, v102
	v_mul_f32_e64 v1, v1, v103
	v_cvt_pk_bf16_f32 v88, v88, v89
	v_cvt_pk_bf16_f32 v12, v12, v13
	v_cvt_pk_bf16_f32 v10, v10, v11
	v_cvt_pk_bf16_f32 v4, v4, v5
	v_mul_f32_e64 v3, v1, v2
	v_mul_f32_e64 v2, v0, v2
	v_and_b32_e32 v89, 0xffff, v88
	v_add_u32_e32 v93, 0xc400, v198
	v_and_b32_e32 v13, 0xffff, v12
	v_and_b32_e32 v11, 0xffff, v10
	v_and_b32_e32 v5, 0xffff, v4
	v_cvt_pk_bf16_f32 v7, v2, v3
	v_mul_f32_e32 v0, v1, v127
	v_lshrrev_b32_e32 v90, 16, v88
	v_lshrrev_b32_e32 v14, 16, v12
	ds_write2_b32 v93, v12, v15 offset0:8 offset1:12
	v_lshrrev_b32_e32 v12, 16, v10
	v_lshrrev_b32_e32 v8, 16, v4
	v_fmac_f32_e32 v91, v29, v0
	v_lshl_or_b32 v0, v92, 16, v89
	v_lshl_or_b32 v1, v15, 16, v13
	v_lshl_or_b32 v2, v86, 16, v11
	v_lshl_or_b32 v3, v7, 16, v5
	s_lshl_b32 s31, s31, 2
	ds_write2_b32 v93, v88, v92 offset1:4
	ds_write2_b32 v93, v10, v86 offset0:16 offset1:20
	ds_write2_b32 v93, v4, v7 offset0:24 offset1:28
	v_and_or_b32 v4, v92, s1, v90
	v_and_or_b32 v5, v15, s1, v14
	v_and_or_b32 v6, v86, s1, v12
	v_and_or_b32 v7, v7, s1, v8
	ds_write_b128 v195, v[0:3] offset:256
	ds_write_b128 v195, v[4:7] offset:384
	v_add_f32_dpp v0, v91, v91 quad_perm:[1,0,3,2] row_mask:0xf bank_mask:0xf bound_ctrl:1
	s_add_u32 s76, s76, s31
	s_addc_u32 s77, s77, 0
	v_add_f32_dpp v0, v0, v0 quad_perm:[2,3,0,1] row_mask:0xf bank_mask:0xf bound_ctrl:1
	s_nop 1
	v_mov_b32_dpp v1, v0 row_half_mirror row_mask:0xf bank_mask:0xf bound_ctrl:1
	s_and_saveexec_b64 s[78:79], s[8:9]
	s_cbranch_execz .LBB0_525
	v_add_f32_e32 v2, v0, v1
	v_lshlrev_b64 v[0:1], 6, v[16:17]
	v_lshl_add_u64 v[0:1], s[76:77], 0, v[0:1]
	global_store_dword v[0:1], v2, off

; __device__ __forceinline__ int crow(int r, int hi) { return (r & 3) + 8 * (r >> 2) + 4 * hi; }
; __device__ void phase_scan(const Params& p, char* lds) {
;     ...
;         if (mat == 0) {
;           float cc[16];
; #pragma unroll
;           for (int r = 0; r < 16; ++r) cc[r] = -0.6065306597126334f * __builtin_amdgcn_rcpf(1.f + __expf(-(acc[r] + bias)));
; #pragma unroll
;           for (int g = 0; g < 4; ++g) { cc[4 * g + 1] += cc[4 * g]; cc[4 * g + 2] += cc[4 * g + 1]; cc[4 * g + 3] += cc[4 * g + 2]; }
;           float run = 0.f;
; #pragma unroll
;           for (int g = 0; g < 4; ++g) {
;             const float own = cc[4 * g + 3];
;             auto rr2 = __builtin_amdgcn_permlane32_swap(__float_as_uint(own), __float_as_uint(own), false, false);
;             const float both = __uint_as_float(rr2[0]) + __uint_as_float(rr2[1]), partner = both - own;
;             const float off = hi ? run + partner : run;
; #pragma unroll
;             for (int e = 0; e < 4; ++e) Pd[crow(4 * g + e, hi) * 64 + jh * 32 + r32] = __expf(off + cc[4 * g + e]);
;             run += both;
;           }
.LBB0_545:
	v_add_f32_e32 v10, v99, v15
	v_mul_f32_e32 v10, 0xbfb8aa3b, v10
	v_exp_f32_e32 v10, v10
	s_andn2_b64 vcc, exec, s[80:81]
	s_add_i32 s90, s88, 0
	v_add_f32_e32 v10, 1.0, v10
	v_rcp_f32_e32 v10, v10
	s_cbranch_vccnz .LBB0_547
	v_mul_f32_e64 v0, v0, s74
	v_mul_f32_e64 v1, v1, s75
	v_mul_f32_e64 v4, v4, s74
	v_mul_f32_e64 v5, v5, s75
	v_sub_f32_e32 v1, v0, v1
	v_fmamk_f32 v12, v86, 0xbf1b4598, v1
	v_sub_f32_e32 v5, v4, v5
	v_fmamk_f32 v13, v87, 0xbf1b4598, v12
	v_fmamk_f32 v86, v8, 0xbf1b4598, v5
	v_fmamk_f32 v87, v9, 0xbf1b4598, v86
	v_mov_b32_e32 v8, v13
	v_mov_b32_e32 v9, v13
	s_nop 1
	v_permlane32_swap_b32_e32 v8, v9
	v_add_f32_e32 v8, v8, v9
	v_sub_f32_e32 v9, v8, v13
	v_add_f32_e32 v9, 0, v9
	v_cndmask_b32_e64 v9, v9, 0, s[26:27]
	v_add_f32_e32 v0, v0, v9
	v_add_f32_e32 v1, v1, v9
	v_mul_f32_e32 v0, 0x3fb8aa3b, v0
	v_mul_f32_e32 v1, 0x3fb8aa3b, v1
	v_add_f32_e32 v12, v12, v9
	v_add_f32_e32 v9, v13, v9
	v_mul_f32_e64 v2, v2, s74
	v_mul_f32_e64 v3, v3, s75
	v_exp_f32_e32 v0, v0
	v_exp_f32_e32 v1, v1
	v_mul_f32_e32 v12, 0x3fb8aa3b, v12
	v_mul_f32_e32 v9, 0x3fb8aa3b, v9
	v_sub_f32_e32 v3, v2, v3
	v_exp_f32_e32 v12, v12
	v_exp_f32_e32 v9, v9
	v_fmamk_f32 v14, v88, 0xbf1b4598, v3
	v_fmamk_f32 v15, v89, 0xbf1b4598, v14
	v_lshl_add_u32 v13, v177, 2, s90
	ds_write2st64_b32 v13, v0, v1 offset1:1
	ds_write2st64_b32 v13, v12, v9 offset0:2 offset1:3
	v_add_f32_e32 v0, 0, v8
	v_mov_b32_e32 v1, v15
	v_mov_b32_e32 v8, v15
	s_nop 1
	v_permlane32_swap_b32_e32 v1, v8
	v_add_f32_e32 v8, v1, v8
	v_sub_f32_e32 v1, v8, v15
	v_add_f32_e32 v1, v0, v1
	v_cndmask_b32_e64 v1, v1, v0, s[26:27]
	v_add_f32_e32 v2, v2, v1
	v_add_f32_e32 v3, v3, v1
	v_add_f32_e32 v9, v14, v1
	v_add_f32_e32 v1, v15, v1
	v_mul_f32_e32 v9, 0x3fb8aa3b, v9
	v_mul_f32_e32 v1, 0x3fb8aa3b, v1
	v_exp_f32_e32 v12, v9
	v_exp_f32_e32 v14, v1
	v_mov_b32_e32 v1, v87
	v_mov_b32_e32 v9, v87
	s_nop 1
	v_permlane32_swap_b32_e32 v1, v9
	v_add_f32_e64 v0, v0, v8
	v_add_f32_e64 v1, v1, v9
	v_mul_f32_e32 v2, 0x3fb8aa3b, v2
	v_sub_f32_e32 v8, v1, v87
	v_add_f32_e32 v8, v0, v8
	v_mul_f32_e32 v3, 0x3fb8aa3b, v3
	v_cndmask_b32_e64 v8, v8, v0, s[26:27]
	v_mul_f32_e64 v6, v6, s74
	v_mul_f32_e64 v7, v7, s75
	v_exp_f32_e32 v2, v2
	v_exp_f32_e32 v3, v3
	v_add_f32_e32 v4, v4, v8
	v_add_f32_e32 v5, v5, v8
	v_sub_f32_e32 v7, v6, v7
	v_mul_f32_e32 v4, 0x3fb8aa3b, v4
	v_mul_f32_e32 v5, 0x3fb8aa3b, v5
	v_add_f32_e32 v9, v86, v8
	v_add_f32_e32 v8, v87, v8
	v_fmamk_f32 v11, v11, 0xbf1b4598, v7
	v_exp_f32_e32 v4, v4
	v_exp_f32_e32 v5, v5
	v_mul_f32_e32 v9, 0x3fb8aa3b, v9
	v_mul_f32_e32 v8, 0x3fb8aa3b, v8
	v_fmamk_f32 v10, v10, 0xbf1b4598, v11
	v_exp_f32_e32 v9, v9
	v_exp_f32_e32 v8, v8
	ds_write2st64_b32 v13, v2, v3 offset0:8 offset1:9
	ds_write2st64_b32 v13, v12, v14 offset0:10 offset1:11
	ds_write2st64_b32 v13, v4, v5 offset0:16 offset1:17
	ds_write2st64_b32 v13, v9, v8 offset0:18 offset1:19
	v_mov_b32_e32 v3, v10
	v_mov_b32_e32 v5, v10
	s_nop 1
	v_permlane32_swap_b32_e32 v3, v5
	v_mov_b32_e32 v2, v0
	v_mov_b32_e32 v4, v1
	v_add_f32_e64 v0, v2, v4
	v_add_f32_e64 v1, v3, v5
	s_mov_b32 s80, s90
	v_sub_f32_e32 v1, v1, v10
	v_add_f32_e32 v1, v0, v1
	v_cndmask_b32_e64 v0, v1, v0, s[26:27]
	v_add_f32_e32 v1, v6, v0
	v_add_f32_e32 v2, v7, v0
	v_add_f32_e32 v3, v11, v0
	v_add_f32_e32 v0, v10, v0
	v_mul_f32_e32 v1, 0x3fb8aa3b, v1
	v_mul_f32_e32 v2, 0x3fb8aa3b, v2
	v_mul_f32_e32 v0, 0x3fb8aa3b, v0
	v_exp_f32_e32 v1, v1
	v_exp_f32_e32 v2, v2
	v_mul_f32_e32 v3, 0x3fb8aa3b, v3
	v_exp_f32_e32 v10, v0
	v_exp_f32_e32 v3, v3
	ds_write2st64_b32 v13, v1, v2 offset0:24 offset1:25
	ds_write_b32 v13, v3 offset:6656
	s_branch .LBB0_548

; __device__ __forceinline__ float lo16(unsigned w) { return __uint_as_float(w << 16); }
; __device__ __forceinline__ float hi16(unsigned w) { return __uint_as_float(w & 0xffff0000u); }
; __device__ __forceinline__ float red8(float v) { v += dpp_f(v, 0); v += dpp_f(v, 1); v += dpp_f(v, 2); return v; }
; __device__ void phase_scan(const Params& p, char* lds) {
;     ...
;         float ss = 0.f;
; #pragma unroll
;         for (int w = 0; w < 4; ++w) {
;           rr[2 * w] = lo16(pR[w]); rr[2 * w + 1] = hi16(pR[w]);
;           kr[2 * w] = lo16(pK[w]); kr[2 * w + 1] = hi16(pK[w]);
;         }
;         const float vv[8] = {lo16(pV[0]), hi16(pV[0]), lo16(pV[1]), hi16(pV[1]), lo16(pV[2]), hi16(pV[2]), lo16(pV[3]), hi16(pV[3])};
;         if (c + 1 < NCH) prefetch(c + 1);
; #pragma unroll
;         for (int e = 0; e < 8; ++e) VV[(pblk * 64 + j0 + e) * 4 + psb] = vv[e];
; #pragma unroll
;         for (int e = 0; e < 8; ++e) { kk[e] = kr[e] * kkc[e]; ss += kk[e] * kk[e]; }
;         ss = red8(ss);
;         const float inv = rsqrtf(fmaxf(ss, 1e-24f));
; #pragma unroll
;         for (int e = 0; e < 8; ++e) kk[e] *= inv;
;       };
;       auto stageB = [&](int c) {
;         char* buf = lds + (c & 1) * SC_BUF;
;         const f32x4 i0 = *(const f32x4*)(IC + pstep * 64 + j0), i1 = *(const f32x4*)(IC + pstep * 64 + j0 + 4);
;         const float ic[8] = {i0[0], i0[1], i0[2], i0[3], i1[0], i1[1], i1[2], i1[3]};
;         const float* Pt = (const float*)(buf + SC_P) + pstep * 64 + j0;
;         const f32x4 pt0 = *(const f32x4*)(Pt), pt1 = *(const f32x4*)(Pt + 4);
;         f32x4 pm0 = {1.f, 1.f, 1.f, 1.f}, pm1 = pm0;
;         if (pstep > 0) { pm0 = *(const f32x4*)(Pt - 64); pm1 = *(const f32x4*)(Pt - 60); }
;         const float pt[8] = {pt0[0], pt0[1], pt0[2], pt0[3], pt1[0], pt1[1], pt1[2], pt1[3]};
;         const float pm[8] = {pm0[0], pm0[1], pm0[2], pm0[3], pm1[0], pm1[1], pm1[2], pm1[3]};
.LBB0_550:
	v_lshlrev_b32_e32 v110, 16, v78
	v_and_b32_e32 v111, 0xffff0000, v78
	v_lshlrev_b32_e32 v106, 16, v80
	v_and_b32_e32 v107, 0xffff0000, v80
	v_lshlrev_b32_e32 v104, 16, v81
	v_and_b32_e32 v105, 0xffff0000, v81
	v_and_b32_e32 v80, 0xffff0000, v82
	v_lshlrev_b32_e32 v81, 16, v82
	v_lshl_add_u32 v82, v188, 2, s90
	v_lshlrev_b32_e32 v108, 16, v79
	v_and_b32_e32 v109, 0xffff0000, v79
	v_and_b32_e32 v12, 0xffff0000, v85
	v_lshlrev_b32_e32 v13, 16, v85
	v_add_u32_e32 v82, 0x6400, v82
	v_mul_f32_e64 v112, v38, v110
	v_mul_f32_e64 v113, v39, v111
	v_and_b32_e32 v14, 0xffff0000, v84
	v_lshlrev_b32_e32 v15, 16, v84
	v_and_b32_e32 v78, 0xffff0000, v83
	v_lshlrev_b32_e32 v79, 16, v83
	ds_write2_b32 v82, v81, v80 offset1:4
	ds_write2_b32 v82, v79, v78 offset0:8 offset1:12
	ds_write2_b32 v82, v15, v14 offset0:16 offset1:20
	ds_write2_b32 v82, v13, v12 offset0:24 offset1:28
	v_mul_f32_e64 v12, v112, v112
	v_mul_f32_e64 v13, v113, v113
	v_mul_f32_e64 v114, v40, v108
	v_mul_f32_e64 v115, v41, v109
	v_add_f32_e32 v12, v12, v13
	v_mul_f32_e64 v14, v114, v114
	v_mul_f32_e64 v15, v115, v115
	v_mul_f32_e64 v116, v34, v106
	v_mul_f32_e64 v117, v35, v107
	v_add_f32_e32 v12, v14, v12
	v_mul_f32_e64 v78, v116, v116
	v_mul_f32_e64 v79, v117, v117
	v_add_f32_e32 v12, v15, v12
	v_mul_f32_e64 v118, v36, v104
	v_mul_f32_e64 v119, v37, v105
	v_add_f32_e32 v12, v78, v12
	v_mul_f32_e64 v80, v118, v118
	v_mul_f32_e64 v81, v119, v119
	v_add_f32_e32 v12, v79, v12
	v_add_f32_e32 v12, v80, v12
	v_add_f32_e32 v12, v81, v12
	v_lshlrev_b32_e32 v78, 2, v138
	v_add3_u32 v125, s90, v218, v78
	v_add_f32_dpp v12, v12, v12 quad_perm:[1,0,3,2] row_mask:0xf bank_mask:0xf bound_ctrl:1
	s_waitcnt lgkmcnt(0)
	s_barrier
	v_add_f32_dpp v123, v12, v12 quad_perm:[2,3,0,1] row_mask:0xf bank_mask:0xf bound_ctrl:1
	ds_read_b128 v[82:85], v190
	ds_read_b128 v[12:15], v190 offset:16
	ds_read_b128 v[86:89], v125
	ds_read_b128 v[78:81], v125 offset:16
	v_mov_b32_dpp v124, v123 row_half_mirror row_mask:0xf bank_mask:0xf bound_ctrl:1
	v_mov_b32_e32 v90, 1.0
	v_mov_b32_e32 v91, 1.0
	v_mov_b32_e32 v92, 1.0
	v_mov_b32_e32 v93, 1.0
	v_mov_b32_e32 v94, 1.0
	v_mov_b32_e32 v95, 1.0
	v_mov_b32_e32 v96, 1.0
	v_mov_b32_e32 v97, 1.0
	s_and_saveexec_b64 s[80:81], s[6:7]
	s_cbranch_execz .LBB0_552
	v_add_u32_e32 v90, 0xffffff10, v125
	v_add_u32_e32 v91, 0xffffff00, v125
	ds_read_b128 v[94:97], v91
	ds_read_b128 v[90:93], v90
; __device__ void phase_scan(const Params& p, char* lds) {
;     ...
;         const float inv = rsqrtf(fmaxf(ss, 1e-24f));
; #pragma unroll
;         for (int e = 0; e < 8; ++e) kk[e] *= inv;
;       };
;       auto stageB = [&](int c) {
;         char* buf = lds + (c & 1) * SC_BUF;
;         const f32x4 i0 = *(const f32x4*)(IC + pstep * 64 + j0), i1 = *(const f32x4*)(IC + pstep * 64 + j0 + 4);
;         const float ic[8] = {i0[0], i0[1], i0[2], i0[3], i1[0], i1[1], i1[2], i1[3]};
;         const float* Pt = (const float*)(buf + SC_P) + pstep * 64 + j0;
;         const f32x4 pt0 = *(const f32x4*)(Pt), pt1 = *(const f32x4*)(Pt + 4);
;         f32x4 pm0 = {1.f, 1.f, 1.f, 1.f}, pm1 = pm0;
;         if (pstep > 0) { pm0 = *(const f32x4*)(Pt - 64); pm1 = *(const f32x4*)(Pt - 60); }
;         const float pt[8] = {pt0[0], pt0[1], pt0[2], pt0[3], pt1[0], pt1[1], pt1[2], pt1[3]};
;         const float pm[8] = {pm0[0], pm0[1], pm0[2], pm0[3], pm1[0], pm1[1], pm1[2], pm1[3]};
;         const u32x4 an = {cvtpk(-kk[0] * pm[0], -kk[1] * pm[1]), cvtpk(-kk[2] * pm[2], -kk[3] * pm[3]), cvtpk(-kk[4] * pm[4], -kk[5] * pm[5]), cvtpk(-kk[6] * pm[6], -kk[7] * pm[7])};
;         const u32x4 rn = {cvtpk(rr[0] * pt[0], rr[1] * pt[1]), cvtpk(rr[2] * pt[2], rr[3] * pt[3]), cvtpk(rr[4] * pt[4], rr[5] * pt[5]), cvtpk(rr[6] * pt[6], rr[7] * pt[7])};
;         bf16_t* ARa = (bf16_t*)(buf + SC_ARA) + (pblk * 4 + psb) * 64; bf16_t* ARr = (bf16_t*)(buf + SC_ARR) + (pblk * 4 + psb) * 64;
;         { u32x2 lo = {an[0], an[1]}, hi2 = {an[2], an[3]}; *(u32x2*)(ARa + apos0) = lo; *(u32x2*)(ARa + apos1) = hi2; }
;         { u32x2 lo = {rn[0], rn[1]}, hi2 = {rn[2], rn[3]}; *(u32x2*)(ARr + apos0) = lo; *(u32x2*)(ARr + apos1) = hi2; }
;         *(u32x4*)(SCR + (pstep * 4 + 0) * 64 + j0) = an; *(u32x4*)(SCR + (pstep * 4 + 1) * 64 + j0) = rn;
;         float bs = 0.f;
;         unsigned bq[8], kq[8];
;         unsigned* BK = (unsigned*)(buf + SC_BK) + (pblk * 64 + j0) * 4 + psb;
; #pragma unroll
;         for (int e = 0; e < 8; ++e) {
;           const float kd = kr[e] * (1.f + (ic[e] - 1.f) * kac[e]);
;           const float ip = __builtin_amdgcn_rcpf(pt[e]);
;           const unsigned pr2 = cvtpk(kk[e] * ic[e] * ip, kd * ip);
;           BK[e * 4] = pr2;
;           bq[e] = pr2 & 0xffffu; kq[e] = pr2 >> 16;
;           bs += rr[e] * kd * rkc[e];
;         }
.LBB0_552:
	s_or_b64 exec, exec, s[80:81]
	v_add_f32_e32 v123, v123, v124
	v_max_f32_e32 v123, 0x179abe15, v123
	v_rsq_f32_e32 v124, v123
	v_lshlrev_b32_e32 v126, 16, v75
	v_and_b32_e32 v127, 0xffff0000, v75
	v_lshlrev_b32_e32 v128, 16, v76
	v_mul_f32_e64 v112, v112, v124
	v_mul_f32_e64 v113, v113, v124
	v_mul_f32_e64 v114, v114, v124
	v_mul_f32_e64 v115, v115, v124
	v_mul_f32_e64 v116, v116, v124
	v_mul_f32_e64 v117, v117, v124
	v_mul_f32_e64 v118, v118, v124
	v_mul_f32_e64 v119, v119, v124
	v_lshlrev_b32_e32 v124, 16, v74
	v_and_b32_e32 v125, 0xffff0000, v74
	v_and_b32_e32 v129, 0xffff0000, v76
	v_lshlrev_b32_e32 v130, 16, v77
	v_and_b32_e32 v131, 0xffff0000, v77
	s_waitcnt lgkmcnt(1)
	v_mul_f32_e64 v74, v94, -v112
	v_mul_f32_e64 v75, v95, -v113
	v_mul_f32_e64 v76, v96, -v114
	v_mul_f32_e64 v77, v97, -v115
	v_cvt_pk_bf16_f32 v74, v74, v75
	v_cvt_pk_bf16_f32 v75, v76, v77
	s_waitcnt lgkmcnt(0)
	v_mul_f32_e64 v76, v90, -v116
	v_mul_f32_e64 v77, v91, -v117
	v_mul_f32_e64 v90, v92, -v118
	v_mul_f32_e64 v91, v93, -v119
	v_cvt_pk_bf16_f32 v76, v76, v77
	v_cvt_pk_bf16_f32 v77, v90, v91
	v_mul_f32_e64 v90, v124, v86
	v_mul_f32_e64 v91, v125, v87
	v_mul_f32_e64 v92, v126, v88
	v_mul_f32_e64 v93, v127, v89
	v_cvt_pk_bf16_f32 v90, v90, v91
	v_cvt_pk_bf16_f32 v91, v92, v93
	v_mul_f32_e64 v92, v128, v78
	v_mul_f32_e64 v93, v129, v79
	v_mul_f32_e64 v94, v130, v80
	v_mul_f32_e64 v95, v131, v81
	v_cvt_pk_bf16_f32 v92, v92, v93
	v_cvt_pk_bf16_f32 v93, v94, v95
	v_add3_u32 v94, s90, v192, v193
	v_add_u32_e32 v95, 0x2000, v94
	v_add_u32_e32 v94, 0x3000, v94
	ds_write2_b64 v95, v[74:75], v[76:77] offset1:2
	ds_write2_b64 v94, v[90:91], v[92:93] offset1:2
	ds_write_b128 v195, v[74:77]
	ds_write_b128 v195, v[90:93] offset:128
	v_rcp_f32_e32 v76, v86
	v_add_f32_e32 v74, -1.0, v82
	v_fma_f32 v75, v22, v74, 1.0
	v_mov_b32_e32 v90, v112
	v_mov_b32_e32 v91, v110
	v_mov_b32_e32 v74, v82
	v_mul_f32_e64 v74, v90, v74
	v_mul_f32_e64 v75, v91, v75
	v_mov_b32_e32 v110, v113
	v_mul_f32_e64 v77, v75, v76
	v_mul_f32_e64 v76, v74, v76
	v_mul_f32_e32 v74, v124, v75
	v_cvt_pk_bf16_f32 v82, v76, v77
	v_rcp_f32_e32 v76, v87
	v_fma_f32 v91, v30, v74, 0
	v_add_f32_e32 v74, -1.0, v83
	v_fma_f32 v75, v23, v74, 1.0
	v_mov_b32_e32 v74, v83
	v_mul_f32_e64 v74, v110, v74
	v_mul_f32_e64 v75, v111, v75
	v_add3_u32 v92, s90, v196, v197
	v_mul_f32_e64 v77, v75, v76
	v_mul_f32_e64 v76, v74, v76
	v_mul_f32_e32 v74, v125, v75
	v_cvt_pk_bf16_f32 v87, v76, v77
	v_rcp_f32_e32 v76, v88
	v_add_u32_e32 v92, 0x4000, v92
	v_fmac_f32_e32 v91, v31, v74
	v_add_f32_e32 v74, -1.0, v84
	v_and_b32_e32 v86, 0xffff, v82
	v_lshrrev_b32_e32 v90, 16, v82
	ds_write2_b32 v92, v82, v87 offset1:4
	v_fma_f32 v75, v24, v74, 1.0
	v_mov_b32_e32 v82, v114
	v_mov_b32_e32 v83, v108
	v_mov_b32_e32 v74, v84
	v_mul_f32_e64 v74, v82, v74
	v_mul_f32_e64 v75, v83, v75
	v_mov_b32_e32 v108, v115
	v_mul_f32_e64 v77, v75, v76
	v_mul_f32_e64 v76, v74, v76
	v_mul_f32_e32 v74, v126, v75
	v_cvt_pk_bf16_f32 v82, v76, v77
	v_rcp_f32_e32 v76, v89
	v_fmac_f32_e32 v91, v32, v74
	v_add_f32_e32 v74, -1.0, v85
	v_fma_f32 v75, v25, v74, 1.0
	v_mov_b32_e32 v74, v85
	v_mul_f32_e64 v74, v108, v74
	v_mul_f32_e64 v75, v109, v75
	v_and_b32_e32 v84, 0xffff, v82
	v_mul_f32_e64 v77, v75, v76
	v_mul_f32_e64 v76, v74, v76
	v_mul_f32_e32 v74, v127, v75
	v_cvt_pk_bf16_f32 v85, v76, v77
	v_fmac_f32_e32 v91, v33, v74
	v_add_f32_e32 v74, -1.0, v12
	v_lshrrev_b32_e32 v88, 16, v82
	ds_write2_b32 v92, v82, v85 offset0:8 offset1:12
	v_fma_f32 v75, v18, v74, 1.0
	v_rcp_f32_e32 v76, v78
	v_mov_b32_e32 v82, v116
	v_mov_b32_e32 v83, v106
	v_mov_b32_e32 v74, v12
	v_mul_f32_e64 v74, v82, v74
	v_mul_f32_e64 v75, v83, v75
	v_mov_b32_e32 v106, v117
	v_mul_f32_e32 v12, v128, v75
	v_fmac_f32_e32 v91, v26, v12
	v_add_f32_e32 v12, -1.0, v13
	v_mul_f32_e64 v77, v75, v76
	v_mul_f32_e64 v76, v74, v76
	v_fma_f32 v75, v19, v12, 1.0
	v_rcp_f32_e32 v12, v79
	v_mov_b32_e32 v74, v13
	v_mul_f32_e64 v74, v106, v74
	v_mul_f32_e64 v75, v107, v75
	v_cvt_pk_bf16_f32 v76, v76, v77
	v_mul_f32_e64 v13, v75, v12
	v_mul_f32_e64 v12, v74, v12
	v_rcp_f32_e32 v74, v80
	v_cvt_pk_bf16_f32 v79, v12, v13
	v_mul_f32_e32 v12, v129, v75
	v_fmac_f32_e32 v91, v27, v12
	v_add_f32_e32 v12, -1.0, v14
	v_and_b32_e32 v78, 0xffff, v76
	v_lshrrev_b32_e32 v82, 16, v76
	ds_write2_b32 v92, v76, v79 offset0:16 offset1:20
	v_fma_f32 v13, v20, v12, 1.0
	v_mov_b32_e32 v76, v118
	v_mov_b32_e32 v77, v104
	v_mov_b32_e32 v12, v14
	v_mul_f32_e64 v12, v76, v12
	v_mul_f32_e64 v13, v77, v13
	v_rcp_f32_e32 v14, v81
	v_mul_f32_e64 v75, v13, v74
	v_mul_f32_e64 v74, v12, v74
	v_mul_f32_e32 v12, v130, v13
	v_fmac_f32_e32 v91, v28, v12
	v_add_f32_e32 v12, -1.0, v15
	v_fma_f32 v13, v21, v12, 1.0
	v_mov_b32_e32 v104, v119
	v_mov_b32_e32 v12, v15
	v_mul_f32_e64 v12, v104, v12
	v_mul_f32_e64 v13, v105, v13
	v_cvt_pk_bf16_f32 v74, v74, v75
	v_mul_f32_e64 v15, v13, v14
	v_mul_f32_e64 v14, v12, v14
	v_and_b32_e32 v75, 0xffff, v74
	v_cvt_pk_bf16_f32 v80, v14, v15
	v_mul_f32_e32 v12, v131, v13
	v_lshrrev_b32_e32 v77, 16, v74
	v_fmac_f32_e32 v91, v29, v12
	v_lshl_or_b32 v12, v87, 16, v86
	v_lshl_or_b32 v13, v85, 16, v84
	v_lshl_or_b32 v14, v79, 16, v78
	v_lshl_or_b32 v15, v80, 16, v75
	ds_write2_b32 v92, v74, v80 offset0:24 offset1:28
	v_and_or_b32 v74, v87, s1, v90
	v_and_or_b32 v75, v85, s1, v88
	v_and_or_b32 v76, v79, s1, v82
	v_and_or_b32 v77, v80, s1, v77
	ds_write_b128 v195, v[12:15] offset:256
	ds_write_b128 v195, v[74:77] offset:384
	v_add_f32_dpp v12, v91, v91 quad_perm:[1,0,3,2] row_mask:0xf bank_mask:0xf bound_ctrl:1
	s_nop 1
	v_add_f32_dpp v12, v12, v12 quad_perm:[2,3,0,1] row_mask:0xf bank_mask:0xf bound_ctrl:1
	s_nop 1
	v_mov_b32_dpp v13, v12 row_half_mirror row_mask:0xf bank_mask:0xf bound_ctrl:1
	s_and_saveexec_b64 s[80:81], s[8:9]
	s_cbranch_execz .LBB0_554
	v_add_f32_e32 v14, v12, v13
	v_add_u32_e32 v12, 64, v122
	v_cmp_gt_i32_e32 vcc, s92, v12
	v_add_u32_e32 v13, 0xffffff40, v122
	s_movk_i32 s88, 0xffc0
	v_cndmask_b32_e32 v15, v220, v221, vcc
	v_cndmask_b32_e32 v12, v13, v12, vcc
	v_mov_b32_e32 v13, s34
	v_mov_b32_e32 v74, s35
	v_add3_u32 v15, v15, v120, s88
	v_cndmask_b32_e32 v13, v13, v74, vcc
	v_cndmask_b32_e64 v12, v15, v12, s[22:23]
	v_add_u32_e32 v12, v12, v13
	v_ashrrev_i32_e32 v13, 31, v12
	v_lshlrev_b64 v[12:13], 6, v[12:13]
	v_lshl_add_u64 v[12:13], s[76:77], 0, v[12:13]
	global_store_dword v[12:13], v14, off

; __device__ void phase_scan(const Params& p, char* lds) {
;     ...
;         for (int blk = 0; blk < 8; ++blk) {
;           ScBlk nxt; sc_ldb(nxt, buf, (blk + 1) & 7, arOff, bkOff, vOff);
;           u32x4 b1 = {cvtpk(St0[0], St0[1]), cvtpk(St0[2], St0[3]), cvtpk(St1[0], St1[1]), cvtpk(St1[2], St1[3])};
;           u32x4 b2 = {cvtpk(St2[0], St2[1]), cvtpk(St2[2], St2[3]), cvtpk(St3[0], St3[1]), cvtpk(St3[2], St3[3])};
;           f32x4 sr = {0.f, 0.f, 0.f, 0.f}, yr = sr;
;           sr = MFMA16(*(bf16x8*)&cur.aa0, *(bf16x8*)&b1, sr); yr = MFMA16(*(bf16x8*)&cur.ar0, *(bf16x8*)&b1, yr);
;           sr = MFMA16(*(bf16x8*)&cur.aa1, *(bf16x8*)&b2, sr); yr = MFMA16(*(bf16x8*)&cur.ar1, *(bf16x8*)&b2, yr);
;           const float v1 = cur.v[0], v2 = cur.v[1], v3 = cur.v[2], v4 = cur.v[3];
;           const f32x4 s0 = cur.s[0], s1 = cur.s[1], s2 = cur.s[2], s3 = cur.s[3], s4 = cur.s[4], s5 = cur.s[5], s6 = cur.s[6], s7 = cur.s[7];
;           const float sa1 = sr[0];
;           const float sa2 = sr[1] + s0[0] * sa1 + s1[2] * v1;
;           const float sa3 = sr[2] + s0[1] * sa1 + s1[3] * v1 + s0[2] * sa2 + s2[0] * v2;
;           const float sa4 = sr[3] + s0[3] * sa1 + s2[1] * v1 + s1[0] * sa2 + s2[2] * v2 + s1[1] * sa3 + s2[3] * v3;
;           f32x4 y;
;           y[0] = yr[0] + s3[0] * sa1 + s5[2] * v1;
;           y[1] = yr[1] + s3[1] * sa1 + s5[3] * v1 + s3[2] * sa2 + s6[0] * v2;
;           y[2] = yr[2] + s3[3] * sa1 + s6[1] * v1 + s4[0] * sa2 + s6[2] * v2 + s4[1] * sa3 + s6[3] * v3;
;           y[3] = yr[3] + s4[2] * sa1 + s7[0] * v1 + s4[3] * sa2 + s7[1] * v2 + s5[0] * sa3 + s7[2] * v3 + s5[1] * sa4 + s7[3] * v4;
;           u32x4 bu = {cvtpk(sa1, v1), cvtpk(sa2, v2), cvtpk(sa3, v3), cvtpk(sa4, v4)};
;           if (q != 0) { bu[0] = 0u; bu[1] = 0u; bu[2] = 0u; bu[3] = 0u; }
;           St0 = MFMA16(*(bf16x8*)&cur.k0, *(bf16x8*)&bu, St0);
;           St1 = MFMA16(*(bf16x8*)&cur.k1, *(bf16x8*)&bu, St1);
;           St2 = MFMA16(*(bf16x8*)&cur.k2, *(bf16x8*)&bu, St2);
;           St3 = MFMA16(*(bf16x8*)&cur.k3, *(bf16x8*)&bu, St3);
;           *(f32x4*)(yb + blk * 1024) = y;
;           cur = nxt;
;           if (blk == 7) {
;             const char* pw = buf + SC_P + 31 * 256 + wOff;
;             St0 *= *(const f32x4*)(pw); St1 *= *(const f32x4*)(pw + 64); St2 *= *(const f32x4*)(pw + 128); St3 *= *(const f32x4*)(pw + 192);
;           }
.LBB0_581:
	v_cvt_pk_bf16_f32 v110, v70, v71
	v_cvt_pk_bf16_f32 v111, v72, v73
	v_cvt_pk_bf16_f32 v112, v74, v75
	v_cvt_pk_bf16_f32 v113, v76, v77
	v_cvt_pk_bf16_f32 v224, v78, v79
	v_cvt_pk_bf16_f32 v225, v80, v81
	s_waitcnt lgkmcnt(14)
	v_mfma_f32_16x16x32_bf16 v[66:69], v[66:69], v[110:113], 0
	v_cvt_pk_bf16_f32 v226, v82, v83
	v_cvt_pk_bf16_f32 v227, v84, v85
	v_add_u32_e32 v86, 0, v234
	v_mfma_f32_16x16x32_bf16 v[62:65], v[62:65], v[110:113], 0
	v_add_u32_e32 v235, 0, v175
	ds_read_b128 v[236:239], v86
	ds_read_b128 v[240:243], v86 offset:64
	ds_read_b128 v[244:247], v86 offset:4096
	ds_read_b128 v[248:251], v86 offset:4160
	v_add_u32_e32 v86, 0, v233
	v_mfma_f32_16x16x32_bf16 v[58:61], v[58:61], v[224:227], v[66:69]
	v_add_u32_e32 v94, 0, v222
	v_add_u32_e32 v118, 0, v16
	ds_read_b128 v[102:105], v86
	ds_read_b128 v[98:101], v86 offset:256
	ds_read_b128 v[90:93], v86 offset:512
	ds_read_b128 v[86:89], v86 offset:768
	s_waitcnt lgkmcnt(14)
	v_mfma_f32_16x16x32_bf16 v[54:57], v[54:57], v[224:227], v[62:65]
	ds_read_b128 v[94:97], v94
	ds_read_b128 v[134:137], v118
	ds_read_b128 v[122:125], v118 offset:16
	ds_read_b128 v[126:129], v118 offset:32
	v_fmac_f32_e32 v59, v50, v58
	v_fmac_f32_e32 v59, v40, v18
	v_fmac_f32_e32 v60, v51, v58
	v_fmac_f32_e32 v60, v41, v18
	v_fmac_f32_e32 v61, v53, v58
	v_fmac_f32_e32 v61, v43, v18
	v_fmac_f32_e32 v60, v52, v59
	v_fmac_f32_e32 v60, v42, v19
	v_fmac_f32_e32 v61, v38, v59
	v_fmac_f32_e32 v61, v44, v19
	v_fmac_f32_e32 v61, v39, v60
	v_fmac_f32_e32 v61, v45, v20
	v_cvt_pk_bf16_f32 v62, v58, v18
	v_cvt_pk_bf16_f32 v63, v59, v19
	v_cvt_pk_bf16_f32 v64, v60, v20
	v_cvt_pk_bf16_f32 v65, v61, v21
	s_waitcnt lgkmcnt(14)
	v_cndmask_b32_e64 v38, 0, v62, s[20:21]
	v_cndmask_b32_e64 v39, 0, v63, s[20:21]
	v_cndmask_b32_e64 v40, 0, v64, s[20:21]
	v_cndmask_b32_e64 v41, 0, v65, s[20:21]
	v_fmac_f32_e32 v54, v46, v58
	v_fmac_f32_e32 v54, v28, v18
	v_mfma_f32_16x16x32_bf16 v[70:73], v[12:15], v[38:41], v[70:73]
	v_fmac_f32_e32 v55, v47, v58
	v_fmac_f32_e32 v55, v29, v18
	v_fmac_f32_e32 v55, v48, v59
	v_fmac_f32_e32 v55, v30, v19
	v_mfma_f32_16x16x32_bf16 v[74:77], v[8:11], v[38:41], v[74:77]
	v_fmac_f32_e32 v56, v49, v58
	v_fmac_f32_e32 v56, v31, v18
	v_fmac_f32_e32 v56, v22, v59
	v_fmac_f32_e32 v56, v32, v19
	v_fmac_f32_e32 v56, v23, v60
	v_fmac_f32_e32 v56, v33, v20
	v_mfma_f32_16x16x32_bf16 v[78:81], v[4:7], v[38:41], v[78:81]
	s_waitcnt lgkmcnt(12)
	v_fmac_f32_e32 v57, v24, v58
	v_fmac_f32_e32 v57, v34, v18
	v_fmac_f32_e32 v57, v25, v59
	v_fmac_f32_e32 v57, v35, v19
	v_mfma_f32_16x16x32_bf16 v[82:85], v[0:3], v[38:41], v[82:85]
	ds_read_b128 v[130:133], v118 offset:48
	ds_read_b128 v[106:109], v118 offset:64
	v_fmac_f32_e32 v57, v26, v60
	v_fmac_f32_e32 v57, v36, v20
	v_fmac_f32_e32 v57, v27, v61
	v_fmac_f32_e32 v57, v37, v21
	v_add_u32_e32 v0, 0x16800, v235
	ds_read_b128 v[110:113], v118 offset:80
	ds_read_b128 v[114:117], v118 offset:96
	ds_read_b128 v[118:121], v118 offset:112
	ds_write_b128 v0, v[54:57]
	v_cvt_pk_bf16_f32 v26, v70, v71
	v_cvt_pk_bf16_f32 v27, v72, v73
	v_cvt_pk_bf16_f32 v28, v74, v75
	v_cvt_pk_bf16_f32 v29, v76, v77
	v_cvt_pk_bf16_f32 v224, v78, v79
	v_cvt_pk_bf16_f32 v225, v80, v81
	s_waitcnt lgkmcnt(14)
	v_mfma_f32_16x16x32_bf16 v[30:33], v[236:239], v[26:29], 0
	v_cvt_pk_bf16_f32 v226, v82, v83
	v_cvt_pk_bf16_f32 v227, v84, v85
	s_and_b32 s24, s34, 6
	v_mfma_f32_16x16x32_bf16 v[236:239], v[244:247], v[26:29], 0
	v_lshl_add_u32 v0, s24, 9, v223
	s_lshl_b32 s25, s24, 10
	s_lshl_b32 s24, s24, 7
	v_mfma_f32_16x16x32_bf16 v[240:243], v[240:243], v[224:227], v[30:33]
	ds_read_b128 v[66:69], v0 offset:8192
	ds_read_b128 v[58:61], v0 offset:8256
	ds_read_b128 v[62:65], v0 offset:12288
	ds_read_b128 v[54:57], v0 offset:12352
	v_add_u32_e32 v0, s25, v231
	v_add_u32_e32 v18, s25, v232
	v_mfma_f32_16x16x32_bf16 v[224:227], v[248:251], v[224:227], v[236:239]
	s_add_i32 s24, s31, s24
	ds_read_b128 v[12:15], v0 offset:16384
	ds_read_b128 v[8:11], v0 offset:16640
	ds_read_b128 v[4:7], v0 offset:16896
	ds_read_b128 v[0:3], v0 offset:17152
	s_waitcnt lgkmcnt(14)
	v_fmac_f32_e32 v241, v134, v240
	v_fmac_f32_e32 v241, v124, v94
	v_fmac_f32_e32 v242, v135, v240
	v_fmac_f32_e32 v242, v125, v94
	v_fmac_f32_e32 v243, v137, v240
	v_fmac_f32_e32 v243, v127, v94
	v_fmac_f32_e32 v242, v136, v241
	v_fmac_f32_e32 v242, v126, v95
	v_fmac_f32_e32 v243, v122, v241
	v_fmac_f32_e32 v243, v128, v95
	v_fmac_f32_e32 v243, v123, v242
	v_fmac_f32_e32 v243, v129, v96
	v_cvt_pk_bf16_f32 v236, v240, v94
	v_cvt_pk_bf16_f32 v237, v241, v95
	v_cvt_pk_bf16_f32 v238, v242, v96
	v_cvt_pk_bf16_f32 v239, v243, v97
	s_waitcnt lgkmcnt(11)
	v_cndmask_b32_e64 v122, 0, v236, s[20:21]
	v_cndmask_b32_e64 v123, 0, v237, s[20:21]
	v_cndmask_b32_e64 v124, 0, v238, s[20:21]
	v_cndmask_b32_e64 v125, 0, v239, s[20:21]
	v_fmac_f32_e32 v224, v130, v240
	v_fmac_f32_e32 v224, v112, v94
	v_mfma_f32_16x16x32_bf16 v[70:73], v[102:105], v[122:125], v[70:73]
	s_waitcnt lgkmcnt(9)
	v_fmac_f32_e32 v225, v131, v240
	v_fmac_f32_e32 v225, v113, v94
	v_fmac_f32_e32 v225, v132, v241
	v_fmac_f32_e32 v225, v114, v95
	v_mfma_f32_16x16x32_bf16 v[74:77], v[98:101], v[122:125], v[74:77]
	v_fmac_f32_e32 v226, v133, v240
	v_fmac_f32_e32 v226, v115, v94
	v_fmac_f32_e32 v226, v106, v241
	v_fmac_f32_e32 v226, v116, v95
	v_fmac_f32_e32 v226, v107, v242
	v_fmac_f32_e32 v226, v117, v96
	v_mfma_f32_16x16x32_bf16 v[78:81], v[90:93], v[122:125], v[78:81]
	v_mov_b32_e32 v34, s24
	ds_read_b128 v[18:21], v18 offset:25600
	ds_read_b128 v[50:53], v34 offset:24576
	ds_read_b128 v[38:41], v34 offset:24592
	ds_read_b128 v[42:45], v34 offset:24608
	v_fmac_f32_e32 v227, v108, v240
	v_fmac_f32_e32 v227, v118, v94
	v_fmac_f32_e32 v227, v109, v241
	v_fmac_f32_e32 v227, v119, v95
	v_fmac_f32_e32 v227, v110, v242
	v_fmac_f32_e32 v227, v120, v96
	v_fmac_f32_e32 v227, v111, v243
	v_fmac_f32_e32 v227, v121, v97
	v_mfma_f32_16x16x32_bf16 v[82:85], v[86:89], v[122:125], v[82:85]
	ds_read_b128 v[46:49], v34 offset:24624
	ds_read_b128 v[22:25], v34 offset:24640
	ds_read_b128 v[26:29], v34 offset:24656
	ds_read_b128 v[30:33], v34 offset:24672
	ds_read_b128 v[34:37], v34 offset:24688
	s_cmp_lg_u32 s34, 8
	v_add_u32_e32 v86, 0x16c00, v235
	ds_write_b128 v86, v[224:227]
	s_cbranch_scc1 .LBB0_583
	v_add_u32_e32 v98, s31, v204
	ds_read_b128 v[86:89], v98 offset:7936
	ds_read_b128 v[90:93], v98 offset:8000
	ds_read_b128 v[94:97], v98 offset:8064
	ds_read_b128 v[98:101], v98 offset:8128
	s_waitcnt lgkmcnt(3)
	v_mul_f32_e64 v72, v72, v88
	v_mul_f32_e64 v73, v73, v89
	v_mul_f32_e64 v70, v70, v86
	v_mul_f32_e64 v71, v71, v87
	s_waitcnt lgkmcnt(2)
	v_mul_f32_e64 v76, v76, v92
	v_mul_f32_e64 v77, v77, v93
	v_mul_f32_e64 v74, v74, v90
	v_mul_f32_e64 v75, v75, v91
	s_waitcnt lgkmcnt(1)
	v_mul_f32_e64 v80, v80, v96
	v_mul_f32_e64 v81, v81, v97
	v_mul_f32_e64 v78, v78, v94
	v_mul_f32_e64 v79, v79, v95
	s_waitcnt lgkmcnt(0)
	v_mul_f32_e64 v84, v84, v100
	v_mul_f32_e64 v85, v85, v101
	v_mul_f32_e64 v82, v82, v98
	v_mul_f32_e64 v83, v83, v99

; __device__ __forceinline__ float lo16(unsigned w) { return __uint_as_float(w << 16); }
; __device__ __forceinline__ float hi16(unsigned w) { return __uint_as_float(w & 0xffff0000u); }
; __device__ void phase_readout(const Params& p) {
;     ...
;     float y[16], v[16], g[16];
; #pragma unroll
;     for (int q = 0; q < 2; ++q) {
; #pragma unroll
;       for (int w = 0; w < 4; ++w) {
;         y[8 * q + 2 * w] = lo16(cur.a[q][w]) + lo16(cur.b[q][w]); y[8 * q + 2 * w + 1] = hi16(cur.a[q][w]) + hi16(cur.b[q][w]);
;         v[8 * q + 2 * w] = lo16(cur.v[q][w]); v[8 * q + 2 * w + 1] = hi16(cur.v[q][w]);
;         g[8 * q + 2 * w] = lo16(cur.g[q][w]); g[8 * q + 2 * w + 1] = hi16(cur.g[q][w]);
;       }
;     }
;     float s = 0.f;
; #pragma unroll
;     for (int e = 0; e < 16; ++e) s += y[e];
;     s += dpp_f(s, 0); s += dpp_f(s, 1);
;     const float mean = s * (1.f / 64.f);
;     float q2 = 0.f;
; #pragma unroll
;     for (int e = 0; e < 16; ++e) { const float dlt = y[e] - mean; q2 += dlt * dlt; }
;     q2 += dpp_f(q2, 0); q2 += dpp_f(q2, 1);
;     const float rs = rsqrtf(q2 * (1.f / 64.f) + 64e-5f);
.LBB0_612:
	s_or_b64 exec, exec, s[6:7]
	s_waitcnt vmcnt(3)
	v_lshlrev_b32_e32 v116, 16, v94
	s_waitcnt vmcnt(0)
	v_add_f32_e32 v102, v102, v104
	v_lshlrev_b32_e32 v104, 16, v83
	v_and_b32_e32 v105, 0xffff0000, v83
	v_and_b32_e32 v117, 0xffff0000, v94
	v_mul_f32_e32 v83, 0xbfb8aa3b, v116
	v_lshlrev_b32_e32 v106, 16, v87
	v_and_b32_e32 v107, 0xffff0000, v87
	v_exp_f32_e32 v87, v83
	v_mul_f32_e32 v83, 0xbfb8aa3b, v117
	v_add_f32_e64 v108, v104, v106
	v_add_f32_e64 v109, v105, v107
	v_lshlrev_b32_e32 v104, 16, v91
	v_and_b32_e32 v105, 0xffff0000, v91
	v_exp_f32_e32 v91, v83
	v_lshlrev_b32_e32 v114, 16, v82
	v_and_b32_e32 v115, 0xffff0000, v82
	v_lshlrev_b32_e32 v82, 16, v86
	v_and_b32_e32 v83, 0xffff0000, v86
	v_add_f32_e32 v86, 1.0, v87
	v_rcp_f32_e32 v94, v86
	v_add_f32_e32 v86, 1.0, v91
	v_lshlrev_b32_e32 v106, 16, v95
	v_and_b32_e32 v107, 0xffff0000, v95
	v_rcp_f32_e32 v95, v86
	v_add_f32_e64 v114, v114, v82
	v_add_f32_e64 v115, v115, v83
	v_lshlrev_b32_e32 v86, 16, v90
	v_and_b32_e32 v87, 0xffff0000, v90
	v_mul_f32_e64 v82, v94, v116
	v_mul_f32_e64 v83, v95, v117
	v_lshlrev_b32_e32 v116, 16, v93
	v_lshlrev_b32_e32 v90, 16, v81
	v_and_b32_e32 v91, 0xffff0000, v81
	v_and_b32_e32 v117, 0xffff0000, v93
	v_mul_f32_e32 v81, 0xbfb8aa3b, v116
	v_exp_f32_e32 v81, v81
	v_mul_f32_e32 v93, 0xbfb8aa3b, v117
	v_exp_f32_e32 v93, v93
	v_lshlrev_b32_e32 v94, 16, v85
	v_add_f32_e32 v81, 1.0, v81
	v_rcp_f32_e32 v118, v81
	v_add_f32_e32 v81, 1.0, v93
	v_rcp_f32_e32 v119, v81
	v_and_b32_e32 v95, 0xffff0000, v85
	v_add_f32_e64 v120, v90, v94
	v_add_f32_e64 v121, v91, v95
	v_lshlrev_b32_e32 v90, 16, v89
	v_mul_f32_e64 v94, v118, v116
	v_mul_f32_e64 v95, v119, v117
	v_lshlrev_b32_e32 v118, 16, v92
	v_and_b32_e32 v119, 0xffff0000, v92
	v_mul_f32_e32 v81, 0xbfb8aa3b, v118
	v_exp_f32_e32 v85, v81
	v_mul_f32_e32 v81, 0xbfb8aa3b, v119
	v_and_b32_e32 v91, 0xffff0000, v89
	v_exp_f32_e32 v89, v81
	v_lshlrev_b32_e32 v116, 16, v80
	v_and_b32_e32 v117, 0xffff0000, v80
	v_lshlrev_b32_e32 v80, 16, v84
	v_and_b32_e32 v81, 0xffff0000, v84
	v_add_f32_e32 v84, 1.0, v85
	v_add_f32_e32 v85, 1.0, v89
	v_rcp_f32_e32 v84, v84
	v_rcp_f32_e32 v85, v85
	v_lshlrev_b32_e32 v92, 16, v88
	v_and_b32_e32 v93, 0xffff0000, v88
	v_lshlrev_b32_e32 v88, 16, v59
	v_mul_f32_e64 v84, v84, v118
	v_mul_f32_e64 v85, v85, v119
	v_lshlrev_b32_e32 v118, 16, v79
	v_and_b32_e32 v89, 0xffff0000, v59
	v_and_b32_e32 v119, 0xffff0000, v79
	v_mul_f32_e32 v59, 0xbfb8aa3b, v118
	v_exp_f32_e32 v59, v59
	v_mul_f32_e32 v79, 0xbfb8aa3b, v119
	v_exp_f32_e32 v79, v79
	v_add_f32_e64 v80, v116, v80
	v_add_f32_e64 v81, v117, v81
	v_lshlrev_b32_e32 v116, 16, v67
	v_and_b32_e32 v117, 0xffff0000, v67
	v_add_f32_e32 v59, 1.0, v59
	v_lshlrev_b32_e32 v124, 16, v78
	v_rcp_f32_e32 v122, v59
	v_add_f32_e32 v59, 1.0, v79
	v_add_f32_e64 v88, v88, v116
	v_add_f32_e64 v89, v89, v117
	v_lshlrev_b32_e32 v116, 16, v35
	v_and_b32_e32 v117, 0xffff0000, v35
	v_and_b32_e32 v125, 0xffff0000, v78
	v_mul_f32_e32 v35, 0xbfb8aa3b, v124
	v_rcp_f32_e32 v123, v59
	v_exp_f32_e32 v35, v35
	v_mul_f32_e32 v59, 0xbfb8aa3b, v125
	v_exp_f32_e32 v67, v59
	v_mul_f32_e64 v118, v122, v118
	v_mul_f32_e64 v119, v123, v119
	v_add_f32_e32 v35, 1.0, v35
	v_lshlrev_b32_e32 v122, 16, v58
	v_and_b32_e32 v123, 0xffff0000, v58
	v_lshlrev_b32_e32 v58, 16, v66
	v_and_b32_e32 v59, 0xffff0000, v66
	v_rcp_f32_e32 v66, v35
	v_add_f32_e32 v35, 1.0, v67
	v_rcp_f32_e32 v67, v35
	v_lshlrev_b32_e32 v78, 16, v34
	v_and_b32_e32 v79, 0xffff0000, v34
	v_add_f32_e64 v58, v122, v58
	v_add_f32_e64 v59, v123, v59
	v_mul_f32_e64 v34, v66, v124
	v_mul_f32_e64 v35, v67, v125
	v_lshlrev_b32_e32 v124, 16, v77
	v_lshlrev_b32_e32 v66, 16, v57
	v_and_b32_e32 v67, 0xffff0000, v57
	v_and_b32_e32 v125, 0xffff0000, v77
	v_mul_f32_e32 v57, 0xbfb8aa3b, v124
	v_exp_f32_e32 v57, v57
	v_mul_f32_e32 v77, 0xbfb8aa3b, v125
	v_exp_f32_e32 v77, v77
	v_lshlrev_b32_e32 v122, 16, v65
	v_add_f32_e32 v57, 1.0, v57
	v_rcp_f32_e32 v126, v57
	v_add_f32_e32 v57, 1.0, v77
	v_rcp_f32_e32 v127, v57
	v_and_b32_e32 v57, 0xffff0000, v64
	v_and_b32_e32 v123, 0xffff0000, v65
	v_add_f32_e64 v66, v66, v122
	v_add_f32_e64 v67, v67, v123
	v_mul_f32_e64 v124, v126, v124
	v_mul_f32_e64 v125, v127, v125
	v_lshlrev_b32_e32 v126, 16, v56
	v_and_b32_e32 v127, 0xffff0000, v56
	v_lshlrev_b32_e32 v56, 16, v64
	v_add_f32_e64 v56, v126, v56
	v_add_f32_e64 v57, v127, v57
	v_lshlrev_b32_e32 v122, 16, v33
	v_and_b32_e32 v123, 0xffff0000, v33
	v_add_f32_e32 v33, 0, v56
	v_add_f32_e32 v33, v57, v33
	v_add_f32_e32 v33, v66, v33
	v_add_f32_e32 v33, v67, v33
	v_add_f32_e32 v33, v58, v33
	v_add_f32_e32 v33, v59, v33
	v_add_f32_e32 v33, v88, v33
	v_add_f32_e32 v33, v89, v33
	v_add_f32_e32 v33, v80, v33
	v_add_f32_e32 v33, v81, v33
	v_add_f32_e32 v33, v120, v33
	v_add_f32_e32 v33, v121, v33
	v_add_f32_e32 v33, v114, v33
	v_add_f32_e32 v33, v115, v33
	v_add_f32_e32 v33, v108, v33
	v_add_f32_e32 v33, v109, v33
	v_lshlrev_b32_e32 v64, 16, v76
	v_and_b32_e32 v65, 0xffff0000, v76
	v_add_f32_dpp v33, v33, v33 quad_perm:[1,0,3,2] row_mask:0xf bank_mask:0xf bound_ctrl:1
	v_mul_f32_e32 v76, 0xbfb8aa3b, v64
	v_mul_f32_e32 v77, 0xbfb8aa3b, v65
	v_add_f32_dpp v33, v33, v33 quad_perm:[2,3,0,1] row_mask:0xf bank_mask:0xf bound_ctrl:1
	v_mul_f32_e32 v126, 0x3c800000, v33
	v_add_f32_e64 v56, v56, -v126
	v_add_f32_e64 v57, v57, -v126
	v_add_f32_e64 v66, v66, -v126
	v_add_f32_e64 v67, v67, -v126
	v_mul_f32_e64 v128, v56, v56
	v_mul_f32_e64 v129, v57, v57
	v_mul_f32_e64 v130, v66, v66
; __device__ __forceinline__ unsigned cvtpk(float lo, float hi) { f32x2 v = {lo, hi}; bf16x2_t b = __builtin_convertvector(v, bf16x2_t); return *(unsigned*)&b; }
; __device__ __forceinline__ float sigmoidf_(float x) { return __builtin_amdgcn_rcpf(1.f + __expf(-x)); }
; __device__ void phase_readout(const Params& p) {
;     ...
;     float q2 = 0.f;
; #pragma unroll
;     for (int e = 0; e < 16; ++e) { const float dlt = y[e] - mean; q2 += dlt * dlt; }
;     q2 += dpp_f(q2, 0); q2 += dpp_f(q2, 1);
;     const float rs = rsqrtf(q2 * (1.f / 64.f) + 64e-5f);
;     const float bonus = cur.b0 + cur.b1;
;     float r[16];
; #pragma unroll
;     for (int e = 0; e < 16; ++e) {
;       const float yn = (y[e] - mean) * rs * lg[e] + lb[e];
;       r[e] = (yn + bonus * v[e]) * (g[e] * sigmoidf_(g[e]));
;     }
;     u32x4 w0 = {cvtpk(r[0], r[1]), cvtpk(r[2], r[3]), cvtpk(r[4], r[5]), cvtpk(r[6], r[7])};
;     u32x4 w1 = {cvtpk(r[8], r[9]), cvtpk(r[10], r[11]), cvtpk(r[12], r[13]), cvtpk(r[14], r[15])};
;     *(u32x4*)(G + o) = w0; *(u32x4*)(G + o + 8) = w1;
;     cur = nxt;
	v_mul_f32_e64 v131, v67, v67
	v_add_f32_e32 v33, v128, v129
	v_add_f32_e64 v58, v58, -v126
	v_add_f32_e64 v59, v59, -v126
	v_add_f32_e32 v33, v130, v33
	v_mul_f32_e64 v132, v58, v58
	v_mul_f32_e64 v133, v59, v59
	v_add_f32_e32 v33, v131, v33
	v_add_f32_e64 v88, v88, -v126
	v_add_f32_e64 v89, v89, -v126
	v_add_f32_e32 v33, v132, v33
	v_mul_f32_e64 v134, v88, v88
	v_mul_f32_e64 v135, v89, v89
	v_add_f32_e32 v33, v133, v33
	v_add_f32_e64 v80, v80, -v126
	v_add_f32_e64 v81, v81, -v126
	v_add_f32_e32 v33, v134, v33
	v_mul_f32_e64 v136, v80, v80
	v_mul_f32_e64 v137, v81, v81
	v_add_f32_e32 v33, v135, v33
	v_add_f32_e64 v120, v120, -v126
	v_add_f32_e64 v121, v121, -v126
	v_add_f32_e32 v33, v136, v33
	v_mul_f32_e64 v138, v120, v120
	v_mul_f32_e64 v139, v121, v121
	v_add_f32_e32 v33, v137, v33
	v_add_f32_e64 v114, v114, -v126
	v_add_f32_e64 v115, v115, -v126
	v_add_f32_e32 v33, v138, v33
	v_mul_f32_e64 v140, v114, v114
	v_mul_f32_e64 v141, v115, v115
	v_add_f32_e32 v33, v139, v33
	v_add_f32_e64 v108, v108, -v126
	v_add_f32_e64 v109, v109, -v126
	v_add_f32_e32 v33, v140, v33
	v_mul_f32_e64 v126, v108, v108
	v_mul_f32_e64 v127, v109, v109
	v_add_f32_e32 v33, v141, v33
	v_add_f32_e32 v33, v126, v33
	v_add_f32_e32 v33, v127, v33
	v_exp_f32_e32 v76, v76
	v_exp_f32_e32 v77, v77
	v_add_f32_dpp v33, v33, v33 quad_perm:[1,0,3,2] row_mask:0xf bank_mask:0xf bound_ctrl:1
	v_lshlrev_b32_e32 v126, 16, v32
	v_add_f32_e32 v76, 1.0, v76
	v_add_f32_dpp v33, v33, v33 quad_perm:[2,3,0,1] row_mask:0xf bank_mask:0xf bound_ctrl:1
	v_fmamk_f32 v33, v33, 0x3c800000, v103
	v_mul_f32_e32 v113, 0x4b800000, v33
	v_cmp_gt_f32_e32 vcc, s2, v33
	v_add_f32_e32 v77, 1.0, v77
	v_rcp_f32_e32 v76, v76
	v_cndmask_b32_e32 v33, v33, v113, vcc
	v_rcp_f32_e32 v77, v77
	v_rsq_f32_e32 v113, v33
	v_and_b32_e32 v127, 0xffff0000, v32
	v_lshl_add_u64 v[98:99], v[98:99], 0, s[18:19]
	v_mul_f32_e64 v32, v76, v64
	v_mul_f32_e64 v33, v77, v65
	v_mul_f32_e32 v64, 0x45800000, v113
	v_cndmask_b32_e32 v64, v113, v64, vcc
	v_mul_f32_e64 v56, v56, v64
	v_mul_f32_e64 v57, v57, v64
	v_mul_f32_e64 v58, v58, v64
	v_mul_f32_e64 v59, v59, v64
	v_fma_f32 v56, v24, v56, v28
	v_fma_f32 v57, v25, v57, v29
	v_fma_f32 v58, v16, v58, v20
	v_fma_f32 v59, v17, v59, v21
	v_fma_f32 v56, v102, v126, v56
	v_fma_f32 v57, v102, v127, v57
	v_fma_f32 v58, v102, v78, v58
	v_fma_f32 v59, v102, v79, v59
	v_mul_f32_e64 v32, v32, v56
	v_mul_f32_e64 v33, v33, v57
	v_mul_f32_e64 v56, v66, v64
	v_mul_f32_e64 v57, v67, v64
	v_mul_f32_e64 v34, v34, v58
	v_mul_f32_e64 v35, v35, v59
	v_mul_f32_e64 v58, v88, v64
	v_mul_f32_e64 v59, v89, v64
	v_mul_f32_e64 v66, v80, v64
	v_mul_f32_e64 v67, v81, v64
	v_mul_f32_e64 v76, v120, v64
	v_mul_f32_e64 v77, v121, v64
	v_mul_f32_e64 v78, v114, v64
	v_mul_f32_e64 v79, v115, v64
	v_mul_f32_e32 v65, 0xbfb8aa3b, v106
	v_exp_f32_e32 v65, v65
	v_mul_f32_e32 v80, 0xbfb8aa3b, v107
	v_exp_f32_e32 v81, v80
	v_fma_f32 v58, v18, v58, v22
	v_fma_f32 v59, v19, v59, v23
	v_add_f32_e32 v65, 1.0, v65
	v_rcp_f32_e32 v80, v65
	v_add_f32_e32 v65, 1.0, v81
	v_rcp_f32_e32 v81, v65
	v_mul_f32_e64 v65, v109, v64
	v_mul_f32_e64 v64, v108, v64
	v_fma_f32 v58, v102, v116, v58
	v_fma_f32 v59, v102, v117, v59
	v_fma_f32 v64, v2, v64, v6
	v_fma_f32 v65, v3, v65, v7
	v_mul_f32_e64 v80, v80, v106
	v_mul_f32_e64 v81, v81, v107
	v_fma_f32 v64, v102, v104, v64
	v_fma_f32 v65, v102, v105, v65
	v_fma_f32 v56, v26, v56, v30
	v_fma_f32 v57, v27, v57, v31
	v_mul_f32_e64 v58, v118, v58
	v_mul_f32_e64 v59, v119, v59
	v_fma_f32 v66, v8, v66, v12
	v_fma_f32 v67, v9, v67, v13
	v_fma_f32 v76, v10, v76, v14
	v_fma_f32 v77, v11, v77, v15
	v_fma_f32 v78, v0, v78, v4
	v_fma_f32 v79, v1, v79, v5
	v_mul_f32_e64 v64, v80, v64
	v_mul_f32_e64 v65, v81, v65
	v_fma_f32 v56, v102, v122, v56
	v_fma_f32 v57, v102, v123, v57
	v_fma_f32 v66, v102, v92, v66
	v_fma_f32 v67, v102, v93, v67
	v_fma_f32 v76, v102, v90, v76
	v_fma_f32 v77, v102, v91, v77
	v_fma_f32 v78, v102, v86, v78
	v_fma_f32 v79, v102, v87, v79
	v_cvt_pk_bf16_f32 v34, v34, v35
	v_cvt_pk_bf16_f32 v35, v58, v59
	v_cvt_pk_bf16_f32 v59, v64, v65
	v_lshl_add_u64 v[64:65], s[86:87], 0, v[96:97]
	v_mul_f32_e64 v56, v124, v56
	v_mul_f32_e64 v57, v125, v57
	v_mul_f32_e64 v66, v84, v66
	v_mul_f32_e64 v67, v85, v67
	v_mul_f32_e64 v76, v94, v76
	v_mul_f32_e64 v77, v95, v77
	v_mul_f32_e64 v78, v82, v78
	v_mul_f32_e64 v79, v83, v79
	v_add_co_u32_e32 v64, vcc, 0x21000000, v64
	v_cvt_pk_bf16_f32 v32, v32, v33
	v_cvt_pk_bf16_f32 v33, v56, v57
	v_cvt_pk_bf16_f32 v56, v66, v67
	v_cvt_pk_bf16_f32 v57, v76, v77
	v_cvt_pk_bf16_f32 v58, v78, v79
	v_addc_co_u32_e32 v65, vcc, 0, v65, vcc
	global_store_dwordx4 v[64:65], v[32:35], off
	global_store_dwordx4 v[64:65], v[56:59], off offset:16
	v_mov_b64_e32 v[82:83], v[42:43]
	v_mov_b64_e32 v[66:67], v[46:47]
	v_mov_b64_e32 v[58:59], v[38:39]
	v_mov_b64_e32 v[86:87], v[50:51]
	v_mov_b64_e32 v[32:33], v[52:53]
	v_mov_b64_e32 v[90:91], v[62:63]
	v_mov_b64_e32 v[78:79], v[70:71]
	v_mov_b64_e32 v[94:95], v[74:75]
	v_lshl_add_u64 v[96:97], v[96:97], 0, s[16:17]
	v_lshl_add_u64 v[100:101], v[100:101], 0, s[16:17]
	v_mov_b64_e32 v[56:57], v[36:37]
	v_mov_b64_e32 v[80:81], v[40:41]
	v_mov_b64_e32 v[64:65], v[44:45]
	v_mov_b64_e32 v[84:85], v[48:49]
	v_mov_b64_e32 v[34:35], v[54:55]
	v_mov_b64_e32 v[88:89], v[60:61]
	v_mov_b64_e32 v[76:77], v[68:69]
	v_mov_b64_e32 v[92:93], v[72:73]
	v_mov_b32_e32 v102, v111
	v_mov_b32_e32 v104, v112
	s_andn2_b64 exec, exec, s[20:21]
	s_cbranch_execz .LBB0_615

;   __device__ __forceinline__ void operator()(int lrow, int nc, const f32x16& a0, const f32x16& a1, float) const {
;     const int lane = threadIdx.x & 63, wid = threadIdx.x >> 6, r32 = lane & 31, hi = lane >> 5;
;     float* sp = (float*)(scr + wid * (32 * 272));
; #pragma unroll
;     for (int g = 0; g < 4; ++g) {
;       const f32x4 v0 = {a0[4 * g], a0[4 * g + 1], a0[4 * g + 2], a0[4 * g + 3]}, v1 = {a1[4 * g], a1[4 * g + 1], a1[4 * g + 2], a1[4 * g + 3]};
;       *(f32x4*)(sp + r32 * 68 + 4 * hi + 8 * g) = v0; *(f32x4*)(sp + r32 * 68 + 32 + 4 * hi + 8 * g) = v1;
;     }
;     asm volatile("s_waitcnt lgkmcnt(0)" ::: "memory");
;     const int c4 = (lane & 15) * 4, colg = n0 + (nc & ~7) + c4;
;     const size_t rbase = (size_t)(lrow - r32) * 1024 + colg;
;     const f32x4 gv = *(const f32x4*)(gvec + colg);
;     f32x4 xv[8];
; #pragma unroll
;     for (int i = 0; i < 8; ++i) xv[i] = *(const f32x4*)(xin + rbase + (size_t)((lane >> 4) + 4 * i) * 1024);
;     asm volatile("" ::: "memory");
; #pragma unroll
;     for (int i = 0; i < 8; ++i) {
;       const int row = (lane >> 4) + 4 * i;
;       const f32x4 av = *(const f32x4*)(sp + row * 68 + c4);
;       f32x4 r; r[0] = xv[i][0] + gv[0] * av[0]; r[1] = xv[i][1] + gv[1] * av[1]; r[2] = xv[i][2] + gv[2] * av[2]; r[3] = xv[i][3] + gv[3] * av[3];
;       *(f32x4*)(xout + rbase + (size_t)row * 1024) = r;
;     }
.LBB0_627:
	ds_write_b128 v237, v[112:115]
	ds_write_b128 v237, v[96:99] offset:128
	ds_write_b128 v237, v[116:119] offset:32
	ds_write_b128 v237, v[100:103] offset:160
	ds_write_b128 v237, v[120:123] offset:64
	ds_write_b128 v237, v[104:107] offset:192
	ds_write_b128 v237, v[124:127] offset:96
	ds_write_b128 v237, v[108:111] offset:224
	v_or_b32_e32 v96, s22, v236
	v_ashrrev_i32_e32 v97, 31, v96
	v_lshl_add_u64 v[104:105], v[96:97], 0, v[170:171]
	s_waitcnt vmcnt(5)
	v_lshlrev_b64 v[136:137], 2, v[104:105]
	v_lshl_add_u64 v[104:105], s[18:19], 0, v[136:137]
	v_lshl_add_u64 v[132:133], v[104:105], 0, v[166:167]
	v_add_co_u32_e32 v108, vcc, s30, v132
	s_waitcnt lgkmcnt(0)
	v_lshl_add_u64 v[98:99], v[96:97], 2, s[20:21]
	s_nop 0
	v_addc_co_u32_e32 v109, vcc, 0, v133, vcc
	v_add_co_u32_e32 v112, vcc, s31, v132
	global_load_dwordx4 v[100:103], v[98:99], off
	s_nop 0
	v_addc_co_u32_e32 v113, vcc, 0, v133, vcc
	v_add_co_u32_e32 v116, vcc, s56, v132
	global_load_dwordx4 v[104:107], v[132:133], off
	s_nop 0
	global_load_dwordx4 v[108:111], v[108:109], off
	v_addc_co_u32_e32 v117, vcc, 0, v133, vcc
	v_add_co_u32_e32 v120, vcc, s34, v132
	global_load_dwordx4 v[112:115], v[112:113], off
	s_nop 0
	global_load_dwordx4 v[116:119], v[116:117], off
	v_addc_co_u32_e32 v121, vcc, 0, v133, vcc
	v_add_co_u32_e32 v124, vcc, s57, v132
	global_load_dwordx4 v[120:123], v[120:121], off
	s_nop 0
	v_addc_co_u32_e32 v125, vcc, 0, v133, vcc
	global_load_dwordx4 v[124:127], v[124:125], off
	v_add_co_u32_e32 v128, vcc, s35, v132
	v_lshl_add_u64 v[218:219], s[16:17], 0, v[136:137]
	s_nop 0
	v_addc_co_u32_e32 v129, vcc, 0, v133, vcc
	v_add_co_u32_e32 v132, vcc, s58, v132
	global_load_dwordx4 v[128:131], v[128:129], off
	s_nop 0
	v_addc_co_u32_e32 v133, vcc, 0, v133, vcc
	global_load_dwordx4 v[132:135], v[132:133], off
	ds_read_b128 v[136:139], v238
	s_waitcnt vmcnt(13)
	ds_read_b128 v[140:143], v238 offset:1088
	s_waitcnt vmcnt(12)
	ds_read_b128 v[144:147], v238 offset:2176
	s_waitcnt vmcnt(11)
	ds_read_b128 v[148:151], v238 offset:3264
	s_waitcnt vmcnt(10)
	ds_read_b128 v[152:155], v238 offset:4352
	s_waitcnt vmcnt(9)
	ds_read_b128 v[156:159], v238 offset:5440
	ds_read_b128 v[214:217], v238 offset:6528
	v_mov_b32_e32 v199, v167
	v_mov_b32_e32 v201, v167
	v_lshl_add_u64 v[220:221], v[218:219], 0, v[198:199]
	v_mov_b32_e32 v203, v167
	v_mov_b32_e32 v205, v167
	v_mov_b32_e32 v207, v167
	v_lshl_add_u64 v[222:223], v[218:219], 0, v[200:201]
	v_mov_b32_e32 v209, v167
	v_lshl_add_u64 v[224:225], v[218:219], 0, v[202:203]
	v_lshl_add_u64 v[226:227], v[218:219], 0, v[204:205]
	v_lshl_add_u64 v[240:241], v[218:219], 0, v[206:207]
	v_mov_b32_e32 v211, v167
	v_mov_b32_e32 v213, v167
	s_cmp_lt_u32 s59, s1
	s_waitcnt vmcnt(7) lgkmcnt(6)
	v_fma_f32 v106, v102, v138, v106
	v_fma_f32 v107, v103, v139, v107
	v_fma_f32 v104, v100, v136, v104
	v_fma_f32 v105, v101, v137, v105
	global_store_dwordx4 v[220:221], v[104:107], off
	s_waitcnt vmcnt(7) lgkmcnt(5)
	s_nop 0
	v_fma_f32 v106, v102, v142, v110
	v_fma_f32 v107, v103, v143, v111
	v_fma_f32 v104, v100, v140, v108
	v_fma_f32 v105, v101, v141, v109
	s_waitcnt vmcnt(6) lgkmcnt(4)
	v_fma_f32 v110, v102, v146, v114
	v_fma_f32 v111, v103, v147, v115
	v_fma_f32 v108, v100, v144, v112
	v_fma_f32 v109, v101, v145, v113
	s_waitcnt vmcnt(5) lgkmcnt(3)
	v_fma_f32 v114, v102, v150, v118
	v_fma_f32 v115, v103, v151, v119
	v_fma_f32 v112, v100, v148, v116
	v_fma_f32 v113, v101, v149, v117
	s_waitcnt vmcnt(4) lgkmcnt(2)
	v_fma_f32 v118, v102, v154, v122
	v_fma_f32 v119, v103, v155, v123
	v_fma_f32 v116, v100, v152, v120
	v_fma_f32 v117, v101, v153, v121
	global_store_dwordx4 v[222:223], v[104:107], off
	global_store_dwordx4 v[224:225], v[108:111], off
	global_store_dwordx4 v[226:227], v[112:115], off
	global_store_dwordx4 v[240:241], v[116:119], off
	s_waitcnt vmcnt(7) lgkmcnt(1)
	v_fma_f32 v122, v102, v158, v126
	v_fma_f32 v123, v103, v159, v127
	v_fma_f32 v120, v100, v156, v124
	v_fma_f32 v121, v101, v157, v125
	v_lshl_add_u64 v[104:105], v[218:219], 0, v[208:209]
	global_store_dwordx4 v[104:105], v[120:123], off
	ds_read_b128 v[104:107], v238 offset:7616
	v_lshl_add_u64 v[112:113], v[218:219], 0, v[210:211]
	s_waitcnt vmcnt(7) lgkmcnt(1)
	v_fma_f32 v110, v102, v216, v130
	v_fma_f32 v111, v103, v217, v131
	v_fma_f32 v108, v100, v214, v128
	v_fma_f32 v109, v101, v215, v129
	global_store_dwordx4 v[112:113], v[108:111], off
	s_waitcnt vmcnt(7) lgkmcnt(0)
	v_fma_f32 v102, v102, v106, v134
	v_fma_f32 v103, v103, v107, v135
	v_fma_f32 v100, v100, v104, v132
	v_fma_f32 v101, v101, v105, v133
	v_lshl_add_u64 v[104:105], v[218:219], 0, v[212:213]
	global_store_dwordx4 v[104:105], v[100:103], off
	s_waitcnt lgkmcnt(0)
	ds_write_b128 v237, v[80:83]
	ds_write_b128 v237, v[64:67] offset:128
	ds_write_b128 v237, v[84:87] offset:32
	ds_write_b128 v237, v[68:71] offset:160
	ds_write_b128 v237, v[88:91] offset:64
	ds_write_b128 v237, v[72:75] offset:192
	ds_write_b128 v237, v[92:95] offset:96
	ds_write_b128 v237, v[76:79] offset:224
	v_lshl_add_u64 v[68:69], v[96:97], 0, v[172:173]
	v_lshlrev_b64 v[104:105], 2, v[68:69]
	v_lshl_add_u64 v[68:69], s[18:19], 0, v[104:105]
	v_lshl_add_u64 v[100:101], v[68:69], 0, v[166:167]
	v_add_co_u32_e32 v72, vcc, s30, v100
	s_waitcnt lgkmcnt(0)
;   __device__ __forceinline__ void operator()(int lrow, int nc, const f32x16& a0, const f32x16& a1, float) const {
;     const int lane = threadIdx.x & 63, wid = threadIdx.x >> 6, r32 = lane & 31, hi = lane >> 5;
;     float* sp = (float*)(scr + wid * (32 * 272));
; #pragma unroll
;     for (int g = 0; g < 4; ++g) {
;       const f32x4 v0 = {a0[4 * g], a0[4 * g + 1], a0[4 * g + 2], a0[4 * g + 3]}, v1 = {a1[4 * g], a1[4 * g + 1], a1[4 * g + 2], a1[4 * g + 3]};
;       *(f32x4*)(sp + r32 * 68 + 4 * hi + 8 * g) = v0; *(f32x4*)(sp + r32 * 68 + 32 + 4 * hi + 8 * g) = v1;
;     }
;     asm volatile("s_waitcnt lgkmcnt(0)" ::: "memory");
;     const int c4 = (lane & 15) * 4, colg = n0 + (nc & ~7) + c4;
;     const size_t rbase = (size_t)(lrow - r32) * 1024 + colg;
;     const f32x4 gv = *(const f32x4*)(gvec + colg);
;     f32x4 xv[8];
; #pragma unroll
;     for (int i = 0; i < 8; ++i) xv[i] = *(const f32x4*)(xin + rbase + (size_t)((lane >> 4) + 4 * i) * 1024);
;     asm volatile("" ::: "memory");
; #pragma unroll
;     for (int i = 0; i < 8; ++i) {
;       const int row = (lane >> 4) + 4 * i;
;       const f32x4 av = *(const f32x4*)(sp + row * 68 + c4);
;       f32x4 r; r[0] = xv[i][0] + gv[0] * av[0]; r[1] = xv[i][1] + gv[1] * av[1]; r[2] = xv[i][2] + gv[2] * av[2]; r[3] = xv[i][3] + gv[3] * av[3];
;       *(f32x4*)(xout + rbase + (size_t)row * 1024) = r;
;     }
	global_load_dwordx4 v[64:67], v[98:99], off
	s_nop 0
	v_addc_co_u32_e32 v73, vcc, 0, v101, vcc
	v_add_co_u32_e32 v76, vcc, s31, v100
	global_load_dwordx4 v[68:71], v[100:101], off
	s_nop 0
	global_load_dwordx4 v[72:75], v[72:73], off
	v_addc_co_u32_e32 v77, vcc, 0, v101, vcc
	v_add_co_u32_e32 v80, vcc, s56, v100
	global_load_dwordx4 v[76:79], v[76:77], off
	s_nop 0
	v_addc_co_u32_e32 v81, vcc, 0, v101, vcc
	global_load_dwordx4 v[80:83], v[80:81], off
	v_add_co_u32_e32 v84, vcc, s34, v100
	v_lshl_add_u64 v[120:121], s[16:17], 0, v[104:105]
	s_nop 0
	v_addc_co_u32_e32 v85, vcc, 0, v101, vcc
	v_add_co_u32_e32 v88, vcc, s57, v100
	global_load_dwordx4 v[84:87], v[84:85], off
	s_nop 0
	v_addc_co_u32_e32 v89, vcc, 0, v101, vcc
	global_load_dwordx4 v[88:91], v[88:89], off
	v_add_co_u32_e32 v92, vcc, s35, v100
	v_lshl_add_u64 v[122:123], v[120:121], 0, v[198:199]
	s_nop 0
	v_addc_co_u32_e32 v93, vcc, 0, v101, vcc
	v_add_co_u32_e32 v100, vcc, s58, v100
	global_load_dwordx4 v[92:95], v[92:93], off
	s_nop 0
	v_addc_co_u32_e32 v101, vcc, 0, v101, vcc
	global_load_dwordx4 v[100:103], v[100:101], off
	ds_read_b128 v[104:107], v238
	ds_read_b128 v[108:111], v238 offset:1088
	ds_read_b128 v[112:115], v238 offset:2176
	ds_read_b128 v[116:119], v238 offset:3264
	v_lshl_add_u64 v[124:125], v[120:121], 0, v[200:201]
	v_lshl_add_u64 v[126:127], v[120:121], 0, v[202:203]
	s_waitcnt vmcnt(7) lgkmcnt(3)
	v_fma_f32 v70, v66, v106, v70
	v_fma_f32 v71, v67, v107, v71
	v_fma_f32 v68, v64, v104, v68
	v_fma_f32 v69, v65, v105, v69
	s_waitcnt vmcnt(6) lgkmcnt(2)
	v_fma_f32 v74, v66, v110, v74
	v_fma_f32 v75, v67, v111, v75
	v_fma_f32 v72, v64, v108, v72
	v_fma_f32 v73, v65, v109, v73
	s_waitcnt vmcnt(5) lgkmcnt(1)
	v_fma_f32 v78, v66, v114, v78
	v_fma_f32 v79, v67, v115, v79
	v_fma_f32 v76, v64, v112, v76
	v_fma_f32 v77, v65, v113, v77
	global_store_dwordx4 v[122:123], v[68:71], off
	global_store_dwordx4 v[124:125], v[72:75], off
	global_store_dwordx4 v[126:127], v[76:79], off
	s_waitcnt vmcnt(7) lgkmcnt(0)
	v_fma_f32 v82, v66, v118, v82
	v_fma_f32 v83, v67, v119, v83
	ds_read_b128 v[68:71], v238 offset:4352
	v_fma_f32 v80, v64, v116, v80
	v_fma_f32 v81, v65, v117, v81
	v_lshl_add_u64 v[72:73], v[120:121], 0, v[204:205]
	global_store_dwordx4 v[72:73], v[80:83], off
	ds_read_b128 v[72:75], v238 offset:5440
	v_lshl_add_u64 v[76:77], v[120:121], 0, v[206:207]
	s_waitcnt vmcnt(7) lgkmcnt(1)
	v_fma_f32 v70, v66, v70, v86
	v_fma_f32 v71, v67, v71, v87
	v_fma_f32 v68, v64, v68, v84
	v_fma_f32 v69, v65, v69, v85
	global_store_dwordx4 v[76:77], v[68:71], off
	s_waitcnt vmcnt(7) lgkmcnt(0)
	s_nop 0
	v_fma_f32 v70, v66, v74, v90
	v_fma_f32 v71, v67, v75, v91
	v_fma_f32 v68, v64, v72, v88
	v_fma_f32 v69, v65, v73, v89
	v_lshl_add_u64 v[72:73], v[120:121], 0, v[208:209]
	ds_read_b128 v[74:77], v238 offset:6528
	global_store_dwordx4 v[72:73], v[68:71], off
	ds_read_b128 v[68:71], v238 offset:7616
	v_lshl_add_u64 v[72:73], v[120:121], 0, v[210:211]
	s_waitcnt vmcnt(7) lgkmcnt(1)
	v_fma_f32 v76, v66, v76, v94
	v_fma_f32 v77, v67, v77, v95
	v_fma_f32 v74, v64, v74, v92
	v_fma_f32 v75, v65, v75, v93
	s_waitcnt vmcnt(6) lgkmcnt(0)
	v_fma_f32 v66, v66, v70, v102
	v_fma_f32 v67, v67, v71, v103
	v_fma_f32 v64, v64, v68, v100
	v_fma_f32 v65, v65, v69, v101
	v_lshl_add_u64 v[68:69], v[120:121], 0, v[212:213]
	global_store_dwordx4 v[72:73], v[74:77], off
	global_store_dwordx4 v[68:69], v[64:67], off
	s_waitcnt lgkmcnt(0)
	ds_write_b128 v237, v[48:51]
	ds_write_b128 v237, v[32:35] offset:128
	ds_write_b128 v237, v[52:55] offset:32
	ds_write_b128 v237, v[36:39] offset:160
	ds_write_b128 v237, v[56:59] offset:64
	ds_write_b128 v237, v[40:43] offset:192
	ds_write_b128 v237, v[60:63] offset:96
	ds_write_b128 v237, v[44:47] offset:224
	v_lshl_add_u64 v[36:37], v[96:97], 0, v[174:175]
	v_lshlrev_b64 v[72:73], 2, v[36:37]
	v_lshl_add_u64 v[36:37], s[18:19], 0, v[72:73]
	v_lshl_add_u64 v[64:65], v[36:37], 0, v[166:167]
	s_waitcnt lgkmcnt(0)
	v_add_co_u32_e32 v40, vcc, s30, v64
	global_load_dwordx4 v[32:35], v[98:99], off
	global_load_dwordx4 v[36:39], v[64:65], off
	v_addc_co_u32_e32 v41, vcc, 0, v65, vcc
	global_load_dwordx4 v[40:43], v[40:41], off
	v_add_co_u32_e32 v44, vcc, s31, v64
	v_lshl_add_u64 v[80:81], s[16:17], 0, v[72:73]
	s_nop 0
	v_addc_co_u32_e32 v45, vcc, 0, v65, vcc
	v_add_co_u32_e32 v48, vcc, s56, v64
	global_load_dwordx4 v[44:47], v[44:45], off
	s_nop 0
	v_addc_co_u32_e32 v49, vcc, 0, v65, vcc
	global_load_dwordx4 v[48:51], v[48:49], off
	v_add_co_u32_e32 v52, vcc, s34, v64
	v_lshl_add_u64 v[82:83], v[80:81], 0, v[198:199]
	s_nop 0
	v_addc_co_u32_e32 v53, vcc, 0, v65, vcc
	v_add_co_u32_e32 v56, vcc, s57, v64
	global_load_dwordx4 v[52:55], v[52:53], off
	s_nop 0
	v_addc_co_u32_e32 v57, vcc, 0, v65, vcc
	global_load_dwordx4 v[56:59], v[56:57], off
	v_add_co_u32_e32 v60, vcc, s35, v64
	s_nop 1
	v_addc_co_u32_e32 v61, vcc, 0, v65, vcc
	v_add_co_u32_e32 v64, vcc, s58, v64
	global_load_dwordx4 v[60:63], v[60:61], off
	s_nop 0
	v_addc_co_u32_e32 v65, vcc, 0, v65, vcc
	global_load_dwordx4 v[64:67], v[64:65], off
	ds_read_b128 v[68:71], v238
	ds_read_b128 v[72:75], v238 offset:1088
	ds_read_b128 v[76:79], v238 offset:2176
	s_waitcnt vmcnt(7) lgkmcnt(2)
	v_fma_f32 v38, v34, v70, v38
	v_fma_f32 v39, v35, v71, v39
	v_fma_f32 v36, v32, v68, v36
	v_fma_f32 v37, v33, v69, v37
	global_store_dwordx4 v[82:83], v[36:39], off
	s_waitcnt vmcnt(7) lgkmcnt(1)
	v_fma_f32 v42, v34, v74, v42
	v_fma_f32 v43, v35, v75, v43
	v_fma_f32 v40, v32, v72, v40
	v_fma_f32 v41, v33, v73, v41
	v_lshl_add_u64 v[36:37], v[80:81], 0, v[200:201]
	global_store_dwordx4 v[36:37], v[40:43], off
	ds_read_b128 v[36:39], v238 offset:3264
	s_waitcnt vmcnt(6) lgkmcnt(0)
;   __device__ __forceinline__ void operator()(int lrow, int nc, const f32x16& a0, const f32x16& a1, float) const {
;     const int lane = threadIdx.x & 63, wid = threadIdx.x >> 6, r32 = lane & 31, hi = lane >> 5;
;     float* sp = (float*)(scr + wid * (32 * 272));
; #pragma unroll
;     for (int g = 0; g < 4; ++g) {
;       const f32x4 v0 = {a0[4 * g], a0[4 * g + 1], a0[4 * g + 2], a0[4 * g + 3]}, v1 = {a1[4 * g], a1[4 * g + 1], a1[4 * g + 2], a1[4 * g + 3]};
;       *(f32x4*)(sp + r32 * 68 + 4 * hi + 8 * g) = v0; *(f32x4*)(sp + r32 * 68 + 32 + 4 * hi + 8 * g) = v1;
;     }
;     asm volatile("s_waitcnt lgkmcnt(0)" ::: "memory");
;     const int c4 = (lane & 15) * 4, colg = n0 + (nc & ~7) + c4;
;     const size_t rbase = (size_t)(lrow - r32) * 1024 + colg;
;     const f32x4 gv = *(const f32x4*)(gvec + colg);
;     f32x4 xv[8];
; #pragma unroll
;     for (int i = 0; i < 8; ++i) xv[i] = *(const f32x4*)(xin + rbase + (size_t)((lane >> 4) + 4 * i) * 1024);
;     asm volatile("" ::: "memory");
; #pragma unroll
;     for (int i = 0; i < 8; ++i) {
;       const int row = (lane >> 4) + 4 * i;
;       const f32x4 av = *(const f32x4*)(sp + row * 68 + c4);
;       f32x4 r; r[0] = xv[i][0] + gv[0] * av[0]; r[1] = xv[i][1] + gv[1] * av[1]; r[2] = xv[i][2] + gv[2] * av[2]; r[3] = xv[i][3] + gv[3] * av[3];
;       *(f32x4*)(xout + rbase + (size_t)row * 1024) = r;
;     }
	v_fma_f32 v38, v34, v38, v50
	v_fma_f32 v39, v35, v39, v51
	v_fma_f32 v42, v34, v78, v46
	v_fma_f32 v43, v35, v79, v47
	v_fma_f32 v40, v32, v76, v44
	v_fma_f32 v41, v33, v77, v45
	v_lshl_add_u64 v[44:45], v[80:81], 0, v[202:203]
	global_store_dwordx4 v[44:45], v[40:43], off
	ds_read_b128 v[40:43], v238 offset:4352
	v_fma_f32 v36, v32, v36, v48
	v_fma_f32 v37, v33, v37, v49
	v_lshl_add_u64 v[44:45], v[80:81], 0, v[204:205]
	global_store_dwordx4 v[44:45], v[36:39], off
	ds_read_b128 v[36:39], v238 offset:5440
	s_waitcnt vmcnt(7) lgkmcnt(1)
	v_fma_f32 v42, v34, v42, v54
	v_fma_f32 v43, v35, v43, v55
	v_fma_f32 v40, v32, v40, v52
	v_fma_f32 v41, v33, v41, v53
	v_lshl_add_u64 v[44:45], v[80:81], 0, v[206:207]
	global_store_dwordx4 v[44:45], v[40:43], off
	s_waitcnt vmcnt(7) lgkmcnt(0)
	v_fma_f32 v38, v34, v38, v58
	v_fma_f32 v39, v35, v39, v59
	v_fma_f32 v36, v32, v36, v56
	v_fma_f32 v37, v33, v37, v57
	v_lshl_add_u64 v[44:45], v[80:81], 0, v[208:209]
	ds_read_b128 v[40:43], v238 offset:6528
	global_store_dwordx4 v[44:45], v[36:39], off
	ds_read_b128 v[36:39], v238 offset:7616
	v_lshl_add_u64 v[44:45], v[80:81], 0, v[210:211]
	s_waitcnt vmcnt(7) lgkmcnt(1)
	v_fma_f32 v42, v34, v42, v62
	v_fma_f32 v43, v35, v43, v63
	v_fma_f32 v40, v32, v40, v60
	v_fma_f32 v41, v33, v41, v61
	s_waitcnt vmcnt(6) lgkmcnt(0)
	v_fma_f32 v34, v34, v38, v66
	v_fma_f32 v35, v35, v39, v67
	v_fma_f32 v32, v32, v36, v64
	v_fma_f32 v33, v33, v37, v65
	v_lshl_add_u64 v[36:37], v[80:81], 0, v[212:213]
	global_store_dwordx4 v[44:45], v[40:43], off
	global_store_dwordx4 v[36:37], v[32:35], off
	s_waitcnt lgkmcnt(0)
	ds_write_b128 v237, v[16:19]
	ds_write_b128 v237, v[0:3] offset:128
	ds_write_b128 v237, v[20:23] offset:32
	ds_write_b128 v237, v[4:7] offset:160
	ds_write_b128 v237, v[24:27] offset:64
	ds_write_b128 v237, v[8:11] offset:192
	ds_write_b128 v237, v[28:31] offset:96
	ds_write_b128 v237, v[12:15] offset:224
	v_lshl_add_u64 v[4:5], v[96:97], 0, v[188:189]
	v_lshlrev_b64 v[44:45], 2, v[4:5]
	v_lshl_add_u64 v[4:5], s[18:19], 0, v[44:45]
	v_lshl_add_u64 v[32:33], v[4:5], 0, v[166:167]
	s_waitcnt lgkmcnt(0)
	v_add_co_u32_e32 v8, vcc, s30, v32
	global_load_dwordx4 v[0:3], v[98:99], off
	global_load_dwordx4 v[4:7], v[32:33], off
	v_addc_co_u32_e32 v9, vcc, 0, v33, vcc
	global_load_dwordx4 v[8:11], v[8:9], off
	v_add_co_u32_e32 v12, vcc, s31, v32
	v_lshl_add_u64 v[44:45], s[16:17], 0, v[44:45]
	s_nop 0
	v_addc_co_u32_e32 v13, vcc, 0, v33, vcc
	v_add_co_u32_e32 v16, vcc, s56, v32
	global_load_dwordx4 v[12:15], v[12:13], off
	s_nop 0
	v_addc_co_u32_e32 v17, vcc, 0, v33, vcc
	global_load_dwordx4 v[16:19], v[16:17], off
	v_add_co_u32_e32 v20, vcc, s34, v32
	s_cselect_b64 s[16:17], -1, 0
	s_nop 0
	v_addc_co_u32_e32 v21, vcc, 0, v33, vcc
	v_add_co_u32_e32 v24, vcc, s57, v32
	global_load_dwordx4 v[20:23], v[20:21], off
	s_nop 0
	v_addc_co_u32_e32 v25, vcc, 0, v33, vcc
	global_load_dwordx4 v[24:27], v[24:25], off
	v_add_co_u32_e32 v28, vcc, s35, v32
	s_nop 1
	v_addc_co_u32_e32 v29, vcc, 0, v33, vcc
	v_add_co_u32_e32 v32, vcc, s58, v32
	global_load_dwordx4 v[28:31], v[28:29], off
	s_nop 0
	v_addc_co_u32_e32 v33, vcc, 0, v33, vcc
	global_load_dwordx4 v[32:35], v[32:33], off
	ds_read_b128 v[36:39], v238
	ds_read_b128 v[40:43], v238 offset:1088
	s_and_b64 vcc, s[16:17], exec
	s_cselect_b32 s10, s33, 0
	s_add_i32 s10, s10, s59
	s_mov_b32 s16, s59
	s_waitcnt vmcnt(7) lgkmcnt(1)
	v_fma_f32 v6, v2, v38, v6
	v_fma_f32 v7, v3, v39, v7
	v_fma_f32 v4, v0, v36, v4
	v_fma_f32 v5, v1, v37, v5
	v_lshl_add_u64 v[36:37], v[44:45], 0, v[198:199]
	global_store_dwordx4 v[36:37], v[4:7], off
	ds_read_b128 v[36:39], v238 offset:2176
	s_waitcnt vmcnt(7) lgkmcnt(1)
	v_fma_f32 v6, v2, v42, v10
	v_fma_f32 v7, v3, v43, v11
	v_fma_f32 v4, v0, v40, v8
	v_fma_f32 v5, v1, v41, v9
	v_lshl_add_u64 v[8:9], v[44:45], 0, v[200:201]
	global_store_dwordx4 v[8:9], v[4:7], off
	ds_read_b128 v[4:7], v238 offset:3264
	s_waitcnt vmcnt(7) lgkmcnt(1)
	v_fma_f32 v10, v2, v38, v14
	v_fma_f32 v11, v3, v39, v15
	v_fma_f32 v8, v0, v36, v12
	v_fma_f32 v9, v1, v37, v13
	v_lshl_add_u64 v[12:13], v[44:45], 0, v[202:203]
	global_store_dwordx4 v[12:13], v[8:11], off
	s_waitcnt vmcnt(7) lgkmcnt(0)
	v_fma_f32 v6, v2, v6, v18
	v_fma_f32 v7, v3, v7, v19
	ds_read_b128 v[8:11], v238 offset:4352
	v_fma_f32 v4, v0, v4, v16
	v_fma_f32 v5, v1, v5, v17
	v_lshl_add_u64 v[12:13], v[44:45], 0, v[204:205]
	global_store_dwordx4 v[12:13], v[4:7], off
	ds_read_b128 v[4:7], v238 offset:5440
	v_lshl_add_u64 v[12:13], v[44:45], 0, v[206:207]
	s_waitcnt vmcnt(7) lgkmcnt(1)
	v_fma_f32 v10, v2, v10, v22
	v_fma_f32 v11, v3, v11, v23
	v_fma_f32 v8, v0, v8, v20
	v_fma_f32 v9, v1, v9, v21
	global_store_dwordx4 v[12:13], v[8:11], off
	s_waitcnt vmcnt(7) lgkmcnt(0)
	v_fma_f32 v6, v2, v6, v26
	v_fma_f32 v7, v3, v7, v27
	v_fma_f32 v4, v0, v4, v24
	v_fma_f32 v5, v1, v5, v25
	v_lshl_add_u64 v[12:13], v[44:45], 0, v[208:209]
	ds_read_b128 v[8:11], v238 offset:6528
	global_store_dwordx4 v[12:13], v[4:7], off
	ds_read_b128 v[4:7], v238 offset:7616
	v_lshl_add_u64 v[12:13], v[44:45], 0, v[210:211]
	s_waitcnt vmcnt(7) lgkmcnt(1)
	v_fma_f32 v10, v2, v10, v30
	v_fma_f32 v11, v3, v11, v31
	v_fma_f32 v8, v0, v8, v28
	v_fma_f32 v9, v1, v9, v29
	global_store_dwordx4 v[12:13], v[8:11], off
	s_waitcnt vmcnt(7) lgkmcnt(0)
	v_fma_f32 v2, v2, v6, v34
	v_fma_f32 v3, v3, v7, v35
	v_fma_f32 v0, v0, v4, v32
	v_fma_f32 v1, v1, v5, v33
	v_lshl_add_u64 v[4:5], v[44:45], 0, v[212:213]
	global_store_dwordx4 v[4:5], v[0:3], off
	s_waitcnt lgkmcnt(0)
	s_cbranch_vccz .LBB0_638

;   __device__ __forceinline__ void operator()(int lrow, int nc, const f32x16& a0, const f32x16& a1, float) const {
;     const int lane = threadIdx.x & 63, wid = threadIdx.x >> 6, r32 = lane & 31, hi = lane >> 5;
;     float* sp = (float*)(scr + wid * (32 * 272));
; #pragma unroll
;     for (int g = 0; g < 4; ++g) {
;       const f32x4 v0 = {a0[4 * g], a0[4 * g + 1], a0[4 * g + 2], a0[4 * g + 3]}, v1 = {a1[4 * g], a1[4 * g + 1], a1[4 * g + 2], a1[4 * g + 3]};
;       *(f32x4*)(sp + r32 * 68 + 4 * hi + 8 * g) = v0; *(f32x4*)(sp + r32 * 68 + 32 + 4 * hi + 8 * g) = v1;
;     }
;     asm volatile("s_waitcnt lgkmcnt(0)" ::: "memory");
;     const int c4 = (lane & 15) * 4, colg = n0 + (nc & ~7) + c4;
;     const size_t rbase = (size_t)(lrow - r32) * 1024 + colg;
;     const f32x4 gv = *(const f32x4*)(gvec + colg);
;     f32x4 xv[8];
; #pragma unroll
;     for (int i = 0; i < 8; ++i) xv[i] = *(const f32x4*)(xin + rbase + (size_t)((lane >> 4) + 4 * i) * 1024);
;     asm volatile("" ::: "memory");
; #pragma unroll
;     for (int i = 0; i < 8; ++i) {
;       const int row = (lane >> 4) + 4 * i;
;       const f32x4 av = *(const f32x4*)(sp + row * 68 + c4);
;       f32x4 r; r[0] = xv[i][0] + gv[0] * av[0]; r[1] = xv[i][1] + gv[1] * av[1]; r[2] = xv[i][2] + gv[2] * av[2]; r[3] = xv[i][3] + gv[3] * av[3];
;       *(f32x4*)(xout + rbase + (size_t)row * 1024) = r;
;     }
.LBB0_657:
	s_add_i32 s14, 0, 0x12000
	s_waitcnt vmcnt(5)
	v_and_b32_e32 v91, 4, v161
	s_movk_i32 s15, 0x2200
	v_mov_b32_e32 v92, s14
	s_waitcnt vmcnt(2)
	v_mad_u32_u24 v102, v182, s15, v92
	v_mul_u32_u24_e32 v92, 0x110, v180
	v_lshlrev_b32_e32 v91, 2, v91
	v_and_b32_e32 v90, 64, v178
	v_add3_u32 v134, v102, v92, v91
	ds_write_b128 v134, v[50:53]
	ds_write_b128 v134, v[34:37] offset:128
	ds_write_b128 v134, v[54:57] offset:32
	ds_write_b128 v134, v[38:41] offset:160
	ds_write_b128 v134, v[58:61] offset:64
	ds_write_b128 v134, v[42:45] offset:192
	ds_write_b128 v134, v[62:65] offset:96
	ds_write_b128 v134, v[46:49] offset:224
	v_or3_b32 v34, v231, v90, s0
	v_lshlrev_b32_e32 v135, 2, v34
	v_lshl_or_b32 v34, v1, 18, v135
	v_mov_b32_e32 v35, 0
	v_lshlrev_b32_e32 v1, 8, v178
	v_lshl_add_u64 v[36:37], s[10:11], 0, v[34:35]
	v_and_b32_e32 v38, 0x3000, v1
	v_mov_b32_e32 v39, v35
	v_lshl_add_u64 v[36:37], v[36:37], 0, v[38:39]
	s_movk_i32 s14, 0x4000
	s_waitcnt lgkmcnt(0)
	v_add_co_u32_e32 v40, vcc, s14, v36
	global_load_dwordx4 v[42:45], v135, s[12:13]
	global_load_dwordx4 v[46:49], v[36:37], off
	v_addc_co_u32_e32 v41, vcc, 0, v37, vcc
	global_load_dwordx4 v[50:53], v[40:41], off
	s_mov_b32 s15, 0x8000
	v_add_co_u32_e32 v40, vcc, s15, v36
	s_mov_b32 s16, 0xc000
	s_nop 0
	v_addc_co_u32_e32 v41, vcc, 0, v37, vcc
	global_load_dwordx4 v[54:57], v[40:41], off
	v_add_co_u32_e32 v40, vcc, s16, v36
	s_mov_b32 s17, 0x10000
	s_nop 0
	v_addc_co_u32_e32 v41, vcc, 0, v37, vcc
	global_load_dwordx4 v[58:61], v[40:41], off
	v_add_co_u32_e32 v40, vcc, s17, v36
	s_mov_b32 s18, 0x14000
	s_nop 0
	v_addc_co_u32_e32 v41, vcc, 0, v37, vcc
	global_load_dwordx4 v[62:65], v[40:41], off
	v_add_co_u32_e32 v40, vcc, s18, v36
	s_mov_b32 s19, 0x18000
	s_nop 0
	v_addc_co_u32_e32 v41, vcc, 0, v37, vcc
	global_load_dwordx4 v[90:93], v[40:41], off
	v_add_co_u32_e32 v40, vcc, s19, v36
	s_mov_b32 s20, 0x1c000
	s_nop 0
	v_addc_co_u32_e32 v41, vcc, 0, v37, vcc
	global_load_dwordx4 v[94:97], v[40:41], off
	v_add_co_u32_e32 v36, vcc, s20, v36
	v_lshlrev_b32_e32 v1, 2, v231
	s_nop 0
	v_addc_co_u32_e32 v37, vcc, 0, v37, vcc
	global_load_dwordx4 v[98:101], v[36:37], off
	v_mul_u32_u24_e32 v41, 0x110, v165
	v_add3_u32 v1, v102, v1, v41
	ds_read_b128 v[102:105], v1
	s_waitcnt vmcnt(10)
	ds_read_b128 v[106:109], v1 offset:1088
	s_waitcnt vmcnt(9)
	ds_read_b128 v[110:113], v1 offset:2176
	v_lshlrev_b32_e32 v36, 12, v165
	v_mov_b32_e32 v37, v35
	v_lshl_add_u64 v[130:131], s[8:9], 0, v[34:35]
	v_or_b32_e32 v40, 0x4000, v36
	v_lshl_add_u64 v[132:133], v[130:131], 0, v[36:37]
	v_mov_b32_e32 v41, v35
	v_or_b32_e32 v34, 0x20000, v34
	s_waitcnt vmcnt(7) lgkmcnt(2)
	v_fma_f32 v48, v44, v104, v48
	v_fma_f32 v49, v45, v105, v49
	v_fma_f32 v46, v42, v102, v46
	v_fma_f32 v47, v43, v103, v47
	global_store_dwordx4 v[132:133], v[46:49], off
	s_waitcnt vmcnt(7) lgkmcnt(1)
	s_nop 0
	v_fma_f32 v48, v44, v108, v52
	v_fma_f32 v49, v45, v109, v53
	v_fma_f32 v46, v42, v106, v50
	v_fma_f32 v47, v43, v107, v51
	v_lshl_add_u64 v[50:51], v[130:131], 0, v[40:41]
	global_store_dwordx4 v[50:51], v[46:49], off
	ds_read_b128 v[46:49], v1 offset:3264
	s_waitcnt vmcnt(7) lgkmcnt(1)
	v_fma_f32 v50, v42, v110, v54
	v_fma_f32 v51, v43, v111, v55
	v_or_b32_e32 v54, 0x8000, v36
	v_mov_b32_e32 v55, v35
	v_fma_f32 v52, v44, v112, v56
	v_fma_f32 v53, v45, v113, v57
	v_lshl_add_u64 v[56:57], v[130:131], 0, v[54:55]
	global_store_dwordx4 v[56:57], v[50:53], off
	v_or_b32_e32 v56, 0xc000, v36
	ds_read_b128 v[50:53], v1 offset:4352
	v_mov_b32_e32 v57, v35
	s_waitcnt vmcnt(7) lgkmcnt(1)
	v_fma_f32 v48, v44, v48, v60
	v_fma_f32 v49, v45, v49, v61
	v_fma_f32 v46, v42, v46, v58
	v_fma_f32 v47, v43, v47, v59
	v_lshl_add_u64 v[58:59], v[130:131], 0, v[56:57]
	global_store_dwordx4 v[58:59], v[46:49], off
	ds_read_b128 v[46:49], v1 offset:5440
	v_or_b32_e32 v58, 0x10000, v36
	v_mov_b32_e32 v59, v35
	s_waitcnt vmcnt(7) lgkmcnt(1)
	v_fma_f32 v52, v44, v52, v64
	v_fma_f32 v53, v45, v53, v65
	v_fma_f32 v50, v42, v50, v62
	v_fma_f32 v51, v43, v51, v63
	v_lshl_add_u64 v[60:61], v[130:131], 0, v[58:59]
	global_store_dwordx4 v[60:61], v[50:53], off
	v_or_b32_e32 v60, 0x14000, v36
	ds_read_b128 v[50:53], v1 offset:6528
	v_mov_b32_e32 v61, v35
	s_waitcnt vmcnt(7) lgkmcnt(1)
;   __device__ __forceinline__ void operator()(int lrow, int nc, const f32x16& a0, const f32x16& a1, float) const {
;     const int lane = threadIdx.x & 63, wid = threadIdx.x >> 6, r32 = lane & 31, hi = lane >> 5;
;     float* sp = (float*)(scr + wid * (32 * 272));
; #pragma unroll
;     for (int g = 0; g < 4; ++g) {
;       const f32x4 v0 = {a0[4 * g], a0[4 * g + 1], a0[4 * g + 2], a0[4 * g + 3]}, v1 = {a1[4 * g], a1[4 * g + 1], a1[4 * g + 2], a1[4 * g + 3]};
;       *(f32x4*)(sp + r32 * 68 + 4 * hi + 8 * g) = v0; *(f32x4*)(sp + r32 * 68 + 32 + 4 * hi + 8 * g) = v1;
;     }
;     asm volatile("s_waitcnt lgkmcnt(0)" ::: "memory");
;     const int c4 = (lane & 15) * 4, colg = n0 + (nc & ~7) + c4;
;     const size_t rbase = (size_t)(lrow - r32) * 1024 + colg;
;     const f32x4 gv = *(const f32x4*)(gvec + colg);
;     f32x4 xv[8];
; #pragma unroll
;     for (int i = 0; i < 8; ++i) xv[i] = *(const f32x4*)(xin + rbase + (size_t)((lane >> 4) + 4 * i) * 1024);
;     asm volatile("" ::: "memory");
; #pragma unroll
;     for (int i = 0; i < 8; ++i) {
;       const int row = (lane >> 4) + 4 * i;
;       const f32x4 av = *(const f32x4*)(sp + row * 68 + c4);
;       f32x4 r; r[0] = xv[i][0] + gv[0] * av[0]; r[1] = xv[i][1] + gv[1] * av[1]; r[2] = xv[i][2] + gv[2] * av[2]; r[3] = xv[i][3] + gv[3] * av[3];
;       *(f32x4*)(xout + rbase + (size_t)row * 1024) = r;
;     }
	v_fma_f32 v48, v44, v48, v92
	v_fma_f32 v49, v45, v49, v93
	v_fma_f32 v46, v42, v46, v90
	v_fma_f32 v47, v43, v47, v91
	v_lshl_add_u64 v[62:63], v[130:131], 0, v[60:61]
	global_store_dwordx4 v[62:63], v[46:49], off
	ds_read_b128 v[46:49], v1 offset:7616
	v_or_b32_e32 v62, 0x18000, v36
	v_mov_b32_e32 v63, v35
	s_waitcnt vmcnt(7) lgkmcnt(1)
	v_fma_f32 v52, v44, v52, v96
	v_fma_f32 v53, v45, v53, v97
	v_fma_f32 v50, v42, v50, v94
	v_fma_f32 v51, v43, v51, v95
	v_lshl_add_u64 v[64:65], v[130:131], 0, v[62:63]
	global_store_dwordx4 v[64:65], v[50:53], off
	v_or_b32_e32 v64, 0x1c000, v36
	v_mov_b32_e32 v65, v35
	s_waitcnt vmcnt(7) lgkmcnt(0)
	v_fma_f32 v44, v44, v48, v100
	v_fma_f32 v45, v45, v49, v101
	v_fma_f32 v42, v42, v46, v98
	v_fma_f32 v43, v43, v47, v99
	v_lshl_add_u64 v[46:47], v[130:131], 0, v[64:65]
	global_store_dwordx4 v[46:47], v[42:45], off
	s_waitcnt lgkmcnt(0)
	ds_write_b128 v134, v[18:21]
	ds_write_b128 v134, v[2:5] offset:128
	ds_write_b128 v134, v[22:25] offset:32
	ds_write_b128 v134, v[6:9] offset:160
	ds_write_b128 v134, v[26:29] offset:64
	ds_write_b128 v134, v[10:13] offset:192
	ds_write_b128 v134, v[30:33] offset:96
	ds_write_b128 v134, v[14:17] offset:224
	v_lshl_add_u64 v[6:7], s[10:11], 0, v[34:35]
	v_lshl_add_u64 v[38:39], v[6:7], 0, v[38:39]
	s_waitcnt lgkmcnt(0)
	v_add_co_u32_e32 v10, vcc, s14, v38
	global_load_dwordx4 v[2:5], v135, s[12:13]
	global_load_dwordx4 v[6:9], v[38:39], off
	v_addc_co_u32_e32 v11, vcc, 0, v39, vcc
	global_load_dwordx4 v[10:13], v[10:11], off
	v_add_co_u32_e32 v14, vcc, s15, v38
	s_mov_b64 s[14:15], 0
	s_nop 0
	v_addc_co_u32_e32 v15, vcc, 0, v39, vcc
	v_add_co_u32_e32 v18, vcc, s16, v38
	global_load_dwordx4 v[14:17], v[14:15], off
	s_nop 0
	v_addc_co_u32_e32 v19, vcc, 0, v39, vcc
	global_load_dwordx4 v[18:21], v[18:19], off
	v_add_co_u32_e32 v22, vcc, s17, v38
	s_nop 1
	v_addc_co_u32_e32 v23, vcc, 0, v39, vcc
	v_add_co_u32_e32 v26, vcc, s18, v38
	global_load_dwordx4 v[22:25], v[22:23], off
	s_nop 0
	v_addc_co_u32_e32 v27, vcc, 0, v39, vcc
	global_load_dwordx4 v[26:29], v[26:27], off
	v_add_co_u32_e32 v30, vcc, s19, v38
	s_nop 1
	v_addc_co_u32_e32 v31, vcc, 0, v39, vcc
	v_add_co_u32_e32 v38, vcc, s20, v38
	global_load_dwordx4 v[30:33], v[30:31], off
	s_nop 0
	v_addc_co_u32_e32 v39, vcc, 0, v39, vcc
	global_load_dwordx4 v[42:45], v[38:39], off
	ds_read_b128 v[46:49], v1
	ds_read_b128 v[50:53], v1 offset:1088
	v_lshl_add_u64 v[38:39], s[8:9], 0, v[34:35]
	v_lshl_add_u64 v[34:35], v[38:39], 0, v[36:37]
	s_waitcnt vmcnt(7) lgkmcnt(1)
	v_fma_f32 v8, v4, v48, v8
	v_fma_f32 v9, v5, v49, v9
	v_fma_f32 v6, v2, v46, v6
	v_fma_f32 v7, v3, v47, v7
	global_store_dwordx4 v[34:35], v[6:9], off
	ds_read_b128 v[34:37], v1 offset:2176
	s_waitcnt vmcnt(7) lgkmcnt(1)
	v_fma_f32 v8, v4, v52, v12
	v_fma_f32 v9, v5, v53, v13
	v_fma_f32 v6, v2, v50, v10
	v_fma_f32 v7, v3, v51, v11
	v_lshl_add_u64 v[10:11], v[38:39], 0, v[40:41]
	global_store_dwordx4 v[10:11], v[6:9], off
	ds_read_b128 v[6:9], v1 offset:3264
	s_waitcnt vmcnt(7) lgkmcnt(1)
	v_fma_f32 v12, v4, v36, v16
	v_fma_f32 v13, v5, v37, v17
	v_fma_f32 v10, v2, v34, v14
	v_fma_f32 v11, v3, v35, v15
	v_lshl_add_u64 v[14:15], v[38:39], 0, v[54:55]
	global_store_dwordx4 v[14:15], v[10:13], off
	s_waitcnt vmcnt(7) lgkmcnt(0)
	v_fma_f32 v8, v4, v8, v20
	v_fma_f32 v9, v5, v9, v21
	ds_read_b128 v[10:13], v1 offset:4352
	v_fma_f32 v6, v2, v6, v18
	v_fma_f32 v7, v3, v7, v19
	v_lshl_add_u64 v[14:15], v[38:39], 0, v[56:57]
	global_store_dwordx4 v[14:15], v[6:9], off
	ds_read_b128 v[6:9], v1 offset:5440
	v_lshl_add_u64 v[14:15], v[38:39], 0, v[58:59]
	s_waitcnt vmcnt(7) lgkmcnt(1)
	v_fma_f32 v12, v4, v12, v24
	v_fma_f32 v13, v5, v13, v25
	v_fma_f32 v10, v2, v10, v22
	v_fma_f32 v11, v3, v11, v23
	global_store_dwordx4 v[14:15], v[10:13], off
	s_waitcnt vmcnt(7) lgkmcnt(0)
	v_fma_f32 v8, v4, v8, v28
	v_fma_f32 v9, v5, v9, v29
	v_fma_f32 v6, v2, v6, v26
	v_fma_f32 v7, v3, v7, v27
	v_lshl_add_u64 v[14:15], v[38:39], 0, v[60:61]
	ds_read_b128 v[10:13], v1 offset:6528
	global_store_dwordx4 v[14:15], v[6:9], off
	ds_read_b128 v[6:9], v1 offset:7616
	v_lshl_add_u64 v[14:15], v[38:39], 0, v[62:63]
	s_waitcnt vmcnt(7) lgkmcnt(1)
	v_fma_f32 v12, v4, v12, v32
	v_fma_f32 v13, v5, v13, v33
	v_fma_f32 v10, v2, v10, v30
	v_fma_f32 v11, v3, v11, v31
	global_store_dwordx4 v[14:15], v[10:13], off
	s_waitcnt vmcnt(7) lgkmcnt(0)
	v_fma_f32 v4, v4, v8, v44
	v_fma_f32 v5, v5, v9, v45
	v_fma_f32 v2, v2, v6, v42
	v_fma_f32 v3, v3, v7, v43
	v_lshl_add_u64 v[6:7], v[38:39], 0, v[64:65]
	global_store_dwordx4 v[6:7], v[2:5], off
	s_waitcnt lgkmcnt(0)

;   __device__ __forceinline__ void operator()(int lrow, int nc, const f32x16& a0, const f32x16& a1, float) const {
;     const int lane = threadIdx.x & 63, wid = threadIdx.x >> 6, r32 = lane & 31, hi = lane >> 5;
;     float* sp = (float*)(scr + wid * (32 * 272));
; #pragma unroll
;     for (int g = 0; g < 4; ++g) {
;       const f32x4 v0 = {a0[4 * g], a0[4 * g + 1], a0[4 * g + 2], a0[4 * g + 3]}, v1 = {a1[4 * g], a1[4 * g + 1], a1[4 * g + 2], a1[4 * g + 3]};
;       *(f32x4*)(sp + r32 * 68 + 4 * hi + 8 * g) = v0; *(f32x4*)(sp + r32 * 68 + 32 + 4 * hi + 8 * g) = v1;
;     }
;     asm volatile("s_waitcnt lgkmcnt(0)" ::: "memory");
;     const int c4 = (lane & 15) * 4, colg = n0 + (nc & ~7) + c4;
;     const size_t rbase = (size_t)(lrow - r32) * 1024 + colg;
;     const f32x4 gv = *(const f32x4*)(gvec + colg);
;     f32x4 xv[8];
; #pragma unroll
;     for (int i = 0; i < 8; ++i) xv[i] = *(const f32x4*)(xin + rbase + (size_t)((lane >> 4) + 4 * i) * 1024);
;     asm volatile("" ::: "memory");
; #pragma unroll
;     for (int i = 0; i < 8; ++i) {
;       const int row = (lane >> 4) + 4 * i;
;       const f32x4 av = *(const f32x4*)(sp + row * 68 + c4);
;       f32x4 r; r[0] = xv[i][0] + gv[0] * av[0]; r[1] = xv[i][1] + gv[1] * av[1]; r[2] = xv[i][2] + gv[2] * av[2]; r[3] = xv[i][3] + gv[3] * av[3];
;       *(f32x4*)(xout + rbase + (size_t)row * 1024) = r;
;     }
.LBB0_665:
	s_movk_i32 s1, 0xc0
	s_waitcnt vmcnt(7)
	v_and_or_b32 v129, v178, s1, v231
	s_add_i32 s1, 0, 0x12000
	v_and_b32_e32 v128, 4, v161
	s_movk_i32 s2, 0x2200
	v_mov_b32_e32 v130, s1
	s_waitcnt vmcnt(3)
	v_mad_u32_u24 v146, v182, s2, v130
	v_mul_u32_u24_e32 v130, 0x110, v180
	v_lshlrev_b32_e32 v128, 2, v128
	v_add3_u32 v128, v146, v130, v128
	ds_write_b128 v128, v[112:115]
	ds_write_b128 v128, v[96:99] offset:128
	ds_write_b128 v128, v[116:119] offset:32
	ds_write_b128 v128, v[100:103] offset:160
	ds_write_b128 v128, v[120:123] offset:64
	ds_write_b128 v128, v[104:107] offset:192
	ds_write_b128 v128, v[124:127] offset:96
	ds_write_b128 v128, v[108:111] offset:224
	v_add_lshl_u32 v117, s0, v129, 2
	v_lshl_or_b32 v96, v232, 19, v117
	v_mov_b32_e32 v97, 0
	v_lshlrev_b32_e32 v100, 8, v178
	v_lshl_add_u64 v[98:99], s[10:11], 0, v[96:97]
	v_and_b32_e32 v100, 0x3000, v100
	v_mov_b32_e32 v101, v97
	v_lshl_add_u64 v[98:99], v[98:99], 0, v[100:101]
	s_movk_i32 s0, 0x4000
	s_waitcnt lgkmcnt(0)
	v_add_co_u32_e32 v102, vcc, s0, v98
	global_load_dwordx4 v[118:121], v117, s[12:13]
	global_load_dwordx4 v[104:107], v[98:99], off
	v_addc_co_u32_e32 v103, vcc, 0, v99, vcc
	global_load_dwordx4 v[108:111], v[102:103], off
	s_mov_b32 s1, 0x8000
	v_add_co_u32_e32 v102, vcc, s1, v98
	s_mov_b32 s2, 0xc000
	s_nop 0
	v_addc_co_u32_e32 v103, vcc, 0, v99, vcc
	global_load_dwordx4 v[112:115], v[102:103], off
	v_add_co_u32_e32 v102, vcc, s2, v98
	s_mov_b32 s14, 0x10000
	s_nop 0
	v_addc_co_u32_e32 v103, vcc, 0, v99, vcc
	global_load_dwordx4 v[122:125], v[102:103], off
	v_add_co_u32_e32 v102, vcc, s14, v98
	s_mov_b32 s15, 0x14000
	s_nop 0
	v_addc_co_u32_e32 v103, vcc, 0, v99, vcc
	global_load_dwordx4 v[130:133], v[102:103], off
	v_add_co_u32_e32 v102, vcc, s15, v98
	s_mov_b32 s16, 0x18000
	s_nop 0
	v_addc_co_u32_e32 v103, vcc, 0, v99, vcc
	global_load_dwordx4 v[134:137], v[102:103], off
	v_add_co_u32_e32 v102, vcc, s16, v98
	s_mov_b32 s17, 0x1c000
	s_nop 0
	v_addc_co_u32_e32 v103, vcc, 0, v99, vcc
	global_load_dwordx4 v[138:141], v[102:103], off
	v_add_co_u32_e32 v98, vcc, s17, v98
	v_mul_u32_u24_e32 v116, 0x110, v165
	s_nop 0
	v_addc_co_u32_e32 v99, vcc, 0, v99, vcc
	global_load_dwordx4 v[142:145], v[98:99], off
	v_lshlrev_b32_e32 v103, 2, v231
	v_add3_u32 v116, v146, v103, v116
	s_waitcnt vmcnt(10)
	ds_read_b128 v[146:149], v116
	ds_read_b128 v[150:153], v116 offset:1088
	s_waitcnt vmcnt(9)
	ds_read_b128 v[154:157], v116 offset:2176
	v_lshlrev_b32_e32 v98, 12, v165
	v_mov_b32_e32 v99, v97
	v_lshl_add_u64 v[126:127], s[8:9], 0, v[96:97]
	v_or_b32_e32 v102, 0x4000, v98
	v_lshl_add_u64 v[158:159], v[126:127], 0, v[98:99]
	v_mov_b32_e32 v103, v97
	s_waitcnt vmcnt(7) lgkmcnt(2)
	v_fma_f32 v106, v120, v148, v106
	v_fma_f32 v107, v121, v149, v107
	v_fma_f32 v104, v118, v146, v104
	v_fma_f32 v105, v119, v147, v105
	global_store_dwordx4 v[158:159], v[104:107], off
	s_waitcnt vmcnt(6) lgkmcnt(0)
	v_fma_f32 v114, v120, v156, v114
	v_fma_f32 v115, v121, v157, v115
	v_fma_f32 v106, v120, v152, v110
	v_fma_f32 v107, v121, v153, v111
	v_fma_f32 v104, v118, v150, v108
	v_fma_f32 v105, v119, v151, v109
	v_lshl_add_u64 v[108:109], v[126:127], 0, v[102:103]
	global_store_dwordx4 v[108:109], v[104:107], off
	ds_read_b128 v[108:111], v116 offset:3264
	v_fma_f32 v112, v118, v154, v112
	v_fma_f32 v113, v119, v155, v113
	v_or_b32_e32 v106, 0x8000, v98
	v_mov_b32_e32 v107, v97
	v_lshl_add_u64 v[104:105], v[126:127], 0, v[106:107]
	global_store_dwordx4 v[104:105], v[112:115], off
	v_or_b32_e32 v104, 0xc000, v98
	v_mov_b32_e32 v105, v97
	ds_read_b128 v[112:115], v116 offset:4352
	s_waitcnt vmcnt(7) lgkmcnt(1)
	v_fma_f32 v110, v120, v110, v124
	v_fma_f32 v111, v121, v111, v125
	v_fma_f32 v108, v118, v108, v122
	v_fma_f32 v109, v119, v109, v123
	v_lshl_add_u64 v[122:123], v[126:127], 0, v[104:105]
	global_store_dwordx4 v[122:123], v[108:111], off
	ds_read_b128 v[122:125], v116 offset:5440
	s_waitcnt vmcnt(7) lgkmcnt(1)
	v_fma_f32 v114, v120, v114, v132
	v_fma_f32 v115, v121, v115, v133
	v_or_b32_e32 v110, 0x10000, v98
	v_mov_b32_e32 v111, v97
	v_fma_f32 v112, v118, v112, v130
	v_fma_f32 v113, v119, v113, v131
	v_lshl_add_u64 v[108:109], v[126:127], 0, v[110:111]
	global_store_dwordx4 v[108:109], v[112:115], off
	v_or_b32_e32 v108, 0x14000, v98
	v_mov_b32_e32 v109, v97
	s_waitcnt vmcnt(7) lgkmcnt(0)
	v_fma_f32 v114, v120, v124, v136
	v_fma_f32 v115, v121, v125, v137
	v_fma_f32 v112, v118, v122, v134
	v_fma_f32 v113, v119, v123, v135
	ds_read_b128 v[122:125], v116 offset:6528
	v_lshl_add_u64 v[130:131], v[126:127], 0, v[108:109]
	global_store_dwordx4 v[130:131], v[112:115], off
	ds_read_b128 v[130:133], v116 offset:7616
	s_waitcnt vmcnt(7) lgkmcnt(1)
	v_fma_f32 v124, v120, v124, v140
	v_fma_f32 v125, v121, v125, v141
	v_or_b32_e32 v112, 0x18000, v98
	v_mov_b32_e32 v113, v97
	v_fma_f32 v122, v118, v122, v138
	v_fma_f32 v123, v119, v123, v139
	v_lshl_add_u64 v[114:115], v[126:127], 0, v[112:113]
	global_store_dwordx4 v[114:115], v[122:125], off
	v_or_b32_e32 v114, 0x1c000, v98
	v_mov_b32_e32 v115, v97
	s_waitcnt vmcnt(7) lgkmcnt(0)
	v_fma_f32 v120, v120, v132, v144
	v_fma_f32 v121, v121, v133, v145
	v_fma_f32 v118, v118, v130, v142
	v_fma_f32 v119, v119, v131, v143
	v_lshl_add_u64 v[122:123], v[126:127], 0, v[114:115]
	global_store_dwordx4 v[122:123], v[118:121], off
	v_or_b32_e32 v126, 0x20000, v96
	v_mov_b32_e32 v127, v97
	s_waitcnt lgkmcnt(0)
	ds_write_b128 v128, v[80:83]
	ds_write_b128 v128, v[64:67] offset:128
	ds_write_b128 v128, v[84:87] offset:32
	ds_write_b128 v128, v[68:71] offset:160
	ds_write_b128 v128, v[88:91] offset:64
	ds_write_b128 v128, v[72:75] offset:192
	ds_write_b128 v128, v[92:95] offset:96
	ds_write_b128 v128, v[76:79] offset:224
	v_lshl_add_u64 v[68:69], s[10:11], 0, v[126:127]
	v_lshl_add_u64 v[118:119], v[68:69], 0, v[100:101]
	s_waitcnt lgkmcnt(0)
;   __device__ __forceinline__ void operator()(int lrow, int nc, const f32x16& a0, const f32x16& a1, float) const {
;     const int lane = threadIdx.x & 63, wid = threadIdx.x >> 6, r32 = lane & 31, hi = lane >> 5;
;     float* sp = (float*)(scr + wid * (32 * 272));
; #pragma unroll
;     for (int g = 0; g < 4; ++g) {
;       const f32x4 v0 = {a0[4 * g], a0[4 * g + 1], a0[4 * g + 2], a0[4 * g + 3]}, v1 = {a1[4 * g], a1[4 * g + 1], a1[4 * g + 2], a1[4 * g + 3]};
;       *(f32x4*)(sp + r32 * 68 + 4 * hi + 8 * g) = v0; *(f32x4*)(sp + r32 * 68 + 32 + 4 * hi + 8 * g) = v1;
;     }
;     asm volatile("s_waitcnt lgkmcnt(0)" ::: "memory");
;     const int c4 = (lane & 15) * 4, colg = n0 + (nc & ~7) + c4;
;     const size_t rbase = (size_t)(lrow - r32) * 1024 + colg;
;     const f32x4 gv = *(const f32x4*)(gvec + colg);
;     f32x4 xv[8];
; #pragma unroll
;     for (int i = 0; i < 8; ++i) xv[i] = *(const f32x4*)(xin + rbase + (size_t)((lane >> 4) + 4 * i) * 1024);
;     asm volatile("" ::: "memory");
; #pragma unroll
;     for (int i = 0; i < 8; ++i) {
;       const int row = (lane >> 4) + 4 * i;
;       const f32x4 av = *(const f32x4*)(sp + row * 68 + c4);
;       f32x4 r; r[0] = xv[i][0] + gv[0] * av[0]; r[1] = xv[i][1] + gv[1] * av[1]; r[2] = xv[i][2] + gv[2] * av[2]; r[3] = xv[i][3] + gv[3] * av[3];
;       *(f32x4*)(xout + rbase + (size_t)row * 1024) = r;
;     }
	v_add_co_u32_e32 v72, vcc, s0, v118
	global_load_dwordx4 v[64:67], v117, s[12:13]
	global_load_dwordx4 v[68:71], v[118:119], off
	v_addc_co_u32_e32 v73, vcc, 0, v119, vcc
	global_load_dwordx4 v[72:75], v[72:73], off
	v_add_co_u32_e32 v76, vcc, s1, v118
	v_lshl_add_u64 v[126:127], s[8:9], 0, v[126:127]
	s_nop 0
	v_addc_co_u32_e32 v77, vcc, 0, v119, vcc
	v_add_co_u32_e32 v80, vcc, s2, v118
	global_load_dwordx4 v[76:79], v[76:77], off
	s_nop 0
	v_addc_co_u32_e32 v81, vcc, 0, v119, vcc
	global_load_dwordx4 v[80:83], v[80:81], off
	v_add_co_u32_e32 v84, vcc, s14, v118
	s_nop 1
	v_addc_co_u32_e32 v85, vcc, 0, v119, vcc
	v_add_co_u32_e32 v88, vcc, s15, v118
	global_load_dwordx4 v[84:87], v[84:85], off
	s_nop 0
	v_addc_co_u32_e32 v89, vcc, 0, v119, vcc
	global_load_dwordx4 v[88:91], v[88:89], off
	v_add_co_u32_e32 v92, vcc, s16, v118
	s_nop 1
	v_addc_co_u32_e32 v93, vcc, 0, v119, vcc
	v_add_co_u32_e32 v118, vcc, s17, v118
	global_load_dwordx4 v[92:95], v[92:93], off
	s_nop 0
	v_addc_co_u32_e32 v119, vcc, 0, v119, vcc
	global_load_dwordx4 v[118:121], v[118:119], off
	ds_read_b128 v[122:125], v116
	ds_read_b128 v[130:133], v116 offset:1088
	s_waitcnt vmcnt(7) lgkmcnt(1)
	v_fma_f32 v70, v66, v124, v70
	v_fma_f32 v71, v67, v125, v71
	v_fma_f32 v68, v64, v122, v68
	v_fma_f32 v69, v65, v123, v69
	v_lshl_add_u64 v[122:123], v[126:127], 0, v[98:99]
	global_store_dwordx4 v[122:123], v[68:71], off
	ds_read_b128 v[122:125], v116 offset:2176
	s_waitcnt vmcnt(7) lgkmcnt(1)
	v_fma_f32 v70, v66, v132, v74
	v_fma_f32 v71, v67, v133, v75
	v_fma_f32 v68, v64, v130, v72
	v_fma_f32 v69, v65, v131, v73
	v_lshl_add_u64 v[72:73], v[126:127], 0, v[102:103]
	global_store_dwordx4 v[72:73], v[68:71], off
	ds_read_b128 v[68:71], v116 offset:3264
	s_waitcnt vmcnt(7) lgkmcnt(1)
	v_fma_f32 v74, v66, v124, v78
	v_fma_f32 v75, v67, v125, v79
	v_fma_f32 v72, v64, v122, v76
	v_fma_f32 v73, v65, v123, v77
	v_lshl_add_u64 v[76:77], v[126:127], 0, v[106:107]
	global_store_dwordx4 v[76:77], v[72:75], off
	s_waitcnt vmcnt(7) lgkmcnt(0)
	v_fma_f32 v70, v66, v70, v82
	v_fma_f32 v71, v67, v71, v83
	ds_read_b128 v[72:75], v116 offset:4352
	v_fma_f32 v68, v64, v68, v80
	v_fma_f32 v69, v65, v69, v81
	v_lshl_add_u64 v[76:77], v[126:127], 0, v[104:105]
	global_store_dwordx4 v[76:77], v[68:71], off
	ds_read_b128 v[68:71], v116 offset:5440
	v_lshl_add_u64 v[76:77], v[126:127], 0, v[110:111]
	s_waitcnt vmcnt(7) lgkmcnt(1)
	v_fma_f32 v74, v66, v74, v86
	v_fma_f32 v75, v67, v75, v87
	v_fma_f32 v72, v64, v72, v84
	v_fma_f32 v73, v65, v73, v85
	global_store_dwordx4 v[76:77], v[72:75], off
	s_waitcnt vmcnt(7) lgkmcnt(0)
	v_fma_f32 v70, v66, v70, v90
	v_fma_f32 v71, v67, v71, v91
	v_fma_f32 v68, v64, v68, v88
	v_fma_f32 v69, v65, v69, v89
	v_lshl_add_u64 v[76:77], v[126:127], 0, v[108:109]
	ds_read_b128 v[72:75], v116 offset:6528
	global_store_dwordx4 v[76:77], v[68:71], off
	ds_read_b128 v[68:71], v116 offset:7616
	v_lshl_add_u64 v[76:77], v[126:127], 0, v[112:113]
	s_waitcnt vmcnt(7) lgkmcnt(1)
	v_fma_f32 v74, v66, v74, v94
	v_fma_f32 v75, v67, v75, v95
	v_fma_f32 v72, v64, v72, v92
	v_fma_f32 v73, v65, v73, v93
	global_store_dwordx4 v[76:77], v[72:75], off
	s_waitcnt vmcnt(7) lgkmcnt(0)
	v_fma_f32 v66, v66, v70, v120
	v_fma_f32 v67, v67, v71, v121
	v_fma_f32 v64, v64, v68, v118
	v_fma_f32 v65, v65, v69, v119
	v_lshl_add_u64 v[68:69], v[126:127], 0, v[114:115]
	global_store_dwordx4 v[68:69], v[64:67], off
	v_or_b32_e32 v76, 0x40000, v96
	v_mov_b32_e32 v77, v97
	s_waitcnt lgkmcnt(0)
	ds_write_b128 v128, v[48:51]
	ds_write_b128 v128, v[32:35] offset:128
	ds_write_b128 v128, v[52:55] offset:32
	ds_write_b128 v128, v[36:39] offset:160
	ds_write_b128 v128, v[56:59] offset:64
	ds_write_b128 v128, v[40:43] offset:192
	ds_write_b128 v128, v[60:63] offset:96
	ds_write_b128 v128, v[44:47] offset:224
	v_lshl_add_u64 v[36:37], s[10:11], 0, v[76:77]
	v_lshl_add_u64 v[64:65], v[36:37], 0, v[100:101]
	s_waitcnt lgkmcnt(0)
	v_add_co_u32_e32 v40, vcc, s0, v64
	global_load_dwordx4 v[32:35], v117, s[12:13]
	global_load_dwordx4 v[36:39], v[64:65], off
	v_addc_co_u32_e32 v41, vcc, 0, v65, vcc
	global_load_dwordx4 v[40:43], v[40:41], off
	v_add_co_u32_e32 v44, vcc, s1, v64
	v_lshl_add_u64 v[76:77], s[8:9], 0, v[76:77]
	s_nop 0
	v_addc_co_u32_e32 v45, vcc, 0, v65, vcc
	v_add_co_u32_e32 v48, vcc, s2, v64
	global_load_dwordx4 v[44:47], v[44:45], off
	s_nop 0
	v_addc_co_u32_e32 v49, vcc, 0, v65, vcc
	global_load_dwordx4 v[48:51], v[48:49], off
	v_add_co_u32_e32 v52, vcc, s14, v64
	v_or_b32_e32 v96, 0x60000, v96
	s_nop 0
	v_addc_co_u32_e32 v53, vcc, 0, v65, vcc
	v_add_co_u32_e32 v56, vcc, s15, v64
	global_load_dwordx4 v[52:55], v[52:53], off
	s_nop 0
	v_addc_co_u32_e32 v57, vcc, 0, v65, vcc
	global_load_dwordx4 v[56:59], v[56:57], off
	v_add_co_u32_e32 v60, vcc, s16, v64
	s_nop 1
	v_addc_co_u32_e32 v61, vcc, 0, v65, vcc
	v_add_co_u32_e32 v64, vcc, s17, v64
	global_load_dwordx4 v[60:63], v[60:61], off
	s_nop 0
	v_addc_co_u32_e32 v65, vcc, 0, v65, vcc
	global_load_dwordx4 v[64:67], v[64:65], off
	ds_read_b128 v[68:71], v116
	ds_read_b128 v[72:75], v116 offset:1088
	s_waitcnt vmcnt(7) lgkmcnt(1)
	v_fma_f32 v38, v34, v70, v38
	v_fma_f32 v39, v35, v71, v39
	v_fma_f32 v36, v32, v68, v36
	v_fma_f32 v37, v33, v69, v37
	v_lshl_add_u64 v[68:69], v[76:77], 0, v[98:99]
	global_store_dwordx4 v[68:69], v[36:39], off
	ds_read_b128 v[68:71], v116 offset:2176
	s_waitcnt vmcnt(7) lgkmcnt(1)
;   __device__ __forceinline__ void operator()(int lrow, int nc, const f32x16& a0, const f32x16& a1, float) const {
;     const int lane = threadIdx.x & 63, wid = threadIdx.x >> 6, r32 = lane & 31, hi = lane >> 5;
;     float* sp = (float*)(scr + wid * (32 * 272));
; #pragma unroll
;     for (int g = 0; g < 4; ++g) {
;       const f32x4 v0 = {a0[4 * g], a0[4 * g + 1], a0[4 * g + 2], a0[4 * g + 3]}, v1 = {a1[4 * g], a1[4 * g + 1], a1[4 * g + 2], a1[4 * g + 3]};
;       *(f32x4*)(sp + r32 * 68 + 4 * hi + 8 * g) = v0; *(f32x4*)(sp + r32 * 68 + 32 + 4 * hi + 8 * g) = v1;
;     }
;     asm volatile("s_waitcnt lgkmcnt(0)" ::: "memory");
;     const int c4 = (lane & 15) * 4, colg = n0 + (nc & ~7) + c4;
;     const size_t rbase = (size_t)(lrow - r32) * 1024 + colg;
;     const f32x4 gv = *(const f32x4*)(gvec + colg);
;     f32x4 xv[8];
; #pragma unroll
;     for (int i = 0; i < 8; ++i) xv[i] = *(const f32x4*)(xin + rbase + (size_t)((lane >> 4) + 4 * i) * 1024);
;     asm volatile("" ::: "memory");
; #pragma unroll
;     for (int i = 0; i < 8; ++i) {
;       const int row = (lane >> 4) + 4 * i;
;       const f32x4 av = *(const f32x4*)(sp + row * 68 + c4);
;       f32x4 r; r[0] = xv[i][0] + gv[0] * av[0]; r[1] = xv[i][1] + gv[1] * av[1]; r[2] = xv[i][2] + gv[2] * av[2]; r[3] = xv[i][3] + gv[3] * av[3];
;       *(f32x4*)(xout + rbase + (size_t)row * 1024) = r;
;     }
	v_fma_f32 v38, v34, v74, v42
	v_fma_f32 v39, v35, v75, v43
	v_fma_f32 v36, v32, v72, v40
	v_fma_f32 v37, v33, v73, v41
	v_lshl_add_u64 v[40:41], v[76:77], 0, v[102:103]
	global_store_dwordx4 v[40:41], v[36:39], off
	ds_read_b128 v[36:39], v116 offset:3264
	s_waitcnt vmcnt(7) lgkmcnt(1)
	v_fma_f32 v42, v34, v70, v46
	v_fma_f32 v43, v35, v71, v47
	v_fma_f32 v40, v32, v68, v44
	v_fma_f32 v41, v33, v69, v45
	v_lshl_add_u64 v[44:45], v[76:77], 0, v[106:107]
	global_store_dwordx4 v[44:45], v[40:43], off
	s_waitcnt vmcnt(7) lgkmcnt(0)
	v_fma_f32 v38, v34, v38, v50
	v_fma_f32 v39, v35, v39, v51
	ds_read_b128 v[40:43], v116 offset:4352
	v_fma_f32 v36, v32, v36, v48
	v_fma_f32 v37, v33, v37, v49
	v_lshl_add_u64 v[44:45], v[76:77], 0, v[104:105]
	global_store_dwordx4 v[44:45], v[36:39], off
	ds_read_b128 v[36:39], v116 offset:5440
	v_lshl_add_u64 v[44:45], v[76:77], 0, v[110:111]
	s_waitcnt vmcnt(7) lgkmcnt(1)
	v_fma_f32 v42, v34, v42, v54
	v_fma_f32 v43, v35, v43, v55
	v_fma_f32 v40, v32, v40, v52
	v_fma_f32 v41, v33, v41, v53
	global_store_dwordx4 v[44:45], v[40:43], off
	s_waitcnt vmcnt(7) lgkmcnt(0)
	v_fma_f32 v38, v34, v38, v58
	v_fma_f32 v39, v35, v39, v59
	v_fma_f32 v36, v32, v36, v56
	v_fma_f32 v37, v33, v37, v57
	v_lshl_add_u64 v[44:45], v[76:77], 0, v[108:109]
	ds_read_b128 v[40:43], v116 offset:6528
	global_store_dwordx4 v[44:45], v[36:39], off
	ds_read_b128 v[36:39], v116 offset:7616
	v_lshl_add_u64 v[44:45], v[76:77], 0, v[112:113]
	s_waitcnt vmcnt(7) lgkmcnt(1)
	v_fma_f32 v42, v34, v42, v62
	v_fma_f32 v43, v35, v43, v63
	v_fma_f32 v40, v32, v40, v60
	v_fma_f32 v41, v33, v41, v61
	global_store_dwordx4 v[44:45], v[40:43], off
	s_waitcnt vmcnt(7) lgkmcnt(0)
	v_fma_f32 v34, v34, v38, v66
	v_fma_f32 v35, v35, v39, v67
	v_fma_f32 v32, v32, v36, v64
	v_fma_f32 v33, v33, v37, v65
	v_lshl_add_u64 v[36:37], v[76:77], 0, v[114:115]
	global_store_dwordx4 v[36:37], v[32:35], off
	s_waitcnt lgkmcnt(0)
	ds_write_b128 v128, v[16:19]
	ds_write_b128 v128, v[0:3] offset:128
	ds_write_b128 v128, v[20:23] offset:32
	ds_write_b128 v128, v[4:7] offset:160
	ds_write_b128 v128, v[24:27] offset:64
	ds_write_b128 v128, v[8:11] offset:192
	ds_write_b128 v128, v[28:31] offset:96
	ds_write_b128 v128, v[12:15] offset:224
	v_lshl_add_u64 v[4:5], s[10:11], 0, v[96:97]
	v_lshl_add_u64 v[32:33], v[4:5], 0, v[100:101]
	s_waitcnt lgkmcnt(0)
	v_add_co_u32_e32 v8, vcc, s0, v32
	global_load_dwordx4 v[0:3], v117, s[12:13]
	global_load_dwordx4 v[4:7], v[32:33], off
	v_addc_co_u32_e32 v9, vcc, 0, v33, vcc
	global_load_dwordx4 v[8:11], v[8:9], off
	v_add_co_u32_e32 v12, vcc, s1, v32
	v_lshl_add_u64 v[44:45], s[8:9], 0, v[96:97]
	s_nop 0
	v_addc_co_u32_e32 v13, vcc, 0, v33, vcc
	v_add_co_u32_e32 v16, vcc, s2, v32
	global_load_dwordx4 v[12:15], v[12:13], off
	s_nop 0
	v_addc_co_u32_e32 v17, vcc, 0, v33, vcc
	global_load_dwordx4 v[16:19], v[16:17], off
	v_add_co_u32_e32 v20, vcc, s14, v32
	s_nop 1
	v_addc_co_u32_e32 v21, vcc, 0, v33, vcc
	v_add_co_u32_e32 v24, vcc, s15, v32
	global_load_dwordx4 v[20:23], v[20:21], off
	s_nop 0
	v_addc_co_u32_e32 v25, vcc, 0, v33, vcc
	global_load_dwordx4 v[24:27], v[24:25], off
	v_add_co_u32_e32 v28, vcc, s16, v32
	s_nop 1
	v_addc_co_u32_e32 v29, vcc, 0, v33, vcc
	v_add_co_u32_e32 v32, vcc, s17, v32
	global_load_dwordx4 v[28:31], v[28:29], off
	s_nop 0
	v_addc_co_u32_e32 v33, vcc, 0, v33, vcc
	global_load_dwordx4 v[32:35], v[32:33], off
	ds_read_b128 v[36:39], v116
	ds_read_b128 v[40:43], v116 offset:1088
	s_waitcnt vmcnt(7) lgkmcnt(1)
	v_fma_f32 v6, v2, v38, v6
	v_fma_f32 v7, v3, v39, v7
	v_fma_f32 v4, v0, v36, v4
	v_fma_f32 v5, v1, v37, v5
	v_lshl_add_u64 v[36:37], v[44:45], 0, v[98:99]
	global_store_dwordx4 v[36:37], v[4:7], off
	ds_read_b128 v[36:39], v116 offset:2176
	s_waitcnt vmcnt(7) lgkmcnt(1)
	v_fma_f32 v6, v2, v42, v10
	v_fma_f32 v7, v3, v43, v11
	v_fma_f32 v4, v0, v40, v8
	v_fma_f32 v5, v1, v41, v9
	v_lshl_add_u64 v[8:9], v[44:45], 0, v[102:103]
	global_store_dwordx4 v[8:9], v[4:7], off
	ds_read_b128 v[4:7], v116 offset:3264
	s_waitcnt vmcnt(7) lgkmcnt(1)
	v_fma_f32 v10, v2, v38, v14
	v_fma_f32 v11, v3, v39, v15
	v_fma_f32 v8, v0, v36, v12
	v_fma_f32 v9, v1, v37, v13
	v_lshl_add_u64 v[12:13], v[44:45], 0, v[106:107]
	global_store_dwordx4 v[12:13], v[8:11], off
	s_waitcnt vmcnt(7) lgkmcnt(0)
	v_fma_f32 v6, v2, v6, v18
	v_fma_f32 v7, v3, v7, v19
	ds_read_b128 v[8:11], v116 offset:4352
	v_fma_f32 v4, v0, v4, v16
	v_fma_f32 v5, v1, v5, v17
	v_lshl_add_u64 v[12:13], v[44:45], 0, v[104:105]
	global_store_dwordx4 v[12:13], v[4:7], off
	ds_read_b128 v[4:7], v116 offset:5440
	v_lshl_add_u64 v[12:13], v[44:45], 0, v[110:111]
	s_waitcnt vmcnt(7) lgkmcnt(1)
	v_fma_f32 v10, v2, v10, v22
	v_fma_f32 v11, v3, v11, v23
	v_fma_f32 v8, v0, v8, v20
	v_fma_f32 v9, v1, v9, v21
	global_store_dwordx4 v[12:13], v[8:11], off
	s_waitcnt vmcnt(7) lgkmcnt(0)
	v_fma_f32 v6, v2, v6, v26
	v_fma_f32 v7, v3, v7, v27
	v_fma_f32 v4, v0, v4, v24
	v_fma_f32 v5, v1, v5, v25
	v_lshl_add_u64 v[12:13], v[44:45], 0, v[108:109]
	ds_read_b128 v[8:11], v116 offset:6528
	global_store_dwordx4 v[12:13], v[4:7], off
	ds_read_b128 v[4:7], v116 offset:7616
	v_lshl_add_u64 v[12:13], v[44:45], 0, v[112:113]
	s_waitcnt vmcnt(7) lgkmcnt(1)
	v_fma_f32 v10, v2, v10, v30
	v_fma_f32 v11, v3, v11, v31
	v_fma_f32 v8, v0, v8, v28
	v_fma_f32 v9, v1, v9, v29
	global_store_dwordx4 v[12:13], v[8:11], off
	s_waitcnt vmcnt(7) lgkmcnt(0)
	v_fma_f32 v2, v2, v6, v34
	v_fma_f32 v3, v3, v7, v35
	v_fma_f32 v0, v0, v4, v32
	v_fma_f32 v1, v1, v5, v33
	v_lshl_add_u64 v[4:5], v[44:45], 0, v[114:115]
	global_store_dwordx4 v[4:5], v[0:3], off
	s_waitcnt lgkmcnt(0)

; __device__ __forceinline__ void st_bf16x4(bf16_t* p, float a, float b, float c, float d) { u32x2 w = {cvtpk(a, b), cvtpk(c, d)}; *(u32x2*)p = w; }
; __device__ void phase_norm(const float* xsrc, const float* csrc, const float* ng, const float* mod, bf16_t* H) {
;     ...
;   for (int n = gw; n < NTOK; n += nw) {
;     if (n + nw < NTOK) { const float* src = row_src(xsrc, csrc, n + nw, bib);
; #pragma unroll
;       for (int i = 0; i < 4; ++i) vb[i] = *(const f32x4*)(src + i * 256 + lane * 4); }
;     float ss = 0.f;
; #pragma unroll
;     for (int i = 0; i < 4; ++i) ss += va[i][0] * va[i][0] + va[i][1] * va[i][1] + va[i][2] * va[i][2] + va[i][3] * va[i][3];
;     ss = wave_sum(ss);
;     const float rstd = rsqrtf(ss * (1.f / 1024.f) + 1e-6f);
;     const float* m = mod + bia * 3072;
; #pragma unroll
;     for (int i = 0; i < 4; ++i) {
;       const int c = i * 256 + lane * 4;
;       const f32x4 sh = *(const f32x4*)(m + c), sc = *(const f32x4*)(m + 1024 + c);
;       float o[4];
; #pragma unroll
;       for (int e = 0; e < 4; ++e) o[e] = va[i][e] * rstd * g4[i][e] * (1.f + sc[e]) + sh[e];
;       st_bf16x4(H + (size_t)n * 1024 + c, o[0], o[1], o[2], o[3]);
;     }
; #pragma unroll
;     for (int i = 0; i < 4; ++i) va[i] = vb[i];
;     bia = bib;
.LBB0_683:
	s_or_b64 exec, exec, s[18:19]
	s_waitcnt vmcnt(11)
	v_mul_lo_u32 v66, v51, s22
	v_ashrrev_i32_e32 v67, 31, v66
	s_waitcnt vmcnt(10)
	v_lshl_add_u64 v[70:71], v[66:67], 2, s[10:11]
	v_lshl_add_u64 v[74:75], v[70:71], 0, s[16:17]
	v_lshl_add_u64 v[66:67], v[74:75], 0, v[166:167]
	global_load_dwordx4 v[66:69], v[66:67], off
	v_lshl_add_u64 v[76:77], v[70:71], 0, v[166:167]
	global_load_dwordx4 v[70:73], v[76:77], off
	s_waitcnt vmcnt(3)
	v_mov_b32_e32 v80, v25
	s_waitcnt vmcnt(2)
	v_mov_b32_e32 v81, v29
	v_mov_b32_e32 v78, v24
	v_mov_b32_e32 v79, v28
	v_mov_b32_e32 v88, v17
	v_mov_b32_e32 v89, v21
	v_mul_f32_e64 v80, v80, v80
	v_mul_f32_e64 v81, v81, v81
	v_mov_b32_e32 v82, v26
	v_mov_b32_e32 v83, v30
	v_mov_b32_e32 v86, v16
	v_mov_b32_e32 v87, v20
	v_mul_f32_e64 v88, v88, v88
	v_mul_f32_e64 v89, v89, v89
	v_fma_f32 v78, v78, v78, v80
	v_fma_f32 v79, v79, v79, v81
	v_mov_b32_e32 v84, v27
	v_mov_b32_e32 v85, v31
	v_mov_b32_e32 v90, v18
	v_mov_b32_e32 v91, v22
	v_fma_f32 v80, v86, v86, v88
	v_fma_f32 v81, v87, v87, v89
	v_fma_f32 v78, v82, v82, v78
	v_fma_f32 v79, v83, v83, v79
	v_mov_b32_e32 v92, v19
	v_mov_b32_e32 v93, v23
	v_fma_f32 v80, v90, v90, v80
	v_fma_f32 v81, v91, v91, v81
	v_fma_f32 v78, v84, v84, v78
	v_fma_f32 v79, v85, v85, v79
	v_fma_f32 v80, v92, v92, v80
	v_fma_f32 v81, v93, v93, v81
	v_add_f32_e32 v51, v78, v79
	v_add_f32_e32 v51, v81, v51
	v_add_f32_e32 v51, v80, v51
	ds_bpermute_b32 v53, v56, v51
	s_and_b64 s[4:5], exec, vcc
	v_mov_b32_e32 v55, v167
	s_or_b64 s[14:15], s[4:5], s[14:15]
	s_waitcnt lgkmcnt(0)
	v_add_f32_e32 v51, v51, v53
	ds_bpermute_b32 v53, v57, v51
	s_waitcnt lgkmcnt(0)
	v_add_f32_e32 v51, v51, v53
	ds_bpermute_b32 v53, v58, v51
	s_waitcnt lgkmcnt(0)
	v_add_f32_e32 v51, v51, v53
	ds_bpermute_b32 v53, v59, v51
	s_waitcnt lgkmcnt(0)
	v_add_f32_e32 v51, v51, v53
	ds_bpermute_b32 v53, v60, v51
	s_waitcnt lgkmcnt(0)
	v_add_f32_e32 v51, v51, v53
	ds_bpermute_b32 v53, v61, v51
	s_waitcnt lgkmcnt(0)
	v_add_f32_e32 v51, v51, v53
	v_fmamk_f32 v51, v51, 0x3a800000, v62
	v_mul_f32_e32 v53, 0x4b800000, v51
	v_cmp_gt_f32_e32 vcc, s21, v51
	s_waitcnt vmcnt(1)
	v_add_f32_e64 v66, v66, 1.0
	v_add_f32_e64 v67, v67, 1.0
	v_cndmask_b32_e32 v51, v51, v53, vcc
	v_rsq_f32_e32 v53, v51
	v_mov_b32_e32 v51, v167
	v_lshl_add_u64 v[78:79], v[74:75], 0, v[50:51]
	v_add_f32_e64 v68, v68, 1.0
	v_add_f32_e64 v69, v69, 1.0
	v_mul_f32_e32 v51, 0x45800000, v53
	v_cndmask_b32_e32 v80, v53, v51, vcc
	v_mul_f32_e64 v28, v28, v80
	v_mul_f32_e64 v29, v29, v80
	v_mul_f32_e64 v30, v30, v80
	v_mul_f32_e64 v31, v31, v80
	v_mul_f32_e64 v28, v8, v28
	v_mul_f32_e64 v29, v9, v29
	v_mul_f32_e64 v30, v10, v30
	v_mul_f32_e64 v31, v11, v31
	s_waitcnt vmcnt(0)
	v_fma_f32 v28, v66, v28, v70
	v_fma_f32 v29, v67, v29, v71
	v_fma_f32 v30, v68, v30, v72
	v_fma_f32 v31, v69, v31, v73
	v_cvt_pk_bf16_f32 v28, v28, v29
	v_cvt_pk_bf16_f32 v29, v30, v31
	global_store_dwordx2 v[48:49], v[28:29], off offset:-1024
	global_load_dwordx4 v[28:31], v[78:79], off
	s_nop 0
	global_load_dwordx4 v[66:69], v[76:77], off offset:1024
	v_mul_f32_e64 v24, v24, v80
	v_mul_f32_e64 v25, v25, v80
	v_mul_f32_e64 v26, v26, v80
	v_mul_f32_e64 v27, v27, v80
	v_mul_f32_e64 v24, v0, v24
	v_mul_f32_e64 v25, v1, v25
	v_mul_f32_e64 v26, v2, v26
	v_mul_f32_e64 v27, v3, v27
	v_mov_b32_e32 v53, v167
	v_lshl_add_u64 v[70:71], v[74:75], 0, v[52:53]
	v_mul_f32_e64 v20, v20, v80
	v_mul_f32_e64 v21, v21, v80
	v_mul_f32_e64 v22, v22, v80
	v_mul_f32_e64 v23, v23, v80
	v_mul_f32_e64 v20, v4, v20
	v_mul_f32_e64 v21, v5, v21
	v_mul_f32_e64 v22, v6, v22
	v_mul_f32_e64 v23, v7, v23
	v_lshl_add_u64 v[74:75], v[74:75], 0, v[54:55]
	v_mov_b32_e32 v53, v63
	v_mov_b32_e32 v51, v64
	s_waitcnt vmcnt(1)
	v_add_f32_e64 v28, v28, 1.0
	v_add_f32_e64 v29, v29, 1.0
	v_add_f32_e64 v30, v30, 1.0
	v_add_f32_e64 v31, v31, 1.0
	s_waitcnt vmcnt(0)
	v_fma_f32 v24, v28, v24, v66
	v_fma_f32 v25, v29, v25, v67
	v_fma_f32 v26, v30, v26, v68
	v_fma_f32 v27, v31, v27, v69
	v_cvt_pk_bf16_f32 v24, v24, v25
	v_cvt_pk_bf16_f32 v25, v26, v27
	global_store_dwordx2 v[48:49], v[24:25], off offset:-512
	global_load_dwordx4 v[24:27], v[70:71], off
	s_nop 0
	global_load_dwordx4 v[28:31], v[76:77], off offset:2048
	s_waitcnt vmcnt(1)
	v_add_f32_e64 v24, v24, 1.0
	v_add_f32_e64 v25, v25, 1.0
	v_add_f32_e64 v26, v26, 1.0
	v_add_f32_e64 v27, v27, 1.0
	s_waitcnt vmcnt(0)
	v_fma_f32 v20, v24, v20, v28
	v_fma_f32 v21, v25, v21, v29
	v_fma_f32 v22, v26, v22, v30
	v_fma_f32 v23, v27, v23, v31
	v_cvt_pk_bf16_f32 v20, v20, v21
	v_cvt_pk_bf16_f32 v21, v22, v23
	global_store_dwordx2 v[48:49], v[20:21], off
	global_load_dwordx4 v[66:69], v[74:75], off
	global_load_dwordx4 v[70:73], v[76:77], off offset:3072
	v_mul_f32_e64 v74, v16, v80
	v_mul_f32_e64 v75, v17, v80
	v_mul_f32_e64 v76, v18, v80
	v_mul_f32_e64 v77, v19, v80
	v_mul_f32_e64 v74, v12, v74
	v_mul_f32_e64 v75, v13, v75
	v_mul_f32_e64 v76, v14, v76
	v_mul_f32_e64 v77, v15, v77
	v_mov_b64_e32 v[16:17], v[44:45]
	v_mov_b64_e32 v[20:21], v[40:41]
	v_mov_b64_e32 v[24:25], v[36:37]
	v_mov_b64_e32 v[28:29], v[32:33]
	v_mov_b64_e32 v[18:19], v[46:47]
	v_mov_b64_e32 v[22:23], v[42:43]
	v_mov_b64_e32 v[26:27], v[38:39]
	v_mov_b64_e32 v[30:31], v[34:35]
	s_waitcnt vmcnt(1)
	v_add_f32_e64 v66, v66, 1.0
	v_add_f32_e64 v67, v67, 1.0
	v_add_f32_e64 v68, v68, 1.0
	v_add_f32_e64 v69, v69, 1.0
	s_waitcnt vmcnt(0)
	v_fma_f32 v66, v74, v66, v70
	v_fma_f32 v67, v75, v67, v71
	v_fma_f32 v68, v76, v68, v72
	v_fma_f32 v69, v77, v69, v73
	v_cvt_pk_bf16_f32 v66, v66, v67
	v_cvt_pk_bf16_f32 v67, v68, v69
	global_store_dwordx2 v[48:49], v[66:67], off offset:512
	v_lshl_add_u64 v[48:49], v[48:49], 0, s[12:13]
	s_andn2_b64 exec, exec, s[14:15]
	s_cbranch_execz .LBB0_689

; __device__ __forceinline__ void st_bf16x4(bf16_t* p, float a, float b, float c, float d) { u32x2 w = {cvtpk(a, b), cvtpk(c, d)}; *(u32x2*)p = w; }
;   __device__ __forceinline__ void rope_one(int lrow, int nc, const f32x16& a) const {
;     ...
;       const f32x2* tr = (const f32x2*)rope + (t >> 6) * 8 + hi4;
;       const f32x2* tc = (const f32x2*)rope + (t & 63) * 8 + hi4;
;       float o1[8], o2[8];
; #pragma unroll
;       for (int e = 0; e < 4; ++e) {
;         const f32x2 cs0 = tr[e], cs1 = tc[e];
;         const float x1a = a[e], x2a = a[8 + e];
;         const float x1b = a[4 + e], x2b = a[12 + e];
;         o1[e] = x1a * cs0[0] - x2a * cs0[1]; o2[e] = x1a * cs0[1] + x2a * cs0[0];
;         o1[4 + e] = x1b * cs1[0] - x2b * cs1[1]; o2[4 + e] = x1b * cs1[1] + x2b * cs1[0];
;       }
;       st_bf16x4(p + hi4, o1[0], o1[1], o1[2], o1[3]);
;       st_bf16x4(p + 8 + hi4, o1[4], o1[5], o1[6], o1[7]);
;       st_bf16x4(p + 16 + hi4, o2[0], o2[1], o2[2], o2[3]);
;       st_bf16x4(p + 24 + hi4, o2[4], o2[5], o2[6], o2[7]);
.LBB0_726:
	s_andn2_saveexec_b64 s[14:15], s[14:15]
	s_cbranch_execz .LBB0_728
	v_lshlrev_b32_e32 v115, 6, v114
	v_ashrrev_i32_e32 v114, 3, v114
	v_and_b32_e32 v114, -16, v114
	v_and_b32_e32 v116, 0x7c0, v115
	v_mov_b32_e32 v117, v169
	v_ashrrev_i32_e32 v115, 31, v114
	v_lshl_add_u64 v[120:121], v[186:187], 0, v[116:117]
	v_lshl_add_u64 v[114:115], v[114:115], 3, v[186:187]
	global_load_dwordx4 v[116:119], v[120:121], off
	s_nop 0
	global_load_dwordx4 v[120:123], v[120:121], off offset:16
	s_nop 0
	global_load_dwordx4 v[124:127], v[114:115], off
	global_load_dwordx4 v[128:131], v[114:115], off offset:16
	v_lshlrev_b32_e32 v114, 1, v172
	v_mov_b32_e32 v115, v169
	v_lshl_add_u64 v[112:113], v[112:113], 0, v[114:115]
	s_waitcnt vmcnt(3)
	v_mov_b32_e32 v114, v116
	v_mov_b32_e32 v115, v118
	v_mov_b32_e32 v118, v117
	s_waitcnt vmcnt(2)
	v_mov_b32_e32 v116, v120
	v_mov_b32_e32 v117, v122
	v_mov_b32_e32 v122, v121
	s_waitcnt vmcnt(1)
	v_mov_b32_e32 v120, v124
	v_mov_b32_e32 v121, v126
	v_mov_b32_e32 v126, v125
	v_mul_f32_e64 v124, v108, v118
	v_mul_f32_e64 v125, v109, v119
	v_mul_f32_e64 v108, v108, v114
	v_mul_f32_e64 v109, v109, v115
	s_waitcnt vmcnt(0)
	v_mov_b32_e32 v133, v130
	v_mov_b32_e32 v130, v129
	v_mov_b32_e32 v132, v128
	v_mul_f32_e64 v128, v110, v122
	v_mul_f32_e64 v129, v111, v123
	v_mul_f32_e64 v110, v110, v116
	v_mul_f32_e64 v111, v111, v117
	v_mul_f32_e64 v134, v104, v126
	v_mul_f32_e64 v135, v105, v127
	v_mul_f32_e64 v104, v104, v120
	v_mul_f32_e64 v105, v105, v121
	v_fma_f32 v114, v100, v114, -v124
	v_fma_f32 v115, v101, v115, -v125
	v_fma_f32 v100, v100, v118, v108
	v_fma_f32 v101, v101, v119, v109
	v_mul_f32_e64 v108, v106, v130
	v_mul_f32_e64 v109, v107, v131
	v_mul_f32_e64 v106, v106, v132
	v_mul_f32_e64 v107, v107, v133
	v_fma_f32 v116, v102, v116, -v128
	v_fma_f32 v117, v103, v117, -v129
	v_fma_f32 v102, v102, v122, v110
	v_fma_f32 v103, v103, v123, v111
	v_fma_f32 v110, v96, v120, -v134
	v_fma_f32 v111, v97, v121, -v135
	v_fma_f32 v96, v96, v126, v104
	v_fma_f32 v97, v97, v127, v105
	v_fma_f32 v104, v98, v132, -v108
	v_fma_f32 v105, v99, v133, -v109
	v_fma_f32 v98, v98, v130, v106
	v_fma_f32 v99, v99, v131, v107
	v_cvt_pk_bf16_f32 v106, v114, v115
	v_cvt_pk_bf16_f32 v107, v116, v117
	v_cvt_pk_bf16_f32 v100, v100, v101
	v_cvt_pk_bf16_f32 v101, v102, v103
	v_cvt_pk_bf16_f32 v102, v110, v111
	v_cvt_pk_bf16_f32 v103, v104, v105
	global_store_dwordx2 v[112:113], v[106:107], off offset:16
	v_cvt_pk_bf16_f32 v96, v96, v97
	v_cvt_pk_bf16_f32 v97, v98, v99
	global_store_dwordx2 v[112:113], v[102:103], off
	global_store_dwordx2 v[112:113], v[96:97], off offset:32
	global_store_dwordx2 v[112:113], v[100:101], off offset:48

; __device__ __forceinline__ void st_bf16x4(bf16_t* p, float a, float b, float c, float d) { u32x2 w = {cvtpk(a, b), cvtpk(c, d)}; *(u32x2*)p = w; }
;   __device__ __forceinline__ void rope_one(int lrow, int nc, const f32x16& a) const {
;     ...
;       const f32x2* tr = (const f32x2*)rope + (t >> 6) * 8 + hi4;
;       const f32x2* tc = (const f32x2*)rope + (t & 63) * 8 + hi4;
;       float o1[8], o2[8];
; #pragma unroll
;       for (int e = 0; e < 4; ++e) {
;         const f32x2 cs0 = tr[e], cs1 = tc[e];
;         const float x1a = a[e], x2a = a[8 + e];
;         const float x1b = a[4 + e], x2b = a[12 + e];
;         o1[e] = x1a * cs0[0] - x2a * cs0[1]; o2[e] = x1a * cs0[1] + x2a * cs0[0];
;         o1[4 + e] = x1b * cs1[0] - x2b * cs1[1]; o2[4 + e] = x1b * cs1[1] + x2b * cs1[0];
;       }
;       st_bf16x4(p + hi4, o1[0], o1[1], o1[2], o1[3]);
;       st_bf16x4(p + 8 + hi4, o1[4], o1[5], o1[6], o1[7]);
;       st_bf16x4(p + 16 + hi4, o2[0], o2[1], o2[2], o2[3]);
;       st_bf16x4(p + 24 + hi4, o2[4], o2[5], o2[6], o2[7]);
.LBB0_747:
	s_andn2_saveexec_b64 s[18:19], s[18:19]
	s_cbranch_execz .LBB0_749
	v_lshlrev_b32_e32 v83, 6, v82
	v_ashrrev_i32_e32 v82, 3, v82
	v_and_b32_e32 v82, -16, v82
	v_and_b32_e32 v84, 0xfc0, v83
	v_mov_b32_e32 v85, v169
	v_ashrrev_i32_e32 v83, 31, v82
	v_lshl_add_u64 v[88:89], v[186:187], 0, v[84:85]
	v_lshl_add_u64 v[82:83], v[82:83], 3, v[186:187]
	global_load_dwordx4 v[84:87], v[88:89], off
	s_nop 0
	global_load_dwordx4 v[88:91], v[88:89], off offset:16
	s_nop 0
	global_load_dwordx4 v[92:95], v[82:83], off
	global_load_dwordx4 v[96:99], v[82:83], off offset:16
	v_lshlrev_b32_e32 v82, 1, v172
	v_mov_b32_e32 v83, v169
	v_lshl_add_u64 v[80:81], v[80:81], 0, v[82:83]
	s_waitcnt vmcnt(3)
	v_mov_b32_e32 v82, v84
	v_mov_b32_e32 v83, v86
	v_mov_b32_e32 v86, v85
	s_waitcnt vmcnt(2)
	v_mov_b32_e32 v84, v88
	v_mov_b32_e32 v85, v90
	v_mov_b32_e32 v90, v89
	s_waitcnt vmcnt(1)
	v_mov_b32_e32 v88, v92
	v_mov_b32_e32 v89, v94
	v_mov_b32_e32 v94, v93
	v_mul_f32_e64 v92, v76, v86
	v_mul_f32_e64 v93, v77, v87
	v_mul_f32_e64 v76, v76, v82
	v_mul_f32_e64 v77, v77, v83
	s_waitcnt vmcnt(0)
	v_mov_b32_e32 v101, v98
	v_mov_b32_e32 v98, v97
	v_mov_b32_e32 v100, v96
	v_mul_f32_e64 v96, v78, v90
	v_mul_f32_e64 v97, v79, v91
	v_mul_f32_e64 v78, v78, v84
	v_mul_f32_e64 v79, v79, v85
	v_mul_f32_e64 v102, v72, v94
	v_mul_f32_e64 v103, v73, v95
	v_mul_f32_e64 v72, v72, v88
	v_mul_f32_e64 v73, v73, v89
	v_fma_f32 v82, v68, v82, -v92
	v_fma_f32 v83, v69, v83, -v93
	v_fma_f32 v68, v68, v86, v76
	v_fma_f32 v69, v69, v87, v77
	v_mul_f32_e64 v76, v74, v98
	v_mul_f32_e64 v77, v75, v99
	v_mul_f32_e64 v74, v74, v100
	v_mul_f32_e64 v75, v75, v101
	v_fma_f32 v84, v70, v84, -v96
	v_fma_f32 v85, v71, v85, -v97
	v_fma_f32 v70, v70, v90, v78
	v_fma_f32 v71, v71, v91, v79
	v_fma_f32 v78, v64, v88, -v102
	v_fma_f32 v79, v65, v89, -v103
	v_fma_f32 v64, v64, v94, v72
	v_fma_f32 v65, v65, v95, v73
	v_fma_f32 v72, v66, v100, -v76
	v_fma_f32 v73, v67, v101, -v77
	v_fma_f32 v66, v66, v98, v74
	v_fma_f32 v67, v67, v99, v75
	v_cvt_pk_bf16_f32 v74, v82, v83
	v_cvt_pk_bf16_f32 v75, v84, v85
	v_cvt_pk_bf16_f32 v68, v68, v69
	v_cvt_pk_bf16_f32 v69, v70, v71
	v_cvt_pk_bf16_f32 v70, v78, v79
	v_cvt_pk_bf16_f32 v71, v72, v73
	global_store_dwordx2 v[80:81], v[74:75], off offset:16
	v_cvt_pk_bf16_f32 v64, v64, v65
	v_cvt_pk_bf16_f32 v65, v66, v67
	global_store_dwordx2 v[80:81], v[70:71], off
	global_store_dwordx2 v[80:81], v[64:65], off offset:32
	global_store_dwordx2 v[80:81], v[68:69], off offset:48

; __device__ __forceinline__ void st_bf16x4(bf16_t* p, float a, float b, float c, float d) { u32x2 w = {cvtpk(a, b), cvtpk(c, d)}; *(u32x2*)p = w; }
;   __device__ __forceinline__ void rope_one(int lrow, int nc, const f32x16& a) const {
;     ...
;       const f32x2* tr = (const f32x2*)rope + (t >> 6) * 8 + hi4;
;       const f32x2* tc = (const f32x2*)rope + (t & 63) * 8 + hi4;
;       float o1[8], o2[8];
; #pragma unroll
;       for (int e = 0; e < 4; ++e) {
;         const f32x2 cs0 = tr[e], cs1 = tc[e];
;         const float x1a = a[e], x2a = a[8 + e];
;         const float x1b = a[4 + e], x2b = a[12 + e];
;         o1[e] = x1a * cs0[0] - x2a * cs0[1]; o2[e] = x1a * cs0[1] + x2a * cs0[0];
;         o1[4 + e] = x1b * cs1[0] - x2b * cs1[1]; o2[4 + e] = x1b * cs1[1] + x2b * cs1[0];
;       }
;       st_bf16x4(p + hi4, o1[0], o1[1], o1[2], o1[3]);
;       st_bf16x4(p + 8 + hi4, o1[4], o1[5], o1[6], o1[7]);
;       st_bf16x4(p + 16 + hi4, o2[0], o2[1], o2[2], o2[3]);
;       st_bf16x4(p + 24 + hi4, o2[4], o2[5], o2[6], o2[7]);
.LBB0_768:
	s_andn2_saveexec_b64 s[18:19], s[18:19]
	s_cbranch_execz .LBB0_770
	v_lshlrev_b32_e32 v51, 6, v50
	v_ashrrev_i32_e32 v50, 3, v50
	v_and_b32_e32 v50, -8, v50
	v_and_b32_e32 v52, 0x7c0, v51
	v_mov_b32_e32 v53, v169
	v_ashrrev_i32_e32 v51, 31, v50
	v_lshl_add_u64 v[56:57], v[186:187], 0, v[52:53]
	v_lshl_add_u64 v[50:51], v[50:51], 3, v[186:187]
	global_load_dwordx4 v[52:55], v[56:57], off
	s_nop 0
	global_load_dwordx4 v[56:59], v[56:57], off offset:16
	s_nop 0
	global_load_dwordx4 v[60:63], v[50:51], off
	global_load_dwordx4 v[64:67], v[50:51], off offset:16
	v_lshlrev_b32_e32 v50, 1, v172
	v_mov_b32_e32 v51, v169
	v_lshl_add_u64 v[48:49], v[48:49], 0, v[50:51]
	s_waitcnt vmcnt(3)
	v_mov_b32_e32 v50, v52
	v_mov_b32_e32 v51, v54
	v_mov_b32_e32 v54, v53
	s_waitcnt vmcnt(2)
	v_mov_b32_e32 v52, v56
	v_mov_b32_e32 v53, v58
	v_mov_b32_e32 v58, v57
	s_waitcnt vmcnt(1)
	v_mov_b32_e32 v56, v60
	v_mov_b32_e32 v57, v62
	v_mov_b32_e32 v62, v61
	v_mul_f32_e64 v60, v44, v54
	v_mul_f32_e64 v61, v45, v55
	v_mul_f32_e64 v44, v44, v50
	v_mul_f32_e64 v45, v45, v51
	s_waitcnt vmcnt(0)
	v_mov_b32_e32 v69, v66
	v_mov_b32_e32 v66, v65
	v_mov_b32_e32 v68, v64
	v_mul_f32_e64 v64, v46, v58
	v_mul_f32_e64 v65, v47, v59
	v_mul_f32_e64 v46, v46, v52
	v_mul_f32_e64 v47, v47, v53
	v_mul_f32_e64 v70, v40, v62
	v_mul_f32_e64 v71, v41, v63
	v_mul_f32_e64 v40, v40, v56
	v_mul_f32_e64 v41, v41, v57
	v_fma_f32 v50, v36, v50, -v60
	v_fma_f32 v51, v37, v51, -v61
	v_fma_f32 v36, v36, v54, v44
	v_fma_f32 v37, v37, v55, v45
	v_mul_f32_e64 v44, v42, v66
	v_mul_f32_e64 v45, v43, v67
	v_mul_f32_e64 v42, v42, v68
	v_mul_f32_e64 v43, v43, v69
	v_fma_f32 v52, v38, v52, -v64
	v_fma_f32 v53, v39, v53, -v65
	v_fma_f32 v38, v38, v58, v46
	v_fma_f32 v39, v39, v59, v47
	v_fma_f32 v46, v32, v56, -v70
	v_fma_f32 v47, v33, v57, -v71
	v_fma_f32 v32, v32, v62, v40
	v_fma_f32 v33, v33, v63, v41
	v_fma_f32 v40, v34, v68, -v44
	v_fma_f32 v41, v35, v69, -v45
	v_fma_f32 v34, v34, v66, v42
	v_fma_f32 v35, v35, v67, v43
	v_cvt_pk_bf16_f32 v42, v50, v51
	v_cvt_pk_bf16_f32 v43, v52, v53
	v_cvt_pk_bf16_f32 v36, v36, v37
	v_cvt_pk_bf16_f32 v37, v38, v39
	v_cvt_pk_bf16_f32 v38, v46, v47
	v_cvt_pk_bf16_f32 v39, v40, v41
	global_store_dwordx2 v[48:49], v[42:43], off offset:16
	v_cvt_pk_bf16_f32 v32, v32, v33
	v_cvt_pk_bf16_f32 v33, v34, v35
	global_store_dwordx2 v[48:49], v[38:39], off
	global_store_dwordx2 v[48:49], v[32:33], off offset:32
	global_store_dwordx2 v[48:49], v[36:37], off offset:48

; __device__ __forceinline__ void st_bf16x4(bf16_t* p, float a, float b, float c, float d) { u32x2 w = {cvtpk(a, b), cvtpk(c, d)}; *(u32x2*)p = w; }
;   __device__ __forceinline__ void rope_one(int lrow, int nc, const f32x16& a) const {
;     ...
;       const f32x2* tr = (const f32x2*)rope + (t >> 6) * 8 + hi4;
;       const f32x2* tc = (const f32x2*)rope + (t & 63) * 8 + hi4;
;       float o1[8], o2[8];
; #pragma unroll
;       for (int e = 0; e < 4; ++e) {
;         const f32x2 cs0 = tr[e], cs1 = tc[e];
;         const float x1a = a[e], x2a = a[8 + e];
;         const float x1b = a[4 + e], x2b = a[12 + e];
;         o1[e] = x1a * cs0[0] - x2a * cs0[1]; o2[e] = x1a * cs0[1] + x2a * cs0[0];
;         o1[4 + e] = x1b * cs1[0] - x2b * cs1[1]; o2[4 + e] = x1b * cs1[1] + x2b * cs1[0];
;       }
;       st_bf16x4(p + hi4, o1[0], o1[1], o1[2], o1[3]);
;       st_bf16x4(p + 8 + hi4, o1[4], o1[5], o1[6], o1[7]);
;       st_bf16x4(p + 16 + hi4, o2[0], o2[1], o2[2], o2[3]);
;       st_bf16x4(p + 24 + hi4, o2[4], o2[5], o2[6], o2[7]);
.LBB0_788:
	s_andn2_saveexec_b64 s[16:17], s[16:17]
	s_cbranch_execz .LBB0_701
	v_lshlrev_b32_e32 v19, 6, v18
	v_ashrrev_i32_e32 v18, 3, v18
	v_and_b32_e32 v18, -8, v18
	v_and_b32_e32 v20, 0xfc0, v19
	v_mov_b32_e32 v21, v169
	v_ashrrev_i32_e32 v19, 31, v18
	v_lshl_add_u64 v[24:25], v[186:187], 0, v[20:21]
	v_lshl_add_u64 v[18:19], v[18:19], 3, v[186:187]
	global_load_dwordx4 v[20:23], v[24:25], off
	s_nop 0
	global_load_dwordx4 v[24:27], v[24:25], off offset:16
	s_nop 0
	global_load_dwordx4 v[28:31], v[18:19], off
	global_load_dwordx4 v[32:35], v[18:19], off offset:16
	v_lshl_add_u64 v[16:17], v[16:17], 0, v[168:169]
	s_waitcnt vmcnt(3)
	v_mov_b32_e32 v18, v20
	v_mov_b32_e32 v19, v22
	v_mov_b32_e32 v22, v21
	s_waitcnt vmcnt(2)
	v_mov_b32_e32 v20, v24
	v_mov_b32_e32 v21, v26
	v_mov_b32_e32 v26, v25
	s_waitcnt vmcnt(1)
	v_mov_b32_e32 v24, v28
	v_mov_b32_e32 v25, v30
	v_mov_b32_e32 v30, v29
	v_mul_f32_e64 v28, v12, v22
	v_mul_f32_e64 v29, v13, v23
	v_mul_f32_e64 v12, v12, v18
	v_mul_f32_e64 v13, v13, v19
	s_waitcnt vmcnt(0)
	v_mov_b32_e32 v37, v34
	v_mov_b32_e32 v34, v33
	v_mov_b32_e32 v36, v32
	v_mul_f32_e64 v32, v14, v26
	v_mul_f32_e64 v33, v15, v27
	v_mul_f32_e64 v14, v14, v20
	v_mul_f32_e64 v15, v15, v21
	v_mul_f32_e64 v38, v8, v30
	v_mul_f32_e64 v39, v9, v31
	v_mul_f32_e64 v8, v8, v24
	v_mul_f32_e64 v9, v9, v25
	v_fma_f32 v18, v4, v18, -v28
	v_fma_f32 v19, v5, v19, -v29
	v_fma_f32 v4, v4, v22, v12
	v_fma_f32 v5, v5, v23, v13
	v_mul_f32_e64 v12, v10, v34
	v_mul_f32_e64 v13, v11, v35
	v_mul_f32_e64 v10, v10, v36
	v_mul_f32_e64 v11, v11, v37
	v_fma_f32 v20, v6, v20, -v32
	v_fma_f32 v21, v7, v21, -v33
	v_fma_f32 v6, v6, v26, v14
	v_fma_f32 v7, v7, v27, v15
	v_fma_f32 v14, v0, v24, -v38
	v_fma_f32 v15, v1, v25, -v39
	v_fma_f32 v0, v0, v30, v8
	v_fma_f32 v1, v1, v31, v9
	v_fma_f32 v8, v2, v36, -v12
	v_fma_f32 v9, v3, v37, -v13
	v_fma_f32 v2, v2, v34, v10
	v_fma_f32 v3, v3, v35, v11
	v_cvt_pk_bf16_f32 v10, v18, v19
	v_cvt_pk_bf16_f32 v11, v20, v21
	v_cvt_pk_bf16_f32 v4, v4, v5
	v_cvt_pk_bf16_f32 v5, v6, v7
	v_cvt_pk_bf16_f32 v6, v14, v15
	v_cvt_pk_bf16_f32 v7, v8, v9
	global_store_dwordx2 v[16:17], v[10:11], off offset:16
	v_cvt_pk_bf16_f32 v0, v0, v1
	v_cvt_pk_bf16_f32 v1, v2, v3
	global_store_dwordx2 v[16:17], v[6:7], off
	global_store_dwordx2 v[16:17], v[0:1], off offset:32
	global_store_dwordx2 v[16:17], v[4:5], off offset:48
	s_branch .LBB0_701

; __device__ __forceinline__ void st_bf16x4(bf16_t* p, float a, float b, float c, float d) { u32x2 w = {cvtpk(a, b), cvtpk(c, d)}; *(u32x2*)p = w; }
;   __device__ __forceinline__ void rope_one(int lrow, int nc, const f32x16& a) const {
;     ...
;       const f32x2* tr = (const f32x2*)rope + (t >> 6) * 8 + hi4;
;       const f32x2* tc = (const f32x2*)rope + (t & 63) * 8 + hi4;
;       float o1[8], o2[8];
; #pragma unroll
;       for (int e = 0; e < 4; ++e) {
;         const f32x2 cs0 = tr[e], cs1 = tc[e];
;         const float x1a = a[e], x2a = a[8 + e];
;         const float x1b = a[4 + e], x2b = a[12 + e];
;         o1[e] = x1a * cs0[0] - x2a * cs0[1]; o2[e] = x1a * cs0[1] + x2a * cs0[0];
;         o1[4 + e] = x1b * cs1[0] - x2b * cs1[1]; o2[4 + e] = x1b * cs1[1] + x2b * cs1[0];
;       }
;       st_bf16x4(p + hi4, o1[0], o1[1], o1[2], o1[3]);
;       st_bf16x4(p + 8 + hi4, o1[4], o1[5], o1[6], o1[7]);
;       st_bf16x4(p + 16 + hi4, o2[0], o2[1], o2[2], o2[3]);
;       st_bf16x4(p + 24 + hi4, o2[4], o2[5], o2[6], o2[7]);
.LBB0_830:
	s_andn2_saveexec_b64 s[12:13], s[12:13]
	s_cbranch_execz .LBB0_832
	v_mov_b32_e32 v65, 0
	v_lshlrev_b32_e32 v51, 6, v50
	v_ashrrev_i32_e32 v50, 3, v50
	v_and_b32_e32 v52, 0x7c0, v51
	v_mov_b32_e32 v53, v65
	v_and_b32_e32 v50, -8, v50
	v_lshlrev_b32_e32 v64, 3, v66
	v_lshl_add_u64 v[52:53], s[4:5], 0, v[52:53]
	v_ashrrev_i32_e32 v51, 31, v50
	v_lshl_add_u64 v[60:61], v[52:53], 0, v[64:65]
	v_lshl_add_u64 v[50:51], v[50:51], 3, s[4:5]
	global_load_dwordx4 v[52:55], v[60:61], off offset:16
	global_load_dwordx4 v[56:59], v[60:61], off
	v_lshl_add_u64 v[50:51], v[50:51], 0, v[64:65]
	global_load_dwordx4 v[60:63], v[50:51], off
	global_load_dwordx4 v[76:79], v[50:51], off offset:16
	v_lshlrev_b32_e32 v64, 1, v66
	v_lshl_add_u64 v[48:49], v[48:49], 0, v[64:65]
	s_waitcnt vmcnt(2)
	v_mov_b32_e32 v50, v56
	v_mov_b32_e32 v51, v58
	v_mov_b32_e32 v58, v57
	v_mov_b32_e32 v56, v52
	v_mov_b32_e32 v57, v54
	v_mov_b32_e32 v54, v53
	s_waitcnt vmcnt(1)
	v_mov_b32_e32 v52, v60
	v_mov_b32_e32 v53, v62
	v_mov_b32_e32 v62, v61
	v_mul_f32_e64 v60, v44, v58
	v_mul_f32_e64 v61, v45, v59
	v_mul_f32_e64 v44, v44, v50
	v_mul_f32_e64 v45, v45, v51
	s_waitcnt vmcnt(0)
	v_mov_b32_e32 v65, v78
	v_mov_b32_e32 v78, v77
	v_mov_b32_e32 v64, v76
	v_mul_f32_e64 v76, v46, v54
	v_mul_f32_e64 v77, v47, v55
	v_mul_f32_e64 v46, v46, v56
	v_mul_f32_e64 v47, v47, v57
	v_mul_f32_e64 v80, v40, v62
	v_mul_f32_e64 v81, v41, v63
	v_mul_f32_e64 v40, v40, v52
	v_mul_f32_e64 v41, v41, v53
	v_fma_f32 v50, v36, v50, -v60
	v_fma_f32 v51, v37, v51, -v61
	v_fma_f32 v36, v36, v58, v44
	v_fma_f32 v37, v37, v59, v45
	v_mul_f32_e64 v44, v42, v78
	v_mul_f32_e64 v45, v43, v79
	v_mul_f32_e64 v42, v42, v64
	v_mul_f32_e64 v43, v43, v65
	v_fma_f32 v56, v38, v56, -v76
	v_fma_f32 v57, v39, v57, -v77
	v_fma_f32 v38, v38, v54, v46
	v_fma_f32 v39, v39, v55, v47
	v_fma_f32 v46, v32, v52, -v80
	v_fma_f32 v47, v33, v53, -v81
	v_fma_f32 v32, v32, v62, v40
	v_fma_f32 v33, v33, v63, v41
	v_fma_f32 v40, v34, v64, -v44
	v_fma_f32 v41, v35, v65, -v45
	v_fma_f32 v34, v34, v78, v42
	v_fma_f32 v35, v35, v79, v43
	v_cvt_pk_bf16_f32 v42, v50, v51
	v_cvt_pk_bf16_f32 v43, v56, v57
	v_cvt_pk_bf16_f32 v36, v36, v37
	v_cvt_pk_bf16_f32 v37, v38, v39
	v_cvt_pk_bf16_f32 v38, v46, v47
	v_cvt_pk_bf16_f32 v39, v40, v41
	global_store_dwordx2 v[48:49], v[42:43], off offset:16
	v_cvt_pk_bf16_f32 v32, v32, v33
	v_cvt_pk_bf16_f32 v33, v34, v35
	global_store_dwordx2 v[48:49], v[38:39], off
	global_store_dwordx2 v[48:49], v[32:33], off offset:32
	global_store_dwordx2 v[48:49], v[36:37], off offset:48

; __device__ __forceinline__ void st_bf16x4(bf16_t* p, float a, float b, float c, float d) { u32x2 w = {cvtpk(a, b), cvtpk(c, d)}; *(u32x2*)p = w; }
;   __device__ __forceinline__ void rope_one(int lrow, int nc, const f32x16& a) const {
;     ...
;       const f32x2* tr = (const f32x2*)rope + (t >> 6) * 8 + hi4;
;       const f32x2* tc = (const f32x2*)rope + (t & 63) * 8 + hi4;
;       float o1[8], o2[8];
; #pragma unroll
;       for (int e = 0; e < 4; ++e) {
;         const f32x2 cs0 = tr[e], cs1 = tc[e];
;         const float x1a = a[e], x2a = a[8 + e];
;         const float x1b = a[4 + e], x2b = a[12 + e];
;         o1[e] = x1a * cs0[0] - x2a * cs0[1]; o2[e] = x1a * cs0[1] + x2a * cs0[0];
;         o1[4 + e] = x1b * cs1[0] - x2b * cs1[1]; o2[4 + e] = x1b * cs1[1] + x2b * cs1[0];
;       }
;       st_bf16x4(p + hi4, o1[0], o1[1], o1[2], o1[3]);
;       st_bf16x4(p + 8 + hi4, o1[4], o1[5], o1[6], o1[7]);
;       st_bf16x4(p + 16 + hi4, o2[0], o2[1], o2[2], o2[3]);
;       st_bf16x4(p + 24 + hi4, o2[4], o2[5], o2[6], o2[7]);
.LBB0_850:
	s_andn2_saveexec_b64 s[12:13], s[12:13]
	s_cbranch_execz .LBB0_852
	v_mov_b32_e32 v37, 0
	v_lshlrev_b32_e32 v20, 6, v19
	v_and_b32_e32 v20, 0xfc0, v20
	v_mov_b32_e32 v21, v37
	v_lshlrev_b32_e32 v36, 3, v66
	v_lshl_add_u64 v[20:21], s[4:5], 0, v[20:21]
	v_lshl_add_u64 v[28:29], v[20:21], 0, v[36:37]
	v_ashrrev_i32_e32 v19, 3, v19
	global_load_dwordx4 v[20:23], v[28:29], off offset:16
	global_load_dwordx4 v[24:27], v[28:29], off
	v_and_b32_e32 v28, -8, v19
	v_ashrrev_i32_e32 v29, 31, v28
	v_lshl_add_u64 v[28:29], v[28:29], 3, s[4:5]
	v_lshl_add_u64 v[38:39], v[28:29], 0, v[36:37]
	global_load_dwordx4 v[28:31], v[38:39], off
	global_load_dwordx4 v[32:35], v[38:39], off offset:16
	v_mov_b32_e32 v19, v37
	v_lshl_add_u64 v[16:17], v[16:17], 0, v[18:19]
	s_waitcnt vmcnt(2)
	v_mov_b32_e32 v18, v24
	v_mov_b32_e32 v19, v26
	v_mov_b32_e32 v26, v25
	v_mov_b32_e32 v24, v20
	v_mov_b32_e32 v25, v22
	v_mov_b32_e32 v22, v21
	s_waitcnt vmcnt(1)
	v_mov_b32_e32 v20, v28
	v_mov_b32_e32 v21, v30
	v_mov_b32_e32 v30, v29
	v_mul_f32_e64 v28, v12, v26
	v_mul_f32_e64 v29, v13, v27
	v_mul_f32_e64 v12, v12, v18
	v_mul_f32_e64 v13, v13, v19
	s_waitcnt vmcnt(0)
	v_mov_b32_e32 v37, v34
	v_mov_b32_e32 v34, v33
	v_mov_b32_e32 v36, v32
	v_mul_f32_e64 v32, v14, v22
	v_mul_f32_e64 v33, v15, v23
	v_mul_f32_e64 v14, v14, v24
	v_mul_f32_e64 v15, v15, v25
	v_mul_f32_e64 v38, v8, v30
	v_mul_f32_e64 v39, v9, v31
	v_mul_f32_e64 v8, v8, v20
	v_mul_f32_e64 v9, v9, v21
	v_fma_f32 v18, v4, v18, -v28
	v_fma_f32 v19, v5, v19, -v29
	v_fma_f32 v4, v4, v26, v12
	v_fma_f32 v5, v5, v27, v13
	v_mul_f32_e64 v12, v10, v34
	v_mul_f32_e64 v13, v11, v35
	v_mul_f32_e64 v10, v10, v36
	v_mul_f32_e64 v11, v11, v37
	v_fma_f32 v24, v6, v24, -v32
	v_fma_f32 v25, v7, v25, -v33
	v_fma_f32 v6, v6, v22, v14
	v_fma_f32 v7, v7, v23, v15
	v_fma_f32 v14, v0, v20, -v38
	v_fma_f32 v15, v1, v21, -v39
	v_fma_f32 v0, v0, v30, v8
	v_fma_f32 v1, v1, v31, v9
	v_fma_f32 v8, v2, v36, -v12
	v_fma_f32 v9, v3, v37, -v13
	v_fma_f32 v2, v2, v34, v10
	v_fma_f32 v3, v3, v35, v11
	v_cvt_pk_bf16_f32 v10, v18, v19
	v_cvt_pk_bf16_f32 v11, v24, v25
	v_cvt_pk_bf16_f32 v4, v4, v5
	v_cvt_pk_bf16_f32 v5, v6, v7
	v_cvt_pk_bf16_f32 v6, v14, v15
	v_cvt_pk_bf16_f32 v7, v8, v9
	global_store_dwordx2 v[16:17], v[10:11], off offset:16
	v_cvt_pk_bf16_f32 v0, v0, v1
	v_cvt_pk_bf16_f32 v1, v2, v3
	global_store_dwordx2 v[16:17], v[6:7], off
	global_store_dwordx2 v[16:17], v[0:1], off offset:32
	global_store_dwordx2 v[16:17], v[4:5], off offset:48

; __device__ __forceinline__ void st_bf16x4(bf16_t* p, float a, float b, float c, float d) { u32x2 w = {cvtpk(a, b), cvtpk(c, d)}; *(u32x2*)p = w; }
;   __device__ __forceinline__ void rope_one(int lrow, int nc, const f32x16& a) const {
;     ...
;       const f32x2* tr = (const f32x2*)rope + (t >> 6) * 8 + hi4;
;       const f32x2* tc = (const f32x2*)rope + (t & 63) * 8 + hi4;
;       float o1[8], o2[8];
; #pragma unroll
;       for (int e = 0; e < 4; ++e) {
;         const f32x2 cs0 = tr[e], cs1 = tc[e];
;         const float x1a = a[e], x2a = a[8 + e];
;         const float x1b = a[4 + e], x2b = a[12 + e];
;         o1[e] = x1a * cs0[0] - x2a * cs0[1]; o2[e] = x1a * cs0[1] + x2a * cs0[0];
;         o1[4 + e] = x1b * cs1[0] - x2b * cs1[1]; o2[4 + e] = x1b * cs1[1] + x2b * cs1[0];
;       }
;       st_bf16x4(p + hi4, o1[0], o1[1], o1[2], o1[3]);
;       st_bf16x4(p + 8 + hi4, o1[4], o1[5], o1[6], o1[7]);
;       st_bf16x4(p + 16 + hi4, o2[0], o2[1], o2[2], o2[3]);
;       st_bf16x4(p + 24 + hi4, o2[4], o2[5], o2[6], o2[7]);
.LBB0_877:
	s_andn2_saveexec_b64 s[10:11], s[10:11]
	s_cbranch_execz .LBB0_879
	v_mov_b32_e32 v143, 0
	v_lshlrev_b32_e32 v115, 6, v114
	v_ashrrev_i32_e32 v114, 3, v114
	v_and_b32_e32 v116, 0x7c0, v115
	v_mov_b32_e32 v117, v143
	v_and_b32_e32 v114, -16, v114
	v_lshlrev_b32_e32 v142, 3, v132
	v_lshl_add_u64 v[116:117], s[4:5], 0, v[116:117]
	v_ashrrev_i32_e32 v115, 31, v114
	v_lshl_add_u64 v[120:121], v[116:117], 0, v[142:143]
	v_lshl_add_u64 v[114:115], v[114:115], 3, s[4:5]
	global_load_dwordx4 v[116:119], v[120:121], off offset:16
	s_nop 0
	global_load_dwordx4 v[120:123], v[120:121], off
	v_lshl_add_u64 v[114:115], v[114:115], 0, v[142:143]
	global_load_dwordx4 v[124:127], v[114:115], off
	global_load_dwordx4 v[128:131], v[114:115], off offset:16
	v_lshlrev_b32_e32 v142, 1, v132
	v_lshl_add_u64 v[112:113], v[112:113], 0, v[142:143]
	s_waitcnt vmcnt(2)
	v_mov_b32_e32 v114, v120
	v_mov_b32_e32 v115, v122
	v_mov_b32_e32 v122, v121
	v_mov_b32_e32 v120, v116
	v_mov_b32_e32 v121, v118
	v_mov_b32_e32 v118, v117
	s_waitcnt vmcnt(1)
	v_mov_b32_e32 v116, v124
	v_mov_b32_e32 v117, v126
	v_mov_b32_e32 v126, v125
	v_mul_f32_e64 v124, v108, v122
	v_mul_f32_e64 v125, v109, v123
	v_mul_f32_e64 v108, v108, v114
	v_mul_f32_e64 v109, v109, v115
	s_waitcnt vmcnt(0)
	v_mov_b32_e32 v143, v130
	v_mov_b32_e32 v130, v129
	v_mov_b32_e32 v142, v128
	v_mul_f32_e64 v128, v110, v118
	v_mul_f32_e64 v129, v111, v119
	v_mul_f32_e64 v110, v110, v120
	v_mul_f32_e64 v111, v111, v121
	v_mul_f32_e64 v144, v104, v126
	v_mul_f32_e64 v145, v105, v127
	v_mul_f32_e64 v104, v104, v116
	v_mul_f32_e64 v105, v105, v117
	v_fma_f32 v114, v100, v114, -v124
	v_fma_f32 v115, v101, v115, -v125
	v_fma_f32 v100, v100, v122, v108
	v_fma_f32 v101, v101, v123, v109
	v_mul_f32_e64 v108, v106, v130
	v_mul_f32_e64 v109, v107, v131
	v_mul_f32_e64 v106, v106, v142
	v_mul_f32_e64 v107, v107, v143
	v_fma_f32 v120, v102, v120, -v128
	v_fma_f32 v121, v103, v121, -v129
	v_fma_f32 v102, v102, v118, v110
	v_fma_f32 v103, v103, v119, v111
	v_fma_f32 v110, v96, v116, -v144
	v_fma_f32 v111, v97, v117, -v145
	v_fma_f32 v96, v96, v126, v104
	v_fma_f32 v97, v97, v127, v105
	v_fma_f32 v104, v98, v142, -v108
	v_fma_f32 v105, v99, v143, -v109
	v_fma_f32 v98, v98, v130, v106
	v_fma_f32 v99, v99, v131, v107
	v_cvt_pk_bf16_f32 v106, v114, v115
	v_cvt_pk_bf16_f32 v107, v120, v121
	v_cvt_pk_bf16_f32 v100, v100, v101
	v_cvt_pk_bf16_f32 v101, v102, v103
	v_cvt_pk_bf16_f32 v102, v110, v111
	v_cvt_pk_bf16_f32 v103, v104, v105
	global_store_dwordx2 v[112:113], v[106:107], off offset:16
	v_cvt_pk_bf16_f32 v96, v96, v97
	v_cvt_pk_bf16_f32 v97, v98, v99
	global_store_dwordx2 v[112:113], v[102:103], off
	global_store_dwordx2 v[112:113], v[96:97], off offset:32
	global_store_dwordx2 v[112:113], v[100:101], off offset:48

; __device__ __forceinline__ void st_bf16x4(bf16_t* p, float a, float b, float c, float d) { u32x2 w = {cvtpk(a, b), cvtpk(c, d)}; *(u32x2*)p = w; }
;   __device__ __forceinline__ void rope_one(int lrow, int nc, const f32x16& a) const {
;     ...
;       const f32x2* tr = (const f32x2*)rope + (t >> 6) * 8 + hi4;
;       const f32x2* tc = (const f32x2*)rope + (t & 63) * 8 + hi4;
;       float o1[8], o2[8];
; #pragma unroll
;       for (int e = 0; e < 4; ++e) {
;         const f32x2 cs0 = tr[e], cs1 = tc[e];
;         const float x1a = a[e], x2a = a[8 + e];
;         const float x1b = a[4 + e], x2b = a[12 + e];
;         o1[e] = x1a * cs0[0] - x2a * cs0[1]; o2[e] = x1a * cs0[1] + x2a * cs0[0];
;         o1[4 + e] = x1b * cs1[0] - x2b * cs1[1]; o2[4 + e] = x1b * cs1[1] + x2b * cs1[0];
;       }
;       st_bf16x4(p + hi4, o1[0], o1[1], o1[2], o1[3]);
;       st_bf16x4(p + 8 + hi4, o1[4], o1[5], o1[6], o1[7]);
;       st_bf16x4(p + 16 + hi4, o2[0], o2[1], o2[2], o2[3]);
;       st_bf16x4(p + 24 + hi4, o2[4], o2[5], o2[6], o2[7]);
.LBB0_896:
	s_andn2_saveexec_b64 s[10:11], s[10:11]
	s_cbranch_execz .LBB0_898
	v_mov_b32_e32 v101, 0
	v_lshlrev_b32_e32 v83, 6, v82
	v_ashrrev_i32_e32 v82, 3, v82
	v_and_b32_e32 v84, 0xfc0, v83
	v_mov_b32_e32 v85, v101
	v_and_b32_e32 v82, -16, v82
	v_lshlrev_b32_e32 v100, 3, v132
	v_lshl_add_u64 v[84:85], s[4:5], 0, v[84:85]
	v_ashrrev_i32_e32 v83, 31, v82
	v_lshl_add_u64 v[88:89], v[84:85], 0, v[100:101]
	v_lshl_add_u64 v[82:83], v[82:83], 3, s[4:5]
	global_load_dwordx4 v[84:87], v[88:89], off offset:16
	s_nop 0
	global_load_dwordx4 v[88:91], v[88:89], off
	v_lshl_add_u64 v[82:83], v[82:83], 0, v[100:101]
	global_load_dwordx4 v[92:95], v[82:83], off
	global_load_dwordx4 v[96:99], v[82:83], off offset:16
	v_lshlrev_b32_e32 v100, 1, v132
	v_lshl_add_u64 v[80:81], v[80:81], 0, v[100:101]
	s_waitcnt vmcnt(2)
	v_mov_b32_e32 v82, v88
	v_mov_b32_e32 v83, v90
	v_mov_b32_e32 v90, v89
	v_mov_b32_e32 v88, v84
	v_mov_b32_e32 v89, v86
	v_mov_b32_e32 v86, v85
	s_waitcnt vmcnt(1)
	v_mov_b32_e32 v84, v92
	v_mov_b32_e32 v85, v94
	v_mov_b32_e32 v94, v93
	v_mul_f32_e64 v92, v76, v90
	v_mul_f32_e64 v93, v77, v91
	v_mul_f32_e64 v76, v76, v82
	v_mul_f32_e64 v77, v77, v83
	s_waitcnt vmcnt(0)
	v_mov_b32_e32 v101, v98
	v_mov_b32_e32 v98, v97
	v_mov_b32_e32 v100, v96
	v_mul_f32_e64 v96, v78, v86
	v_mul_f32_e64 v97, v79, v87
	v_mul_f32_e64 v78, v78, v88
	v_mul_f32_e64 v79, v79, v89
	v_mul_f32_e64 v102, v72, v94
	v_mul_f32_e64 v103, v73, v95
	v_mul_f32_e64 v72, v72, v84
	v_mul_f32_e64 v73, v73, v85
	v_fma_f32 v82, v68, v82, -v92
	v_fma_f32 v83, v69, v83, -v93
	v_fma_f32 v68, v68, v90, v76
	v_fma_f32 v69, v69, v91, v77
	v_mul_f32_e64 v76, v74, v98
	v_mul_f32_e64 v77, v75, v99
	v_mul_f32_e64 v74, v74, v100
	v_mul_f32_e64 v75, v75, v101
	v_fma_f32 v88, v70, v88, -v96
	v_fma_f32 v89, v71, v89, -v97
	v_fma_f32 v70, v70, v86, v78
	v_fma_f32 v71, v71, v87, v79
	v_fma_f32 v78, v64, v84, -v102
	v_fma_f32 v79, v65, v85, -v103
	v_fma_f32 v64, v64, v94, v72
	v_fma_f32 v65, v65, v95, v73
	v_fma_f32 v72, v66, v100, -v76
	v_fma_f32 v73, v67, v101, -v77
	v_fma_f32 v66, v66, v98, v74
	v_fma_f32 v67, v67, v99, v75
	v_cvt_pk_bf16_f32 v74, v82, v83
	v_cvt_pk_bf16_f32 v75, v88, v89
	v_cvt_pk_bf16_f32 v68, v68, v69
	v_cvt_pk_bf16_f32 v69, v70, v71
	v_cvt_pk_bf16_f32 v70, v78, v79
	v_cvt_pk_bf16_f32 v71, v72, v73
	global_store_dwordx2 v[80:81], v[74:75], off offset:16
	v_cvt_pk_bf16_f32 v64, v64, v65
	v_cvt_pk_bf16_f32 v65, v66, v67
	global_store_dwordx2 v[80:81], v[70:71], off
	global_store_dwordx2 v[80:81], v[64:65], off offset:32
	global_store_dwordx2 v[80:81], v[68:69], off offset:48

; __device__ __forceinline__ void st_bf16x4(bf16_t* p, float a, float b, float c, float d) { u32x2 w = {cvtpk(a, b), cvtpk(c, d)}; *(u32x2*)p = w; }
;   __device__ __forceinline__ void rope_one(int lrow, int nc, const f32x16& a) const {
;     ...
;       const f32x2* tr = (const f32x2*)rope + (t >> 6) * 8 + hi4;
;       const f32x2* tc = (const f32x2*)rope + (t & 63) * 8 + hi4;
;       float o1[8], o2[8];
; #pragma unroll
;       for (int e = 0; e < 4; ++e) {
;         const f32x2 cs0 = tr[e], cs1 = tc[e];
;         const float x1a = a[e], x2a = a[8 + e];
;         const float x1b = a[4 + e], x2b = a[12 + e];
;         o1[e] = x1a * cs0[0] - x2a * cs0[1]; o2[e] = x1a * cs0[1] + x2a * cs0[0];
;         o1[4 + e] = x1b * cs1[0] - x2b * cs1[1]; o2[4 + e] = x1b * cs1[1] + x2b * cs1[0];
;       }
;       st_bf16x4(p + hi4, o1[0], o1[1], o1[2], o1[3]);
;       st_bf16x4(p + 8 + hi4, o1[4], o1[5], o1[6], o1[7]);
;       st_bf16x4(p + 16 + hi4, o2[0], o2[1], o2[2], o2[3]);
;       st_bf16x4(p + 24 + hi4, o2[4], o2[5], o2[6], o2[7]);
.LBB0_915:
	s_andn2_saveexec_b64 s[10:11], s[10:11]
	s_cbranch_execz .LBB0_917
	v_mov_b32_e32 v69, 0
	v_lshlrev_b32_e32 v51, 6, v50
	v_ashrrev_i32_e32 v50, 3, v50
	v_and_b32_e32 v52, 0x7c0, v51
	v_mov_b32_e32 v53, v69
	v_and_b32_e32 v50, -8, v50
	v_lshlrev_b32_e32 v68, 3, v132
	v_lshl_add_u64 v[52:53], s[4:5], 0, v[52:53]
	v_ashrrev_i32_e32 v51, 31, v50
	v_lshl_add_u64 v[60:61], v[52:53], 0, v[68:69]
	v_lshl_add_u64 v[50:51], v[50:51], 3, s[4:5]
	global_load_dwordx4 v[52:55], v[60:61], off offset:16
	global_load_dwordx4 v[56:59], v[60:61], off
	v_lshl_add_u64 v[50:51], v[50:51], 0, v[68:69]
	global_load_dwordx4 v[60:63], v[50:51], off
	global_load_dwordx4 v[64:67], v[50:51], off offset:16
	v_lshlrev_b32_e32 v68, 1, v132
	v_lshl_add_u64 v[48:49], v[48:49], 0, v[68:69]
	s_waitcnt vmcnt(2)
	v_mov_b32_e32 v50, v56
	v_mov_b32_e32 v51, v58
	v_mov_b32_e32 v58, v57
	v_mov_b32_e32 v56, v52
	v_mov_b32_e32 v57, v54
	v_mov_b32_e32 v54, v53
	s_waitcnt vmcnt(1)
	v_mov_b32_e32 v52, v60
	v_mov_b32_e32 v53, v62
	v_mov_b32_e32 v62, v61
	v_mul_f32_e64 v60, v44, v58
	v_mul_f32_e64 v61, v45, v59
	v_mul_f32_e64 v44, v44, v50
	v_mul_f32_e64 v45, v45, v51
	s_waitcnt vmcnt(0)
	v_mov_b32_e32 v69, v66
	v_mov_b32_e32 v66, v65
	v_mov_b32_e32 v68, v64
	v_mul_f32_e64 v64, v46, v54
	v_mul_f32_e64 v65, v47, v55
	v_mul_f32_e64 v46, v46, v56
	v_mul_f32_e64 v47, v47, v57
	v_mul_f32_e64 v70, v40, v62
	v_mul_f32_e64 v71, v41, v63
	v_mul_f32_e64 v40, v40, v52
	v_mul_f32_e64 v41, v41, v53
	v_fma_f32 v50, v36, v50, -v60
	v_fma_f32 v51, v37, v51, -v61
	v_fma_f32 v36, v36, v58, v44
	v_fma_f32 v37, v37, v59, v45
	v_mul_f32_e64 v44, v42, v66
	v_mul_f32_e64 v45, v43, v67
	v_mul_f32_e64 v42, v42, v68
	v_mul_f32_e64 v43, v43, v69
	v_fma_f32 v56, v38, v56, -v64
	v_fma_f32 v57, v39, v57, -v65
	v_fma_f32 v38, v38, v54, v46
	v_fma_f32 v39, v39, v55, v47
	v_fma_f32 v46, v32, v52, -v70
	v_fma_f32 v47, v33, v53, -v71
	v_fma_f32 v32, v32, v62, v40
	v_fma_f32 v33, v33, v63, v41
	v_fma_f32 v40, v34, v68, -v44
	v_fma_f32 v41, v35, v69, -v45
	v_fma_f32 v34, v34, v66, v42
	v_fma_f32 v35, v35, v67, v43
	v_cvt_pk_bf16_f32 v42, v50, v51
	v_cvt_pk_bf16_f32 v43, v56, v57
	v_cvt_pk_bf16_f32 v36, v36, v37
	v_cvt_pk_bf16_f32 v37, v38, v39
	v_cvt_pk_bf16_f32 v38, v46, v47
	v_cvt_pk_bf16_f32 v39, v40, v41
	global_store_dwordx2 v[48:49], v[42:43], off offset:16
	v_cvt_pk_bf16_f32 v32, v32, v33
	v_cvt_pk_bf16_f32 v33, v34, v35
	global_store_dwordx2 v[48:49], v[38:39], off
	global_store_dwordx2 v[48:49], v[32:33], off offset:32
	global_store_dwordx2 v[48:49], v[36:37], off offset:48

; __device__ __forceinline__ void st_bf16x4(bf16_t* p, float a, float b, float c, float d) { u32x2 w = {cvtpk(a, b), cvtpk(c, d)}; *(u32x2*)p = w; }
;   __device__ __forceinline__ void rope_one(int lrow, int nc, const f32x16& a) const {
;     ...
;       const f32x2* tr = (const f32x2*)rope + (t >> 6) * 8 + hi4;
;       const f32x2* tc = (const f32x2*)rope + (t & 63) * 8 + hi4;
;       float o1[8], o2[8];
; #pragma unroll
;       for (int e = 0; e < 4; ++e) {
;         const f32x2 cs0 = tr[e], cs1 = tc[e];
;         const float x1a = a[e], x2a = a[8 + e];
;         const float x1b = a[4 + e], x2b = a[12 + e];
;         o1[e] = x1a * cs0[0] - x2a * cs0[1]; o2[e] = x1a * cs0[1] + x2a * cs0[0];
;         o1[4 + e] = x1b * cs1[0] - x2b * cs1[1]; o2[4 + e] = x1b * cs1[1] + x2b * cs1[0];
;       }
;       st_bf16x4(p + hi4, o1[0], o1[1], o1[2], o1[3]);
;       st_bf16x4(p + 8 + hi4, o1[4], o1[5], o1[6], o1[7]);
;       st_bf16x4(p + 16 + hi4, o2[0], o2[1], o2[2], o2[3]);
;       st_bf16x4(p + 24 + hi4, o2[4], o2[5], o2[6], o2[7]);
.LBB0_934:
	s_andn2_saveexec_b64 s[0:1], s[6:7]
	s_cbranch_execz .LBB0_936
	v_mov_b32_e32 v37, 0
	v_lshlrev_b32_e32 v20, 6, v19
	v_and_b32_e32 v20, 0xfc0, v20
	v_mov_b32_e32 v21, v37
	v_lshlrev_b32_e32 v36, 3, v132
	v_lshl_add_u64 v[20:21], s[4:5], 0, v[20:21]
	v_lshl_add_u64 v[28:29], v[20:21], 0, v[36:37]
	v_ashrrev_i32_e32 v19, 3, v19
	global_load_dwordx4 v[20:23], v[28:29], off offset:16
	global_load_dwordx4 v[24:27], v[28:29], off
	v_and_b32_e32 v28, -8, v19
	v_ashrrev_i32_e32 v29, 31, v28
	v_lshl_add_u64 v[28:29], v[28:29], 3, s[4:5]
	v_lshl_add_u64 v[38:39], v[28:29], 0, v[36:37]
	global_load_dwordx4 v[28:31], v[38:39], off
	global_load_dwordx4 v[32:35], v[38:39], off offset:16
	v_mov_b32_e32 v19, v37
	v_lshl_add_u64 v[16:17], v[16:17], 0, v[18:19]
	s_waitcnt vmcnt(2)
	v_mov_b32_e32 v18, v24
	v_mov_b32_e32 v19, v26
	v_mov_b32_e32 v26, v25
	v_mov_b32_e32 v24, v20
	v_mov_b32_e32 v25, v22
	v_mov_b32_e32 v22, v21
	s_waitcnt vmcnt(1)
	v_mov_b32_e32 v20, v28
	v_mov_b32_e32 v21, v30
	v_mov_b32_e32 v30, v29
	v_mul_f32_e64 v28, v12, v26
	v_mul_f32_e64 v29, v13, v27
	v_mul_f32_e64 v12, v12, v18
	v_mul_f32_e64 v13, v13, v19
	s_waitcnt vmcnt(0)
	v_mov_b32_e32 v37, v34
	v_mov_b32_e32 v34, v33
	v_mov_b32_e32 v36, v32
	v_mul_f32_e64 v32, v14, v22
	v_mul_f32_e64 v33, v15, v23
	v_mul_f32_e64 v14, v14, v24
	v_mul_f32_e64 v15, v15, v25
	v_mul_f32_e64 v38, v8, v30
	v_mul_f32_e64 v39, v9, v31
	v_mul_f32_e64 v8, v8, v20
	v_mul_f32_e64 v9, v9, v21
	v_fma_f32 v18, v4, v18, -v28
	v_fma_f32 v19, v5, v19, -v29
	v_fma_f32 v4, v4, v26, v12
	v_fma_f32 v5, v5, v27, v13
	v_mul_f32_e64 v12, v10, v34
	v_mul_f32_e64 v13, v11, v35
	v_mul_f32_e64 v10, v10, v36
	v_mul_f32_e64 v11, v11, v37
	v_fma_f32 v24, v6, v24, -v32
	v_fma_f32 v25, v7, v25, -v33
	v_fma_f32 v6, v6, v22, v14
	v_fma_f32 v7, v7, v23, v15
	v_fma_f32 v14, v0, v20, -v38
	v_fma_f32 v15, v1, v21, -v39
	v_fma_f32 v0, v0, v30, v8
	v_fma_f32 v1, v1, v31, v9
	v_fma_f32 v8, v2, v36, -v12
	v_fma_f32 v9, v3, v37, -v13
	v_fma_f32 v2, v2, v34, v10
	v_fma_f32 v3, v3, v35, v11
	v_cvt_pk_bf16_f32 v10, v18, v19
	v_cvt_pk_bf16_f32 v11, v24, v25
	v_cvt_pk_bf16_f32 v4, v4, v5
	v_cvt_pk_bf16_f32 v5, v6, v7
	v_cvt_pk_bf16_f32 v6, v14, v15
	v_cvt_pk_bf16_f32 v7, v8, v9
	global_store_dwordx2 v[16:17], v[10:11], off offset:16
	v_cvt_pk_bf16_f32 v0, v0, v1
	v_cvt_pk_bf16_f32 v1, v2, v3
	global_store_dwordx2 v[16:17], v[6:7], off
	global_store_dwordx2 v[16:17], v[0:1], off offset:32
	global_store_dwordx2 v[16:17], v[4:5], off offset:48

;   __device__ __forceinline__ void operator()(int lrow, int nc, const f32x16& a0, const f32x16& a1, float aux) const {
;     const int lane = threadIdx.x & 63, wid = threadIdx.x >> 6, r32 = lane & 31, hi = lane >> 5;
;     float sc = 1.f;
;     if (invK > 0.f) sc = rsqrtf(aux * invK + 1e-6f);
;     char* sp = scr + wid * (32 * 144);
;     char* wp = sp + r32 * 144 + 32 * hi;
;     if (act) {
;     ...
;       const u32x4 w0 = {cvtpk(TANH_(a0[0]), TANH_(a0[1])), cvtpk(TANH_(a0[2]), TANH_(a0[3])), cvtpk(TANH_(a0[4]), TANH_(a0[5])), cvtpk(TANH_(a0[6]), TANH_(a0[7]))};
;       const u32x4 w1 = {cvtpk(TANH_(a0[8]), TANH_(a0[9])), cvtpk(TANH_(a0[10]), TANH_(a0[11])), cvtpk(TANH_(a0[12]), TANH_(a0[13])), cvtpk(TANH_(a0[14]), TANH_(a0[15]))};
;       const u32x4 w2 = {cvtpk(TANH_(a1[0]), TANH_(a1[1])), cvtpk(TANH_(a1[2]), TANH_(a1[3])), cvtpk(TANH_(a1[4]), TANH_(a1[5])), cvtpk(TANH_(a1[6]), TANH_(a1[7]))};
;       const u32x4 w3 = {cvtpk(TANH_(a1[8]), TANH_(a1[9])), cvtpk(TANH_(a1[10]), TANH_(a1[11])), cvtpk(TANH_(a1[12]), TANH_(a1[13])), cvtpk(TANH_(a1[14]), TANH_(a1[15]))};
;     ...
;       *(u32x4*)(wp) = w0; *(u32x4*)(wp + 16) = w1; *(u32x4*)(wp + 64) = w2; *(u32x4*)(wp + 80) = w3;
;     } else {
;       const u32x4 w0 = {cvtpk(a0[0] * sc, a0[1] * sc), cvtpk(a0[2] * sc, a0[3] * sc), cvtpk(a0[4] * sc, a0[5] * sc), cvtpk(a0[6] * sc, a0[7] * sc)};
;       const u32x4 w1 = {cvtpk(a0[8] * sc, a0[9] * sc), cvtpk(a0[10] * sc, a0[11] * sc), cvtpk(a0[12] * sc, a0[13] * sc), cvtpk(a0[14] * sc, a0[15] * sc)};
;       const u32x4 w2 = {cvtpk(a1[0] * sc, a1[1] * sc), cvtpk(a1[2] * sc, a1[3] * sc), cvtpk(a1[4] * sc, a1[5] * sc), cvtpk(a1[6] * sc, a1[7] * sc)};
;       const u32x4 w3 = {cvtpk(a1[8] * sc, a1[9] * sc), cvtpk(a1[10] * sc, a1[11] * sc), cvtpk(a1[12] * sc, a1[13] * sc), cvtpk(a1[14] * sc, a1[15] * sc)};
;       *(u32x4*)(wp) = w0; *(u32x4*)(wp + 16) = w1; *(u32x4*)(wp + 64) = w2; *(u32x4*)(wp + 80) = w3;
;     }
;     asm volatile("s_waitcnt lgkmcnt(0)" ::: "memory");
;     bf16_t* gp = dst + (size_t)(m0 + lrow - r32) * ldd + col0 + (nc & ~7) + (lane & 7) * 8;
; #pragma unroll
;     for (int i = 0; i < 4; ++i) {
;       const int row = (lane >> 3) + 8 * i;
;       *(u32x4*)(gp + (size_t)row * ldd) = *(const u32x4*)(sp + row * 144 + (lane & 7) * 16);
;     }
;     asm volatile("s_waitcnt lgkmcnt(0)" ::: "memory");
.LBB0_949:
	s_or_b64 exec, exec, s[8:9]
	s_waitcnt lgkmcnt(0)
	s_barrier
	ds_read_b32 v128, v212
	s_lshl_b32 s6, s18, 9
	v_mov_b32_e32 v187, v169
	v_mov_b32_e32 v191, v169
	s_cmpk_lt_u32 s16, 0xc0
	s_waitcnt lgkmcnt(0)
	v_fmamk_f32 v128, v128, 0x3b2aaaab, v217
	v_mul_f32_e32 v129, 0x4b800000, v128
	v_cmp_gt_f32_e32 vcc, s13, v128
	s_nop 1
	v_cndmask_b32_e32 v128, v128, v129, vcc
	v_rsq_f32_e32 v128, v128
	s_nop 0
	v_mul_f32_e32 v129, 0x45800000, v128
	v_cndmask_b32_e32 v128, v128, v129, vcc
	v_mul_f32_e64 v112, v112, v128
	v_mul_f32_e64 v113, v113, v128
	v_mul_f32_e64 v114, v114, v128
	v_mul_f32_e64 v115, v115, v128
	v_mul_f32_e64 v116, v116, v128
	v_mul_f32_e64 v117, v117, v128
	v_mul_f32_e64 v96, v96, v128
	v_mul_f32_e64 v97, v97, v128
	v_mul_f32_e64 v98, v98, v128
	v_mul_f32_e64 v99, v99, v128
	v_cvt_pk_bf16_f32 v112, v112, v113
	v_cvt_pk_bf16_f32 v113, v114, v115
	v_cvt_pk_bf16_f32 v114, v116, v117
	v_mul_f32_e64 v116, v118, v128
	v_mul_f32_e64 v117, v119, v128
	v_cvt_pk_bf16_f32 v96, v96, v97
	v_cvt_pk_bf16_f32 v97, v98, v99
	v_mul_f32_e64 v98, v100, v128
	v_mul_f32_e64 v99, v101, v128
	v_mul_f32_e64 v100, v102, v128
	v_mul_f32_e64 v101, v103, v128
	v_cvt_pk_bf16_f32 v115, v116, v117
	v_mul_f32_e64 v116, v120, v128
	v_mul_f32_e64 v117, v121, v128
	v_mul_f32_e64 v118, v122, v128
	v_mul_f32_e64 v119, v123, v128
	v_cvt_pk_bf16_f32 v98, v98, v99
	v_cvt_pk_bf16_f32 v99, v100, v101
	v_mul_f32_e64 v100, v104, v128
	v_mul_f32_e64 v101, v105, v128
	v_mul_f32_e64 v102, v106, v128
	v_mul_f32_e64 v103, v107, v128
	v_cvt_pk_bf16_f32 v116, v116, v117
	v_cvt_pk_bf16_f32 v117, v118, v119
	v_mul_f32_e64 v118, v124, v128
	v_mul_f32_e64 v119, v125, v128
	v_mul_f32_e64 v120, v126, v128
	v_mul_f32_e64 v121, v127, v128
	v_cvt_pk_bf16_f32 v100, v100, v101
	v_cvt_pk_bf16_f32 v101, v102, v103
	v_mul_f32_e64 v102, v108, v128
	v_mul_f32_e64 v103, v109, v128
	v_mul_f32_e64 v104, v110, v128
	v_mul_f32_e64 v105, v111, v128
	v_cvt_pk_bf16_f32 v118, v118, v119
	v_cvt_pk_bf16_f32 v119, v120, v121
	v_cvt_pk_bf16_f32 v102, v102, v103
	v_cvt_pk_bf16_f32 v103, v104, v105
	ds_write_b128 v218, v[112:115]
	ds_write_b128 v218, v[116:119] offset:16
	ds_write_b128 v218, v[96:99] offset:64
	ds_write_b128 v218, v[100:103] offset:80
	v_add_u32_e32 v98, s17, v207
	v_mov_b64_e32 v[96:97], s[28:29]
	v_mad_i64_i32 v[98:99], s[8:9], v98, s14, v[96:97]
	s_waitcnt lgkmcnt(0)
	v_lshl_add_u64 v[98:99], v[98:99], 0, s[6:7]
	v_lshl_add_u64 v[102:103], v[98:99], 0, v[168:169]
	ds_read_b128 v[98:101], v219
	v_lshl_add_u64 v[102:103], v[102:103], 0, v[186:187]
	v_lshl_add_u64 v[106:107], v[102:103], 0, v[190:191]
	ds_read_b128 v[102:105], v219 offset:1152
	s_waitcnt lgkmcnt(1)
	global_store_dwordx4 v[106:107], v[98:101], off
	s_nop 1
	v_add_co_u32_e32 v98, vcc, s15, v106
	s_nop 1
	v_addc_co_u32_e32 v99, vcc, 0, v107, vcc
	s_waitcnt lgkmcnt(0)
	global_store_dwordx4 v[98:99], v[102:105], off
	ds_read_b128 v[98:101], v219 offset:2304
	ds_read_b128 v[102:105], v219 offset:3456
	v_add_co_u32_e32 v108, vcc, s11, v106
	s_nop 1
	v_addc_co_u32_e32 v109, vcc, 0, v107, vcc
	s_waitcnt lgkmcnt(1)
	global_store_dwordx4 v[108:109], v[98:101], off
	s_nop 1
	v_add_co_u32_e32 v98, vcc, s2, v106
	s_nop 1
	v_addc_co_u32_e32 v99, vcc, 0, v107, vcc
	s_waitcnt lgkmcnt(0)
	global_store_dwordx4 v[98:99], v[102:105], off
	s_waitcnt lgkmcnt(0)
	ds_read_b32 v98, v214 offset:128
	s_waitcnt lgkmcnt(0)
	v_fmamk_f32 v98, v98, 0x3b2aaaab, v217
	v_mul_f32_e32 v99, 0x4b800000, v98
	v_cmp_gt_f32_e32 vcc, s13, v98
	s_nop 1
	v_cndmask_b32_e32 v98, v98, v99, vcc
	v_rsq_f32_e32 v98, v98
	s_nop 0
	v_mul_f32_e32 v99, 0x45800000, v98
	v_cndmask_b32_e32 v98, v98, v99, vcc
	v_mul_f32_e64 v80, v80, v98
	v_mul_f32_e64 v81, v81, v98
	v_mul_f32_e64 v82, v82, v98
	v_mul_f32_e64 v83, v83, v98
	v_mul_f32_e64 v64, v64, v98
	v_mul_f32_e64 v65, v65, v98
	v_mul_f32_e64 v66, v66, v98
	v_mul_f32_e64 v67, v67, v98
	v_cvt_pk_bf16_f32 v80, v80, v81
	v_cvt_pk_bf16_f32 v81, v82, v83
	v_mul_f32_e64 v82, v84, v98
	v_mul_f32_e64 v83, v85, v98
	v_mul_f32_e64 v84, v86, v98
	v_mul_f32_e64 v85, v87, v98
	v_cvt_pk_bf16_f32 v64, v64, v65
	v_cvt_pk_bf16_f32 v65, v66, v67
	v_mul_f32_e64 v66, v68, v98
	v_mul_f32_e64 v67, v69, v98
	v_mul_f32_e64 v68, v70, v98
	v_mul_f32_e64 v69, v71, v98
	v_cvt_pk_bf16_f32 v82, v82, v83
	v_cvt_pk_bf16_f32 v83, v84, v85
	v_mul_f32_e64 v84, v88, v98
	v_mul_f32_e64 v85, v89, v98
	v_mul_f32_e64 v86, v90, v98
	v_mul_f32_e64 v87, v91, v98
	v_cvt_pk_bf16_f32 v66, v66, v67
	v_cvt_pk_bf16_f32 v67, v68, v69
	v_mul_f32_e64 v68, v72, v98
	v_mul_f32_e64 v69, v73, v98
	v_mul_f32_e64 v70, v74, v98
	v_mul_f32_e64 v71, v75, v98
	v_cvt_pk_bf16_f32 v84, v84, v85
	v_cvt_pk_bf16_f32 v85, v86, v87
	v_mul_f32_e64 v86, v92, v98
	v_mul_f32_e64 v87, v93, v98
	v_mul_f32_e64 v88, v94, v98
	v_mul_f32_e64 v89, v95, v98
	v_cvt_pk_bf16_f32 v68, v68, v69
	v_cvt_pk_bf16_f32 v69, v70, v71
	v_mul_f32_e64 v70, v76, v98
	v_mul_f32_e64 v71, v77, v98
	v_mul_f32_e64 v72, v78, v98
	v_mul_f32_e64 v73, v79, v98
	v_cvt_pk_bf16_f32 v86, v86, v87
	v_cvt_pk_bf16_f32 v87, v88, v89
	v_cvt_pk_bf16_f32 v70, v70, v71
	v_cvt_pk_bf16_f32 v71, v72, v73
	ds_write_b128 v218, v[80:83]
	ds_write_b128 v218, v[84:87] offset:16
	ds_write_b128 v218, v[64:67] offset:64
	ds_write_b128 v218, v[68:71] offset:80
	v_add_u32_e32 v64, s17, v213
	v_mad_i64_i32 v[64:65], s[8:9], v64, s14, v[96:97]
	s_waitcnt lgkmcnt(0)
	v_lshl_add_u64 v[68:69], v[64:65], 0, s[6:7]
	ds_read_b128 v[64:67], v219
	v_lshl_add_u64 v[68:69], v[68:69], 0, v[168:169]
	v_lshl_add_u64 v[68:69], v[68:69], 0, v[186:187]
	v_lshl_add_u64 v[72:73], v[68:69], 0, v[190:191]
	ds_read_b128 v[68:71], v219 offset:1152
	s_waitcnt lgkmcnt(1)
;   __device__ __forceinline__ void operator()(int lrow, int nc, const f32x16& a0, const f32x16& a1, float aux) const {
;     const int lane = threadIdx.x & 63, wid = threadIdx.x >> 6, r32 = lane & 31, hi = lane >> 5;
;     float sc = 1.f;
;     if (invK > 0.f) sc = rsqrtf(aux * invK + 1e-6f);
;     char* sp = scr + wid * (32 * 144);
;     char* wp = sp + r32 * 144 + 32 * hi;
;     if (act) {
;     ...
;       const u32x4 w0 = {cvtpk(TANH_(a0[0]), TANH_(a0[1])), cvtpk(TANH_(a0[2]), TANH_(a0[3])), cvtpk(TANH_(a0[4]), TANH_(a0[5])), cvtpk(TANH_(a0[6]), TANH_(a0[7]))};
;       const u32x4 w1 = {cvtpk(TANH_(a0[8]), TANH_(a0[9])), cvtpk(TANH_(a0[10]), TANH_(a0[11])), cvtpk(TANH_(a0[12]), TANH_(a0[13])), cvtpk(TANH_(a0[14]), TANH_(a0[15]))};
;       const u32x4 w2 = {cvtpk(TANH_(a1[0]), TANH_(a1[1])), cvtpk(TANH_(a1[2]), TANH_(a1[3])), cvtpk(TANH_(a1[4]), TANH_(a1[5])), cvtpk(TANH_(a1[6]), TANH_(a1[7]))};
;       const u32x4 w3 = {cvtpk(TANH_(a1[8]), TANH_(a1[9])), cvtpk(TANH_(a1[10]), TANH_(a1[11])), cvtpk(TANH_(a1[12]), TANH_(a1[13])), cvtpk(TANH_(a1[14]), TANH_(a1[15]))};
;     ...
;       *(u32x4*)(wp) = w0; *(u32x4*)(wp + 16) = w1; *(u32x4*)(wp + 64) = w2; *(u32x4*)(wp + 80) = w3;
;     } else {
;       const u32x4 w0 = {cvtpk(a0[0] * sc, a0[1] * sc), cvtpk(a0[2] * sc, a0[3] * sc), cvtpk(a0[4] * sc, a0[5] * sc), cvtpk(a0[6] * sc, a0[7] * sc)};
;       const u32x4 w1 = {cvtpk(a0[8] * sc, a0[9] * sc), cvtpk(a0[10] * sc, a0[11] * sc), cvtpk(a0[12] * sc, a0[13] * sc), cvtpk(a0[14] * sc, a0[15] * sc)};
;       const u32x4 w2 = {cvtpk(a1[0] * sc, a1[1] * sc), cvtpk(a1[2] * sc, a1[3] * sc), cvtpk(a1[4] * sc, a1[5] * sc), cvtpk(a1[6] * sc, a1[7] * sc)};
;       const u32x4 w3 = {cvtpk(a1[8] * sc, a1[9] * sc), cvtpk(a1[10] * sc, a1[11] * sc), cvtpk(a1[12] * sc, a1[13] * sc), cvtpk(a1[14] * sc, a1[15] * sc)};
;       *(u32x4*)(wp) = w0; *(u32x4*)(wp + 16) = w1; *(u32x4*)(wp + 64) = w2; *(u32x4*)(wp + 80) = w3;
;     }
;     asm volatile("s_waitcnt lgkmcnt(0)" ::: "memory");
;     bf16_t* gp = dst + (size_t)(m0 + lrow - r32) * ldd + col0 + (nc & ~7) + (lane & 7) * 8;
; #pragma unroll
;     for (int i = 0; i < 4; ++i) {
;       const int row = (lane >> 3) + 8 * i;
;       *(u32x4*)(gp + (size_t)row * ldd) = *(const u32x4*)(sp + row * 144 + (lane & 7) * 16);
;     }
;     asm volatile("s_waitcnt lgkmcnt(0)" ::: "memory");
	global_store_dwordx4 v[72:73], v[64:67], off
	s_nop 1
	v_add_co_u32_e32 v64, vcc, s15, v72
	s_nop 1
	v_addc_co_u32_e32 v65, vcc, 0, v73, vcc
	s_waitcnt lgkmcnt(0)
	global_store_dwordx4 v[64:65], v[68:71], off
	ds_read_b128 v[64:67], v219 offset:2304
	ds_read_b128 v[68:71], v219 offset:3456
	v_add_co_u32_e32 v74, vcc, s11, v72
	s_nop 1
	v_addc_co_u32_e32 v75, vcc, 0, v73, vcc
	s_waitcnt lgkmcnt(1)
	global_store_dwordx4 v[74:75], v[64:67], off
	s_nop 1
	v_add_co_u32_e32 v64, vcc, s2, v72
	s_nop 1
	v_addc_co_u32_e32 v65, vcc, 0, v73, vcc
	s_waitcnt lgkmcnt(0)
	global_store_dwordx4 v[64:65], v[68:71], off
	s_waitcnt lgkmcnt(0)
	ds_read_b32 v64, v214 offset:256
	s_waitcnt lgkmcnt(0)
	v_fmamk_f32 v64, v64, 0x3b2aaaab, v217
	v_mul_f32_e32 v65, 0x4b800000, v64
	v_cmp_gt_f32_e32 vcc, s13, v64
	s_nop 1
	v_cndmask_b32_e32 v64, v64, v65, vcc
	v_rsq_f32_e32 v64, v64
	s_nop 0
	v_mul_f32_e32 v65, 0x45800000, v64
	v_cndmask_b32_e32 v64, v64, v65, vcc
	v_mul_f32_e64 v48, v48, v64
	v_mul_f32_e64 v49, v49, v64
	v_mul_f32_e64 v50, v50, v64
	v_mul_f32_e64 v51, v51, v64
	v_mul_f32_e64 v32, v32, v64
	v_mul_f32_e64 v33, v33, v64
	v_mul_f32_e64 v34, v34, v64
	v_mul_f32_e64 v35, v35, v64
	v_cvt_pk_bf16_f32 v48, v48, v49
	v_cvt_pk_bf16_f32 v49, v50, v51
	v_mul_f32_e64 v50, v52, v64
	v_mul_f32_e64 v51, v53, v64
	v_mul_f32_e64 v52, v54, v64
	v_mul_f32_e64 v53, v55, v64
	v_cvt_pk_bf16_f32 v32, v32, v33
	v_cvt_pk_bf16_f32 v33, v34, v35
	v_mul_f32_e64 v34, v36, v64
	v_mul_f32_e64 v35, v37, v64
	v_mul_f32_e64 v36, v38, v64
	v_mul_f32_e64 v37, v39, v64
	v_cvt_pk_bf16_f32 v50, v50, v51
	v_cvt_pk_bf16_f32 v51, v52, v53
	v_mul_f32_e64 v52, v56, v64
	v_mul_f32_e64 v53, v57, v64
	v_mul_f32_e64 v54, v58, v64
	v_mul_f32_e64 v55, v59, v64
	v_cvt_pk_bf16_f32 v34, v34, v35
	v_cvt_pk_bf16_f32 v35, v36, v37
	v_mul_f32_e64 v36, v40, v64
	v_mul_f32_e64 v37, v41, v64
	v_mul_f32_e64 v38, v42, v64
	v_mul_f32_e64 v39, v43, v64
	v_cvt_pk_bf16_f32 v52, v52, v53
	v_cvt_pk_bf16_f32 v53, v54, v55
	v_mul_f32_e64 v54, v60, v64
	v_mul_f32_e64 v55, v61, v64
	v_mul_f32_e64 v56, v62, v64
	v_mul_f32_e64 v57, v63, v64
	v_cvt_pk_bf16_f32 v36, v36, v37
	v_cvt_pk_bf16_f32 v37, v38, v39
	v_mul_f32_e64 v38, v44, v64
	v_mul_f32_e64 v39, v45, v64
	v_mul_f32_e64 v40, v46, v64
	v_mul_f32_e64 v41, v47, v64
	v_cvt_pk_bf16_f32 v54, v54, v55
	v_cvt_pk_bf16_f32 v55, v56, v57
	v_cvt_pk_bf16_f32 v38, v38, v39
	v_cvt_pk_bf16_f32 v39, v40, v41
	ds_write_b128 v218, v[48:51]
	ds_write_b128 v218, v[52:55] offset:16
	ds_write_b128 v218, v[32:35] offset:64
	ds_write_b128 v218, v[36:39] offset:80
	v_add_u32_e32 v32, s17, v215
	v_mad_i64_i32 v[32:33], s[8:9], v32, s14, v[96:97]
	s_waitcnt lgkmcnt(0)
	v_lshl_add_u64 v[36:37], v[32:33], 0, s[6:7]
	ds_read_b128 v[32:35], v219
	v_lshl_add_u64 v[36:37], v[36:37], 0, v[168:169]
	v_lshl_add_u64 v[36:37], v[36:37], 0, v[186:187]
	v_lshl_add_u64 v[40:41], v[36:37], 0, v[190:191]
	ds_read_b128 v[36:39], v219 offset:1152
	s_waitcnt lgkmcnt(1)
	global_store_dwordx4 v[40:41], v[32:35], off
	s_nop 1
	v_add_co_u32_e32 v32, vcc, s15, v40
	s_nop 1
	v_addc_co_u32_e32 v33, vcc, 0, v41, vcc
	s_waitcnt lgkmcnt(0)
	global_store_dwordx4 v[32:33], v[36:39], off
	ds_read_b128 v[32:35], v219 offset:2304
	ds_read_b128 v[36:39], v219 offset:3456
	v_add_co_u32_e32 v42, vcc, s11, v40
	s_nop 1
	v_addc_co_u32_e32 v43, vcc, 0, v41, vcc
	s_waitcnt lgkmcnt(1)
	global_store_dwordx4 v[42:43], v[32:35], off
	s_nop 1
	v_add_co_u32_e32 v32, vcc, s2, v40
	s_nop 1
	v_addc_co_u32_e32 v33, vcc, 0, v41, vcc
	s_waitcnt lgkmcnt(0)
	global_store_dwordx4 v[32:33], v[36:39], off
	s_waitcnt lgkmcnt(0)
	ds_read_b32 v32, v214 offset:384
	s_waitcnt lgkmcnt(0)
	v_fmamk_f32 v32, v32, 0x3b2aaaab, v217
	v_mul_f32_e32 v33, 0x4b800000, v32
	v_cmp_gt_f32_e32 vcc, s13, v32
	s_nop 1
	v_cndmask_b32_e32 v32, v32, v33, vcc
	v_rsq_f32_e32 v32, v32
	s_nop 0
	v_mul_f32_e32 v33, 0x45800000, v32
	v_cndmask_b32_e32 v32, v32, v33, vcc
	v_mul_f32_e64 v16, v16, v32
	v_mul_f32_e64 v17, v17, v32
	v_mul_f32_e64 v18, v18, v32
	v_mul_f32_e64 v19, v19, v32
	v_mul_f32_e64 v0, v0, v32
	v_mul_f32_e64 v1, v1, v32
	v_mul_f32_e64 v2, v2, v32
	v_mul_f32_e64 v3, v3, v32
	v_cvt_pk_bf16_f32 v16, v16, v17
	v_cvt_pk_bf16_f32 v17, v18, v19
	v_mul_f32_e64 v18, v20, v32
	v_mul_f32_e64 v19, v21, v32
	v_mul_f32_e64 v20, v22, v32
	v_mul_f32_e64 v21, v23, v32
	v_cvt_pk_bf16_f32 v0, v0, v1
	v_cvt_pk_bf16_f32 v1, v2, v3
	v_mul_f32_e64 v2, v4, v32
	v_mul_f32_e64 v3, v5, v32
	v_mul_f32_e64 v4, v6, v32
	v_mul_f32_e64 v5, v7, v32
	v_cvt_pk_bf16_f32 v18, v18, v19
	v_cvt_pk_bf16_f32 v19, v20, v21
	v_mul_f32_e64 v20, v24, v32
	v_mul_f32_e64 v21, v25, v32
	v_mul_f32_e64 v22, v26, v32
	v_mul_f32_e64 v23, v27, v32
	v_cvt_pk_bf16_f32 v2, v2, v3
	v_cvt_pk_bf16_f32 v3, v4, v5
	v_mul_f32_e64 v4, v8, v32
	v_mul_f32_e64 v5, v9, v32
	v_mul_f32_e64 v6, v10, v32
	v_mul_f32_e64 v7, v11, v32
	v_cvt_pk_bf16_f32 v20, v20, v21
	v_cvt_pk_bf16_f32 v21, v22, v23
	v_mul_f32_e64 v22, v28, v32
	v_mul_f32_e64 v23, v29, v32
	v_mul_f32_e64 v24, v30, v32
	v_mul_f32_e64 v25, v31, v32
	v_cvt_pk_bf16_f32 v4, v4, v5
	v_cvt_pk_bf16_f32 v5, v6, v7
	v_mul_f32_e64 v6, v12, v32
	v_mul_f32_e64 v7, v13, v32
	v_mul_f32_e64 v8, v14, v32
	v_mul_f32_e64 v9, v15, v32
	v_cvt_pk_bf16_f32 v22, v22, v23
	v_cvt_pk_bf16_f32 v23, v24, v25
	v_cvt_pk_bf16_f32 v6, v6, v7
	v_cvt_pk_bf16_f32 v7, v8, v9
	ds_write_b128 v218, v[16:19]
	ds_write_b128 v218, v[20:23] offset:16
	ds_write_b128 v218, v[0:3] offset:64
	ds_write_b128 v218, v[4:7] offset:80
	v_add_u32_e32 v0, s17, v216
	v_mad_i64_i32 v[0:1], s[8:9], v0, s14, v[96:97]
	s_waitcnt lgkmcnt(0)
	v_lshl_add_u64 v[4:5], v[0:1], 0, s[6:7]
	ds_read_b128 v[0:3], v219
	v_lshl_add_u64 v[4:5], v[4:5], 0, v[168:169]
	v_lshl_add_u64 v[4:5], v[4:5], 0, v[186:187]
	v_lshl_add_u64 v[8:9], v[4:5], 0, v[190:191]
	ds_read_b128 v[4:7], v219 offset:1152
	s_waitcnt lgkmcnt(1)
	global_store_dwordx4 v[8:9], v[0:3], off
	s_cselect_b64 s[8:9], -1, 0
	s_nop 0
	v_add_co_u32_e32 v0, vcc, 0x6000, v8
	s_nop 1
	v_addc_co_u32_e32 v1, vcc, 0, v9, vcc
	s_waitcnt lgkmcnt(0)
	global_store_dwordx4 v[0:1], v[4:7], off
	ds_read_b128 v[0:3], v219 offset:2304
	ds_read_b128 v[4:7], v219 offset:3456
	v_add_co_u32_e32 v10, vcc, 0xc000, v8
	s_nop 1
	v_addc_co_u32_e32 v11, vcc, 0, v9, vcc
	s_waitcnt lgkmcnt(1)
	global_store_dwordx4 v[10:11], v[0:3], off
	s_nop 1
	v_add_co_u32_e32 v0, vcc, 0x12000, v8
	s_nop 1
	v_addc_co_u32_e32 v1, vcc, 0, v9, vcc
	s_waitcnt lgkmcnt(0)
	global_store_dwordx4 v[0:1], v[4:7], off
	s_waitcnt lgkmcnt(0)
	s_and_b64 vcc, exec, s[8:9]
	s_cselect_b32 s6, s33, 0
	s_add_i32 s8, s6, s16
	s_cbranch_vccz .LBB0_964
; template <int AMODE, int BN, class Epi>
; __device__ __forceinline__ void gemm_tile(const bf16_t* A, const int lda, const bf16_t* Bt, const int K, const int m0, const float* mu, char* lds, const Epi& epi) {
;     ...
;   auto gload = [&](int k0) {
; #pragma unroll
;     for (int i = 0; i < 4; ++i) {
;       const bf16_t* ap = A + (size_t)(m0 + srow + 64 * i) * lda + k0 + scc;
;       ra[i] = *(const bf16x8*)ap;
;       if constexpr (AMODE == 1) { rp[i] = *(const bf16x8*)(ap - dprev[i] * lda); rn[i] = *(const bf16x8*)(ap + dnext[i] * lda); }
;     }
; #pragma unroll
;     for (int i = 0; i < NBR; ++i) rb[i] = *(const bf16x8*)(Bt + (size_t)browi[i] * K + k0 + scc);
;   };
;     ...
;   const int nk = K >> 6;
;   gload(0);
;   lstore(0, 0);
;   if (nk > 1) gload(64);
;   __syncthreads();
; __global__ __launch_bounds__(NTHR, 1) void fwd_megakernel(Params p) {
;     ...
;       {
;         int mt2, nt; tile_mn(o, 6, mt2, nt);
;         const int b = mt2 >> 5, m0 = b * TL + (mt2 & 31) * 256;
;         e.dst = (bf16_t*)(ws + OFF_Q); e.ldd = 1536; e.col0 = nt * 256; e.m0 = m0; e.invK = 1.f / 384.f;
;         gemm_tile<2, 256>((const bf16_t*)(ws + OFF_QC), 384, WQ + (size_t)nt * 256 * 384, 384, m0, nullptr, lds, e);
.LBB0_950:
	s_add_i32 s6, s16, s0
	s_mul_hi_u32 s9, s6, 0xaaaaaaab
	s_lshr_b32 s17, s9, 7
	s_lshl_b32 s9, s9, 6
	s_lshl_b32 s16, s16, 8
	s_and_b32 s16, s16, 0x700
	s_and_b32 s9, s9, 0x1800
	s_mulk_i32 s17, 0x2100
	s_or_b32 s9, s9, s16
	s_add_i32 s17, s9, s17
	v_or_b32_e32 v54, s17, v161
	v_add_u32_e32 v55, 64, v54
	s_lshr_b32 s6, s6, 3
	v_mad_u64_u32 v[32:33], s[18:19], v54, s10, v[172:173]
	v_mad_u64_u32 v[34:35], s[18:19], v55, s10, v[172:173]
	v_or_b32_e32 v56, 0x80, v54
	v_add_u32_e32 v57, 0xc0, v54
	s_mul_hi_u32 s9, s6, 0x2aaaaaab
	global_load_dwordx4 v[0:3], v[32:33], off
	global_load_dwordx4 v[4:7], v[34:35], off
	v_mad_u64_u32 v[36:37], s[18:19], v56, s10, v[172:173]
	v_mad_i64_i32 v[38:39], s[18:19], v57, s10, v[172:173]
	s_mul_i32 s9, s9, 6
	global_load_dwordx4 v[8:11], v[36:37], off
	global_load_dwordx4 v[12:15], v[38:39], off
	s_sub_i32 s18, s6, s9
	s_mul_i32 s6, s18, 0x30000
	v_lshl_add_u64 v[16:17], v[170:171], 0, s[6:7]
	v_lshl_add_u64 v[40:41], v[16:17], 0, v[188:189]
	v_add_co_u32_e32 v42, vcc, s11, v40
	global_load_dwordx4 v[16:19], v[40:41], off
	s_nop 0
	v_addc_co_u32_e32 v43, vcc, 0, v41, vcc
	v_add_co_u32_e32 v44, vcc, s12, v40
	s_mov_b32 s16, s8
	s_nop 0
	v_addc_co_u32_e32 v45, vcc, 0, v41, vcc
	v_add_co_u32_e32 v46, vcc, s1, v40
	global_load_dwordx4 v[20:23], v[42:43], off
	global_load_dwordx4 v[24:27], v[44:45], off
	v_addc_co_u32_e32 v47, vcc, 0, v41, vcc
	global_load_dwordx4 v[28:31], v[46:47], off
	global_load_dwordx4 v[128:131], v[32:33], off offset:128
	global_load_dwordx4 v[132:135], v[34:35], off offset:128
	global_load_dwordx4 v[136:139], v[36:37], off offset:128
	global_load_dwordx4 v[140:143], v[38:39], off offset:128
	global_load_dwordx4 v[144:147], v[40:41], off offset:128
	global_load_dwordx4 v[148:151], v[42:43], off offset:128
	global_load_dwordx4 v[152:155], v[44:45], off offset:128
	global_load_dwordx4 v[156:159], v[46:47], off offset:128
	v_mad_i64_i32 v[198:199], s[8:9], v57, s10, v[184:185]
	v_mad_u64_u32 v[200:201], s[8:9], v56, s10, v[184:185]
	v_mad_u64_u32 v[202:203], s[8:9], v55, s10, v[184:185]
	v_mad_u64_u32 v[204:205], s[8:9], v54, s10, v[184:185]
	v_lshl_add_u64 v[196:197], v[174:175], 0, s[6:7]
	s_mov_b64 s[8:9], 0
	s_mov_b32 s6, 0
	v_mov_b32_e32 v40, v169
	v_mov_b32_e32 v41, v169
	v_mov_b32_e32 v42, v169
	v_mov_b32_e32 v43, v169
	v_mov_b32_e32 v44, v169
	v_mov_b32_e32 v45, v169
	v_mov_b32_e32 v46, v169
	v_mov_b32_e32 v47, v169
	v_mov_b32_e32 v54, v169
	v_mov_b32_e32 v55, v169
	v_mov_b32_e32 v56, v169
	v_mov_b32_e32 v57, v169
	s_waitcnt vmcnt(21)
	v_mov_b32_e32 v58, v169
	v_mov_b32_e32 v59, v169
	v_mov_b32_e32 v60, v169
	v_mov_b32_e32 v61, v169
	s_waitcnt vmcnt(20)
	v_mov_b32_e32 v62, v169
	v_mov_b32_e32 v63, v169
	v_mov_b32_e32 v64, 0
	v_mov_b32_e32 v65, v169
	s_waitcnt vmcnt(19)
	v_mov_b32_e32 v66, v169
	v_mov_b32_e32 v67, v169
	v_mov_b32_e32 v68, v169
	v_mov_b32_e32 v69, v169
	s_waitcnt vmcnt(18)
	v_mov_b32_e32 v70, v169
	v_mov_b32_e32 v71, v169
	v_mov_b32_e32 v72, v169
	v_mov_b32_e32 v73, v169
	v_mov_b32_e32 v74, v169
	v_mov_b32_e32 v75, v169
	v_mov_b32_e32 v76, v169
	v_mov_b32_e32 v77, v169
	v_mov_b32_e32 v78, v169
	v_mov_b32_e32 v79, v169
	v_mov_b32_e32 v80, 0
	s_waitcnt vmcnt(15)
	ds_write_b128 v206, v[0:3]
	v_lshlrev_b32_e32 v32, 16, v0
	v_and_b32_e32 v0, 0xffff0000, v0
	v_lshlrev_b32_e32 v34, 16, v1
	v_and_b32_e32 v36, 0xffff0000, v1
	s_waitcnt vmcnt(14)
	v_and_b32_e32 v1, 0xffff0000, v4
	v_and_b32_e32 v37, 0xffff0000, v5
	v_lshlrev_b32_e32 v38, 16, v2
	v_and_b32_e32 v2, 0xffff0000, v2
	v_lshlrev_b32_e32 v48, 16, v3
	v_and_b32_e32 v50, 0xffff0000, v3
	ds_write_b128 v206, v[4:7] offset:9216
	v_lshlrev_b32_e32 v33, 16, v4
	v_lshlrev_b32_e32 v35, 16, v5
	v_lshlrev_b32_e32 v39, 16, v6
	v_and_b32_e32 v3, 0xffff0000, v6
	v_lshlrev_b32_e32 v49, 16, v7
	v_and_b32_e32 v51, 0xffff0000, v7
	s_waitcnt vmcnt(13)
	ds_write_b128 v206, v[8:11] offset:18432
	v_lshlrev_b32_e32 v4, 16, v8
	v_and_b32_e32 v6, 0xffff0000, v8
	v_lshlrev_b32_e32 v8, 16, v9
	v_and_b32_e32 v52, 0xffff0000, v9
	s_waitcnt vmcnt(12)
; __device__ __forceinline__ float lo16(unsigned w) { return __uint_as_float(w << 16); }
; __device__ __forceinline__ float hi16(unsigned w) { return __uint_as_float(w & 0xffff0000u); }
; template <int AMODE, int BN, class Epi>
; __device__ __forceinline__ void gemm_tile(const bf16_t* A, const int lda, const bf16_t* Bt, const int K, const int m0, const float* mu, char* lds, const Epi& epi) {
;     ...
; #pragma unroll
;   for (int i = 0; i < MI; ++i)
; #pragma unroll
;     for (int j = 0; j < 2; ++j)
; #pragma unroll
;       for (int r = 0; r < 16; ++r) acc[i][j][r] = 0.f;
;     ...
; #pragma unroll
;       for (int i = 0; i < 4; ++i) {
;         *(bf16x8*)(base + (srow + 64 * i) * G_LDT + scc * 2) = ra[i];
;         if constexpr (AMODE == 2) {
;           const u32x4 hc = *(const u32x4*)&ra[i];
; #pragma unroll
;           for (int q = 0; q < 4; ++q) { const float c0 = lo16(hc[q]), c1 = hi16(hc[q]); ssq[i] += c0 * c0 + c1 * c1; }
;         }
;       }
;     ...
;   __syncthreads();
	ds_write_b128 v206, v[12:15] offset:27648
	v_lshlrev_b32_e32 v5, 16, v12
	v_and_b32_e32 v7, 0xffff0000, v12
	v_lshlrev_b32_e32 v9, 16, v13
	v_and_b32_e32 v53, 0xffff0000, v13
	v_mul_f32_e64 v0, v0, v0
	v_mul_f32_e64 v1, v1, v1
	v_mul_f32_e64 v12, v36, v36
	v_mul_f32_e64 v13, v37, v37
	v_mul_f32_e64 v2, v2, v2
	v_mul_f32_e64 v3, v3, v3
	v_fma_f32 v0, v32, v32, v0
	v_fma_f32 v1, v33, v33, v1
	v_fma_f32 v12, v34, v34, v12
	v_fma_f32 v13, v35, v35, v13
	v_mul_f32_e64 v36, v50, v50
	v_mul_f32_e64 v37, v51, v51
	v_fma_f32 v2, v38, v38, v2
	v_fma_f32 v3, v39, v39, v3
	v_add_f32_e64 v0, v12, v0
	v_add_f32_e64 v1, v13, v1
	v_fma_f32 v32, v48, v48, v36
	v_fma_f32 v33, v49, v49, v37
	v_add_f32_e64 v0, v2, v0
	v_add_f32_e64 v1, v3, v1
	v_mul_f32_e64 v6, v6, v6
	v_mul_f32_e64 v7, v7, v7
	v_add_f32_e64 v194, v32, v0
	v_add_f32_e64 v195, v33, v1
	v_mul_f32_e64 v0, v52, v52
	v_mul_f32_e64 v1, v53, v53
	v_fma_f32 v4, v4, v4, v6
	v_fma_f32 v5, v5, v5, v7
	v_fma_f32 v0, v8, v8, v0
	v_fma_f32 v1, v9, v9, v1
	v_lshlrev_b32_e32 v3, 16, v14
	v_add_f32_e64 v0, v0, v4
	v_add_f32_e64 v1, v1, v5
	v_and_b32_e32 v5, 0xffff0000, v14
	v_and_b32_e32 v4, 0xffff0000, v10
	v_lshlrev_b32_e32 v2, 16, v10
	v_mul_f32_e64 v4, v4, v4
	v_mul_f32_e64 v5, v5, v5
	s_waitcnt vmcnt(11)
	ds_write_b128 v206, v[16:19] offset:36864
	v_fma_f32 v2, v2, v2, v4
	v_fma_f32 v3, v3, v3, v5
	v_and_b32_e32 v5, 0xffff0000, v15
	v_and_b32_e32 v4, 0xffff0000, v11
	v_add_f32_e64 v0, v2, v0
	v_add_f32_e64 v1, v3, v1
	v_lshlrev_b32_e32 v3, 16, v15
	v_lshlrev_b32_e32 v2, 16, v11
	v_mul_f32_e64 v4, v4, v4
	v_mul_f32_e64 v5, v5, v5
	s_waitcnt vmcnt(10)
	ds_write_b128 v206, v[20:23] offset:46080
	v_fma_f32 v2, v2, v2, v4
	v_fma_f32 v3, v3, v3, v5
	s_waitcnt vmcnt(9)
	ds_write_b128 v206, v[24:27] offset:55296
	v_add_f32_e64 v192, v2, v0
	v_add_f32_e64 v193, v3, v1
	s_waitcnt vmcnt(8)
	ds_write_b128 v206, v[28:31] offset:64512
	v_mov_b32_e32 v0, 0
	v_mov_b32_e32 v1, v169
	v_mov_b32_e32 v2, v169
	v_mov_b32_e32 v3, v169
	v_mov_b32_e32 v4, v169
	v_mov_b32_e32 v5, v169
	v_mov_b32_e32 v6, v169
	v_mov_b32_e32 v7, v169
	v_mov_b32_e32 v8, v169
	v_mov_b32_e32 v9, v169
	v_mov_b32_e32 v10, v169
	v_mov_b32_e32 v11, v169
	v_mov_b32_e32 v12, v169
	v_mov_b32_e32 v13, v169
	v_mov_b32_e32 v14, v169
	v_mov_b32_e32 v15, v169
	v_mov_b32_e32 v16, 0
	v_mov_b32_e32 v17, v169
	v_mov_b32_e32 v18, v169
	v_mov_b32_e32 v19, v169
	v_mov_b32_e32 v20, v169
	v_mov_b32_e32 v21, v169
	v_mov_b32_e32 v22, v169
	v_mov_b32_e32 v23, v169
	v_mov_b32_e32 v24, v169
	v_mov_b32_e32 v25, v169
	v_mov_b32_e32 v26, v169
	v_mov_b32_e32 v27, v169
	v_mov_b32_e32 v28, v169
	v_mov_b32_e32 v29, v169
	v_mov_b32_e32 v30, v169
	v_mov_b32_e32 v31, v169
	v_mov_b32_e32 v32, 0
	v_mov_b32_e32 v33, v169
	v_mov_b32_e32 v34, v169
	v_mov_b32_e32 v35, v169
	v_mov_b32_e32 v36, v169
	v_mov_b32_e32 v37, v169
	v_mov_b32_e32 v38, v169
	v_mov_b32_e32 v39, v169
	v_mov_b32_e32 v48, 0
	v_mov_b32_e32 v49, v169
	v_mov_b32_e32 v50, v169
	v_mov_b32_e32 v51, v169
	v_mov_b32_e32 v52, v169
	v_mov_b32_e32 v53, v169
	v_mov_b32_e32 v81, v169
	v_mov_b32_e32 v82, v169
	v_mov_b32_e32 v83, v169
	v_mov_b32_e32 v84, v169
	v_mov_b32_e32 v85, v169
	v_mov_b32_e32 v86, v169
	v_mov_b32_e32 v87, v169
	v_mov_b32_e32 v88, v169
	v_mov_b32_e32 v89, v169
	v_mov_b32_e32 v90, v169
	v_mov_b32_e32 v91, v169
	v_mov_b32_e32 v92, v169
	v_mov_b32_e32 v93, v169
	v_mov_b32_e32 v94, v169
	v_mov_b32_e32 v95, v169
	v_mov_b32_e32 v96, 0
	v_mov_b32_e32 v97, v169
	v_mov_b32_e32 v98, v169
	v_mov_b32_e32 v99, v169
	v_mov_b32_e32 v100, v169
	v_mov_b32_e32 v101, v169
	v_mov_b32_e32 v102, v169
	v_mov_b32_e32 v103, v169
	v_mov_b32_e32 v104, v169
	v_mov_b32_e32 v105, v169
	v_mov_b32_e32 v106, v169
	v_mov_b32_e32 v107, v169
	v_mov_b32_e32 v108, v169
	v_mov_b32_e32 v109, v169
	v_mov_b32_e32 v110, v169
	v_mov_b32_e32 v111, v169
	v_mov_b32_e32 v112, 0
	v_mov_b32_e32 v113, v169
	v_mov_b32_e32 v114, v169
	v_mov_b32_e32 v115, v169
	v_mov_b32_e32 v116, v169
	v_mov_b32_e32 v117, v169
	v_mov_b32_e32 v118, v169
	v_mov_b32_e32 v119, v169
	v_mov_b32_e32 v120, v169
	v_mov_b32_e32 v121, v169
	v_mov_b32_e32 v122, v169
	v_mov_b32_e32 v123, v169
	v_mov_b32_e32 v124, v169
	v_mov_b32_e32 v125, v169
	v_mov_b32_e32 v126, v169
	v_mov_b32_e32 v127, v169
	s_waitcnt lgkmcnt(0)
	s_barrier
	s_branch .LBB0_952

; __device__ __forceinline__ float lo16(unsigned w) { return __uint_as_float(w << 16); }
; __device__ __forceinline__ float hi16(unsigned w) { return __uint_as_float(w & 0xffff0000u); }
; template <int AMODE, int BN, class Epi>
; __device__ __forceinline__ void gemm_tile(const bf16_t* A, const int lda, const bf16_t* Bt, const int K, const int m0, const float* mu, char* lds, const Epi& epi) {
;     ...
; #pragma unroll
;       for (int i = 0; i < 4; ++i) {
;         *(bf16x8*)(base + (srow + 64 * i) * G_LDT + scc * 2) = ra[i];
;         if constexpr (AMODE == 2) {
;           const u32x4 hc = *(const u32x4*)&ra[i];
; #pragma unroll
;           for (int q = 0; q < 4; ++q) { const float c0 = lo16(hc[q]), c1 = hi16(hc[q]); ssq[i] += c0 * c0 + c1 * c1; }
;         }
;       }
;     ...
;   for (int kt = 0; kt < nk; ++kt) {
;     const int s = kt & 1;
;     if (kt + 1 < nk) lstore(s ^ 1, (kt + 1) * 64);
.LBB0_952:
	s_and_b32 s19, s6, 1
	s_cmp_gt_u32 s6, 4
	s_cbranch_scc1 .LBB0_954
	s_waitcnt vmcnt(6)
	v_and_b32_e32 v223, 0xffff0000, v132
	v_and_b32_e32 v222, 0xffff0000, v128
	v_lshlrev_b32_e32 v221, 16, v132
	v_lshlrev_b32_e32 v220, 16, v128
	v_mul_f32_e64 v222, v222, v222
	v_mul_f32_e64 v223, v223, v223
	s_xor_b32 s20, s19, 1
	v_fma_f32 v220, v220, v220, v222
	v_fma_f32 v221, v221, v221, v223
	v_and_b32_e32 v223, 0xffff0000, v133
	v_and_b32_e32 v222, 0xffff0000, v129
	v_add_f32_e64 v194, v194, v220
	v_add_f32_e64 v195, v195, v221
	v_lshlrev_b32_e32 v221, 16, v133
	v_lshlrev_b32_e32 v220, 16, v129
	v_mul_f32_e64 v222, v222, v222
	v_mul_f32_e64 v223, v223, v223
	s_mul_i32 s20, s20, 0x12000
	v_fma_f32 v220, v220, v220, v222
	v_fma_f32 v221, v221, v221, v223
	v_and_b32_e32 v223, 0xffff0000, v134
	v_and_b32_e32 v222, 0xffff0000, v130
	v_add_f32_e64 v194, v220, v194
	v_add_f32_e64 v195, v221, v195
	v_lshlrev_b32_e32 v221, 16, v134
	v_lshlrev_b32_e32 v220, 16, v130
	v_mul_f32_e64 v222, v222, v222
	v_mul_f32_e64 v223, v223, v223
	v_add_u32_e32 v187, s20, v206
	v_fma_f32 v220, v220, v220, v222
	v_fma_f32 v221, v221, v221, v223
	v_and_b32_e32 v223, 0xffff0000, v135
	v_and_b32_e32 v222, 0xffff0000, v131
	v_add_f32_e64 v194, v220, v194
	v_add_f32_e64 v195, v221, v195
	v_lshlrev_b32_e32 v221, 16, v135
	v_lshlrev_b32_e32 v220, 16, v131
	v_mul_f32_e64 v222, v222, v222
	v_mul_f32_e64 v223, v223, v223
	ds_write_b128 v187, v[128:131]
	ds_write_b128 v187, v[132:135] offset:9216
	v_fma_f32 v220, v220, v220, v222
	v_fma_f32 v221, v221, v221, v223
	s_waitcnt vmcnt(4)
	v_and_b32_e32 v223, 0xffff0000, v140
	v_and_b32_e32 v222, 0xffff0000, v136
	v_add_f32_e64 v194, v220, v194
	v_add_f32_e64 v195, v221, v195
	v_lshlrev_b32_e32 v221, 16, v140
	v_lshlrev_b32_e32 v220, 16, v136
	v_mul_f32_e64 v222, v222, v222
	v_mul_f32_e64 v223, v223, v223
	ds_write_b128 v187, v[136:139] offset:18432
	ds_write_b128 v187, v[140:143] offset:27648
	v_fma_f32 v220, v220, v220, v222
	v_fma_f32 v221, v221, v221, v223
	v_and_b32_e32 v223, 0xffff0000, v141
	v_and_b32_e32 v222, 0xffff0000, v137
	v_add_f32_e64 v192, v192, v220
	v_add_f32_e64 v193, v193, v221
	v_lshlrev_b32_e32 v221, 16, v141
	v_lshlrev_b32_e32 v220, 16, v137
	v_mul_f32_e64 v222, v222, v222
	v_mul_f32_e64 v223, v223, v223
	s_waitcnt vmcnt(3)
	ds_write_b128 v187, v[144:147] offset:36864
	s_waitcnt vmcnt(2)
	ds_write_b128 v187, v[148:151] offset:46080
	s_waitcnt vmcnt(1)
	ds_write_b128 v187, v[152:155] offset:55296
	s_waitcnt vmcnt(0)
	ds_write_b128 v187, v[156:159] offset:64512
	v_fma_f32 v220, v220, v220, v222
	v_fma_f32 v221, v221, v221, v223
	v_and_b32_e32 v223, 0xffff0000, v142
	v_and_b32_e32 v222, 0xffff0000, v138
	v_add_f32_e64 v192, v220, v192
	v_add_f32_e64 v193, v221, v193
	v_lshlrev_b32_e32 v221, 16, v142
	v_lshlrev_b32_e32 v220, 16, v138
	v_mul_f32_e64 v222, v222, v222
	v_mul_f32_e64 v223, v223, v223
	s_nop 0
	v_fma_f32 v220, v220, v220, v222
	v_fma_f32 v221, v221, v221, v223
	v_and_b32_e32 v223, 0xffff0000, v143
	v_and_b32_e32 v222, 0xffff0000, v139
	v_add_f32_e64 v192, v220, v192
	v_add_f32_e64 v193, v221, v193
	v_lshlrev_b32_e32 v221, 16, v143
	v_lshlrev_b32_e32 v220, 16, v139
	v_mul_f32_e64 v222, v222, v222
	v_mul_f32_e64 v223, v223, v223
	s_nop 0
	v_fma_f32 v220, v220, v220, v222
	v_fma_f32 v221, v221, v221, v223
	s_nop 0
	v_add_f32_e64 v192, v220, v192
	v_add_f32_e64 v193, v221, v193

;   __device__ __forceinline__ void operator()(int lrow, int nc, const f32x16& a0, const f32x16& a1, float aux) const {
;     const int lane = threadIdx.x & 63, wid = threadIdx.x >> 6, r32 = lane & 31, hi = lane >> 5;
;     float sc = 1.f;
;     if (invK > 0.f) sc = rsqrtf(aux * invK + 1e-6f);
;     char* sp = scr + wid * (32 * 144);
;     char* wp = sp + r32 * 144 + 32 * hi;
;     if (act) {
;     ...
;       const u32x4 w0 = {cvtpk(TANH_(a0[0]), TANH_(a0[1])), cvtpk(TANH_(a0[2]), TANH_(a0[3])), cvtpk(TANH_(a0[4]), TANH_(a0[5])), cvtpk(TANH_(a0[6]), TANH_(a0[7]))};
;       const u32x4 w1 = {cvtpk(TANH_(a0[8]), TANH_(a0[9])), cvtpk(TANH_(a0[10]), TANH_(a0[11])), cvtpk(TANH_(a0[12]), TANH_(a0[13])), cvtpk(TANH_(a0[14]), TANH_(a0[15]))};
;       const u32x4 w2 = {cvtpk(TANH_(a1[0]), TANH_(a1[1])), cvtpk(TANH_(a1[2]), TANH_(a1[3])), cvtpk(TANH_(a1[4]), TANH_(a1[5])), cvtpk(TANH_(a1[6]), TANH_(a1[7]))};
;       const u32x4 w3 = {cvtpk(TANH_(a1[8]), TANH_(a1[9])), cvtpk(TANH_(a1[10]), TANH_(a1[11])), cvtpk(TANH_(a1[12]), TANH_(a1[13])), cvtpk(TANH_(a1[14]), TANH_(a1[15]))};
;     ...
;       *(u32x4*)(wp) = w0; *(u32x4*)(wp + 16) = w1; *(u32x4*)(wp + 64) = w2; *(u32x4*)(wp + 80) = w3;
;     } else {
;       const u32x4 w0 = {cvtpk(a0[0] * sc, a0[1] * sc), cvtpk(a0[2] * sc, a0[3] * sc), cvtpk(a0[4] * sc, a0[5] * sc), cvtpk(a0[6] * sc, a0[7] * sc)};
;       const u32x4 w1 = {cvtpk(a0[8] * sc, a0[9] * sc), cvtpk(a0[10] * sc, a0[11] * sc), cvtpk(a0[12] * sc, a0[13] * sc), cvtpk(a0[14] * sc, a0[15] * sc)};
;       const u32x4 w2 = {cvtpk(a1[0] * sc, a1[1] * sc), cvtpk(a1[2] * sc, a1[3] * sc), cvtpk(a1[4] * sc, a1[5] * sc), cvtpk(a1[6] * sc, a1[7] * sc)};
;       const u32x4 w3 = {cvtpk(a1[8] * sc, a1[9] * sc), cvtpk(a1[10] * sc, a1[11] * sc), cvtpk(a1[12] * sc, a1[13] * sc), cvtpk(a1[14] * sc, a1[15] * sc)};
;       *(u32x4*)(wp) = w0; *(u32x4*)(wp + 16) = w1; *(u32x4*)(wp + 64) = w2; *(u32x4*)(wp + 80) = w3;
;     }
;     asm volatile("s_waitcnt lgkmcnt(0)" ::: "memory");
;     bf16_t* gp = dst + (size_t)(m0 + lrow - r32) * ldd + col0 + (nc & ~7) + (lane & 7) * 8;
; #pragma unroll
;     for (int i = 0; i < 4; ++i) {
;       const int row = (lane >> 3) + 8 * i;
;       *(u32x4*)(gp + (size_t)row * ldd) = *(const u32x4*)(sp + row * 144 + (lane & 7) * 16);
;     }
;     asm volatile("s_waitcnt lgkmcnt(0)" ::: "memory");
.LBB0_966:
	s_or_b64 exec, exec, s[10:11]
	s_waitcnt lgkmcnt(0)
	s_barrier
	ds_read_b32 v128, v218
	s_lshl_b32 s6, s16, 9
	v_mov_b32_e32 v187, v169
	v_mov_b32_e32 v191, v169
	v_mov_b32_e32 v193, v169
	s_waitcnt lgkmcnt(0)
	v_fmamk_f32 v128, v128, 0x3b800000, v222
	v_mul_f32_e32 v129, 0x4b800000, v128
	v_cmp_gt_f32_e32 vcc, s13, v128
	v_mov_b32_e32 v195, v169
	v_mov_b32_e32 v197, v169
	v_cndmask_b32_e32 v128, v128, v129, vcc
	v_rsq_f32_e32 v128, v128
	s_cmpk_lt_u32 s15, 0x108
	s_cselect_b64 s[10:11], -1, 0
	v_mul_f32_e32 v129, 0x45800000, v128
	v_cndmask_b32_e32 v128, v128, v129, vcc
	v_mul_f32_e64 v112, v112, v128
	v_mul_f32_e64 v113, v113, v128
	v_mul_f32_e64 v114, v114, v128
	v_mul_f32_e64 v115, v115, v128
	v_mul_f32_e64 v116, v116, v128
	v_mul_f32_e64 v117, v117, v128
	v_mul_f32_e64 v96, v96, v128
	v_mul_f32_e64 v97, v97, v128
	v_mul_f32_e64 v98, v98, v128
	v_mul_f32_e64 v99, v99, v128
	v_cvt_pk_bf16_f32 v112, v112, v113
	v_cvt_pk_bf16_f32 v113, v114, v115
	v_cvt_pk_bf16_f32 v114, v116, v117
	v_mul_f32_e64 v116, v118, v128
	v_mul_f32_e64 v117, v119, v128
	v_cvt_pk_bf16_f32 v96, v96, v97
	v_cvt_pk_bf16_f32 v97, v98, v99
	v_mul_f32_e64 v98, v100, v128
	v_mul_f32_e64 v99, v101, v128
	v_mul_f32_e64 v100, v102, v128
	v_mul_f32_e64 v101, v103, v128
	v_cvt_pk_bf16_f32 v115, v116, v117
	v_mul_f32_e64 v116, v120, v128
	v_mul_f32_e64 v117, v121, v128
	v_mul_f32_e64 v118, v122, v128
	v_mul_f32_e64 v119, v123, v128
	v_cvt_pk_bf16_f32 v98, v98, v99
	v_cvt_pk_bf16_f32 v99, v100, v101
	v_mul_f32_e64 v100, v104, v128
	v_mul_f32_e64 v101, v105, v128
	v_mul_f32_e64 v102, v106, v128
	v_mul_f32_e64 v103, v107, v128
	v_cvt_pk_bf16_f32 v116, v116, v117
	v_cvt_pk_bf16_f32 v117, v118, v119
	v_mul_f32_e64 v118, v124, v128
	v_mul_f32_e64 v119, v125, v128
	v_mul_f32_e64 v120, v126, v128
	v_mul_f32_e64 v121, v127, v128
	v_cvt_pk_bf16_f32 v100, v100, v101
	v_cvt_pk_bf16_f32 v101, v102, v103
	v_mul_f32_e64 v102, v108, v128
	v_mul_f32_e64 v103, v109, v128
	v_mul_f32_e64 v104, v110, v128
	v_mul_f32_e64 v105, v111, v128
	v_cvt_pk_bf16_f32 v118, v118, v119
	v_cvt_pk_bf16_f32 v119, v120, v121
	v_cvt_pk_bf16_f32 v102, v102, v103
	v_cvt_pk_bf16_f32 v103, v104, v105
	ds_write_b128 v223, v[112:115]
	ds_write_b128 v223, v[116:119] offset:16
	ds_write_b128 v223, v[96:99] offset:64
	ds_write_b128 v223, v[100:103] offset:80
	v_add_u32_e32 v96, s14, v213
	v_ashrrev_i32_e32 v97, 31, v96
	v_lshlrev_b64 v[96:97], 12, v[96:97]
	v_lshl_add_u64 v[96:97], s[26:27], 0, v[96:97]
	s_waitcnt lgkmcnt(0)
	v_lshl_add_u64 v[96:97], v[96:97], 0, s[6:7]
	v_lshl_add_u64 v[100:101], v[96:97], 0, v[168:169]
	ds_read_b128 v[96:99], v225
	v_lshl_add_u64 v[104:105], v[100:101], 0, v[186:187]
	ds_read_b128 v[100:103], v225 offset:1152
	v_lshl_add_u64 v[106:107], v[104:105], 0, v[190:191]
	s_waitcnt lgkmcnt(1)
	global_store_dwordx4 v[106:107], v[96:99], off
	v_lshl_add_u64 v[106:107], v[104:105], 0, v[192:193]
	ds_read_b128 v[96:99], v225 offset:2304
	s_waitcnt lgkmcnt(1)
	global_store_dwordx4 v[106:107], v[100:103], off
	ds_read_b128 v[100:103], v225 offset:3456
	v_lshl_add_u64 v[106:107], v[104:105], 0, v[194:195]
	s_waitcnt lgkmcnt(1)
	global_store_dwordx4 v[106:107], v[96:99], off
	s_nop 1
	v_lshl_add_u64 v[96:97], v[104:105], 0, v[196:197]
	s_waitcnt lgkmcnt(0)
	global_store_dwordx4 v[96:97], v[100:103], off
	s_waitcnt lgkmcnt(0)
	ds_read_b32 v96, v167 offset:128
	s_waitcnt lgkmcnt(0)
	v_fmamk_f32 v96, v96, 0x3b800000, v222
	v_mul_f32_e32 v97, 0x4b800000, v96
	v_cmp_gt_f32_e32 vcc, s13, v96
	s_nop 1
	v_cndmask_b32_e32 v96, v96, v97, vcc
	v_rsq_f32_e32 v96, v96
	s_nop 0
	v_mul_f32_e32 v97, 0x45800000, v96
	v_cndmask_b32_e32 v96, v96, v97, vcc
	v_mul_f32_e64 v80, v80, v96
	v_mul_f32_e64 v81, v81, v96
	v_mul_f32_e64 v82, v82, v96
	v_mul_f32_e64 v83, v83, v96
	v_mul_f32_e64 v64, v64, v96
	v_mul_f32_e64 v65, v65, v96
	v_mul_f32_e64 v66, v66, v96
	v_mul_f32_e64 v67, v67, v96
	v_cvt_pk_bf16_f32 v80, v80, v81
	v_cvt_pk_bf16_f32 v81, v82, v83
	v_mul_f32_e64 v82, v84, v96
	v_mul_f32_e64 v83, v85, v96
	v_mul_f32_e64 v84, v86, v96
	v_mul_f32_e64 v85, v87, v96
	v_cvt_pk_bf16_f32 v64, v64, v65
	v_cvt_pk_bf16_f32 v65, v66, v67
	v_mul_f32_e64 v66, v68, v96
	v_mul_f32_e64 v67, v69, v96
	v_mul_f32_e64 v68, v70, v96
	v_mul_f32_e64 v69, v71, v96
	v_cvt_pk_bf16_f32 v82, v82, v83
	v_cvt_pk_bf16_f32 v83, v84, v85
	v_mul_f32_e64 v84, v88, v96
	v_mul_f32_e64 v85, v89, v96
	v_mul_f32_e64 v86, v90, v96
	v_mul_f32_e64 v87, v91, v96
	v_cvt_pk_bf16_f32 v66, v66, v67
	v_cvt_pk_bf16_f32 v67, v68, v69
	v_mul_f32_e64 v68, v72, v96
	v_mul_f32_e64 v69, v73, v96
	v_mul_f32_e64 v70, v74, v96
	v_mul_f32_e64 v71, v75, v96
	v_cvt_pk_bf16_f32 v84, v84, v85
	v_cvt_pk_bf16_f32 v85, v86, v87
	v_mul_f32_e64 v86, v92, v96
	v_mul_f32_e64 v87, v93, v96
	v_mul_f32_e64 v88, v94, v96
	v_mul_f32_e64 v89, v95, v96
	v_cvt_pk_bf16_f32 v68, v68, v69
	v_cvt_pk_bf16_f32 v69, v70, v71
	v_mul_f32_e64 v70, v76, v96
	v_mul_f32_e64 v71, v77, v96
	v_mul_f32_e64 v72, v78, v96
	v_mul_f32_e64 v73, v79, v96
	v_cvt_pk_bf16_f32 v86, v86, v87
	v_cvt_pk_bf16_f32 v87, v88, v89
	v_cvt_pk_bf16_f32 v70, v70, v71
	v_cvt_pk_bf16_f32 v71, v72, v73
	ds_write_b128 v223, v[80:83]
	ds_write_b128 v223, v[84:87] offset:16
	ds_write_b128 v223, v[64:67] offset:64
	ds_write_b128 v223, v[68:71] offset:80
	v_add_u32_e32 v64, s14, v219
	v_ashrrev_i32_e32 v65, 31, v64
	v_lshlrev_b64 v[64:65], 12, v[64:65]
	s_waitcnt lgkmcnt(0)
	v_lshl_add_u64 v[64:65], s[26:27], 0, v[64:65]
	v_lshl_add_u64 v[68:69], v[64:65], 0, s[6:7]
	ds_read_b128 v[64:67], v225
	v_lshl_add_u64 v[68:69], v[68:69], 0, v[168:169]
	v_lshl_add_u64 v[76:77], v[68:69], 0, v[186:187]
	v_lshl_add_u64 v[72:73], v[76:77], 0, v[190:191]
	ds_read_b128 v[68:71], v225 offset:1152
	s_waitcnt lgkmcnt(1)
;   __device__ __forceinline__ void operator()(int lrow, int nc, const f32x16& a0, const f32x16& a1, float aux) const {
;     const int lane = threadIdx.x & 63, wid = threadIdx.x >> 6, r32 = lane & 31, hi = lane >> 5;
;     float sc = 1.f;
;     if (invK > 0.f) sc = rsqrtf(aux * invK + 1e-6f);
;     char* sp = scr + wid * (32 * 144);
;     char* wp = sp + r32 * 144 + 32 * hi;
;     if (act) {
;     ...
;       const u32x4 w0 = {cvtpk(TANH_(a0[0]), TANH_(a0[1])), cvtpk(TANH_(a0[2]), TANH_(a0[3])), cvtpk(TANH_(a0[4]), TANH_(a0[5])), cvtpk(TANH_(a0[6]), TANH_(a0[7]))};
;       const u32x4 w1 = {cvtpk(TANH_(a0[8]), TANH_(a0[9])), cvtpk(TANH_(a0[10]), TANH_(a0[11])), cvtpk(TANH_(a0[12]), TANH_(a0[13])), cvtpk(TANH_(a0[14]), TANH_(a0[15]))};
;       const u32x4 w2 = {cvtpk(TANH_(a1[0]), TANH_(a1[1])), cvtpk(TANH_(a1[2]), TANH_(a1[3])), cvtpk(TANH_(a1[4]), TANH_(a1[5])), cvtpk(TANH_(a1[6]), TANH_(a1[7]))};
;       const u32x4 w3 = {cvtpk(TANH_(a1[8]), TANH_(a1[9])), cvtpk(TANH_(a1[10]), TANH_(a1[11])), cvtpk(TANH_(a1[12]), TANH_(a1[13])), cvtpk(TANH_(a1[14]), TANH_(a1[15]))};
;     ...
;       *(u32x4*)(wp) = w0; *(u32x4*)(wp + 16) = w1; *(u32x4*)(wp + 64) = w2; *(u32x4*)(wp + 80) = w3;
;     } else {
;       const u32x4 w0 = {cvtpk(a0[0] * sc, a0[1] * sc), cvtpk(a0[2] * sc, a0[3] * sc), cvtpk(a0[4] * sc, a0[5] * sc), cvtpk(a0[6] * sc, a0[7] * sc)};
;       const u32x4 w1 = {cvtpk(a0[8] * sc, a0[9] * sc), cvtpk(a0[10] * sc, a0[11] * sc), cvtpk(a0[12] * sc, a0[13] * sc), cvtpk(a0[14] * sc, a0[15] * sc)};
;       const u32x4 w2 = {cvtpk(a1[0] * sc, a1[1] * sc), cvtpk(a1[2] * sc, a1[3] * sc), cvtpk(a1[4] * sc, a1[5] * sc), cvtpk(a1[6] * sc, a1[7] * sc)};
;       const u32x4 w3 = {cvtpk(a1[8] * sc, a1[9] * sc), cvtpk(a1[10] * sc, a1[11] * sc), cvtpk(a1[12] * sc, a1[13] * sc), cvtpk(a1[14] * sc, a1[15] * sc)};
;       *(u32x4*)(wp) = w0; *(u32x4*)(wp + 16) = w1; *(u32x4*)(wp + 64) = w2; *(u32x4*)(wp + 80) = w3;
;     }
;     asm volatile("s_waitcnt lgkmcnt(0)" ::: "memory");
;     bf16_t* gp = dst + (size_t)(m0 + lrow - r32) * ldd + col0 + (nc & ~7) + (lane & 7) * 8;
; #pragma unroll
;     for (int i = 0; i < 4; ++i) {
;       const int row = (lane >> 3) + 8 * i;
;       *(u32x4*)(gp + (size_t)row * ldd) = *(const u32x4*)(sp + row * 144 + (lane & 7) * 16);
;     }
;     asm volatile("s_waitcnt lgkmcnt(0)" ::: "memory");
	global_store_dwordx4 v[72:73], v[64:67], off
	ds_read_b128 v[64:67], v225 offset:2304
	ds_read_b128 v[72:75], v225 offset:3456
	v_lshl_add_u64 v[78:79], v[76:77], 0, v[192:193]
	s_waitcnt lgkmcnt(2)
	global_store_dwordx4 v[78:79], v[68:71], off
	s_nop 1
	v_lshl_add_u64 v[68:69], v[76:77], 0, v[194:195]
	s_waitcnt lgkmcnt(1)
	global_store_dwordx4 v[68:69], v[64:67], off
	s_nop 1
	v_lshl_add_u64 v[64:65], v[76:77], 0, v[196:197]
	s_waitcnt lgkmcnt(0)
	global_store_dwordx4 v[64:65], v[72:75], off
	s_waitcnt lgkmcnt(0)
	ds_read_b32 v64, v167 offset:256
	s_waitcnt lgkmcnt(0)
	v_fmamk_f32 v64, v64, 0x3b800000, v222
	v_mul_f32_e32 v65, 0x4b800000, v64
	v_cmp_gt_f32_e32 vcc, s13, v64
	s_nop 1
	v_cndmask_b32_e32 v64, v64, v65, vcc
	v_rsq_f32_e32 v64, v64
	s_nop 0
	v_mul_f32_e32 v65, 0x45800000, v64
	v_cndmask_b32_e32 v64, v64, v65, vcc
	v_mul_f32_e64 v48, v48, v64
	v_mul_f32_e64 v49, v49, v64
	v_mul_f32_e64 v50, v50, v64
	v_mul_f32_e64 v51, v51, v64
	v_mul_f32_e64 v32, v32, v64
	v_mul_f32_e64 v33, v33, v64
	v_mul_f32_e64 v34, v34, v64
	v_mul_f32_e64 v35, v35, v64
	v_cvt_pk_bf16_f32 v48, v48, v49
	v_cvt_pk_bf16_f32 v49, v50, v51
	v_mul_f32_e64 v50, v52, v64
	v_mul_f32_e64 v51, v53, v64
	v_mul_f32_e64 v52, v54, v64
	v_mul_f32_e64 v53, v55, v64
	v_cvt_pk_bf16_f32 v32, v32, v33
	v_cvt_pk_bf16_f32 v33, v34, v35
	v_mul_f32_e64 v34, v36, v64
	v_mul_f32_e64 v35, v37, v64
	v_mul_f32_e64 v36, v38, v64
	v_mul_f32_e64 v37, v39, v64
	v_cvt_pk_bf16_f32 v50, v50, v51
	v_cvt_pk_bf16_f32 v51, v52, v53
	v_mul_f32_e64 v52, v56, v64
	v_mul_f32_e64 v53, v57, v64
	v_mul_f32_e64 v54, v58, v64
	v_mul_f32_e64 v55, v59, v64
	v_cvt_pk_bf16_f32 v34, v34, v35
	v_cvt_pk_bf16_f32 v35, v36, v37
	v_mul_f32_e64 v36, v40, v64
	v_mul_f32_e64 v37, v41, v64
	v_mul_f32_e64 v38, v42, v64
	v_mul_f32_e64 v39, v43, v64
	v_cvt_pk_bf16_f32 v52, v52, v53
	v_cvt_pk_bf16_f32 v53, v54, v55
	v_mul_f32_e64 v54, v60, v64
	v_mul_f32_e64 v55, v61, v64
	v_mul_f32_e64 v56, v62, v64
	v_mul_f32_e64 v57, v63, v64
	v_cvt_pk_bf16_f32 v36, v36, v37
	v_cvt_pk_bf16_f32 v37, v38, v39
	v_mul_f32_e64 v38, v44, v64
	v_mul_f32_e64 v39, v45, v64
	v_mul_f32_e64 v40, v46, v64
	v_mul_f32_e64 v41, v47, v64
	v_cvt_pk_bf16_f32 v54, v54, v55
	v_cvt_pk_bf16_f32 v55, v56, v57
	v_cvt_pk_bf16_f32 v38, v38, v39
	v_cvt_pk_bf16_f32 v39, v40, v41
	ds_write_b128 v223, v[48:51]
	ds_write_b128 v223, v[52:55] offset:16
	ds_write_b128 v223, v[32:35] offset:64
	ds_write_b128 v223, v[36:39] offset:80
	v_add_u32_e32 v32, s14, v220
	v_ashrrev_i32_e32 v33, 31, v32
	v_lshlrev_b64 v[32:33], 12, v[32:33]
	s_waitcnt lgkmcnt(0)
	v_lshl_add_u64 v[32:33], s[26:27], 0, v[32:33]
	v_lshl_add_u64 v[36:37], v[32:33], 0, s[6:7]
	ds_read_b128 v[32:35], v225
	v_lshl_add_u64 v[36:37], v[36:37], 0, v[168:169]
	v_lshl_add_u64 v[44:45], v[36:37], 0, v[186:187]
	v_lshl_add_u64 v[40:41], v[44:45], 0, v[190:191]
	ds_read_b128 v[36:39], v225 offset:1152
	s_waitcnt lgkmcnt(1)
	global_store_dwordx4 v[40:41], v[32:35], off
	ds_read_b128 v[32:35], v225 offset:2304
	ds_read_b128 v[40:43], v225 offset:3456
	v_lshl_add_u64 v[46:47], v[44:45], 0, v[192:193]
	s_waitcnt lgkmcnt(2)
	global_store_dwordx4 v[46:47], v[36:39], off
	s_nop 1
	v_lshl_add_u64 v[36:37], v[44:45], 0, v[194:195]
	s_waitcnt lgkmcnt(1)
	global_store_dwordx4 v[36:37], v[32:35], off
	s_nop 1
	v_lshl_add_u64 v[32:33], v[44:45], 0, v[196:197]
	s_waitcnt lgkmcnt(0)
	global_store_dwordx4 v[32:33], v[40:43], off
	s_waitcnt lgkmcnt(0)
	ds_read_b32 v32, v167 offset:384
	s_waitcnt lgkmcnt(0)
	v_fmamk_f32 v32, v32, 0x3b800000, v222
	v_mul_f32_e32 v33, 0x4b800000, v32
	v_cmp_gt_f32_e32 vcc, s13, v32
	s_nop 1
	v_cndmask_b32_e32 v32, v32, v33, vcc
	v_rsq_f32_e32 v32, v32
	s_nop 0
	v_mul_f32_e32 v33, 0x45800000, v32
	v_cndmask_b32_e32 v32, v32, v33, vcc
	v_mul_f32_e64 v16, v16, v32
	v_mul_f32_e64 v17, v17, v32
	v_mul_f32_e64 v18, v18, v32
	v_mul_f32_e64 v19, v19, v32
	v_mul_f32_e64 v0, v0, v32
	v_mul_f32_e64 v1, v1, v32
	v_mul_f32_e64 v2, v2, v32
	v_mul_f32_e64 v3, v3, v32
	v_cvt_pk_bf16_f32 v16, v16, v17
	v_cvt_pk_bf16_f32 v17, v18, v19
	v_mul_f32_e64 v18, v20, v32
	v_mul_f32_e64 v19, v21, v32
	v_mul_f32_e64 v20, v22, v32
	v_mul_f32_e64 v21, v23, v32
	v_cvt_pk_bf16_f32 v0, v0, v1
	v_cvt_pk_bf16_f32 v1, v2, v3
	v_mul_f32_e64 v2, v4, v32
	v_mul_f32_e64 v3, v5, v32
	v_mul_f32_e64 v4, v6, v32
	v_mul_f32_e64 v5, v7, v32
	v_cvt_pk_bf16_f32 v18, v18, v19
	v_cvt_pk_bf16_f32 v19, v20, v21
	v_mul_f32_e64 v20, v24, v32
	v_mul_f32_e64 v21, v25, v32
	v_mul_f32_e64 v22, v26, v32
	v_mul_f32_e64 v23, v27, v32
	v_cvt_pk_bf16_f32 v2, v2, v3
	v_cvt_pk_bf16_f32 v3, v4, v5
	v_mul_f32_e64 v4, v8, v32
	v_mul_f32_e64 v5, v9, v32
	v_mul_f32_e64 v6, v10, v32
	v_mul_f32_e64 v7, v11, v32
	v_cvt_pk_bf16_f32 v20, v20, v21
	v_cvt_pk_bf16_f32 v21, v22, v23
	v_mul_f32_e64 v22, v28, v32
	v_mul_f32_e64 v23, v29, v32
	v_mul_f32_e64 v24, v30, v32
	v_mul_f32_e64 v25, v31, v32
	v_cvt_pk_bf16_f32 v4, v4, v5
	v_cvt_pk_bf16_f32 v5, v6, v7
	v_mul_f32_e64 v6, v12, v32
	v_mul_f32_e64 v7, v13, v32
	v_mul_f32_e64 v8, v14, v32
	v_mul_f32_e64 v9, v15, v32
	v_cvt_pk_bf16_f32 v22, v22, v23
	v_cvt_pk_bf16_f32 v23, v24, v25
	v_cvt_pk_bf16_f32 v6, v6, v7
	v_cvt_pk_bf16_f32 v7, v8, v9
	ds_write_b128 v223, v[16:19]
	ds_write_b128 v223, v[20:23] offset:16
	ds_write_b128 v223, v[0:3] offset:64
	ds_write_b128 v223, v[4:7] offset:80
	v_add_u32_e32 v0, s14, v221
	v_ashrrev_i32_e32 v1, 31, v0
	v_lshlrev_b64 v[0:1], 12, v[0:1]
	s_waitcnt lgkmcnt(0)
	v_lshl_add_u64 v[0:1], s[26:27], 0, v[0:1]
	v_lshl_add_u64 v[4:5], v[0:1], 0, s[6:7]
	ds_read_b128 v[0:3], v225
	v_lshl_add_u64 v[4:5], v[4:5], 0, v[168:169]
	v_lshl_add_u64 v[12:13], v[4:5], 0, v[186:187]
	v_lshl_add_u64 v[8:9], v[12:13], 0, v[190:191]
	ds_read_b128 v[4:7], v225 offset:1152
	s_waitcnt lgkmcnt(1)
	global_store_dwordx4 v[8:9], v[0:3], off
	ds_read_b128 v[0:3], v225 offset:2304
	ds_read_b128 v[8:11], v225 offset:3456
	v_lshl_add_u64 v[14:15], v[12:13], 0, v[192:193]
	s_waitcnt lgkmcnt(2)
	global_store_dwordx4 v[14:15], v[4:7], off
	s_and_b64 vcc, s[10:11], exec
	s_cselect_b32 s6, s33, 0
	v_lshl_add_u64 v[4:5], v[12:13], 0, v[194:195]
	s_waitcnt lgkmcnt(1)
	global_store_dwordx4 v[4:5], v[0:3], off
	s_add_i32 s10, s6, s15
	s_nop 0
	v_lshl_add_u64 v[0:1], v[12:13], 0, v[196:197]
	s_waitcnt lgkmcnt(0)
	global_store_dwordx4 v[0:1], v[8:11], off
	s_waitcnt lgkmcnt(0)
	s_cbranch_vccz .LBB0_981
; __device__ __forceinline__ float lo16(unsigned w) { return __uint_as_float(w << 16); }
; __device__ __forceinline__ float hi16(unsigned w) { return __uint_as_float(w & 0xffff0000u); }
; template <int AMODE, int BN, class Epi>
; __device__ __forceinline__ void gemm_tile(const bf16_t* A, const int lda, const bf16_t* Bt, const int K, const int m0, const float* mu, char* lds, const Epi& epi) {
;     ...
;   auto gload = [&](int k0) {
; #pragma unroll
;     for (int i = 0; i < 4; ++i) {
;       const bf16_t* ap = A + (size_t)(m0 + srow + 64 * i) * lda + k0 + scc;
;       ra[i] = *(const bf16x8*)ap;
;       if constexpr (AMODE == 1) { rp[i] = *(const bf16x8*)(ap - dprev[i] * lda); rn[i] = *(const bf16x8*)(ap + dnext[i] * lda); }
;     }
; #pragma unroll
;     for (int i = 0; i < NBR; ++i) rb[i] = *(const bf16x8*)(Bt + (size_t)browi[i] * K + k0 + scc);
;   };
;     ...
; #pragma unroll
;       for (int i = 0; i < 4; ++i) {
;         *(bf16x8*)(base + (srow + 64 * i) * G_LDT + scc * 2) = ra[i];
;         if constexpr (AMODE == 2) {
;           const u32x4 hc = *(const u32x4*)&ra[i];
; #pragma unroll
;           for (int q = 0; q < 4; ++q) { const float c0 = lo16(hc[q]), c1 = hi16(hc[q]); ssq[i] += c0 * c0 + c1 * c1; }
;         }
;       }
; __global__ __launch_bounds__(NTHR, 1) void fwd_megakernel(Params p) {
;     ...
;       EpiBf16 e; e.act = 0; e.scr = lds + G_EPI_SCR;
;       {
;         int mt, nt; tile_mn(o, 8, mt, nt);
;         const int m0 = mt * 256;
;         e.dst = (bf16_t*)(ws + OFF_KV); e.ldd = 2048; e.col0 = nt * 256; e.m0 = m0; e.invK = 1.f / 256.f;
;         gemm_tile<2, 256>((const bf16_t*)(ws + OFF_KVC), 256, WKV + (size_t)nt * 256 * 256, 256, m0, nullptr, lds, e);
.LBB0_967:
	s_add_i32 s6, s15, s0
	s_lshl_b32 s11, s6, 5
	s_lshl_b32 s14, s15, 8
	s_and_b32 s11, s11, 0xfffff800
	s_and_b32 s14, s14, 0x700
	s_or_b32 s14, s11, s14
	v_or_b32_e32 v12, s14, v161
	v_ashrrev_i32_e32 v13, 31, v12
	v_lshlrev_b64 v[32:33], 9, v[12:13]
	v_lshl_add_u64 v[36:37], v[32:33], 0, s[8:9]
	v_lshl_add_u64 v[34:35], v[172:173], 0, v[32:33]
	v_lshl_add_u64 v[38:39], v[172:173], 0, v[36:37]
	global_load_dwordx4 v[0:3], v[34:35], off
	global_load_dwordx4 v[4:7], v[38:39], off
	v_or_b32_e32 v8, 0x80, v12
	v_add_u32_e32 v12, 0xc0, v12
	s_bfe_u32 s16, s6, 0x30003
	v_ashrrev_i32_e32 v9, 31, v8
	v_ashrrev_i32_e32 v13, 31, v12
	s_lshl_b32 s6, s16, 17
	v_lshlrev_b64 v[40:41], 9, v[8:9]
	v_lshlrev_b64 v[44:45], 9, v[12:13]
	v_lshl_add_u64 v[16:17], v[170:171], 0, s[6:7]
	v_lshl_add_u64 v[42:43], v[172:173], 0, v[40:41]
	v_lshl_add_u64 v[46:47], v[172:173], 0, v[44:45]
	v_lshl_add_u64 v[48:49], v[16:17], 0, v[188:189]
	global_load_dwordx4 v[8:11], v[42:43], off
	global_load_dwordx4 v[12:15], v[46:47], off
	v_add_co_u32_e32 v50, vcc, s1, v48
	global_load_dwordx4 v[16:19], v[48:49], off
	s_nop 0
	v_addc_co_u32_e32 v51, vcc, 0, v49, vcc
	v_add_co_u32_e32 v52, vcc, s2, v48
	s_mov_b32 s15, s10
	s_nop 0
	v_addc_co_u32_e32 v53, vcc, 0, v49, vcc
	v_add_co_u32_e32 v54, vcc, s12, v48
	global_load_dwordx4 v[20:23], v[50:51], off
	global_load_dwordx4 v[24:27], v[52:53], off
	v_addc_co_u32_e32 v55, vcc, 0, v49, vcc
	global_load_dwordx4 v[28:31], v[54:55], off
	global_load_dwordx4 v[128:131], v[34:35], off offset:128
	global_load_dwordx4 v[132:135], v[38:39], off offset:128
	global_load_dwordx4 v[136:139], v[42:43], off offset:128
	global_load_dwordx4 v[140:143], v[46:47], off offset:128
	global_load_dwordx4 v[144:147], v[48:49], off offset:128
	global_load_dwordx4 v[148:151], v[50:51], off offset:128
	global_load_dwordx4 v[152:155], v[52:53], off offset:128
	global_load_dwordx4 v[156:159], v[54:55], off offset:128
	v_lshl_add_u64 v[202:203], v[174:175], 0, s[6:7]
	v_lshl_add_u64 v[204:205], v[184:185], 0, v[44:45]
	v_lshl_add_u64 v[206:207], v[184:185], 0, v[40:41]
	v_lshl_add_u64 v[208:209], v[184:185], 0, v[36:37]
	v_lshl_add_u64 v[210:211], v[184:185], 0, v[32:33]
	s_mov_b64 s[10:11], 0
	s_mov_b32 s6, 0
	v_mov_b32_e32 v32, 0
	v_mov_b32_e32 v33, v169
	v_mov_b32_e32 v36, v169
	v_mov_b32_e32 v37, v169
	v_mov_b32_e32 v40, v169
	v_mov_b32_e32 v41, v169
	v_mov_b32_e32 v44, v169
	v_mov_b32_e32 v45, v169
	v_mov_b32_e32 v48, 0
	v_mov_b32_e32 v49, v169
	v_mov_b32_e32 v50, v169
	v_mov_b32_e32 v51, v169
	v_mov_b32_e32 v52, v169
	v_mov_b32_e32 v53, v169
	v_mov_b32_e32 v54, v169
	v_mov_b32_e32 v55, v169
	s_waitcnt vmcnt(20)
	v_mov_b32_e32 v62, v169
	v_mov_b32_e32 v63, v169
	v_mov_b32_e32 v64, 0
	v_mov_b32_e32 v65, v169
	s_waitcnt vmcnt(19)
	v_mov_b32_e32 v66, v169
	v_mov_b32_e32 v67, v169
	v_mov_b32_e32 v68, v169
	v_mov_b32_e32 v69, v169
	s_waitcnt vmcnt(18)
	v_mov_b32_e32 v70, v169
	v_mov_b32_e32 v71, v169
	v_mov_b32_e32 v72, v169
	v_mov_b32_e32 v73, v169
	v_mov_b32_e32 v74, v169
	v_mov_b32_e32 v75, v169
	v_mov_b32_e32 v76, v169
	v_mov_b32_e32 v77, v169
	v_mov_b32_e32 v78, v169
	v_mov_b32_e32 v79, v169
	v_mov_b32_e32 v80, 0
	v_mov_b32_e32 v81, v169
	s_waitcnt vmcnt(15)
	ds_write_b128 v212, v[0:3]
	v_lshlrev_b32_e32 v34, 16, v0
	v_and_b32_e32 v0, 0xffff0000, v0
	v_lshlrev_b32_e32 v38, 16, v1
	v_and_b32_e32 v42, 0xffff0000, v1
	s_waitcnt vmcnt(14)
	v_and_b32_e32 v1, 0xffff0000, v4
	v_and_b32_e32 v43, 0xffff0000, v5
	v_lshlrev_b32_e32 v46, 16, v2
	v_and_b32_e32 v2, 0xffff0000, v2
	v_lshlrev_b32_e32 v56, 16, v3
	v_and_b32_e32 v58, 0xffff0000, v3
	v_lshlrev_b32_e32 v35, 16, v4
	v_lshlrev_b32_e32 v39, 16, v5
	v_and_b32_e32 v3, 0xffff0000, v6
	v_mul_f32_e64 v0, v0, v0
	v_mul_f32_e64 v1, v1, v1
	v_mul_f32_e64 v42, v42, v42
	v_mul_f32_e64 v43, v43, v43
	v_lshlrev_b32_e32 v47, 16, v6
	v_and_b32_e32 v59, 0xffff0000, v7
	v_mul_f32_e64 v2, v2, v2
	v_mul_f32_e64 v3, v3, v3
	v_fma_f32 v0, v34, v34, v0
	v_fma_f32 v1, v35, v35, v1
	v_fma_f32 v34, v38, v38, v42
	v_fma_f32 v35, v39, v39, v43
	v_lshlrev_b32_e32 v57, 16, v7
	v_mul_f32_e64 v58, v58, v58
	v_mul_f32_e64 v59, v59, v59
	v_fma_f32 v2, v46, v46, v2
	v_fma_f32 v3, v47, v47, v3
	v_add_f32_e64 v0, v34, v0
	v_add_f32_e64 v1, v35, v1
	ds_write_b128 v212, v[4:7] offset:9216
	s_waitcnt vmcnt(13)
; __device__ __forceinline__ float lo16(unsigned w) { return __uint_as_float(w << 16); }
; __device__ __forceinline__ float hi16(unsigned w) { return __uint_as_float(w & 0xffff0000u); }
; template <int AMODE, int BN, class Epi>
; __device__ __forceinline__ void gemm_tile(const bf16_t* A, const int lda, const bf16_t* Bt, const int K, const int m0, const float* mu, char* lds, const Epi& epi) {
;     ...
; #pragma unroll
;   for (int i = 0; i < MI; ++i)
; #pragma unroll
;     for (int j = 0; j < 2; ++j)
; #pragma unroll
;       for (int r = 0; r < 16; ++r) acc[i][j][r] = 0.f;
;     ...
; #pragma unroll
;       for (int i = 0; i < 4; ++i) {
;         *(bf16x8*)(base + (srow + 64 * i) * G_LDT + scc * 2) = ra[i];
;         if constexpr (AMODE == 2) {
;           const u32x4 hc = *(const u32x4*)&ra[i];
; #pragma unroll
;           for (int q = 0; q < 4; ++q) { const float c0 = lo16(hc[q]), c1 = hi16(hc[q]); ssq[i] += c0 * c0 + c1 * c1; }
;         }
;       }
;     ...
;   __syncthreads();
	v_and_b32_e32 v6, 0xffff0000, v8
	v_and_b32_e32 v60, 0xffff0000, v9
	s_waitcnt vmcnt(12)
	v_and_b32_e32 v7, 0xffff0000, v12
	v_and_b32_e32 v61, 0xffff0000, v13
	v_fma_f32 v38, v56, v56, v58
	v_fma_f32 v39, v57, v57, v59
	v_add_f32_e64 v0, v2, v0
	v_add_f32_e64 v1, v3, v1
	ds_write_b128 v212, v[8:11] offset:18432
	v_lshlrev_b32_e32 v4, 16, v8
	v_lshlrev_b32_e32 v8, 16, v9
	v_lshlrev_b32_e32 v5, 16, v12
	v_lshlrev_b32_e32 v9, 16, v13
	v_mul_f32_e64 v6, v6, v6
	v_mul_f32_e64 v7, v7, v7
	v_mul_f32_e64 v60, v60, v60
	v_mul_f32_e64 v61, v61, v61
	v_add_f32_e64 v200, v38, v0
	v_add_f32_e64 v201, v39, v1
	v_and_b32_e32 v1, 0xffff0000, v14
	v_and_b32_e32 v0, 0xffff0000, v10
	ds_write_b128 v212, v[12:15] offset:27648
	v_lshlrev_b32_e32 v13, 16, v14
	v_lshlrev_b32_e32 v12, 16, v10
	v_fma_f32 v4, v4, v4, v6
	v_fma_f32 v5, v5, v5, v7
	v_fma_f32 v6, v8, v8, v60
	v_fma_f32 v7, v9, v9, v61
	v_mul_f32_e64 v0, v0, v0
	v_mul_f32_e64 v1, v1, v1
	v_add_f32_e64 v4, v6, v4
	v_add_f32_e64 v5, v7, v5
	v_fma_f32 v0, v12, v12, v0
	v_fma_f32 v1, v13, v13, v1
	v_lshlrev_b32_e32 v3, 16, v15
	v_add_f32_e64 v0, v0, v4
	v_add_f32_e64 v1, v1, v5
	v_and_b32_e32 v5, 0xffff0000, v15
	v_and_b32_e32 v4, 0xffff0000, v11
	v_lshlrev_b32_e32 v2, 16, v11
	v_mul_f32_e64 v4, v4, v4
	v_mul_f32_e64 v5, v5, v5
	s_waitcnt vmcnt(11)
	ds_write_b128 v212, v[16:19] offset:36864
	v_fma_f32 v2, v2, v2, v4
	v_fma_f32 v3, v3, v3, v5
	s_waitcnt vmcnt(10)
	ds_write_b128 v212, v[20:23] offset:46080
	v_add_f32_e64 v198, v2, v0
	v_add_f32_e64 v199, v3, v1
	s_waitcnt vmcnt(9)
	ds_write_b128 v212, v[24:27] offset:55296
	s_waitcnt vmcnt(8)
	ds_write_b128 v212, v[28:31] offset:64512
	v_mov_b32_e32 v0, 0
	v_mov_b32_e32 v1, v169
	v_mov_b32_e32 v2, v169
	v_mov_b32_e32 v3, v169
	v_mov_b32_e32 v4, v169
	v_mov_b32_e32 v5, v169
	v_mov_b32_e32 v6, v169
	v_mov_b32_e32 v7, v169
	v_mov_b32_e32 v8, v169
	v_mov_b32_e32 v9, v169
	v_mov_b32_e32 v10, v169
	v_mov_b32_e32 v11, v169
	v_mov_b32_e32 v12, v169
	v_mov_b32_e32 v13, v169
	v_mov_b32_e32 v14, v169
	v_mov_b32_e32 v15, v169
	v_mov_b32_e32 v16, 0
	v_mov_b32_e32 v17, v169
	v_mov_b32_e32 v18, v169
	v_mov_b32_e32 v19, v169
	v_mov_b32_e32 v20, v169
	v_mov_b32_e32 v21, v169
	v_mov_b32_e32 v22, v169
	v_mov_b32_e32 v23, v169
	v_mov_b32_e32 v24, v169
	v_mov_b32_e32 v25, v169
	v_mov_b32_e32 v26, v169
	v_mov_b32_e32 v27, v169
	v_mov_b32_e32 v28, v169
	v_mov_b32_e32 v29, v169
	v_mov_b32_e32 v30, v169
	v_mov_b32_e32 v31, v169
	v_mov_b32_e32 v34, v169
	v_mov_b32_e32 v35, v169
	v_mov_b32_e32 v38, v169
	v_mov_b32_e32 v39, v169
	v_mov_b32_e32 v42, v169
	v_mov_b32_e32 v43, v169
	v_mov_b32_e32 v46, v169
	v_mov_b32_e32 v47, v169
	v_mov_b32_e32 v56, v169
	v_mov_b32_e32 v57, v169
	v_mov_b32_e32 v58, v169
	v_mov_b32_e32 v59, v169
	v_mov_b32_e32 v60, v169
	v_mov_b32_e32 v61, v169
	v_mov_b32_e32 v82, v169
	v_mov_b32_e32 v83, v169
	v_mov_b32_e32 v84, v169
	v_mov_b32_e32 v85, v169
	v_mov_b32_e32 v86, v169
	v_mov_b32_e32 v87, v169
	v_mov_b32_e32 v88, v169
	v_mov_b32_e32 v89, v169
	v_mov_b32_e32 v90, v169
	v_mov_b32_e32 v91, v169
	v_mov_b32_e32 v92, v169
	v_mov_b32_e32 v93, v169
	v_mov_b32_e32 v94, v169
	v_mov_b32_e32 v95, v169
	v_mov_b32_e32 v96, 0
	v_mov_b32_e32 v97, v169
	v_mov_b32_e32 v98, v169
	v_mov_b32_e32 v99, v169
	v_mov_b32_e32 v100, v169
	v_mov_b32_e32 v101, v169
	v_mov_b32_e32 v102, v169
	v_mov_b32_e32 v103, v169
	v_mov_b32_e32 v104, v169
	v_mov_b32_e32 v105, v169
	v_mov_b32_e32 v106, v169
	v_mov_b32_e32 v107, v169
	v_mov_b32_e32 v108, v169
	v_mov_b32_e32 v109, v169
	v_mov_b32_e32 v110, v169
	v_mov_b32_e32 v111, v169
	v_mov_b32_e32 v112, 0
	v_mov_b32_e32 v113, v169
	v_mov_b32_e32 v114, v169
	v_mov_b32_e32 v115, v169
	v_mov_b32_e32 v116, v169
	v_mov_b32_e32 v117, v169
	v_mov_b32_e32 v118, v169
	v_mov_b32_e32 v119, v169
	v_mov_b32_e32 v120, v169
	v_mov_b32_e32 v121, v169
	v_mov_b32_e32 v122, v169
	v_mov_b32_e32 v123, v169
	v_mov_b32_e32 v124, v169
	v_mov_b32_e32 v125, v169
	v_mov_b32_e32 v126, v169
	v_mov_b32_e32 v127, v169
	s_waitcnt lgkmcnt(0)
	s_barrier
	s_branch .LBB0_969

; __device__ __forceinline__ float lo16(unsigned w) { return __uint_as_float(w << 16); }
; __device__ __forceinline__ float hi16(unsigned w) { return __uint_as_float(w & 0xffff0000u); }
; template <int AMODE, int BN, class Epi>
; __device__ __forceinline__ void gemm_tile(const bf16_t* A, const int lda, const bf16_t* Bt, const int K, const int m0, const float* mu, char* lds, const Epi& epi) {
;     ...
; #pragma unroll
;       for (int i = 0; i < 4; ++i) {
;         *(bf16x8*)(base + (srow + 64 * i) * G_LDT + scc * 2) = ra[i];
;         if constexpr (AMODE == 2) {
;           const u32x4 hc = *(const u32x4*)&ra[i];
; #pragma unroll
;           for (int q = 0; q < 4; ++q) { const float c0 = lo16(hc[q]), c1 = hi16(hc[q]); ssq[i] += c0 * c0 + c1 * c1; }
;         }
;       }
;     ...
;   for (int kt = 0; kt < nk; ++kt) {
;     const int s = kt & 1;
;     if (kt + 1 < nk) lstore(s ^ 1, (kt + 1) * 64);
.LBB0_969:
	s_and_b32 s17, s6, 1
	s_cmp_gt_u32 s6, 2
	s_cbranch_scc1 .LBB0_971
	s_waitcnt vmcnt(6)
	v_and_b32_e32 v235, 0xffff0000, v132
	v_and_b32_e32 v234, 0xffff0000, v128
	v_lshlrev_b32_e32 v227, 16, v132
	v_lshlrev_b32_e32 v226, 16, v128
	v_mul_f32_e64 v234, v234, v234
	v_mul_f32_e64 v235, v235, v235
	s_xor_b32 s18, s17, 1
	v_fma_f32 v226, v226, v226, v234
	v_fma_f32 v227, v227, v227, v235
	v_and_b32_e32 v235, 0xffff0000, v133
	v_and_b32_e32 v234, 0xffff0000, v129
	v_add_f32_e64 v200, v200, v226
	v_add_f32_e64 v201, v201, v227
	v_lshlrev_b32_e32 v227, 16, v133
	v_lshlrev_b32_e32 v226, 16, v129
	v_mul_f32_e64 v234, v234, v234
	v_mul_f32_e64 v235, v235, v235
	s_mul_i32 s18, s18, 0x12000
	v_fma_f32 v226, v226, v226, v234
	v_fma_f32 v227, v227, v227, v235
	v_and_b32_e32 v235, 0xffff0000, v134
	v_and_b32_e32 v234, 0xffff0000, v130
	v_add_f32_e64 v200, v226, v200
	v_add_f32_e64 v201, v227, v201
	v_lshlrev_b32_e32 v227, 16, v134
	v_lshlrev_b32_e32 v226, 16, v130
	v_mul_f32_e64 v234, v234, v234
	v_mul_f32_e64 v235, v235, v235
	v_add_u32_e32 v181, s18, v212
	v_fma_f32 v226, v226, v226, v234
	v_fma_f32 v227, v227, v227, v235
	v_and_b32_e32 v235, 0xffff0000, v135
	v_and_b32_e32 v234, 0xffff0000, v131
	v_add_f32_e64 v200, v226, v200
	v_add_f32_e64 v201, v227, v201
	v_lshlrev_b32_e32 v227, 16, v135
	v_lshlrev_b32_e32 v226, 16, v131
	v_mul_f32_e64 v234, v234, v234
	v_mul_f32_e64 v235, v235, v235
	ds_write_b128 v181, v[128:131]
	ds_write_b128 v181, v[132:135] offset:9216
	v_fma_f32 v226, v226, v226, v234
	v_fma_f32 v227, v227, v227, v235
	s_waitcnt vmcnt(4)
	v_and_b32_e32 v235, 0xffff0000, v140
	v_and_b32_e32 v234, 0xffff0000, v136
	v_add_f32_e64 v200, v226, v200
	v_add_f32_e64 v201, v227, v201
	v_lshlrev_b32_e32 v227, 16, v140
	v_lshlrev_b32_e32 v226, 16, v136
	v_mul_f32_e64 v234, v234, v234
	v_mul_f32_e64 v235, v235, v235
	ds_write_b128 v181, v[136:139] offset:18432
	ds_write_b128 v181, v[140:143] offset:27648
	v_fma_f32 v226, v226, v226, v234
	v_fma_f32 v227, v227, v227, v235
	v_and_b32_e32 v235, 0xffff0000, v141
	v_and_b32_e32 v234, 0xffff0000, v137
	v_add_f32_e64 v198, v198, v226
	v_add_f32_e64 v199, v199, v227
	v_lshlrev_b32_e32 v227, 16, v141
	v_lshlrev_b32_e32 v226, 16, v137
	v_mul_f32_e64 v234, v234, v234
	v_mul_f32_e64 v235, v235, v235
	s_waitcnt vmcnt(3)
	ds_write_b128 v181, v[144:147] offset:36864
	s_waitcnt vmcnt(2)
	ds_write_b128 v181, v[148:151] offset:46080
	s_waitcnt vmcnt(1)
	ds_write_b128 v181, v[152:155] offset:55296
	s_waitcnt vmcnt(0)
	ds_write_b128 v181, v[156:159] offset:64512
	v_fma_f32 v226, v226, v226, v234
	v_fma_f32 v227, v227, v227, v235
	v_and_b32_e32 v235, 0xffff0000, v142
	v_and_b32_e32 v234, 0xffff0000, v138
	v_add_f32_e64 v198, v226, v198
	v_add_f32_e64 v199, v227, v199
	v_lshlrev_b32_e32 v227, 16, v142
	v_lshlrev_b32_e32 v226, 16, v138
	v_mul_f32_e64 v234, v234, v234
	v_mul_f32_e64 v235, v235, v235
	s_nop 0
	v_fma_f32 v226, v226, v226, v234
	v_fma_f32 v227, v227, v227, v235
	v_and_b32_e32 v235, 0xffff0000, v143
	v_and_b32_e32 v234, 0xffff0000, v139
	v_add_f32_e64 v198, v226, v198
	v_add_f32_e64 v199, v227, v199
	v_lshlrev_b32_e32 v227, 16, v143
	v_lshlrev_b32_e32 v226, 16, v139
	v_mul_f32_e64 v234, v234, v234
	v_mul_f32_e64 v235, v235, v235
	s_nop 0
	v_fma_f32 v226, v226, v226, v234
	v_fma_f32 v227, v227, v227, v235
	s_nop 0
	v_add_f32_e64 v198, v226, v198
	v_add_f32_e64 v199, v227, v199

;   __device__ __forceinline__ bool next(int& o) { if (idx >= count) return false; o = start + idx; idx += step; return true; }
;   __device__ __forceinline__ void operator()(int lrow, int nc, const f32x16& a0, const f32x16& a1, float) const {
;     const int lane = threadIdx.x & 63, wid = threadIdx.x >> 6, r32 = lane & 31, hi = lane >> 5;
;     float* sp = (float*)(scr + wid * (32 * 272));
; #pragma unroll
;     for (int g = 0; g < 4; ++g) {
;       const f32x4 v0 = {a0[4 * g], a0[4 * g + 1], a0[4 * g + 2], a0[4 * g + 3]}, v1 = {a1[4 * g], a1[4 * g + 1], a1[4 * g + 2], a1[4 * g + 3]};
;       *(f32x4*)(sp + r32 * 68 + 4 * hi + 8 * g) = v0; *(f32x4*)(sp + r32 * 68 + 32 + 4 * hi + 8 * g) = v1;
;     }
;     asm volatile("s_waitcnt lgkmcnt(0)" ::: "memory");
;     const int c4 = (lane & 15) * 4, colg = n0 + (nc & ~7) + c4;
;     const size_t rbase = (size_t)(lrow - r32) * 1024 + colg;
;     const f32x4 gv = *(const f32x4*)(gvec + colg);
;     f32x4 xv[8];
; #pragma unroll
;     for (int i = 0; i < 8; ++i) xv[i] = *(const f32x4*)(xin + rbase + (size_t)((lane >> 4) + 4 * i) * 1024);
;     asm volatile("" ::: "memory");
; #pragma unroll
;     for (int i = 0; i < 8; ++i) {
;       const int row = (lane >> 4) + 4 * i;
;       const f32x4 av = *(const f32x4*)(sp + row * 68 + c4);
;       f32x4 r; r[0] = xv[i][0] + gv[0] * av[0]; r[1] = xv[i][1] + gv[1] * av[1]; r[2] = xv[i][2] + gv[2] * av[2]; r[3] = xv[i][3] + gv[3] * av[3];
;       *(f32x4*)(xout + rbase + (size_t)row * 1024) = r;
;     }
;     asm volatile("s_waitcnt lgkmcnt(0)" ::: "memory");
;   }
; __global__ __launch_bounds__(NTHR, 1) void fwd_megakernel(Params p) {
;     ...
;     while (wk.next(o)) {
;       int mt2, nt; tile_mn(o, 4, mt2, nt);
;       const int b = mt2 >> 5, t0 = (mt2 & 31) * 256, m0 = b * TL + t0;
;       const size_t orow = (size_t)b * T + t0;
;       EpiResid e; e.xin = p.out + orow * 1024; e.xout = p.out + orow * 1024; e.gvec = mod + (size_t)(9 + b) * 3072 + 2048; e.n0 = nt * 256; e.scr = lds + G_EPI_SCR;
;       gemm_tile<0, 256>(A, 1024, W + (size_t)nt * 256 * 1024, 1024, m0, nullptr, lds, e);
;     }
.LBB0_1032:
	s_ashr_i32 s11, s10, 31
	s_lshl_b64 s[12:13], s[10:11], 25
	s_add_u32 s9, s84, s12
	s_addc_u32 s13, s85, s13
	s_add_i32 s10, s10, 9
	s_mul_hi_i32 s11, s10, 0x3000
	s_mulk_i32 s10, 0x3000
	s_add_u32 s10, s38, s10
	s_addc_u32 s11, s39, s11
	s_lshl_b32 s12, s25, 12
	ds_write_b128 v211, v[112:115]
	ds_write_b128 v211, v[96:99] offset:128
	ds_write_b128 v211, v[116:119] offset:32
	ds_write_b128 v211, v[100:103] offset:160
	ds_write_b128 v211, v[120:123] offset:64
	ds_write_b128 v211, v[104:107] offset:192
	ds_write_b128 v211, v[124:127] offset:96
	ds_write_b128 v211, v[108:111] offset:224
	v_lshl_or_b32 v96, s8, 8, v212
	s_add_u32 s12, s9, s12
	v_ashrrev_i32_e32 v97, 31, v96
	s_addc_u32 s13, s13, 0
	v_lshlrev_b64 v[98:99], 2, v[96:97]
	v_lshl_add_u64 v[96:97], s[10:11], 0, v[98:99]
	v_lshl_add_u64 v[98:99], s[12:13], 0, v[98:99]
	v_add_co_u32_e32 v96, vcc, s14, v96
	v_lshl_add_u64 v[98:99], v[98:99], 0, v[168:169]
	v_mov_b32_e32 v183, v169
	v_addc_co_u32_e32 v97, vcc, 0, v97, vcc
	s_waitcnt vmcnt(2)
	v_lshl_add_u64 v[132:133], v[98:99], 0, v[182:183]
	v_add_co_u32_e32 v108, vcc, s15, v132
	s_waitcnt lgkmcnt(0)
	global_load_dwordx4 v[100:103], v[96:97], off
	s_nop 0
	v_addc_co_u32_e32 v109, vcc, 0, v133, vcc
	v_add_co_u32_e32 v112, vcc, s19, v132
	global_load_dwordx4 v[104:107], v[132:133], off
	s_nop 0
	global_load_dwordx4 v[108:111], v[108:109], off
	v_addc_co_u32_e32 v113, vcc, 0, v133, vcc
	v_add_co_u32_e32 v116, vcc, s20, v132
	global_load_dwordx4 v[112:115], v[112:113], off
	s_nop 0
	v_addc_co_u32_e32 v117, vcc, 0, v133, vcc
	global_load_dwordx4 v[116:119], v[116:117], off
	v_add_co_u32_e32 v120, vcc, s21, v132
	v_mov_b32_e32 v165, v169
	s_nop 0
	v_addc_co_u32_e32 v121, vcc, 0, v133, vcc
	v_add_co_u32_e32 v124, vcc, s22, v132
	global_load_dwordx4 v[120:123], v[120:121], off
	s_nop 0
	v_addc_co_u32_e32 v125, vcc, 0, v133, vcc
	global_load_dwordx4 v[124:127], v[124:125], off
	v_add_co_u32_e32 v128, vcc, s23, v132
	v_mov_b32_e32 v185, v169
	s_nop 0
	v_addc_co_u32_e32 v129, vcc, 0, v133, vcc
	v_add_co_u32_e32 v132, vcc, s24, v132
	global_load_dwordx4 v[128:131], v[128:129], off
	s_nop 0
	v_addc_co_u32_e32 v133, vcc, 0, v133, vcc
	global_load_dwordx4 v[132:135], v[132:133], off
	ds_read_b128 v[136:139], v213
	s_waitcnt vmcnt(10)
	ds_read_b128 v[140:143], v213 offset:1088
	ds_read_b128 v[144:147], v213 offset:2176
	s_waitcnt vmcnt(9)
	ds_read_b128 v[148:151], v213 offset:3264
	ds_read_b128 v[152:155], v213 offset:4352
	v_lshl_add_u64 v[156:157], v[98:99], 0, v[164:165]
	v_mov_b32_e32 v187, v169
	v_mov_b32_e32 v189, v169
	v_lshl_add_u64 v[158:159], v[98:99], 0, v[184:185]
	v_lshl_add_u64 v[198:199], v[98:99], 0, v[186:187]
	v_lshl_add_u64 v[200:201], v[98:99], 0, v[188:189]
	v_mov_b32_e32 v191, v169
	v_mov_b32_e32 v193, v169
	v_mov_b32_e32 v195, v169
	v_mov_b32_e32 v197, v169
	s_add_i32 s9, s1, s0
	s_cmpk_lt_u32 s1, 0x80
	s_cselect_b64 s[10:11], -1, 0
	s_waitcnt vmcnt(7) lgkmcnt(4)
	v_fma_f32 v106, v102, v138, v106
	v_fma_f32 v107, v103, v139, v107
	v_fma_f32 v104, v100, v136, v104
	v_fma_f32 v105, v101, v137, v105
	global_store_dwordx4 v[156:157], v[104:107], off
	s_waitcnt vmcnt(7) lgkmcnt(3)
	s_nop 0
	v_fma_f32 v106, v102, v142, v110
	v_fma_f32 v107, v103, v143, v111
	v_fma_f32 v104, v100, v140, v108
	v_fma_f32 v105, v101, v141, v109
	s_waitcnt vmcnt(6) lgkmcnt(2)
	v_fma_f32 v110, v102, v146, v114
	v_fma_f32 v111, v103, v147, v115
	v_fma_f32 v108, v100, v144, v112
	v_fma_f32 v109, v101, v145, v113
	s_waitcnt vmcnt(5) lgkmcnt(1)
	v_fma_f32 v114, v102, v150, v118
	v_fma_f32 v115, v103, v151, v119
	v_fma_f32 v112, v100, v148, v116
	v_fma_f32 v113, v101, v149, v117
	global_store_dwordx4 v[158:159], v[104:107], off
	global_store_dwordx4 v[198:199], v[108:111], off
	global_store_dwordx4 v[200:201], v[112:115], off
	ds_read_b128 v[104:107], v213 offset:5440
	v_lshl_add_u64 v[116:117], v[98:99], 0, s[2:3]
	v_lshl_add_u64 v[112:113], v[98:99], 0, v[190:191]
	v_lshl_add_u64 v[118:119], v[116:117], 0, v[164:165]
	s_waitcnt vmcnt(7) lgkmcnt(1)
	v_fma_f32 v110, v102, v154, v122
	v_fma_f32 v111, v103, v155, v123
	v_fma_f32 v108, v100, v152, v120
	v_fma_f32 v109, v101, v153, v121
	global_store_dwordx4 v[112:113], v[108:111], off
	ds_read_b128 v[108:111], v213 offset:6528
	s_waitcnt vmcnt(7) lgkmcnt(1)
	v_fma_f32 v106, v102, v106, v126
	v_fma_f32 v107, v103, v107, v127
	v_fma_f32 v104, v100, v104, v124
	v_fma_f32 v105, v101, v105, v125
	v_lshl_add_u64 v[112:113], v[98:99], 0, v[192:193]
	global_store_dwordx4 v[112:113], v[104:107], off
	ds_read_b128 v[104:107], v213 offset:7616
	v_lshl_add_u64 v[112:113], v[98:99], 0, v[194:195]
	v_lshl_add_u64 v[120:121], v[116:117], 0, v[184:185]
	s_waitcnt vmcnt(7) lgkmcnt(1)
	v_fma_f32 v110, v102, v110, v130
	v_fma_f32 v111, v103, v111, v131
	v_fma_f32 v108, v100, v108, v128
	v_fma_f32 v109, v101, v109, v129
	global_store_dwordx4 v[112:113], v[108:111], off
	s_waitcnt vmcnt(7) lgkmcnt(0)
	v_fma_f32 v102, v102, v106, v134
	v_fma_f32 v103, v103, v107, v135
	v_fma_f32 v100, v100, v104, v132
	v_fma_f32 v101, v101, v105, v133
	v_lshl_add_u64 v[104:105], v[98:99], 0, v[196:197]
	global_store_dwordx4 v[104:105], v[100:103], off
	s_waitcnt lgkmcnt(0)
	ds_write_b128 v211, v[80:83]
	ds_write_b128 v211, v[64:67] offset:128
	ds_write_b128 v211, v[84:87] offset:32
	ds_write_b128 v211, v[68:71] offset:160
	ds_write_b128 v211, v[88:91] offset:64
	ds_write_b128 v211, v[72:75] offset:192
	ds_write_b128 v211, v[92:95] offset:96
	ds_write_b128 v211, v[76:79] offset:224
	v_lshl_add_u64 v[100:101], v[116:117], 0, v[182:183]
	s_waitcnt lgkmcnt(0)
;   __device__ __forceinline__ bool next(int& o) { if (idx >= count) return false; o = start + idx; idx += step; return true; }
;   __device__ __forceinline__ void operator()(int lrow, int nc, const f32x16& a0, const f32x16& a1, float) const {
;     const int lane = threadIdx.x & 63, wid = threadIdx.x >> 6, r32 = lane & 31, hi = lane >> 5;
;     float* sp = (float*)(scr + wid * (32 * 272));
; #pragma unroll
;     for (int g = 0; g < 4; ++g) {
;       const f32x4 v0 = {a0[4 * g], a0[4 * g + 1], a0[4 * g + 2], a0[4 * g + 3]}, v1 = {a1[4 * g], a1[4 * g + 1], a1[4 * g + 2], a1[4 * g + 3]};
;       *(f32x4*)(sp + r32 * 68 + 4 * hi + 8 * g) = v0; *(f32x4*)(sp + r32 * 68 + 32 + 4 * hi + 8 * g) = v1;
;     }
;     asm volatile("s_waitcnt lgkmcnt(0)" ::: "memory");
;     const int c4 = (lane & 15) * 4, colg = n0 + (nc & ~7) + c4;
;     const size_t rbase = (size_t)(lrow - r32) * 1024 + colg;
;     const f32x4 gv = *(const f32x4*)(gvec + colg);
;     f32x4 xv[8];
; #pragma unroll
;     for (int i = 0; i < 8; ++i) xv[i] = *(const f32x4*)(xin + rbase + (size_t)((lane >> 4) + 4 * i) * 1024);
;     asm volatile("" ::: "memory");
; #pragma unroll
;     for (int i = 0; i < 8; ++i) {
;       const int row = (lane >> 4) + 4 * i;
;       const f32x4 av = *(const f32x4*)(sp + row * 68 + c4);
;       f32x4 r; r[0] = xv[i][0] + gv[0] * av[0]; r[1] = xv[i][1] + gv[1] * av[1]; r[2] = xv[i][2] + gv[2] * av[2]; r[3] = xv[i][3] + gv[3] * av[3];
;       *(f32x4*)(xout + rbase + (size_t)row * 1024) = r;
;     }
;     asm volatile("s_waitcnt lgkmcnt(0)" ::: "memory");
;   }
; __global__ __launch_bounds__(NTHR, 1) void fwd_megakernel(Params p) {
;     ...
;     while (wk.next(o)) {
;       int mt2, nt; tile_mn(o, 4, mt2, nt);
;       const int b = mt2 >> 5, t0 = (mt2 & 31) * 256, m0 = b * TL + t0;
;       const size_t orow = (size_t)b * T + t0;
;       EpiResid e; e.xin = p.out + orow * 1024; e.xout = p.out + orow * 1024; e.gvec = mod + (size_t)(9 + b) * 3072 + 2048; e.n0 = nt * 256; e.scr = lds + G_EPI_SCR;
;       gemm_tile<0, 256>(A, 1024, W + (size_t)nt * 256 * 1024, 1024, m0, nullptr, lds, e);
;     }
	v_add_co_u32_e32 v72, vcc, s15, v100
	global_load_dwordx4 v[64:67], v[96:97], off
	s_nop 0
	v_addc_co_u32_e32 v73, vcc, 0, v101, vcc
	global_load_dwordx4 v[68:71], v[100:101], off
	s_nop 0
	global_load_dwordx4 v[72:75], v[72:73], off
	v_add_co_u32_e32 v76, vcc, s19, v100
	s_nop 1
	v_addc_co_u32_e32 v77, vcc, 0, v101, vcc
	v_add_co_u32_e32 v80, vcc, s20, v100
	global_load_dwordx4 v[76:79], v[76:77], off
	s_nop 0
	v_addc_co_u32_e32 v81, vcc, 0, v101, vcc
	global_load_dwordx4 v[80:83], v[80:81], off
	v_add_co_u32_e32 v84, vcc, s21, v100
	s_nop 1
	v_addc_co_u32_e32 v85, vcc, 0, v101, vcc
	v_add_co_u32_e32 v88, vcc, s22, v100
	global_load_dwordx4 v[84:87], v[84:85], off
	s_nop 0
	v_addc_co_u32_e32 v89, vcc, 0, v101, vcc
	global_load_dwordx4 v[88:91], v[88:89], off
	v_add_co_u32_e32 v92, vcc, s23, v100
	s_nop 1
	v_addc_co_u32_e32 v93, vcc, 0, v101, vcc
	v_add_co_u32_e32 v100, vcc, s24, v100
	global_load_dwordx4 v[92:95], v[92:93], off
	s_nop 0
	v_addc_co_u32_e32 v101, vcc, 0, v101, vcc
	global_load_dwordx4 v[100:103], v[100:101], off
	ds_read_b128 v[104:107], v213
	ds_read_b128 v[108:111], v213 offset:1088
	ds_read_b128 v[112:115], v213 offset:2176
	s_waitcnt vmcnt(7) lgkmcnt(2)
	v_fma_f32 v70, v66, v106, v70
	v_fma_f32 v71, v67, v107, v71
	v_fma_f32 v68, v64, v104, v68
	v_fma_f32 v69, v65, v105, v69
	s_waitcnt vmcnt(6) lgkmcnt(1)
	v_fma_f32 v74, v66, v110, v74
	v_fma_f32 v75, v67, v111, v75
	v_fma_f32 v72, v64, v108, v72
	v_fma_f32 v73, v65, v109, v73
	global_store_dwordx4 v[118:119], v[68:71], off
	global_store_dwordx4 v[120:121], v[72:75], off
	ds_read_b128 v[68:71], v213 offset:3264
	s_waitcnt vmcnt(7) lgkmcnt(1)
	v_fma_f32 v74, v66, v114, v78
	v_fma_f32 v75, v67, v115, v79
	v_fma_f32 v72, v64, v112, v76
	v_fma_f32 v73, v65, v113, v77
	v_lshl_add_u64 v[76:77], v[116:117], 0, v[186:187]
	global_store_dwordx4 v[76:77], v[72:75], off
	ds_read_b128 v[72:75], v213 offset:4352
	s_waitcnt vmcnt(7) lgkmcnt(1)
	v_fma_f32 v70, v66, v70, v82
	v_fma_f32 v71, v67, v71, v83
	v_fma_f32 v68, v64, v68, v80
	v_fma_f32 v69, v65, v69, v81
	v_lshl_add_u64 v[76:77], v[116:117], 0, v[188:189]
	global_store_dwordx4 v[76:77], v[68:71], off
	ds_read_b128 v[68:71], v213 offset:5440
	v_lshl_add_u64 v[76:77], v[116:117], 0, v[190:191]
	s_waitcnt vmcnt(7) lgkmcnt(1)
	v_fma_f32 v74, v66, v74, v86
	v_fma_f32 v75, v67, v75, v87
	v_fma_f32 v72, v64, v72, v84
	v_fma_f32 v73, v65, v73, v85
	global_store_dwordx4 v[76:77], v[72:75], off
	ds_read_b128 v[72:75], v213 offset:6528
	s_waitcnt vmcnt(7) lgkmcnt(1)
	v_fma_f32 v70, v66, v70, v90
	v_fma_f32 v71, v67, v71, v91
	v_fma_f32 v68, v64, v68, v88
	v_fma_f32 v69, v65, v69, v89
	v_lshl_add_u64 v[76:77], v[116:117], 0, v[192:193]
	global_store_dwordx4 v[76:77], v[68:71], off
	ds_read_b128 v[68:71], v213 offset:7616
	v_lshl_add_u64 v[76:77], v[116:117], 0, v[194:195]
	s_waitcnt vmcnt(7) lgkmcnt(1)
	v_fma_f32 v74, v66, v74, v94
	v_fma_f32 v75, v67, v75, v95
	v_fma_f32 v72, v64, v72, v92
	v_fma_f32 v73, v65, v73, v93
	global_store_dwordx4 v[76:77], v[72:75], off
	s_waitcnt vmcnt(7) lgkmcnt(0)
	v_fma_f32 v66, v66, v70, v102
	v_fma_f32 v67, v67, v71, v103
	v_fma_f32 v64, v64, v68, v100
	v_fma_f32 v65, v65, v69, v101
	v_lshl_add_u64 v[68:69], v[116:117], 0, v[196:197]
	global_store_dwordx4 v[68:69], v[64:67], off
	v_lshl_add_u64 v[76:77], v[98:99], 0, s[4:5]
	s_waitcnt lgkmcnt(0)
	ds_write_b128 v211, v[48:51]
	ds_write_b128 v211, v[32:35] offset:128
	ds_write_b128 v211, v[52:55] offset:32
	ds_write_b128 v211, v[36:39] offset:160
	ds_write_b128 v211, v[56:59] offset:64
	ds_write_b128 v211, v[40:43] offset:192
	ds_write_b128 v211, v[60:63] offset:96
	ds_write_b128 v211, v[44:47] offset:224
	v_lshl_add_u64 v[64:65], v[76:77], 0, v[182:183]
	s_waitcnt lgkmcnt(0)
	v_add_co_u32_e32 v40, vcc, s15, v64
	global_load_dwordx4 v[32:35], v[96:97], off
	global_load_dwordx4 v[36:39], v[64:65], off
	v_addc_co_u32_e32 v41, vcc, 0, v65, vcc
	global_load_dwordx4 v[40:43], v[40:41], off
	v_add_co_u32_e32 v44, vcc, s19, v64
	s_nop 1
	v_addc_co_u32_e32 v45, vcc, 0, v65, vcc
	v_add_co_u32_e32 v48, vcc, s20, v64
	global_load_dwordx4 v[44:47], v[44:45], off
	s_nop 0
	v_addc_co_u32_e32 v49, vcc, 0, v65, vcc
	global_load_dwordx4 v[48:51], v[48:49], off
	v_add_co_u32_e32 v52, vcc, s21, v64
	s_nop 1
	v_addc_co_u32_e32 v53, vcc, 0, v65, vcc
	v_add_co_u32_e32 v56, vcc, s22, v64
	global_load_dwordx4 v[52:55], v[52:53], off
	s_nop 0
	v_addc_co_u32_e32 v57, vcc, 0, v65, vcc
	global_load_dwordx4 v[56:59], v[56:57], off
	v_add_co_u32_e32 v60, vcc, s23, v64
	s_nop 1
	v_addc_co_u32_e32 v61, vcc, 0, v65, vcc
	v_add_co_u32_e32 v64, vcc, s24, v64
	global_load_dwordx4 v[60:63], v[60:61], off
	s_nop 0
	v_addc_co_u32_e32 v65, vcc, 0, v65, vcc
	global_load_dwordx4 v[64:67], v[64:65], off
	ds_read_b128 v[68:71], v213
	ds_read_b128 v[72:75], v213 offset:1088
	s_waitcnt vmcnt(7) lgkmcnt(1)
	v_fma_f32 v38, v34, v70, v38
	v_fma_f32 v39, v35, v71, v39
	v_fma_f32 v36, v32, v68, v36
	v_fma_f32 v37, v33, v69, v37
	v_lshl_add_u64 v[68:69], v[76:77], 0, v[164:165]
	global_store_dwordx4 v[68:69], v[36:39], off
	ds_read_b128 v[68:71], v213 offset:2176
	s_waitcnt vmcnt(7) lgkmcnt(1)
	v_fma_f32 v38, v34, v74, v42
	v_fma_f32 v39, v35, v75, v43
	v_fma_f32 v36, v32, v72, v40
	v_fma_f32 v37, v33, v73, v41
	v_lshl_add_u64 v[40:41], v[76:77], 0, v[184:185]
	global_store_dwordx4 v[40:41], v[36:39], off
	ds_read_b128 v[36:39], v213 offset:3264
	s_waitcnt vmcnt(7) lgkmcnt(1)
;   __device__ __forceinline__ bool next(int& o) { if (idx >= count) return false; o = start + idx; idx += step; return true; }
;   __device__ __forceinline__ void operator()(int lrow, int nc, const f32x16& a0, const f32x16& a1, float) const {
;     const int lane = threadIdx.x & 63, wid = threadIdx.x >> 6, r32 = lane & 31, hi = lane >> 5;
;     float* sp = (float*)(scr + wid * (32 * 272));
; #pragma unroll
;     for (int g = 0; g < 4; ++g) {
;       const f32x4 v0 = {a0[4 * g], a0[4 * g + 1], a0[4 * g + 2], a0[4 * g + 3]}, v1 = {a1[4 * g], a1[4 * g + 1], a1[4 * g + 2], a1[4 * g + 3]};
;       *(f32x4*)(sp + r32 * 68 + 4 * hi + 8 * g) = v0; *(f32x4*)(sp + r32 * 68 + 32 + 4 * hi + 8 * g) = v1;
;     }
;     asm volatile("s_waitcnt lgkmcnt(0)" ::: "memory");
;     const int c4 = (lane & 15) * 4, colg = n0 + (nc & ~7) + c4;
;     const size_t rbase = (size_t)(lrow - r32) * 1024 + colg;
;     const f32x4 gv = *(const f32x4*)(gvec + colg);
;     f32x4 xv[8];
; #pragma unroll
;     for (int i = 0; i < 8; ++i) xv[i] = *(const f32x4*)(xin + rbase + (size_t)((lane >> 4) + 4 * i) * 1024);
;     asm volatile("" ::: "memory");
; #pragma unroll
;     for (int i = 0; i < 8; ++i) {
;       const int row = (lane >> 4) + 4 * i;
;       const f32x4 av = *(const f32x4*)(sp + row * 68 + c4);
;       f32x4 r; r[0] = xv[i][0] + gv[0] * av[0]; r[1] = xv[i][1] + gv[1] * av[1]; r[2] = xv[i][2] + gv[2] * av[2]; r[3] = xv[i][3] + gv[3] * av[3];
;       *(f32x4*)(xout + rbase + (size_t)row * 1024) = r;
;     }
;     asm volatile("s_waitcnt lgkmcnt(0)" ::: "memory");
;   }
; __global__ __launch_bounds__(NTHR, 1) void fwd_megakernel(Params p) {
;     ...
;     while (wk.next(o)) {
;       int mt2, nt; tile_mn(o, 4, mt2, nt);
;       const int b = mt2 >> 5, t0 = (mt2 & 31) * 256, m0 = b * TL + t0;
;       const size_t orow = (size_t)b * T + t0;
;       EpiResid e; e.xin = p.out + orow * 1024; e.xout = p.out + orow * 1024; e.gvec = mod + (size_t)(9 + b) * 3072 + 2048; e.n0 = nt * 256; e.scr = lds + G_EPI_SCR;
;       gemm_tile<0, 256>(A, 1024, W + (size_t)nt * 256 * 1024, 1024, m0, nullptr, lds, e);
;     }
	v_fma_f32 v42, v34, v70, v46
	v_fma_f32 v43, v35, v71, v47
	v_fma_f32 v40, v32, v68, v44
	v_fma_f32 v41, v33, v69, v45
	v_lshl_add_u64 v[44:45], v[76:77], 0, v[186:187]
	global_store_dwordx4 v[44:45], v[40:43], off
	s_waitcnt vmcnt(7) lgkmcnt(0)
	v_fma_f32 v38, v34, v38, v50
	v_fma_f32 v39, v35, v39, v51
	ds_read_b128 v[40:43], v213 offset:4352
	v_fma_f32 v36, v32, v36, v48
	v_fma_f32 v37, v33, v37, v49
	v_lshl_add_u64 v[44:45], v[76:77], 0, v[188:189]
	global_store_dwordx4 v[44:45], v[36:39], off
	ds_read_b128 v[36:39], v213 offset:5440
	v_lshl_add_u64 v[44:45], v[76:77], 0, v[190:191]
	s_waitcnt vmcnt(7) lgkmcnt(1)
	v_fma_f32 v42, v34, v42, v54
	v_fma_f32 v43, v35, v43, v55
	v_fma_f32 v40, v32, v40, v52
	v_fma_f32 v41, v33, v41, v53
	global_store_dwordx4 v[44:45], v[40:43], off
	s_waitcnt vmcnt(7) lgkmcnt(0)
	v_fma_f32 v38, v34, v38, v58
	v_fma_f32 v39, v35, v39, v59
	v_fma_f32 v36, v32, v36, v56
	v_fma_f32 v37, v33, v37, v57
	v_lshl_add_u64 v[44:45], v[76:77], 0, v[192:193]
	ds_read_b128 v[40:43], v213 offset:6528
	global_store_dwordx4 v[44:45], v[36:39], off
	ds_read_b128 v[36:39], v213 offset:7616
	v_lshl_add_u64 v[44:45], v[76:77], 0, v[194:195]
	s_waitcnt vmcnt(7) lgkmcnt(1)
	v_fma_f32 v42, v34, v42, v62
	v_fma_f32 v43, v35, v43, v63
	v_fma_f32 v40, v32, v40, v60
	v_fma_f32 v41, v33, v41, v61
	global_store_dwordx4 v[44:45], v[40:43], off
	s_waitcnt vmcnt(7) lgkmcnt(0)
	v_fma_f32 v34, v34, v38, v66
	v_fma_f32 v35, v35, v39, v67
	v_fma_f32 v32, v32, v36, v64
	v_fma_f32 v33, v33, v37, v65
	v_lshl_add_u64 v[36:37], v[76:77], 0, v[196:197]
	global_store_dwordx4 v[36:37], v[32:35], off
	v_lshl_add_u64 v[44:45], v[98:99], 0, s[6:7]
	s_waitcnt lgkmcnt(0)
	ds_write_b128 v211, v[16:19]
	ds_write_b128 v211, v[0:3] offset:128
	ds_write_b128 v211, v[20:23] offset:32
	ds_write_b128 v211, v[4:7] offset:160
	ds_write_b128 v211, v[24:27] offset:64
	ds_write_b128 v211, v[8:11] offset:192
	ds_write_b128 v211, v[28:31] offset:96
	ds_write_b128 v211, v[12:15] offset:224
	v_lshl_add_u64 v[32:33], v[44:45], 0, v[182:183]
	s_waitcnt lgkmcnt(0)
	v_add_co_u32_e32 v8, vcc, s15, v32
	global_load_dwordx4 v[0:3], v[96:97], off
	global_load_dwordx4 v[4:7], v[32:33], off
	v_addc_co_u32_e32 v9, vcc, 0, v33, vcc
	global_load_dwordx4 v[8:11], v[8:9], off
	v_add_co_u32_e32 v12, vcc, s19, v32
	s_nop 1
	v_addc_co_u32_e32 v13, vcc, 0, v33, vcc
	v_add_co_u32_e32 v16, vcc, s20, v32
	global_load_dwordx4 v[12:15], v[12:13], off
	s_nop 0
	v_addc_co_u32_e32 v17, vcc, 0, v33, vcc
	global_load_dwordx4 v[16:19], v[16:17], off
	v_add_co_u32_e32 v20, vcc, s21, v32
	s_nop 1
	v_addc_co_u32_e32 v21, vcc, 0, v33, vcc
	v_add_co_u32_e32 v24, vcc, s22, v32
	global_load_dwordx4 v[20:23], v[20:21], off
	s_nop 0
	v_addc_co_u32_e32 v25, vcc, 0, v33, vcc
	global_load_dwordx4 v[24:27], v[24:25], off
	v_add_co_u32_e32 v28, vcc, s23, v32
	s_nop 1
	v_addc_co_u32_e32 v29, vcc, 0, v33, vcc
	v_add_co_u32_e32 v32, vcc, s24, v32
	global_load_dwordx4 v[28:31], v[28:29], off
	s_nop 0
	v_addc_co_u32_e32 v33, vcc, 0, v33, vcc
	global_load_dwordx4 v[32:35], v[32:33], off
	ds_read_b128 v[36:39], v213
	ds_read_b128 v[40:43], v213 offset:1088
	s_and_b64 vcc, s[10:11], exec
	s_cselect_b32 s8, s33, 0
	s_add_i32 s1, s8, s1
	s_waitcnt vmcnt(7) lgkmcnt(1)
	v_fma_f32 v6, v2, v38, v6
	v_fma_f32 v7, v3, v39, v7
	v_fma_f32 v4, v0, v36, v4
	v_fma_f32 v5, v1, v37, v5
	v_lshl_add_u64 v[36:37], v[44:45], 0, v[164:165]
	global_store_dwordx4 v[36:37], v[4:7], off
	ds_read_b128 v[36:39], v213 offset:2176
	s_waitcnt vmcnt(7) lgkmcnt(1)
	v_fma_f32 v6, v2, v42, v10
	v_fma_f32 v7, v3, v43, v11
	v_fma_f32 v4, v0, v40, v8
	v_fma_f32 v5, v1, v41, v9
	v_lshl_add_u64 v[8:9], v[44:45], 0, v[184:185]
	global_store_dwordx4 v[8:9], v[4:7], off
	ds_read_b128 v[4:7], v213 offset:3264
	s_waitcnt vmcnt(7) lgkmcnt(1)
	v_fma_f32 v10, v2, v38, v14
	v_fma_f32 v11, v3, v39, v15
	v_fma_f32 v8, v0, v36, v12
	v_fma_f32 v9, v1, v37, v13
	v_lshl_add_u64 v[12:13], v[44:45], 0, v[186:187]
	global_store_dwordx4 v[12:13], v[8:11], off
	s_waitcnt vmcnt(7) lgkmcnt(0)
	v_fma_f32 v6, v2, v6, v18
	v_fma_f32 v7, v3, v7, v19
	ds_read_b128 v[8:11], v213 offset:4352
	v_fma_f32 v4, v0, v4, v16
	v_fma_f32 v5, v1, v5, v17
	v_lshl_add_u64 v[12:13], v[44:45], 0, v[188:189]
	global_store_dwordx4 v[12:13], v[4:7], off
	ds_read_b128 v[4:7], v213 offset:5440
	v_lshl_add_u64 v[12:13], v[44:45], 0, v[190:191]
	s_waitcnt vmcnt(7) lgkmcnt(1)
	v_fma_f32 v10, v2, v10, v22
	v_fma_f32 v11, v3, v11, v23
	v_fma_f32 v8, v0, v8, v20
	v_fma_f32 v9, v1, v9, v21
	global_store_dwordx4 v[12:13], v[8:11], off
	s_waitcnt vmcnt(7) lgkmcnt(0)
	v_fma_f32 v6, v2, v6, v26
	v_fma_f32 v7, v3, v7, v27
	v_fma_f32 v4, v0, v4, v24
	v_fma_f32 v5, v1, v5, v25
	v_lshl_add_u64 v[12:13], v[44:45], 0, v[192:193]
	ds_read_b128 v[8:11], v213 offset:6528
	global_store_dwordx4 v[12:13], v[4:7], off
	ds_read_b128 v[4:7], v213 offset:7616
	v_lshl_add_u64 v[12:13], v[44:45], 0, v[194:195]
	s_waitcnt vmcnt(7) lgkmcnt(1)
	v_fma_f32 v10, v2, v10, v30
	v_fma_f32 v11, v3, v11, v31
	v_fma_f32 v8, v0, v8, v28
	v_fma_f32 v9, v1, v9, v29
	global_store_dwordx4 v[12:13], v[8:11], off
	s_waitcnt vmcnt(7) lgkmcnt(0)
	v_fma_f32 v2, v2, v6, v34
	v_fma_f32 v3, v3, v7, v35
	v_fma_f32 v0, v0, v4, v32
	v_fma_f32 v1, v1, v5, v33
	v_lshl_add_u64 v[4:5], v[44:45], 0, v[196:197]
	global_store_dwordx4 v[4:5], v[0:3], off
	s_waitcnt lgkmcnt(0)
	s_cbranch_vccz .LBB0_1039

; __device__ void phase_final(float* out, const float* fg) {
;     ...
;     float ss = 0.f;
; #pragma unroll
;     for (int i = 0; i < 4; ++i) ss += va[i][0] * va[i][0] + va[i][1] * va[i][1] + va[i][2] * va[i][2] + va[i][3] * va[i][3];
;     ss = wave_sum(ss);
;     const float rstd = rsqrtf(ss * (1.f / 1024.f) + 1e-6f);
; #pragma unroll
;     for (int i = 0; i < 4; ++i) {
;       f32x4 o;
; #pragma unroll
;       for (int e = 0; e < 4; ++e) o[e] = va[i][e] * rstd * g4[i][e];
;       *(f32x4*)(out + (size_t)n * D + i * 256 + lane * 4) = o;
;     }
; #pragma unroll
;     for (int i = 0; i < 4; ++i) va[i] = vb[i];
.LBB0_1051:
	s_or_b64 exec, exec, s[6:7]
	s_waitcnt vmcnt(2)
	v_mov_b32_e32 v62, v25
	v_mov_b32_e32 v63, v29
	v_mov_b32_e32 v60, v24
	v_mov_b32_e32 v61, v28
	v_mul_f32_e64 v62, v62, v62
	v_mul_f32_e64 v63, v63, v63
	s_waitcnt vmcnt(0)
	v_mov_b32_e32 v64, v17
	v_fma_f32 v60, v60, v60, v62
	v_fma_f32 v61, v61, v61, v63
	v_mov_b32_e32 v62, v26
	v_mov_b32_e32 v63, v30
	v_fma_f32 v60, v62, v62, v60
	v_fma_f32 v61, v63, v63, v61
	v_mov_b32_e32 v62, v27
	v_mov_b32_e32 v63, v31
	v_mov_b32_e32 v65, v21
	v_fma_f32 v60, v62, v62, v60
	v_fma_f32 v61, v63, v63, v61
	v_mov_b32_e32 v62, v16
	v_mov_b32_e32 v63, v20
	v_mul_f32_e64 v64, v64, v64
	v_mul_f32_e64 v65, v65, v65
	v_add_f32_e32 v59, v60, v61
	v_fma_f32 v62, v62, v62, v64
	v_fma_f32 v63, v63, v63, v65
	v_mov_b32_e32 v64, v18
	v_mov_b32_e32 v65, v22
	v_fma_f32 v62, v64, v64, v62
	v_fma_f32 v63, v65, v65, v63
	v_mov_b32_e32 v64, v19
	v_mov_b32_e32 v65, v23
	v_fma_f32 v62, v64, v64, v62
	v_fma_f32 v63, v65, v65, v63
	s_and_b64 s[6:7], exec, vcc
	v_add_f32_e32 v59, v63, v59
	v_add_f32_e32 v59, v62, v59
	ds_bpermute_b32 v60, v52, v59
	s_or_b64 s[4:5], s[6:7], s[4:5]
	v_lshl_add_u64 v[50:51], v[50:51], 0, s[2:3]
	s_waitcnt lgkmcnt(0)
	v_add_f32_e32 v59, v59, v60
	ds_bpermute_b32 v60, v53, v59
	s_waitcnt lgkmcnt(0)
	v_add_f32_e32 v59, v59, v60
	ds_bpermute_b32 v60, v54, v59
	s_waitcnt lgkmcnt(0)
	v_add_f32_e32 v59, v59, v60
	ds_bpermute_b32 v60, v55, v59
	s_waitcnt lgkmcnt(0)
	v_add_f32_e32 v59, v59, v60
	ds_bpermute_b32 v60, v56, v59
	s_waitcnt lgkmcnt(0)
	v_add_f32_e32 v59, v59, v60
	ds_bpermute_b32 v60, v57, v59
	s_waitcnt lgkmcnt(0)
	v_add_f32_e32 v59, v59, v60
	v_fmamk_f32 v59, v59, 0x3a800000, v58
	v_mul_f32_e32 v60, 0x4b800000, v59
	v_cmp_gt_f32_e64 s[0:1], s10, v59
	s_nop 1
	v_cndmask_b32_e64 v59, v59, v60, s[0:1]
	v_rsq_f32_e32 v59, v59
	v_lshl_add_u64 v[60:61], v[48:49], 0, v[166:167]
	v_lshl_add_u64 v[48:49], v[48:49], 0, s[2:3]
	v_mul_f32_e32 v62, 0x45800000, v59
	v_cndmask_b32_e64 v62, v59, v62, s[0:1]
	v_mul_f32_e64 v28, v28, v62
	v_mul_f32_e64 v29, v29, v62
	v_mul_f32_e64 v30, v30, v62
	v_mul_f32_e64 v31, v31, v62
	v_mul_f32_e64 v64, v24, v62
	v_mul_f32_e64 v65, v25, v62
	v_mul_f32_e64 v66, v26, v62
	v_mul_f32_e64 v67, v27, v62
	v_mul_f32_e64 v26, v14, v30
	v_mul_f32_e64 v27, v15, v31
	v_mul_f32_e64 v24, v12, v28
	v_mul_f32_e64 v25, v13, v29
	v_mul_f32_e64 v20, v20, v62
	v_mul_f32_e64 v21, v21, v62
	v_mul_f32_e64 v22, v22, v62
	v_mul_f32_e64 v23, v23, v62
	v_mul_f32_e64 v16, v16, v62
	v_mul_f32_e64 v17, v17, v62
	v_mul_f32_e64 v18, v18, v62
	v_mul_f32_e64 v19, v19, v62
	global_store_dwordx4 v[60:61], v[24:27], off
	v_mul_f32_e64 v22, v6, v22
	v_mul_f32_e64 v23, v7, v23
	v_mul_f32_e64 v20, v4, v20
	v_mul_f32_e64 v21, v5, v21
	v_mul_f32_e64 v26, v10, v66
	v_mul_f32_e64 v27, v11, v67
	v_mul_f32_e64 v24, v8, v64
	v_mul_f32_e64 v25, v9, v65
	v_mul_f32_e64 v18, v2, v18
	v_mul_f32_e64 v19, v3, v19
	v_mul_f32_e64 v16, v0, v16
	v_mul_f32_e64 v17, v1, v17
	global_store_dwordx4 v[60:61], v[24:27], off offset:1024
	global_store_dwordx4 v[60:61], v[20:23], off offset:2048
	global_store_dwordx4 v[60:61], v[16:19], off offset:3072
	v_mov_b64_e32 v[24:25], v[40:41]
	v_mov_b64_e32 v[20:21], v[36:37]
	v_mov_b64_e32 v[16:17], v[32:33]
	v_mov_b64_e32 v[28:29], v[44:45]
	v_mov_b64_e32 v[18:19], v[34:35]
	v_mov_b64_e32 v[22:23], v[38:39]
	v_mov_b64_e32 v[26:27], v[42:43]
	v_mov_b64_e32 v[30:31], v[46:47]
	s_andn2_b64 exec, exec, s[4:5]
	s_cbranch_execz .LBB0_1054
